# residual epilogues: one hand-over barrier behind the first 16 loads (trailing wave row issues its loads while the leading row works)
# baseline (speedup 1.0000x reference)
; #define PG8_STAGE(bufoff, gbase, voff) do { _Pragma("unroll") for (int _i = 0; _i < 2; ++_i) \
;         __builtin_amdgcn_global_load_lds((const unsigned*)((const char*)(gbase) + (voff)[_i]), (LAS unsigned*)(lds + (bufoff) + ldsw + _i * 8192), 16, 0, 0); } while (0)
; #define PG8_LDA(dst, b, h) do { _Pragma("unroll") for (int m = 0; m < 4; ++m) _Pragma("unroll") for (int k = 0; k < 2; ++k) dst[m][k] = *(const LAS bf16x8*)(lds + PG8_SA(b, h) + aoff + m * 2048 + k * 1024); } while (0)
; #define PG8_LDB(dst, b, h) do { _Pragma("unroll") for (int n = 0; n < 2; ++n) _Pragma("unroll") for (int k = 0; k < 2; ++k) dst[n][k] = *(const LAS bf16x8*)(lds + PG8_SB(b, h) + boff + n * 2048 + k * 1024); } while (0)
; #define PG8_MMA(ai, bj, At, Bt) do { __builtin_amdgcn_s_setprio(1); _Pragma("unroll") for (int m = 0; m < 4; ++m) _Pragma("unroll") for (int n = 0; n < 2; ++n) _Pragma("unroll") for (int k = 0; k < 2; ++k) \
;         acc[ai][bj][m][n] = __builtin_amdgcn_mfma_f32_16x16x32_bf16(Bt[n][k], At[m][k], acc[ai][bj][m][n], 0, 0, 0); __builtin_amdgcn_s_setprio(0); } while (0)
; #define PG8_WAIT_V(n) asm volatile("s_waitcnt vmcnt(" #n ")" ::: "memory")
; #define PG8_WAIT_L(n) asm volatile("s_waitcnt lgkmcnt(" #n ")" ::: "memory")
; #define PG8_BAR __builtin_amdgcn_s_barrier()
; #define PG8_SCHED __builtin_amdgcn_sched_barrier(0)
; template <class Epi>
; __device__ __forceinline__ void gemm_phase(LAS unsigned char* lds, const Gemm g, const StaticOrder& S, const Epi& E) {
;     ...
;             PG8_LDB(B0, 0, 0); PG8_SCHED; PG8_LDA(At, 0, 0); PG8_STAGE(PG8_SA(1, 1), a1 + hstepA, voffA);
;             PG8_WAIT_L(8); PG8_BAR; PG8_WAIT_L(0); PG8_MMA(0, 0, At, B0); PG8_BAR; PG8_SCHED;
;             PG8_LDB(B1, 0, 1); PG8_STAGE(PG8_SB(0, 0), b2, voffB);
;             PG8_BAR; PG8_WAIT_L(0); PG8_MMA(0, 1, At, B1); PG8_BAR;
;             PG8_LDA(At, 0, 1); PG8_STAGE(PG8_SA(0, 0), a2, voffA);
;             PG8_BAR; PG8_WAIT_L(0); PG8_MMA(1, 0, At, B0); PG8_BAR; PG8_SCHED;
;             PG8_STAGE(PG8_SB(0, 1), b2 + hstepB, voffB);
;             PG8_WAIT_V(6); PG8_BAR; PG8_MMA(1, 1, At, B1); PG8_BAR;
.LBB0_411:
	ds_read_b128 v[140:143], v149
	ds_read_b128 v[152:155], v149 offset:1024
	ds_read_b128 v[156:159], v149 offset:2048
	ds_read_b128 v[160:163], v149 offset:3072
	s_add_u32 s28, s26, 0x100
	s_addc_u32 s29, s27, 0
	s_cmp_eq_u32 s68, 40
	s_cselect_b32 s35, s11, s29
	s_cselect_b32 s34, s10, s28
	s_cselect_b32 s31, s13, s63
	s_cselect_b32 s30, s12, s49
	v_lshl_add_u64 v[144:145], s[26:27], 0, v[132:133]
	s_add_i32 m0, s36, 0xc000
	ds_read_b128 v[164:167], v150
	ds_read_b128 v[168:171], v150 offset:1024
	ds_read_b128 v[172:175], v150 offset:2048
	ds_read_b128 v[176:179], v150 offset:3072
	ds_read_b128 v[180:183], v150 offset:4096
	ds_read_b128 v[184:187], v150 offset:5120
	ds_read_b128 v[188:191], v150 offset:6144
	ds_read_b128 v[192:195], v150 offset:7168
	global_load_lds_dwordx4 v[144:145], off
	v_lshl_add_u64 v[144:145], s[26:27], 0, v[134:135]
	s_add_i32 m0, s36, 0xe000
	s_nop 0
	global_load_lds_dwordx4 v[144:145], off
	ds_read_b128 v[196:199], v151
	ds_read_b128 v[200:203], v151 offset:1024
	ds_read_b128 v[204:207], v151 offset:2048
	ds_read_b128 v[208:211], v151 offset:3072
	s_waitcnt lgkmcnt(0)
	s_barrier
	s_setprio 1
	v_mfma_f32_16x16x32_bf16 v[124:127], v[140:143], v[164:167], v[124:127]
	v_mfma_f32_16x16x32_bf16 v[120:123], v[156:159], v[164:167], v[120:123]
	v_mfma_f32_16x16x32_bf16 v[112:115], v[140:143], v[172:175], v[112:115]
	v_mfma_f32_16x16x32_bf16 v[104:107], v[156:159], v[172:175], v[104:107]
	v_mfma_f32_16x16x32_bf16 v[92:95], v[140:143], v[180:183], v[92:95]
	v_mfma_f32_16x16x32_bf16 v[88:91], v[156:159], v[180:183], v[88:91]
	v_mfma_f32_16x16x32_bf16 v[80:83], v[140:143], v[188:191], v[80:83]
	v_mfma_f32_16x16x32_bf16 v[72:75], v[156:159], v[188:191], v[72:75]
	v_mfma_f32_16x16x32_bf16 v[124:127], v[152:155], v[168:171], v[124:127]
	v_mfma_f32_16x16x32_bf16 v[120:123], v[160:163], v[168:171], v[120:123]
	v_mfma_f32_16x16x32_bf16 v[112:115], v[152:155], v[176:179], v[112:115]
	v_mfma_f32_16x16x32_bf16 v[104:107], v[160:163], v[176:179], v[104:107]
	v_mfma_f32_16x16x32_bf16 v[92:95], v[152:155], v[184:187], v[92:95]
	v_mfma_f32_16x16x32_bf16 v[88:91], v[160:163], v[184:187], v[88:91]
	v_mfma_f32_16x16x32_bf16 v[80:83], v[152:155], v[192:195], v[80:83]
	v_mfma_f32_16x16x32_bf16 v[72:75], v[160:163], v[192:195], v[72:75]
	v_mfma_f32_16x16x32_bf16 v[116:119], v[196:199], v[164:167], v[116:119]
	v_mfma_f32_16x16x32_bf16 v[108:111], v[204:207], v[164:167], v[108:111]
	v_mfma_f32_16x16x32_bf16 v[100:103], v[196:199], v[172:175], v[100:103]
	v_mfma_f32_16x16x32_bf16 v[96:99], v[204:207], v[172:175], v[96:99]
	v_mfma_f32_16x16x32_bf16 v[84:87], v[196:199], v[180:183], v[84:87]
	v_mfma_f32_16x16x32_bf16 v[76:79], v[204:207], v[180:183], v[76:79]
	v_mfma_f32_16x16x32_bf16 v[68:71], v[196:199], v[188:191], v[68:71]
	v_mfma_f32_16x16x32_bf16 v[64:67], v[204:207], v[188:191], v[64:67]
	v_mfma_f32_16x16x32_bf16 v[116:119], v[200:203], v[168:171], v[116:119]
	v_mfma_f32_16x16x32_bf16 v[108:111], v[208:211], v[168:171], v[108:111]
	v_mfma_f32_16x16x32_bf16 v[100:103], v[200:203], v[176:179], v[100:103]
	v_mfma_f32_16x16x32_bf16 v[96:99], v[208:211], v[176:179], v[96:99]
	v_mfma_f32_16x16x32_bf16 v[84:87], v[200:203], v[184:187], v[84:87]
	v_mfma_f32_16x16x32_bf16 v[76:79], v[208:211], v[184:187], v[76:79]
	v_mfma_f32_16x16x32_bf16 v[68:71], v[200:203], v[192:195], v[68:71]
	v_mfma_f32_16x16x32_bf16 v[64:67], v[208:211], v[192:195], v[64:67]
	s_setprio 0
	s_barrier
	s_nop 1
	ds_read_b128 v[164:167], v150 offset:16384
	ds_read_b128 v[168:171], v150 offset:17408
	ds_read_b128 v[172:175], v150 offset:18432
	ds_read_b128 v[176:179], v150 offset:19456
	ds_read_b128 v[180:183], v150 offset:20480
	ds_read_b128 v[184:187], v150 offset:21504
	ds_read_b128 v[188:191], v150 offset:22528
	ds_read_b128 v[192:195], v150 offset:23552
	s_add_i32 s26, s43, s7
	v_lshl_add_u64 v[144:145], s[30:31], 0, v[128:129]
	s_mov_b32 m0, s26
	s_nop 0
	global_load_lds_dwordx4 v[144:145], off
	v_lshl_add_u64 v[212:213], s[30:31], 0, v[130:131]
	s_add_i32 m0, s26, 0x2000
	s_nop 0
	global_load_lds_dwordx4 v[212:213], off
	s_mov_b32 m0, s36
	v_lshl_add_u64 v[214:215], s[34:35], 0, v[128:129]
	global_load_lds_dwordx4 v[214:215], off
	v_lshl_add_u64 v[216:217], s[34:35], 0, v[130:131]
	s_mov_b32 m0, s37
	s_nop 0
	global_load_lds_dwordx4 v[216:217], off
	s_add_u32 s26, s30, 0xb0000
	s_addc_u32 s27, s31, 0
	s_add_i32 s69, s44, s7
	v_lshl_add_u64 v[254:255], s[26:27], 0, v[128:129]
	s_mov_b32 m0, s69
	s_nop 0
	global_load_lds_dwordx4 v[254:255], off
	v_lshl_add_u64 v[254:255], s[26:27], 0, v[130:131]
	s_add_i32 m0, s69, 0x2000
	s_nop 0
	global_load_lds_dwordx4 v[254:255], off
	s_waitcnt vmcnt(6)
	s_waitcnt lgkmcnt(0)
	s_barrier
; #define PG8_STAGE(bufoff, gbase, voff) do { _Pragma("unroll") for (int _i = 0; _i < 2; ++_i) \
;         __builtin_amdgcn_global_load_lds((const unsigned*)((const char*)(gbase) + (voff)[_i]), (LAS unsigned*)(lds + (bufoff) + ldsw + _i * 8192), 16, 0, 0); } while (0)
; #define PG8_LDA(dst, b, h) do { _Pragma("unroll") for (int m = 0; m < 4; ++m) _Pragma("unroll") for (int k = 0; k < 2; ++k) dst[m][k] = *(const LAS bf16x8*)(lds + PG8_SA(b, h) + aoff + m * 2048 + k * 1024); } while (0)
; #define PG8_LDB(dst, b, h) do { _Pragma("unroll") for (int n = 0; n < 2; ++n) _Pragma("unroll") for (int k = 0; k < 2; ++k) dst[n][k] = *(const LAS bf16x8*)(lds + PG8_SB(b, h) + boff + n * 2048 + k * 1024); } while (0)
; #define PG8_MMA(ai, bj, At, Bt) do { __builtin_amdgcn_s_setprio(1); _Pragma("unroll") for (int m = 0; m < 4; ++m) _Pragma("unroll") for (int n = 0; n < 2; ++n) _Pragma("unroll") for (int k = 0; k < 2; ++k) \
;         acc[ai][bj][m][n] = __builtin_amdgcn_mfma_f32_16x16x32_bf16(Bt[n][k], At[m][k], acc[ai][bj][m][n], 0, 0, 0); __builtin_amdgcn_s_setprio(0); } while (0)
; #define PG8_WAIT_V(n) asm volatile("s_waitcnt vmcnt(" #n ")" ::: "memory")
; #define PG8_WAIT_L(n) asm volatile("s_waitcnt lgkmcnt(" #n ")" ::: "memory")
; #define PG8_BAR __builtin_amdgcn_s_barrier()
; #define PG8_SCHED __builtin_amdgcn_sched_barrier(0)
; template <class Epi>
; __device__ __forceinline__ void gemm_phase(LAS unsigned char* lds, const Gemm g, const StaticOrder& S, const Epi& E) {
;     ...
;             PG8_BAR; PG8_WAIT_L(0); PG8_MMA(1, 0, At, B0); PG8_BAR; PG8_SCHED;
;             PG8_STAGE(PG8_SB(0, 1), b2 + hstepB, voffB);
;             PG8_WAIT_V(6); PG8_BAR; PG8_MMA(1, 1, At, B1); PG8_BAR;
;             PG8_LDB(B0, 1, 0); PG8_SCHED; PG8_LDA(At, 1, 0); PG8_STAGE(PG8_SA(0, 1), a2 + hstepA, voffA);
;             PG8_WAIT_L(8); PG8_BAR; PG8_WAIT_L(0); PG8_MMA(0, 0, At, B0); PG8_BAR; PG8_SCHED;
;             PG8_LDB(B1, 1, 1); PG8_STAGE(PG8_SB(1, 0), b3, voffB);
;             PG8_BAR; PG8_WAIT_L(0); PG8_MMA(0, 1, At, B1); PG8_BAR;
;             PG8_LDA(At, 1, 1); PG8_STAGE(PG8_SA(1, 0), a3, voffA);
;             PG8_BAR; PG8_WAIT_L(0); PG8_MMA(1, 0, At, B0); PG8_BAR; PG8_SCHED;
	s_setprio 1
	v_mfma_f32_16x16x32_bf16 v[60:63], v[140:143], v[164:167], v[60:63]
	v_mfma_f32_16x16x32_bf16 v[56:59], v[156:159], v[164:167], v[56:59]
	v_mfma_f32_16x16x32_bf16 v[48:51], v[140:143], v[172:175], v[48:51]
	v_mfma_f32_16x16x32_bf16 v[40:43], v[156:159], v[172:175], v[40:43]
	v_mfma_f32_16x16x32_bf16 v[28:31], v[140:143], v[180:183], v[28:31]
	v_mfma_f32_16x16x32_bf16 v[24:27], v[156:159], v[180:183], v[24:27]
	v_mfma_f32_16x16x32_bf16 v[16:19], v[140:143], v[188:191], v[16:19]
	v_mfma_f32_16x16x32_bf16 v[8:11], v[156:159], v[188:191], v[8:11]
	v_mfma_f32_16x16x32_bf16 v[60:63], v[152:155], v[168:171], v[60:63]
	v_mfma_f32_16x16x32_bf16 v[56:59], v[160:163], v[168:171], v[56:59]
	v_mfma_f32_16x16x32_bf16 v[48:51], v[152:155], v[176:179], v[48:51]
	v_mfma_f32_16x16x32_bf16 v[40:43], v[160:163], v[176:179], v[40:43]
	v_mfma_f32_16x16x32_bf16 v[28:31], v[152:155], v[184:187], v[28:31]
	v_mfma_f32_16x16x32_bf16 v[24:27], v[160:163], v[184:187], v[24:27]
	v_mfma_f32_16x16x32_bf16 v[16:19], v[152:155], v[192:195], v[16:19]
	v_mfma_f32_16x16x32_bf16 v[8:11], v[160:163], v[192:195], v[8:11]
	v_mfma_f32_16x16x32_bf16 v[52:55], v[196:199], v[164:167], v[52:55]
	v_mfma_f32_16x16x32_bf16 v[44:47], v[204:207], v[164:167], v[44:47]
	v_mfma_f32_16x16x32_bf16 v[36:39], v[196:199], v[172:175], v[36:39]
	v_mfma_f32_16x16x32_bf16 v[32:35], v[204:207], v[172:175], v[32:35]
	v_mfma_f32_16x16x32_bf16 v[20:23], v[196:199], v[180:183], v[20:23]
	v_mfma_f32_16x16x32_bf16 v[12:15], v[204:207], v[180:183], v[12:15]
	v_mfma_f32_16x16x32_bf16 v[4:7], v[196:199], v[188:191], v[4:7]
	v_mfma_f32_16x16x32_bf16 v[0:3], v[204:207], v[188:191], v[0:3]
	v_mfma_f32_16x16x32_bf16 v[52:55], v[200:203], v[168:171], v[52:55]
	v_mfma_f32_16x16x32_bf16 v[44:47], v[208:211], v[168:171], v[44:47]
	v_mfma_f32_16x16x32_bf16 v[36:39], v[200:203], v[176:179], v[36:39]
	v_mfma_f32_16x16x32_bf16 v[32:35], v[208:211], v[176:179], v[32:35]
	v_mfma_f32_16x16x32_bf16 v[20:23], v[200:203], v[184:187], v[20:23]
	v_mfma_f32_16x16x32_bf16 v[12:15], v[208:211], v[184:187], v[12:15]
	v_mfma_f32_16x16x32_bf16 v[4:7], v[200:203], v[192:195], v[4:7]
	v_mfma_f32_16x16x32_bf16 v[0:3], v[208:211], v[192:195], v[0:3]
	s_setprio 0
	s_add_i32 s69, 0, 0x18000
	v_add_u32_e32 v160, s69, v147
	s_barrier
	ds_read_b128 v[140:143], v160
	ds_read_b128 v[152:155], v160 offset:1024
	ds_read_b128 v[156:159], v160 offset:2048
	ds_read_b128 v[160:163], v160 offset:3072
	s_add_u32 s26, s34, 0xb0000
	s_addc_u32 s27, s35, 0
	s_mov_b32 m0, s38
	v_lshl_add_u64 v[196:197], s[26:27], 0, v[128:129]
	ds_read_b128 v[164:167], v150 offset:32768
	ds_read_b128 v[168:171], v150 offset:33792
	ds_read_b128 v[172:175], v150 offset:34816
	ds_read_b128 v[176:179], v150 offset:35840
	ds_read_b128 v[180:183], v150 offset:36864
	ds_read_b128 v[184:187], v150 offset:37888
	ds_read_b128 v[188:191], v150 offset:38912
	ds_read_b128 v[192:195], v150 offset:39936
	global_load_lds_dwordx4 v[196:197], off
	v_lshl_add_u64 v[196:197], s[26:27], 0, v[130:131]
	s_mov_b32 m0, s39
	s_nop 0
	global_load_lds_dwordx4 v[196:197], off
	s_add_i32 s34, 0, 0x1c000
	v_add_u32_e32 v208, s34, v147
	ds_read_b128 v[196:199], v208
	ds_read_b128 v[200:203], v208 offset:1024
	ds_read_b128 v[204:207], v208 offset:2048
	ds_read_b128 v[208:211], v208 offset:3072
	s_waitcnt lgkmcnt(0)
	s_barrier
	s_setprio 1
	v_mfma_f32_16x16x32_bf16 v[124:127], v[140:143], v[164:167], v[124:127]
	v_mfma_f32_16x16x32_bf16 v[120:123], v[156:159], v[164:167], v[120:123]
	v_mfma_f32_16x16x32_bf16 v[112:115], v[140:143], v[172:175], v[112:115]
	v_mfma_f32_16x16x32_bf16 v[104:107], v[156:159], v[172:175], v[104:107]
	v_mfma_f32_16x16x32_bf16 v[92:95], v[140:143], v[180:183], v[92:95]
	v_mfma_f32_16x16x32_bf16 v[88:91], v[156:159], v[180:183], v[88:91]
	v_mfma_f32_16x16x32_bf16 v[80:83], v[140:143], v[188:191], v[80:83]
	v_mfma_f32_16x16x32_bf16 v[72:75], v[156:159], v[188:191], v[72:75]
	v_mfma_f32_16x16x32_bf16 v[124:127], v[152:155], v[168:171], v[124:127]
	v_mfma_f32_16x16x32_bf16 v[120:123], v[160:163], v[168:171], v[120:123]
	v_mfma_f32_16x16x32_bf16 v[112:115], v[152:155], v[176:179], v[112:115]
	v_mfma_f32_16x16x32_bf16 v[104:107], v[160:163], v[176:179], v[104:107]
	v_mfma_f32_16x16x32_bf16 v[92:95], v[152:155], v[184:187], v[92:95]
	v_mfma_f32_16x16x32_bf16 v[88:91], v[160:163], v[184:187], v[88:91]
	v_mfma_f32_16x16x32_bf16 v[80:83], v[152:155], v[192:195], v[80:83]
	v_mfma_f32_16x16x32_bf16 v[72:75], v[160:163], v[192:195], v[72:75]
	v_mfma_f32_16x16x32_bf16 v[116:119], v[196:199], v[164:167], v[116:119]
	v_mfma_f32_16x16x32_bf16 v[108:111], v[204:207], v[164:167], v[108:111]
	v_mfma_f32_16x16x32_bf16 v[100:103], v[196:199], v[172:175], v[100:103]
	v_mfma_f32_16x16x32_bf16 v[96:99], v[204:207], v[172:175], v[96:99]
	v_mfma_f32_16x16x32_bf16 v[84:87], v[196:199], v[180:183], v[84:87]
	v_mfma_f32_16x16x32_bf16 v[76:79], v[204:207], v[180:183], v[76:79]
	v_mfma_f32_16x16x32_bf16 v[68:71], v[196:199], v[188:191], v[68:71]
	v_mfma_f32_16x16x32_bf16 v[64:67], v[204:207], v[188:191], v[64:67]
	v_mfma_f32_16x16x32_bf16 v[116:119], v[200:203], v[168:171], v[116:119]
	v_mfma_f32_16x16x32_bf16 v[108:111], v[208:211], v[168:171], v[108:111]
	v_mfma_f32_16x16x32_bf16 v[100:103], v[200:203], v[176:179], v[100:103]
	v_mfma_f32_16x16x32_bf16 v[96:99], v[208:211], v[176:179], v[96:99]
	v_mfma_f32_16x16x32_bf16 v[84:87], v[200:203], v[184:187], v[84:87]
	v_mfma_f32_16x16x32_bf16 v[76:79], v[208:211], v[184:187], v[76:79]
	v_mfma_f32_16x16x32_bf16 v[68:71], v[200:203], v[192:195], v[68:71]
	v_mfma_f32_16x16x32_bf16 v[64:67], v[208:211], v[192:195], v[64:67]
	s_setprio 0
	s_barrier
; #define PG8_STAGE(bufoff, gbase, voff) do { _Pragma("unroll") for (int _i = 0; _i < 2; ++_i) \
;         __builtin_amdgcn_global_load_lds((const unsigned*)((const char*)(gbase) + (voff)[_i]), (LAS unsigned*)(lds + (bufoff) + ldsw + _i * 8192), 16, 0, 0); } while (0)
; #define PG8_MMA(ai, bj, At, Bt) do { __builtin_amdgcn_s_setprio(1); _Pragma("unroll") for (int m = 0; m < 4; ++m) _Pragma("unroll") for (int n = 0; n < 2; ++n) _Pragma("unroll") for (int k = 0; k < 2; ++k) \
;         acc[ai][bj][m][n] = __builtin_amdgcn_mfma_f32_16x16x32_bf16(Bt[n][k], At[m][k], acc[ai][bj][m][n], 0, 0, 0); __builtin_amdgcn_s_setprio(0); } while (0)
; #define PG8_WAIT_V(n) asm volatile("s_waitcnt vmcnt(" #n ")" ::: "memory")
; #define PG8_WAIT_L(n) asm volatile("s_waitcnt lgkmcnt(" #n ")" ::: "memory")
; #define PG8_BAR __builtin_amdgcn_s_barrier()
; #define PG8_SCHED __builtin_amdgcn_sched_barrier(0)
; template <class Epi>
; __device__ __forceinline__ void gemm_phase(LAS unsigned char* lds, const Gemm g, const StaticOrder& S, const Epi& E) {
;     ...
;             PG8_BAR; PG8_WAIT_L(0); PG8_MMA(1, 0, At, B0); PG8_BAR; PG8_SCHED;
;             PG8_STAGE(PG8_SB(1, 1), b3 + hstepB, voffB);
;             PG8_WAIT_V(6); PG8_BAR; PG8_MMA(1, 1, At, B1); PG8_BAR;
;     __device__ __forceinline__ void operator()(AccRef acc, const Unit& u, int wr, int wc, int fr, int fq) const {
;         const int row0 = u.pm * 256 + wr * 64 + fr, col0 = u.pn * 256 + wc * 32 + 4 * fq;
;         f32x4 sv[2][2], bv[2][2];
; #pragma unroll
;         for (int bj = 0; bj < 2; ++bj)
; #pragma unroll
;             for (int n = 0; n < 2; ++n) {
;                 sv[bj][n] = scale ? *(const f32x4*)(scale + col0 + bj * 128 + n * 16) : (f32x4){1.f, 1.f, 1.f, 1.f};
;                 bv[bj][n] = bias ? *(const f32x4*)(bias + col0 + bj * 128 + n * 16) : (f32x4){0.f, 0.f, 0.f, 0.f}; }
; #pragma unroll
;         for (int ai = 0; ai < 2; ++ai)
; #pragma unroll
;             for (int mh = 0; mh < 2; ++mh) {
;                 f32x4 bs[2][2][2];
; #pragma unroll
;                 for (int m = 0; m < 2; ++m)
; #pragma unroll
;                     for (int bj = 0; bj < 2; ++bj)
; #pragma unroll
;                         for (int n = 0; n < 2; ++n) bs[m][bj][n] = *(const f32x4*)(base + (size_t)(row0 + ai * 128 + (2 * mh + m) * 16) * D + col0 + bj * 128 + n * 16);
	s_nop 1
	ds_read_b128 v[164:167], v150 offset:49152
	ds_read_b128 v[168:171], v150 offset:50176
	ds_read_b128 v[172:175], v150 offset:51200
	ds_read_b128 v[176:179], v150 offset:52224
	ds_read_b128 v[180:183], v150 offset:53248
	ds_read_b128 v[184:187], v150 offset:54272
	ds_read_b128 v[188:191], v150 offset:55296
	ds_read_b128 v[192:195], v150 offset:56320
	s_add_i32 s26, s69, s7
	v_lshl_add_u64 v[254:255], v[144:145], 0, s[16:17]
	s_mov_b32 m0, s26
	s_nop 0
	global_load_lds_dwordx4 v[254:255], off
	v_lshl_add_u64 v[254:255], v[212:213], 0, s[16:17]
	s_add_i32 m0, s26, 0x2000
	s_nop 0
	global_load_lds_dwordx4 v[254:255], off
	s_mov_b32 m0, s41
	v_lshl_add_u64 v[254:255], v[214:215], 0, s[16:17]
	global_load_lds_dwordx4 v[254:255], off
	v_lshl_add_u64 v[144:145], v[216:217], 0, s[16:17]
	s_mov_b32 m0, s42
	s_nop 0
	global_load_lds_dwordx4 v[144:145], off
	s_add_u32 s26, s30, 0xb0080
	s_addc_u32 s27, s31, 0
	s_add_i32 s30, s34, s7
	v_lshl_add_u64 v[254:255], s[26:27], 0, v[128:129]
	s_mov_b32 m0, s30
	s_nop 0
	global_load_lds_dwordx4 v[254:255], off
	v_lshl_add_u64 v[254:255], s[26:27], 0, v[130:131]
	s_add_i32 m0, s30, 0x2000
	s_nop 0
	global_load_lds_dwordx4 v[254:255], off
	s_waitcnt vmcnt(6)
	s_waitcnt lgkmcnt(0)
	s_barrier
	s_setprio 1
	v_mfma_f32_16x16x32_bf16 v[60:63], v[140:143], v[164:167], v[60:63]
	v_mfma_f32_16x16x32_bf16 v[56:59], v[156:159], v[164:167], v[56:59]
	v_mfma_f32_16x16x32_bf16 v[48:51], v[140:143], v[172:175], v[48:51]
	v_mfma_f32_16x16x32_bf16 v[40:43], v[156:159], v[172:175], v[40:43]
	v_mfma_f32_16x16x32_bf16 v[28:31], v[140:143], v[180:183], v[28:31]
	v_mfma_f32_16x16x32_bf16 v[24:27], v[156:159], v[180:183], v[24:27]
	v_mfma_f32_16x16x32_bf16 v[16:19], v[140:143], v[188:191], v[16:19]
	v_mfma_f32_16x16x32_bf16 v[8:11], v[156:159], v[188:191], v[8:11]
	v_mfma_f32_16x16x32_bf16 v[60:63], v[152:155], v[168:171], v[60:63]
	v_mfma_f32_16x16x32_bf16 v[56:59], v[160:163], v[168:171], v[56:59]
	v_mfma_f32_16x16x32_bf16 v[48:51], v[152:155], v[176:179], v[48:51]
	v_mfma_f32_16x16x32_bf16 v[40:43], v[160:163], v[176:179], v[40:43]
	v_mfma_f32_16x16x32_bf16 v[28:31], v[152:155], v[184:187], v[28:31]
	v_mfma_f32_16x16x32_bf16 v[24:27], v[160:163], v[184:187], v[24:27]
	v_mfma_f32_16x16x32_bf16 v[16:19], v[152:155], v[192:195], v[16:19]
	v_mfma_f32_16x16x32_bf16 v[8:11], v[160:163], v[192:195], v[8:11]
	v_mfma_f32_16x16x32_bf16 v[52:55], v[196:199], v[164:167], v[52:55]
	v_mfma_f32_16x16x32_bf16 v[44:47], v[204:207], v[164:167], v[44:47]
	v_mfma_f32_16x16x32_bf16 v[36:39], v[196:199], v[172:175], v[36:39]
	v_mfma_f32_16x16x32_bf16 v[32:35], v[204:207], v[172:175], v[32:35]
	v_mfma_f32_16x16x32_bf16 v[20:23], v[196:199], v[180:183], v[20:23]
	v_mfma_f32_16x16x32_bf16 v[12:15], v[204:207], v[180:183], v[12:15]
	v_mfma_f32_16x16x32_bf16 v[4:7], v[196:199], v[188:191], v[4:7]
	v_mfma_f32_16x16x32_bf16 v[0:3], v[204:207], v[188:191], v[0:3]
	v_mfma_f32_16x16x32_bf16 v[52:55], v[200:203], v[168:171], v[52:55]
	v_mfma_f32_16x16x32_bf16 v[44:47], v[208:211], v[168:171], v[44:47]
	v_mfma_f32_16x16x32_bf16 v[36:39], v[200:203], v[176:179], v[36:39]
	v_mfma_f32_16x16x32_bf16 v[32:35], v[208:211], v[176:179], v[32:35]
	v_mfma_f32_16x16x32_bf16 v[20:23], v[200:203], v[184:187], v[20:23]
	v_mfma_f32_16x16x32_bf16 v[12:15], v[208:211], v[184:187], v[12:15]
	v_mfma_f32_16x16x32_bf16 v[4:7], v[200:203], v[192:195], v[4:7]
	v_mfma_f32_16x16x32_bf16 v[0:3], v[208:211], v[192:195], v[0:3]
	s_setprio 0
	s_add_i32 s68, s68, 2
	s_add_u32 s49, s49, 0x100
	s_addc_u32 s63, s63, 0
	s_cmp_gt_u32 s68, 41
	s_mov_b64 s[26:27], s[28:29]
	s_barrier
	s_cbranch_scc0 .LBB0_411
	v_lshl_or_b32 v144, s47, 8, v148
	v_lshl_add_u32 v145, s48, 8, v146
	v_lshlrev_b32_e32 v144, 2, v144
	v_lshl_add_u32 v145, v145, 12, v144
	v_add_u32_e32 v216, 0x10000, v145
	v_add_u32_e32 v217, 0x20000, v145
	v_add_u32_e32 v218, 0x30000, v145
	v_add_u32_e32 v220, 0x80000, v145
	v_add_u32_e32 v221, 0x90000, v145
	v_add_u32_e32 v222, 0xa0000, v145
	v_add_u32_e32 v223, 0xb0000, v145
	v_and_b32_e32 v235, 8, v146
	v_cmp_ne_u32_e32 vcc, 0, v235
	v_mov_b32_e32 v232, 0xffff8040
	s_nop 0
	v_cndmask_b32_e32 v232, 0, v232, vcc
	v_mov_b32_e32 v233, 64
	v_mov_b32_e32 v235, 0x8000
	v_cndmask_b32_e32 v233, v235, v233, vcc
	v_add_u32_e32 v224, v145, v232
	v_add_u32_e32 v225, v216, v232
	v_add_u32_e32 v226, v217, v232
	v_add_u32_e32 v227, v218, v232
	v_add_u32_e32 v228, v220, v232
	v_add_u32_e32 v229, v221, v232
	v_add_u32_e32 v230, v222, v232
	v_add_u32_e32 v231, v223, v232
	s_and_b64 vcc, exec, s[8:9]
	s_mov_b32 s47, s45
	s_mov_b32 s48, s46
	s_mov_b64 s[28:29], s[12:13]
	s_mov_b64 s[26:27], s[10:11]
	global_load_dwordx4 v[140:143], v224, s[52:53]
	v_add_u32_e32 v144, v145, v233
	global_load_dwordx4 v[152:155], v144, s[52:53]
	global_load_dwordx4 v[156:159], v224, s[52:53] offset:512
	v_add_u32_e32 v144, v145, v233
	global_load_dwordx4 v[160:163], v144, s[52:53] offset:512
	global_load_dwordx4 v[164:167], v225, s[52:53]
	v_add_u32_e32 v144, v216, v233
	global_load_dwordx4 v[168:171], v144, s[52:53]
	global_load_dwordx4 v[172:175], v225, s[52:53] offset:512
	v_add_u32_e32 v144, v216, v233
	global_load_dwordx4 v[176:179], v144, s[52:53] offset:512
	global_load_dwordx4 v[180:183], v226, s[52:53]
	v_add_u32_e32 v144, v217, v233
	global_load_dwordx4 v[184:187], v144, s[52:53]
	global_load_dwordx4 v[188:191], v226, s[52:53] offset:512
	v_add_u32_e32 v144, v217, v233
	global_load_dwordx4 v[192:195], v144, s[52:53] offset:512
	global_load_dwordx4 v[196:199], v227, s[52:53]
	v_add_u32_e32 v144, v218, v233
	global_load_dwordx4 v[200:203], v144, s[52:53]
	global_load_dwordx4 v[204:207], v227, s[52:53] offset:512
	v_add_u32_e32 v144, v218, v233
	global_load_dwordx4 v[208:211], v144, s[52:53] offset:512
	s_barrier
;     __device__ __forceinline__ void operator()(AccRef acc, const Unit& u, int wr, int wc, int fr, int fq) const {
;     ...
;                 sv[bj][n] = scale ? *(const f32x4*)(scale + col0 + bj * 128 + n * 16) : (f32x4){1.f, 1.f, 1.f, 1.f};
;                 bv[bj][n] = bias ? *(const f32x4*)(bias + col0 + bj * 128 + n * 16) : (f32x4){0.f, 0.f, 0.f, 0.f}; }
; #pragma unroll
;         for (int ai = 0; ai < 2; ++ai)
; #pragma unroll
;             for (int mh = 0; mh < 2; ++mh) {
;                 f32x4 bs[2][2][2];
; #pragma unroll
;                 for (int m = 0; m < 2; ++m)
; #pragma unroll
;                     for (int bj = 0; bj < 2; ++bj)
; #pragma unroll
;                         for (int n = 0; n < 2; ++n) bs[m][bj][n] = *(const f32x4*)(base + (size_t)(row0 + ai * 128 + (2 * mh + m) * 16) * D + col0 + bj * 128 + n * 16);
; #pragma unroll
;                 for (int m = 0; m < 2; ++m)
; #pragma unroll
;                     for (int bj = 0; bj < 2; ++bj)
; #pragma unroll
;                         for (int n = 0; n < 2; ++n) *(f32x4*)(out + (size_t)(row0 + ai * 128 + (2 * mh + m) * 16) * D + col0 + bj * 128 + n * 16) = bs[m][bj][n] + sv[bj][n] * (acc[ai][bj][2 * mh + m][n] + bv[bj][n]);
	v_pk_add_f32 v[124:125], v[124:125], 0 op_sel_hi:[1,0]
	v_pk_add_f32 v[126:127], v[126:127], 0 op_sel_hi:[1,0]
	v_pk_add_f32 v[120:121], v[120:121], 0 op_sel_hi:[1,0]
	v_pk_add_f32 v[122:123], v[122:123], 0 op_sel_hi:[1,0]
	v_pk_add_f32 v[116:117], v[116:117], 0 op_sel_hi:[1,0]
	v_pk_add_f32 v[118:119], v[118:119], 0 op_sel_hi:[1,0]
	v_pk_add_f32 v[108:109], v[108:109], 0 op_sel_hi:[1,0]
	v_pk_add_f32 v[110:111], v[110:111], 0 op_sel_hi:[1,0]
	v_pk_add_f32 v[112:113], v[112:113], 0 op_sel_hi:[1,0]
	v_pk_add_f32 v[114:115], v[114:115], 0 op_sel_hi:[1,0]
	v_pk_add_f32 v[104:105], v[104:105], 0 op_sel_hi:[1,0]
	v_pk_add_f32 v[106:107], v[106:107], 0 op_sel_hi:[1,0]
	v_pk_add_f32 v[100:101], v[100:101], 0 op_sel_hi:[1,0]
	v_pk_add_f32 v[102:103], v[102:103], 0 op_sel_hi:[1,0]
	v_pk_add_f32 v[96:97], v[96:97], 0 op_sel_hi:[1,0]
	v_pk_add_f32 v[98:99], v[98:99], 0 op_sel_hi:[1,0]
	v_pk_add_f32 v[92:93], v[92:93], 0 op_sel_hi:[1,0]
	v_pk_add_f32 v[94:95], v[94:95], 0 op_sel_hi:[1,0]
	v_pk_add_f32 v[88:89], v[88:89], 0 op_sel_hi:[1,0]
	v_pk_add_f32 v[90:91], v[90:91], 0 op_sel_hi:[1,0]
	v_pk_add_f32 v[84:85], v[84:85], 0 op_sel_hi:[1,0]
	v_pk_add_f32 v[86:87], v[86:87], 0 op_sel_hi:[1,0]
	v_pk_add_f32 v[76:77], v[76:77], 0 op_sel_hi:[1,0]
	v_pk_add_f32 v[78:79], v[78:79], 0 op_sel_hi:[1,0]
	v_pk_add_f32 v[80:81], v[80:81], 0 op_sel_hi:[1,0]
	v_pk_add_f32 v[82:83], v[82:83], 0 op_sel_hi:[1,0]
	v_pk_add_f32 v[72:73], v[72:73], 0 op_sel_hi:[1,0]
	v_pk_add_f32 v[74:75], v[74:75], 0 op_sel_hi:[1,0]
	v_pk_add_f32 v[68:69], v[68:69], 0 op_sel_hi:[1,0]
	v_pk_add_f32 v[70:71], v[70:71], 0 op_sel_hi:[1,0]
	v_pk_add_f32 v[64:65], v[64:65], 0 op_sel_hi:[1,0]
	v_pk_add_f32 v[66:67], v[66:67], 0 op_sel_hi:[1,0]
	v_pk_add_f32 v[60:61], v[60:61], 0 op_sel_hi:[1,0]
	v_pk_add_f32 v[62:63], v[62:63], 0 op_sel_hi:[1,0]
	v_pk_add_f32 v[56:57], v[56:57], 0 op_sel_hi:[1,0]
	v_pk_add_f32 v[58:59], v[58:59], 0 op_sel_hi:[1,0]
	v_pk_add_f32 v[52:53], v[52:53], 0 op_sel_hi:[1,0]
	v_pk_add_f32 v[54:55], v[54:55], 0 op_sel_hi:[1,0]
	v_pk_add_f32 v[44:45], v[44:45], 0 op_sel_hi:[1,0]
	v_pk_add_f32 v[46:47], v[46:47], 0 op_sel_hi:[1,0]
	v_pk_add_f32 v[48:49], v[48:49], 0 op_sel_hi:[1,0]
	v_pk_add_f32 v[50:51], v[50:51], 0 op_sel_hi:[1,0]
	v_pk_add_f32 v[40:41], v[40:41], 0 op_sel_hi:[1,0]
	v_pk_add_f32 v[42:43], v[42:43], 0 op_sel_hi:[1,0]
	v_pk_add_f32 v[36:37], v[36:37], 0 op_sel_hi:[1,0]
	v_pk_add_f32 v[38:39], v[38:39], 0 op_sel_hi:[1,0]
	v_pk_add_f32 v[32:33], v[32:33], 0 op_sel_hi:[1,0]
	v_pk_add_f32 v[34:35], v[34:35], 0 op_sel_hi:[1,0]
	v_pk_add_f32 v[28:29], v[28:29], 0 op_sel_hi:[1,0]
	v_pk_add_f32 v[30:31], v[30:31], 0 op_sel_hi:[1,0]
	v_pk_add_f32 v[24:25], v[24:25], 0 op_sel_hi:[1,0]
	v_pk_add_f32 v[26:27], v[26:27], 0 op_sel_hi:[1,0]
	v_pk_add_f32 v[20:21], v[20:21], 0 op_sel_hi:[1,0]
	v_pk_add_f32 v[22:23], v[22:23], 0 op_sel_hi:[1,0]
	v_pk_add_f32 v[12:13], v[12:13], 0 op_sel_hi:[1,0]
	v_pk_add_f32 v[14:15], v[14:15], 0 op_sel_hi:[1,0]
	v_pk_add_f32 v[16:17], v[16:17], 0 op_sel_hi:[1,0]
	v_pk_add_f32 v[18:19], v[18:19], 0 op_sel_hi:[1,0]
	v_pk_add_f32 v[8:9], v[8:9], 0 op_sel_hi:[1,0]
	v_pk_add_f32 v[10:11], v[10:11], 0 op_sel_hi:[1,0]
	v_pk_add_f32 v[4:5], v[4:5], 0 op_sel_hi:[1,0]
	v_pk_add_f32 v[6:7], v[6:7], 0 op_sel_hi:[1,0]
	v_pk_add_f32 v[0:1], v[0:1], 0 op_sel_hi:[1,0]
	v_pk_add_f32 v[2:3], v[2:3], 0 op_sel_hi:[1,0]
	s_waitcnt vmcnt(8)
	v_mov_b32_e32 v212, v124
	v_mov_b32_e32 v213, v125
	v_mov_b32_e32 v214, v126
	v_mov_b32_e32 v215, v127
	s_nop 0
	v_mov_b32_dpp v124, v120 row_shr:8 row_mask:0xf bank_mask:0xc
	v_mov_b32_dpp v125, v121 row_shr:8 row_mask:0xf bank_mask:0xc
	v_mov_b32_dpp v126, v122 row_shr:8 row_mask:0xf bank_mask:0xc
	v_mov_b32_dpp v127, v123 row_shr:8 row_mask:0xf bank_mask:0xc
	v_mov_b32_dpp v120, v212 row_shl:8 row_mask:0xf bank_mask:0x3
	v_mov_b32_dpp v121, v213 row_shl:8 row_mask:0xf bank_mask:0x3
	v_mov_b32_dpp v122, v214 row_shl:8 row_mask:0xf bank_mask:0x3
	v_mov_b32_dpp v123, v215 row_shl:8 row_mask:0xf bank_mask:0x3
	v_mov_b32_e32 v212, v116
	v_mov_b32_e32 v213, v117
	v_mov_b32_e32 v214, v118
	v_mov_b32_e32 v215, v119
	s_nop 0
	v_mov_b32_dpp v116, v108 row_shr:8 row_mask:0xf bank_mask:0xc
	v_mov_b32_dpp v117, v109 row_shr:8 row_mask:0xf bank_mask:0xc
	v_mov_b32_dpp v118, v110 row_shr:8 row_mask:0xf bank_mask:0xc
	v_mov_b32_dpp v119, v111 row_shr:8 row_mask:0xf bank_mask:0xc
	v_mov_b32_dpp v108, v212 row_shl:8 row_mask:0xf bank_mask:0x3
	v_mov_b32_dpp v109, v213 row_shl:8 row_mask:0xf bank_mask:0x3
	v_mov_b32_dpp v110, v214 row_shl:8 row_mask:0xf bank_mask:0x3
	v_mov_b32_dpp v111, v215 row_shl:8 row_mask:0xf bank_mask:0x3
	v_mov_b32_e32 v212, v112
	v_mov_b32_e32 v213, v113
	v_mov_b32_e32 v214, v114
	v_mov_b32_e32 v215, v115
	s_nop 0
	v_mov_b32_dpp v112, v104 row_shr:8 row_mask:0xf bank_mask:0xc
	v_mov_b32_dpp v113, v105 row_shr:8 row_mask:0xf bank_mask:0xc
	v_mov_b32_dpp v114, v106 row_shr:8 row_mask:0xf bank_mask:0xc
	v_mov_b32_dpp v115, v107 row_shr:8 row_mask:0xf bank_mask:0xc
	v_mov_b32_dpp v104, v212 row_shl:8 row_mask:0xf bank_mask:0x3
	v_mov_b32_dpp v105, v213 row_shl:8 row_mask:0xf bank_mask:0x3
	v_mov_b32_dpp v106, v214 row_shl:8 row_mask:0xf bank_mask:0x3
	v_mov_b32_dpp v107, v215 row_shl:8 row_mask:0xf bank_mask:0x3
	v_mov_b32_e32 v212, v100
	v_mov_b32_e32 v213, v101
	v_mov_b32_e32 v214, v102
	v_mov_b32_e32 v215, v103
	s_nop 0
	v_mov_b32_dpp v100, v96 row_shr:8 row_mask:0xf bank_mask:0xc
	v_mov_b32_dpp v101, v97 row_shr:8 row_mask:0xf bank_mask:0xc
	v_mov_b32_dpp v102, v98 row_shr:8 row_mask:0xf bank_mask:0xc
	v_mov_b32_dpp v103, v99 row_shr:8 row_mask:0xf bank_mask:0xc
	v_mov_b32_dpp v96, v212 row_shl:8 row_mask:0xf bank_mask:0x3
;     __device__ __forceinline__ void operator()(AccRef acc, const Unit& u, int wr, int wc, int fr, int fq) const {
;     ...
;                         for (int n = 0; n < 2; ++n) bs[m][bj][n] = *(const f32x4*)(base + (size_t)(row0 + ai * 128 + (2 * mh + m) * 16) * D + col0 + bj * 128 + n * 16);
; #pragma unroll
;                 for (int m = 0; m < 2; ++m)
; #pragma unroll
;                     for (int bj = 0; bj < 2; ++bj)
; #pragma unroll
;                         for (int n = 0; n < 2; ++n) *(f32x4*)(out + (size_t)(row0 + ai * 128 + (2 * mh + m) * 16) * D + col0 + bj * 128 + n * 16) = bs[m][bj][n] + sv[bj][n] * (acc[ai][bj][2 * mh + m][n] + bv[bj][n]);
;                 asm volatile("" ::: "memory"); }
	v_mov_b32_dpp v97, v213 row_shl:8 row_mask:0xf bank_mask:0x3
	v_mov_b32_dpp v98, v214 row_shl:8 row_mask:0xf bank_mask:0x3
	v_mov_b32_dpp v99, v215 row_shl:8 row_mask:0xf bank_mask:0x3
	v_pk_add_f32 v[124:125], v[124:125], v[140:141]
	v_pk_add_f32 v[126:127], v[126:127], v[142:143]
	v_pk_add_f32 v[120:121], v[120:121], v[152:153]
	v_pk_add_f32 v[122:123], v[122:123], v[154:155]
	v_pk_add_f32 v[116:117], v[116:117], v[156:157]
	v_pk_add_f32 v[118:119], v[118:119], v[158:159]
	v_pk_add_f32 v[108:109], v[108:109], v[160:161]
	v_pk_add_f32 v[110:111], v[110:111], v[162:163]
	v_pk_add_f32 v[112:113], v[112:113], v[164:165]
	v_pk_add_f32 v[114:115], v[114:115], v[166:167]
	v_pk_add_f32 v[104:105], v[104:105], v[168:169]
	v_pk_add_f32 v[106:107], v[106:107], v[170:171]
	v_pk_add_f32 v[100:101], v[100:101], v[172:173]
	v_pk_add_f32 v[102:103], v[102:103], v[174:175]
	v_pk_add_f32 v[96:97], v[96:97], v[176:177]
	v_pk_add_f32 v[98:99], v[98:99], v[178:179]
	global_store_dwordx4 v224, v[124:127], s[52:53]
	v_add_u32_e32 v144, v145, v233
	global_store_dwordx4 v144, v[120:123], s[52:53]
	global_store_dwordx4 v224, v[116:119], s[52:53] offset:512
	v_add_u32_e32 v144, v145, v233
	global_store_dwordx4 v144, v[108:111], s[52:53] offset:512
	global_store_dwordx4 v225, v[112:115], s[52:53]
	v_add_u32_e32 v144, v216, v233
	global_store_dwordx4 v144, v[104:107], s[52:53]
	global_store_dwordx4 v225, v[100:103], s[52:53] offset:512
	v_add_u32_e32 v144, v216, v233
	global_store_dwordx4 v144, v[96:99], s[52:53] offset:512
	global_load_dwordx4 v[140:143], v228, s[52:53]
	v_add_u32_e32 v144, v220, v233
	global_load_dwordx4 v[152:155], v144, s[52:53]
	global_load_dwordx4 v[156:159], v228, s[52:53] offset:512
	v_add_u32_e32 v144, v220, v233
	global_load_dwordx4 v[160:163], v144, s[52:53] offset:512
	global_load_dwordx4 v[164:167], v229, s[52:53]
	v_add_u32_e32 v144, v221, v233
	global_load_dwordx4 v[168:171], v144, s[52:53]
	global_load_dwordx4 v[172:175], v229, s[52:53] offset:512
	v_add_u32_e32 v144, v221, v233
	global_load_dwordx4 v[176:179], v144, s[52:53] offset:512
	s_waitcnt vmcnt(16)
	v_mov_b32_e32 v212, v92
	v_mov_b32_e32 v213, v93
	v_mov_b32_e32 v214, v94
	v_mov_b32_e32 v215, v95
	s_nop 0
	v_mov_b32_dpp v92, v88 row_shr:8 row_mask:0xf bank_mask:0xc
	v_mov_b32_dpp v93, v89 row_shr:8 row_mask:0xf bank_mask:0xc
	v_mov_b32_dpp v94, v90 row_shr:8 row_mask:0xf bank_mask:0xc
	v_mov_b32_dpp v95, v91 row_shr:8 row_mask:0xf bank_mask:0xc
	v_mov_b32_dpp v88, v212 row_shl:8 row_mask:0xf bank_mask:0x3
	v_mov_b32_dpp v89, v213 row_shl:8 row_mask:0xf bank_mask:0x3
	v_mov_b32_dpp v90, v214 row_shl:8 row_mask:0xf bank_mask:0x3
	v_mov_b32_dpp v91, v215 row_shl:8 row_mask:0xf bank_mask:0x3
	v_mov_b32_e32 v212, v84
	v_mov_b32_e32 v213, v85
	v_mov_b32_e32 v214, v86
	v_mov_b32_e32 v215, v87
	s_nop 0
	v_mov_b32_dpp v84, v76 row_shr:8 row_mask:0xf bank_mask:0xc
	v_mov_b32_dpp v85, v77 row_shr:8 row_mask:0xf bank_mask:0xc
	v_mov_b32_dpp v86, v78 row_shr:8 row_mask:0xf bank_mask:0xc
	v_mov_b32_dpp v87, v79 row_shr:8 row_mask:0xf bank_mask:0xc
	v_mov_b32_dpp v76, v212 row_shl:8 row_mask:0xf bank_mask:0x3
	v_mov_b32_dpp v77, v213 row_shl:8 row_mask:0xf bank_mask:0x3
	v_mov_b32_dpp v78, v214 row_shl:8 row_mask:0xf bank_mask:0x3
	v_mov_b32_dpp v79, v215 row_shl:8 row_mask:0xf bank_mask:0x3
	v_mov_b32_e32 v212, v80
	v_mov_b32_e32 v213, v81
	v_mov_b32_e32 v214, v82
	v_mov_b32_e32 v215, v83
	s_nop 0
	v_mov_b32_dpp v80, v72 row_shr:8 row_mask:0xf bank_mask:0xc
	v_mov_b32_dpp v81, v73 row_shr:8 row_mask:0xf bank_mask:0xc
	v_mov_b32_dpp v82, v74 row_shr:8 row_mask:0xf bank_mask:0xc
	v_mov_b32_dpp v83, v75 row_shr:8 row_mask:0xf bank_mask:0xc
	v_mov_b32_dpp v72, v212 row_shl:8 row_mask:0xf bank_mask:0x3
	v_mov_b32_dpp v73, v213 row_shl:8 row_mask:0xf bank_mask:0x3
	v_mov_b32_dpp v74, v214 row_shl:8 row_mask:0xf bank_mask:0x3
	v_mov_b32_dpp v75, v215 row_shl:8 row_mask:0xf bank_mask:0x3
	v_mov_b32_e32 v212, v68
	v_mov_b32_e32 v213, v69
	v_mov_b32_e32 v214, v70
	v_mov_b32_e32 v215, v71
	s_nop 0
	v_mov_b32_dpp v68, v64 row_shr:8 row_mask:0xf bank_mask:0xc
	v_mov_b32_dpp v69, v65 row_shr:8 row_mask:0xf bank_mask:0xc
	v_mov_b32_dpp v70, v66 row_shr:8 row_mask:0xf bank_mask:0xc
	v_mov_b32_dpp v71, v67 row_shr:8 row_mask:0xf bank_mask:0xc
	v_mov_b32_dpp v64, v212 row_shl:8 row_mask:0xf bank_mask:0x3
	v_mov_b32_dpp v65, v213 row_shl:8 row_mask:0xf bank_mask:0x3
	v_mov_b32_dpp v66, v214 row_shl:8 row_mask:0xf bank_mask:0x3
	v_mov_b32_dpp v67, v215 row_shl:8 row_mask:0xf bank_mask:0x3
	v_pk_add_f32 v[92:93], v[92:93], v[180:181]
	v_pk_add_f32 v[94:95], v[94:95], v[182:183]
	v_pk_add_f32 v[88:89], v[88:89], v[184:185]
	v_pk_add_f32 v[90:91], v[90:91], v[186:187]
	v_pk_add_f32 v[84:85], v[84:85], v[188:189]
	v_pk_add_f32 v[86:87], v[86:87], v[190:191]
	v_pk_add_f32 v[76:77], v[76:77], v[192:193]
	v_pk_add_f32 v[78:79], v[78:79], v[194:195]
	v_pk_add_f32 v[80:81], v[80:81], v[196:197]
	v_pk_add_f32 v[82:83], v[82:83], v[198:199]
	v_pk_add_f32 v[72:73], v[72:73], v[200:201]
	v_pk_add_f32 v[74:75], v[74:75], v[202:203]
	v_pk_add_f32 v[68:69], v[68:69], v[204:205]
	v_pk_add_f32 v[70:71], v[70:71], v[206:207]
	v_pk_add_f32 v[64:65], v[64:65], v[208:209]
	v_pk_add_f32 v[66:67], v[66:67], v[210:211]
	global_store_dwordx4 v226, v[92:95], s[52:53]
	v_add_u32_e32 v144, v217, v233
	global_store_dwordx4 v144, v[88:91], s[52:53]
	global_store_dwordx4 v226, v[84:87], s[52:53] offset:512
	v_add_u32_e32 v144, v217, v233
	global_store_dwordx4 v144, v[76:79], s[52:53] offset:512
	global_store_dwordx4 v227, v[80:83], s[52:53]
	v_add_u32_e32 v144, v218, v233
	global_store_dwordx4 v144, v[72:75], s[52:53]
	global_store_dwordx4 v227, v[68:71], s[52:53] offset:512
	v_add_u32_e32 v144, v218, v233
	global_store_dwordx4 v144, v[64:67], s[52:53] offset:512
	global_load_dwordx4 v[180:183], v230, s[52:53]
	v_add_u32_e32 v144, v222, v233
	global_load_dwordx4 v[184:187], v144, s[52:53]
	global_load_dwordx4 v[188:191], v230, s[52:53] offset:512
	v_add_u32_e32 v144, v222, v233
	global_load_dwordx4 v[192:195], v144, s[52:53] offset:512
	global_load_dwordx4 v[196:199], v231, s[52:53]
	v_add_u32_e32 v144, v223, v233
	global_load_dwordx4 v[200:203], v144, s[52:53]
	global_load_dwordx4 v[204:207], v231, s[52:53] offset:512
	v_add_u32_e32 v144, v223, v233
	global_load_dwordx4 v[208:211], v144, s[52:53] offset:512
	s_waitcnt vmcnt(16)
;     __device__ __forceinline__ void operator()(AccRef acc, const Unit& u, int wr, int wc, int fr, int fq) const {
;     ...
;                         for (int n = 0; n < 2; ++n) bs[m][bj][n] = *(const f32x4*)(base + (size_t)(row0 + ai * 128 + (2 * mh + m) * 16) * D + col0 + bj * 128 + n * 16);
; #pragma unroll
;                 for (int m = 0; m < 2; ++m)
; #pragma unroll
;                     for (int bj = 0; bj < 2; ++bj)
; #pragma unroll
;                         for (int n = 0; n < 2; ++n) *(f32x4*)(out + (size_t)(row0 + ai * 128 + (2 * mh + m) * 16) * D + col0 + bj * 128 + n * 16) = bs[m][bj][n] + sv[bj][n] * (acc[ai][bj][2 * mh + m][n] + bv[bj][n]);
;                 asm volatile("" ::: "memory"); }
	v_mov_b32_e32 v212, v60
	v_mov_b32_e32 v213, v61
	v_mov_b32_e32 v214, v62
	v_mov_b32_e32 v215, v63
	s_nop 0
	v_mov_b32_dpp v60, v56 row_shr:8 row_mask:0xf bank_mask:0xc
	v_mov_b32_dpp v61, v57 row_shr:8 row_mask:0xf bank_mask:0xc
	v_mov_b32_dpp v62, v58 row_shr:8 row_mask:0xf bank_mask:0xc
	v_mov_b32_dpp v63, v59 row_shr:8 row_mask:0xf bank_mask:0xc
	v_mov_b32_dpp v56, v212 row_shl:8 row_mask:0xf bank_mask:0x3
	v_mov_b32_dpp v57, v213 row_shl:8 row_mask:0xf bank_mask:0x3
	v_mov_b32_dpp v58, v214 row_shl:8 row_mask:0xf bank_mask:0x3
	v_mov_b32_dpp v59, v215 row_shl:8 row_mask:0xf bank_mask:0x3
	v_mov_b32_e32 v212, v52
	v_mov_b32_e32 v213, v53
	v_mov_b32_e32 v214, v54
	v_mov_b32_e32 v215, v55
	s_nop 0
	v_mov_b32_dpp v52, v44 row_shr:8 row_mask:0xf bank_mask:0xc
	v_mov_b32_dpp v53, v45 row_shr:8 row_mask:0xf bank_mask:0xc
	v_mov_b32_dpp v54, v46 row_shr:8 row_mask:0xf bank_mask:0xc
	v_mov_b32_dpp v55, v47 row_shr:8 row_mask:0xf bank_mask:0xc
	v_mov_b32_dpp v44, v212 row_shl:8 row_mask:0xf bank_mask:0x3
	v_mov_b32_dpp v45, v213 row_shl:8 row_mask:0xf bank_mask:0x3
	v_mov_b32_dpp v46, v214 row_shl:8 row_mask:0xf bank_mask:0x3
	v_mov_b32_dpp v47, v215 row_shl:8 row_mask:0xf bank_mask:0x3
	v_mov_b32_e32 v212, v48
	v_mov_b32_e32 v213, v49
	v_mov_b32_e32 v214, v50
	v_mov_b32_e32 v215, v51
	s_nop 0
	v_mov_b32_dpp v48, v40 row_shr:8 row_mask:0xf bank_mask:0xc
	v_mov_b32_dpp v49, v41 row_shr:8 row_mask:0xf bank_mask:0xc
	v_mov_b32_dpp v50, v42 row_shr:8 row_mask:0xf bank_mask:0xc
	v_mov_b32_dpp v51, v43 row_shr:8 row_mask:0xf bank_mask:0xc
	v_mov_b32_dpp v40, v212 row_shl:8 row_mask:0xf bank_mask:0x3
	v_mov_b32_dpp v41, v213 row_shl:8 row_mask:0xf bank_mask:0x3
	v_mov_b32_dpp v42, v214 row_shl:8 row_mask:0xf bank_mask:0x3
	v_mov_b32_dpp v43, v215 row_shl:8 row_mask:0xf bank_mask:0x3
	v_mov_b32_e32 v212, v36
	v_mov_b32_e32 v213, v37
	v_mov_b32_e32 v214, v38
	v_mov_b32_e32 v215, v39
	s_nop 0
	v_mov_b32_dpp v36, v32 row_shr:8 row_mask:0xf bank_mask:0xc
	v_mov_b32_dpp v37, v33 row_shr:8 row_mask:0xf bank_mask:0xc
	v_mov_b32_dpp v38, v34 row_shr:8 row_mask:0xf bank_mask:0xc
	v_mov_b32_dpp v39, v35 row_shr:8 row_mask:0xf bank_mask:0xc
	v_mov_b32_dpp v32, v212 row_shl:8 row_mask:0xf bank_mask:0x3
	v_mov_b32_dpp v33, v213 row_shl:8 row_mask:0xf bank_mask:0x3
	v_mov_b32_dpp v34, v214 row_shl:8 row_mask:0xf bank_mask:0x3
	v_mov_b32_dpp v35, v215 row_shl:8 row_mask:0xf bank_mask:0x3
	v_pk_add_f32 v[60:61], v[60:61], v[140:141]
	v_pk_add_f32 v[62:63], v[62:63], v[142:143]
	v_pk_add_f32 v[56:57], v[56:57], v[152:153]
	v_pk_add_f32 v[58:59], v[58:59], v[154:155]
	v_pk_add_f32 v[52:53], v[52:53], v[156:157]
	v_pk_add_f32 v[54:55], v[54:55], v[158:159]
	v_pk_add_f32 v[44:45], v[44:45], v[160:161]
	v_pk_add_f32 v[46:47], v[46:47], v[162:163]
	v_pk_add_f32 v[48:49], v[48:49], v[164:165]
	v_pk_add_f32 v[50:51], v[50:51], v[166:167]
	v_pk_add_f32 v[40:41], v[40:41], v[168:169]
	v_pk_add_f32 v[42:43], v[42:43], v[170:171]
	v_pk_add_f32 v[36:37], v[36:37], v[172:173]
	v_pk_add_f32 v[38:39], v[38:39], v[174:175]
	v_pk_add_f32 v[32:33], v[32:33], v[176:177]
	v_pk_add_f32 v[34:35], v[34:35], v[178:179]
	global_store_dwordx4 v228, v[60:63], s[52:53]
	v_add_u32_e32 v144, v220, v233
	global_store_dwordx4 v144, v[56:59], s[52:53]
	global_store_dwordx4 v228, v[52:55], s[52:53] offset:512
	v_add_u32_e32 v144, v220, v233
	global_store_dwordx4 v144, v[44:47], s[52:53] offset:512
	global_store_dwordx4 v229, v[48:51], s[52:53]
	v_add_u32_e32 v144, v221, v233
	global_store_dwordx4 v144, v[40:43], s[52:53]
	global_store_dwordx4 v229, v[36:39], s[52:53] offset:512
	v_add_u32_e32 v144, v221, v233
	global_store_dwordx4 v144, v[32:35], s[52:53] offset:512
	s_waitcnt vmcnt(8)
; #define PG8_WAIT_V(n) asm volatile("s_waitcnt vmcnt(" #n ")" ::: "memory")
; #define PG8_BAR __builtin_amdgcn_s_barrier()
; template <class Epi>
; __device__ __forceinline__ void gemm_phase(LAS unsigned char* lds, const Gemm g, const StaticOrder& S, const Epi& E) {
;     ...
;     PG8_WAIT_V(0);
;     if (wr == 0) PG8_BAR;
;     PG8_BAR;
;     __device__ __forceinline__ void operator()(AccRef acc, const Unit& u, int wr, int wc, int fr, int fq) const {
;     ...
;                         for (int n = 0; n < 2; ++n) bs[m][bj][n] = *(const f32x4*)(base + (size_t)(row0 + ai * 128 + (2 * mh + m) * 16) * D + col0 + bj * 128 + n * 16);
; #pragma unroll
;                 for (int m = 0; m < 2; ++m)
; #pragma unroll
;                     for (int bj = 0; bj < 2; ++bj)
; #pragma unroll
;                         for (int n = 0; n < 2; ++n) *(f32x4*)(out + (size_t)(row0 + ai * 128 + (2 * mh + m) * 16) * D + col0 + bj * 128 + n * 16) = bs[m][bj][n] + sv[bj][n] * (acc[ai][bj][2 * mh + m][n] + bv[bj][n]);
;                 asm volatile("" ::: "memory"); }
	v_mov_b32_e32 v212, v28
	v_mov_b32_e32 v213, v29
	v_mov_b32_e32 v214, v30
	v_mov_b32_e32 v215, v31
	s_nop 0
	v_mov_b32_dpp v28, v24 row_shr:8 row_mask:0xf bank_mask:0xc
	v_mov_b32_dpp v29, v25 row_shr:8 row_mask:0xf bank_mask:0xc
	v_mov_b32_dpp v30, v26 row_shr:8 row_mask:0xf bank_mask:0xc
	v_mov_b32_dpp v31, v27 row_shr:8 row_mask:0xf bank_mask:0xc
	v_mov_b32_dpp v24, v212 row_shl:8 row_mask:0xf bank_mask:0x3
	v_mov_b32_dpp v25, v213 row_shl:8 row_mask:0xf bank_mask:0x3
	v_mov_b32_dpp v26, v214 row_shl:8 row_mask:0xf bank_mask:0x3
	v_mov_b32_dpp v27, v215 row_shl:8 row_mask:0xf bank_mask:0x3
	v_mov_b32_e32 v212, v20
	v_mov_b32_e32 v213, v21
	v_mov_b32_e32 v214, v22
	v_mov_b32_e32 v215, v23
	s_nop 0
	v_mov_b32_dpp v20, v12 row_shr:8 row_mask:0xf bank_mask:0xc
	v_mov_b32_dpp v21, v13 row_shr:8 row_mask:0xf bank_mask:0xc
	v_mov_b32_dpp v22, v14 row_shr:8 row_mask:0xf bank_mask:0xc
	v_mov_b32_dpp v23, v15 row_shr:8 row_mask:0xf bank_mask:0xc
	v_mov_b32_dpp v12, v212 row_shl:8 row_mask:0xf bank_mask:0x3
	v_mov_b32_dpp v13, v213 row_shl:8 row_mask:0xf bank_mask:0x3
	v_mov_b32_dpp v14, v214 row_shl:8 row_mask:0xf bank_mask:0x3
	v_mov_b32_dpp v15, v215 row_shl:8 row_mask:0xf bank_mask:0x3
	v_mov_b32_e32 v212, v16
	v_mov_b32_e32 v213, v17
	v_mov_b32_e32 v214, v18
	v_mov_b32_e32 v215, v19
	s_nop 0
	v_mov_b32_dpp v16, v8 row_shr:8 row_mask:0xf bank_mask:0xc
	v_mov_b32_dpp v17, v9 row_shr:8 row_mask:0xf bank_mask:0xc
	v_mov_b32_dpp v18, v10 row_shr:8 row_mask:0xf bank_mask:0xc
	v_mov_b32_dpp v19, v11 row_shr:8 row_mask:0xf bank_mask:0xc
	v_mov_b32_dpp v8, v212 row_shl:8 row_mask:0xf bank_mask:0x3
	v_mov_b32_dpp v9, v213 row_shl:8 row_mask:0xf bank_mask:0x3
	v_mov_b32_dpp v10, v214 row_shl:8 row_mask:0xf bank_mask:0x3
	v_mov_b32_dpp v11, v215 row_shl:8 row_mask:0xf bank_mask:0x3
	v_mov_b32_e32 v212, v4
	v_mov_b32_e32 v213, v5
	v_mov_b32_e32 v214, v6
	v_mov_b32_e32 v215, v7
	s_nop 0
	v_mov_b32_dpp v4, v0 row_shr:8 row_mask:0xf bank_mask:0xc
	v_mov_b32_dpp v5, v1 row_shr:8 row_mask:0xf bank_mask:0xc
	v_mov_b32_dpp v6, v2 row_shr:8 row_mask:0xf bank_mask:0xc
	v_mov_b32_dpp v7, v3 row_shr:8 row_mask:0xf bank_mask:0xc
	v_mov_b32_dpp v0, v212 row_shl:8 row_mask:0xf bank_mask:0x3
	v_mov_b32_dpp v1, v213 row_shl:8 row_mask:0xf bank_mask:0x3
	v_mov_b32_dpp v2, v214 row_shl:8 row_mask:0xf bank_mask:0x3
	v_mov_b32_dpp v3, v215 row_shl:8 row_mask:0xf bank_mask:0x3
	v_pk_add_f32 v[28:29], v[28:29], v[180:181]
	v_pk_add_f32 v[30:31], v[30:31], v[182:183]
	v_pk_add_f32 v[24:25], v[24:25], v[184:185]
	v_pk_add_f32 v[26:27], v[26:27], v[186:187]
	v_pk_add_f32 v[20:21], v[20:21], v[188:189]
	v_pk_add_f32 v[22:23], v[22:23], v[190:191]
	v_pk_add_f32 v[12:13], v[12:13], v[192:193]
	v_pk_add_f32 v[14:15], v[14:15], v[194:195]
	v_pk_add_f32 v[16:17], v[16:17], v[196:197]
	v_pk_add_f32 v[18:19], v[18:19], v[198:199]
	v_pk_add_f32 v[8:9], v[8:9], v[200:201]
	v_pk_add_f32 v[10:11], v[10:11], v[202:203]
	v_pk_add_f32 v[4:5], v[4:5], v[204:205]
	v_pk_add_f32 v[6:7], v[6:7], v[206:207]
	v_pk_add_f32 v[0:1], v[0:1], v[208:209]
	v_pk_add_f32 v[2:3], v[2:3], v[210:211]
	global_store_dwordx4 v230, v[28:31], s[52:53]
	v_add_u32_e32 v144, v222, v233
	global_store_dwordx4 v144, v[24:27], s[52:53]
	global_store_dwordx4 v230, v[20:23], s[52:53] offset:512
	v_add_u32_e32 v144, v222, v233
	global_store_dwordx4 v144, v[12:15], s[52:53] offset:512
	global_store_dwordx4 v231, v[16:19], s[52:53]
	v_add_u32_e32 v144, v223, v233
	global_store_dwordx4 v144, v[8:11], s[52:53]
	global_store_dwordx4 v231, v[4:7], s[52:53] offset:512
	v_add_u32_e32 v144, v223, v233
	global_store_dwordx4 v144, v[0:3], s[52:53] offset:512
	s_cbranch_vccz .LBB0_400
	s_waitcnt vmcnt(0)
	s_cmpk_gt_u32 s4, 0xff
	s_cbranch_scc1 .LBB0_415
	s_barrier

; #define PG8_STAGE(bufoff, gbase, voff) do { _Pragma("unroll") for (int _i = 0; _i < 2; ++_i) \
;         __builtin_amdgcn_global_load_lds((const unsigned*)((const char*)(gbase) + (voff)[_i]), (LAS unsigned*)(lds + (bufoff) + ldsw + _i * 8192), 16, 0, 0); } while (0)
; #define PG8_LDA(dst, b, h) do { _Pragma("unroll") for (int m = 0; m < 4; ++m) _Pragma("unroll") for (int k = 0; k < 2; ++k) dst[m][k] = *(const LAS bf16x8*)(lds + PG8_SA(b, h) + aoff + m * 2048 + k * 1024); } while (0)
; #define PG8_LDB(dst, b, h) do { _Pragma("unroll") for (int n = 0; n < 2; ++n) _Pragma("unroll") for (int k = 0; k < 2; ++k) dst[n][k] = *(const LAS bf16x8*)(lds + PG8_SB(b, h) + boff + n * 2048 + k * 1024); } while (0)
; #define PG8_MMA(ai, bj, At, Bt) do { __builtin_amdgcn_s_setprio(1); _Pragma("unroll") for (int m = 0; m < 4; ++m) _Pragma("unroll") for (int n = 0; n < 2; ++n) _Pragma("unroll") for (int k = 0; k < 2; ++k) \
;         acc[ai][bj][m][n] = __builtin_amdgcn_mfma_f32_16x16x32_bf16(Bt[n][k], At[m][k], acc[ai][bj][m][n], 0, 0, 0); __builtin_amdgcn_s_setprio(0); } while (0)
; #define PG8_WAIT_V(n) asm volatile("s_waitcnt vmcnt(" #n ")" ::: "memory")
; #define PG8_WAIT_L(n) asm volatile("s_waitcnt lgkmcnt(" #n ")" ::: "memory")
; #define PG8_BAR __builtin_amdgcn_s_barrier()
; #define PG8_SCHED __builtin_amdgcn_sched_barrier(0)
; template <class Epi>
; __device__ __forceinline__ void gemm_phase(LAS unsigned char* lds, const Gemm g, const StaticOrder& S, const Epi& E) {
;     ...
;             PG8_LDB(B0, 0, 0); PG8_SCHED; PG8_LDA(At, 0, 0); PG8_STAGE(PG8_SA(1, 1), a1 + hstepA, voffA);
;             PG8_WAIT_L(8); PG8_BAR; PG8_WAIT_L(0); PG8_MMA(0, 0, At, B0); PG8_BAR; PG8_SCHED;
;             PG8_LDB(B1, 0, 1); PG8_STAGE(PG8_SB(0, 0), b2, voffB);
;             PG8_BAR; PG8_WAIT_L(0); PG8_MMA(0, 1, At, B1); PG8_BAR;
;             PG8_LDA(At, 0, 1); PG8_STAGE(PG8_SA(0, 0), a2, voffA);
;             PG8_BAR; PG8_WAIT_L(0); PG8_MMA(1, 0, At, B0); PG8_BAR; PG8_SCHED;
;             PG8_STAGE(PG8_SB(0, 1), b2 + hstepB, voffB);
;             PG8_WAIT_V(6); PG8_BAR; PG8_MMA(1, 1, At, B1); PG8_BAR;
.LBB0_860:
	ds_read_b128 v[140:143], v149
	ds_read_b128 v[152:155], v149 offset:1024
	ds_read_b128 v[156:159], v149 offset:2048
	ds_read_b128 v[160:163], v149 offset:3072
	s_add_u32 s30, s28, 0x100
	s_addc_u32 s31, s29, 0
	s_cmp_eq_u32 s68, 40
	s_cselect_b32 s37, s13, s31
	s_cselect_b32 s36, s12, s30
	s_cselect_b32 s35, s15, s63
	s_cselect_b32 s34, s14, s49
	v_lshl_add_u64 v[144:145], s[28:29], 0, v[132:133]
	s_add_i32 m0, s8, 0xc000
	ds_read_b128 v[164:167], v150
	ds_read_b128 v[168:171], v150 offset:1024
	ds_read_b128 v[172:175], v150 offset:2048
	ds_read_b128 v[176:179], v150 offset:3072
	ds_read_b128 v[180:183], v150 offset:4096
	ds_read_b128 v[184:187], v150 offset:5120
	ds_read_b128 v[188:191], v150 offset:6144
	ds_read_b128 v[192:195], v150 offset:7168
	global_load_lds_dwordx4 v[144:145], off
	v_lshl_add_u64 v[144:145], s[28:29], 0, v[134:135]
	s_add_i32 m0, s8, 0xe000
	s_nop 0
	global_load_lds_dwordx4 v[144:145], off
	ds_read_b128 v[196:199], v151
	ds_read_b128 v[200:203], v151 offset:1024
	ds_read_b128 v[204:207], v151 offset:2048
	ds_read_b128 v[208:211], v151 offset:3072
	s_waitcnt lgkmcnt(0)
	s_barrier
	s_setprio 1
	v_mfma_f32_16x16x32_bf16 v[124:127], v[140:143], v[164:167], v[124:127]
	v_mfma_f32_16x16x32_bf16 v[120:123], v[156:159], v[164:167], v[120:123]
	v_mfma_f32_16x16x32_bf16 v[112:115], v[140:143], v[172:175], v[112:115]
	v_mfma_f32_16x16x32_bf16 v[104:107], v[156:159], v[172:175], v[104:107]
	v_mfma_f32_16x16x32_bf16 v[92:95], v[140:143], v[180:183], v[92:95]
	v_mfma_f32_16x16x32_bf16 v[88:91], v[156:159], v[180:183], v[88:91]
	v_mfma_f32_16x16x32_bf16 v[80:83], v[140:143], v[188:191], v[80:83]
	v_mfma_f32_16x16x32_bf16 v[72:75], v[156:159], v[188:191], v[72:75]
	v_mfma_f32_16x16x32_bf16 v[124:127], v[152:155], v[168:171], v[124:127]
	v_mfma_f32_16x16x32_bf16 v[120:123], v[160:163], v[168:171], v[120:123]
	v_mfma_f32_16x16x32_bf16 v[112:115], v[152:155], v[176:179], v[112:115]
	v_mfma_f32_16x16x32_bf16 v[104:107], v[160:163], v[176:179], v[104:107]
	v_mfma_f32_16x16x32_bf16 v[92:95], v[152:155], v[184:187], v[92:95]
	v_mfma_f32_16x16x32_bf16 v[88:91], v[160:163], v[184:187], v[88:91]
	v_mfma_f32_16x16x32_bf16 v[80:83], v[152:155], v[192:195], v[80:83]
	v_mfma_f32_16x16x32_bf16 v[72:75], v[160:163], v[192:195], v[72:75]
	v_mfma_f32_16x16x32_bf16 v[116:119], v[196:199], v[164:167], v[116:119]
	v_mfma_f32_16x16x32_bf16 v[108:111], v[204:207], v[164:167], v[108:111]
	v_mfma_f32_16x16x32_bf16 v[100:103], v[196:199], v[172:175], v[100:103]
	v_mfma_f32_16x16x32_bf16 v[96:99], v[204:207], v[172:175], v[96:99]
	v_mfma_f32_16x16x32_bf16 v[84:87], v[196:199], v[180:183], v[84:87]
	v_mfma_f32_16x16x32_bf16 v[76:79], v[204:207], v[180:183], v[76:79]
	v_mfma_f32_16x16x32_bf16 v[68:71], v[196:199], v[188:191], v[68:71]
	v_mfma_f32_16x16x32_bf16 v[64:67], v[204:207], v[188:191], v[64:67]
	v_mfma_f32_16x16x32_bf16 v[116:119], v[200:203], v[168:171], v[116:119]
	v_mfma_f32_16x16x32_bf16 v[108:111], v[208:211], v[168:171], v[108:111]
	v_mfma_f32_16x16x32_bf16 v[100:103], v[200:203], v[176:179], v[100:103]
	v_mfma_f32_16x16x32_bf16 v[96:99], v[208:211], v[176:179], v[96:99]
	v_mfma_f32_16x16x32_bf16 v[84:87], v[200:203], v[184:187], v[84:87]
	v_mfma_f32_16x16x32_bf16 v[76:79], v[208:211], v[184:187], v[76:79]
	v_mfma_f32_16x16x32_bf16 v[68:71], v[200:203], v[192:195], v[68:71]
	v_mfma_f32_16x16x32_bf16 v[64:67], v[208:211], v[192:195], v[64:67]
	s_setprio 0
	s_barrier
	s_nop 1
	ds_read_b128 v[164:167], v150 offset:16384
	ds_read_b128 v[168:171], v150 offset:17408
	ds_read_b128 v[172:175], v150 offset:18432
	ds_read_b128 v[176:179], v150 offset:19456
	ds_read_b128 v[180:183], v150 offset:20480
	ds_read_b128 v[184:187], v150 offset:21504
	ds_read_b128 v[188:191], v150 offset:22528
	ds_read_b128 v[192:195], v150 offset:23552
	s_add_i32 s28, s43, s7
	v_lshl_add_u64 v[144:145], s[34:35], 0, v[128:129]
	s_mov_b32 m0, s28
	s_nop 0
	global_load_lds_dwordx4 v[144:145], off
	v_lshl_add_u64 v[212:213], s[34:35], 0, v[130:131]
	s_add_i32 m0, s28, 0x2000
	s_nop 0
	global_load_lds_dwordx4 v[212:213], off
	s_mov_b32 m0, s8
	v_lshl_add_u64 v[214:215], s[36:37], 0, v[128:129]
	global_load_lds_dwordx4 v[214:215], off
	v_lshl_add_u64 v[216:217], s[36:37], 0, v[130:131]
	s_mov_b32 m0, s9
	s_nop 0
	global_load_lds_dwordx4 v[216:217], off
	s_add_u32 s28, s34, 0xb0000
	s_addc_u32 s29, s35, 0
	s_add_i32 s69, s44, s7
	v_lshl_add_u64 v[254:255], s[28:29], 0, v[128:129]
	s_mov_b32 m0, s69
	s_nop 0
	global_load_lds_dwordx4 v[254:255], off
	v_lshl_add_u64 v[254:255], s[28:29], 0, v[130:131]
	s_add_i32 m0, s69, 0x2000
	s_nop 0
	global_load_lds_dwordx4 v[254:255], off
	s_waitcnt vmcnt(6)
	s_waitcnt lgkmcnt(0)
	s_barrier
; #define PG8_STAGE(bufoff, gbase, voff) do { _Pragma("unroll") for (int _i = 0; _i < 2; ++_i) \
;         __builtin_amdgcn_global_load_lds((const unsigned*)((const char*)(gbase) + (voff)[_i]), (LAS unsigned*)(lds + (bufoff) + ldsw + _i * 8192), 16, 0, 0); } while (0)
; #define PG8_LDA(dst, b, h) do { _Pragma("unroll") for (int m = 0; m < 4; ++m) _Pragma("unroll") for (int k = 0; k < 2; ++k) dst[m][k] = *(const LAS bf16x8*)(lds + PG8_SA(b, h) + aoff + m * 2048 + k * 1024); } while (0)
; #define PG8_LDB(dst, b, h) do { _Pragma("unroll") for (int n = 0; n < 2; ++n) _Pragma("unroll") for (int k = 0; k < 2; ++k) dst[n][k] = *(const LAS bf16x8*)(lds + PG8_SB(b, h) + boff + n * 2048 + k * 1024); } while (0)
; #define PG8_MMA(ai, bj, At, Bt) do { __builtin_amdgcn_s_setprio(1); _Pragma("unroll") for (int m = 0; m < 4; ++m) _Pragma("unroll") for (int n = 0; n < 2; ++n) _Pragma("unroll") for (int k = 0; k < 2; ++k) \
;         acc[ai][bj][m][n] = __builtin_amdgcn_mfma_f32_16x16x32_bf16(Bt[n][k], At[m][k], acc[ai][bj][m][n], 0, 0, 0); __builtin_amdgcn_s_setprio(0); } while (0)
; #define PG8_WAIT_V(n) asm volatile("s_waitcnt vmcnt(" #n ")" ::: "memory")
; #define PG8_WAIT_L(n) asm volatile("s_waitcnt lgkmcnt(" #n ")" ::: "memory")
; #define PG8_BAR __builtin_amdgcn_s_barrier()
; #define PG8_SCHED __builtin_amdgcn_sched_barrier(0)
; template <class Epi>
; __device__ __forceinline__ void gemm_phase(LAS unsigned char* lds, const Gemm g, const StaticOrder& S, const Epi& E) {
;     ...
;             PG8_BAR; PG8_WAIT_L(0); PG8_MMA(1, 0, At, B0); PG8_BAR; PG8_SCHED;
;             PG8_STAGE(PG8_SB(0, 1), b2 + hstepB, voffB);
;             PG8_WAIT_V(6); PG8_BAR; PG8_MMA(1, 1, At, B1); PG8_BAR;
;             PG8_LDB(B0, 1, 0); PG8_SCHED; PG8_LDA(At, 1, 0); PG8_STAGE(PG8_SA(0, 1), a2 + hstepA, voffA);
;             PG8_WAIT_L(8); PG8_BAR; PG8_WAIT_L(0); PG8_MMA(0, 0, At, B0); PG8_BAR; PG8_SCHED;
;             PG8_LDB(B1, 1, 1); PG8_STAGE(PG8_SB(1, 0), b3, voffB);
;             PG8_BAR; PG8_WAIT_L(0); PG8_MMA(0, 1, At, B1); PG8_BAR;
;             PG8_LDA(At, 1, 1); PG8_STAGE(PG8_SA(1, 0), a3, voffA);
;             PG8_BAR; PG8_WAIT_L(0); PG8_MMA(1, 0, At, B0); PG8_BAR; PG8_SCHED;
	s_setprio 1
	v_mfma_f32_16x16x32_bf16 v[60:63], v[140:143], v[164:167], v[60:63]
	v_mfma_f32_16x16x32_bf16 v[56:59], v[156:159], v[164:167], v[56:59]
	v_mfma_f32_16x16x32_bf16 v[48:51], v[140:143], v[172:175], v[48:51]
	v_mfma_f32_16x16x32_bf16 v[40:43], v[156:159], v[172:175], v[40:43]
	v_mfma_f32_16x16x32_bf16 v[28:31], v[140:143], v[180:183], v[28:31]
	v_mfma_f32_16x16x32_bf16 v[24:27], v[156:159], v[180:183], v[24:27]
	v_mfma_f32_16x16x32_bf16 v[16:19], v[140:143], v[188:191], v[16:19]
	v_mfma_f32_16x16x32_bf16 v[8:11], v[156:159], v[188:191], v[8:11]
	v_mfma_f32_16x16x32_bf16 v[60:63], v[152:155], v[168:171], v[60:63]
	v_mfma_f32_16x16x32_bf16 v[56:59], v[160:163], v[168:171], v[56:59]
	v_mfma_f32_16x16x32_bf16 v[48:51], v[152:155], v[176:179], v[48:51]
	v_mfma_f32_16x16x32_bf16 v[40:43], v[160:163], v[176:179], v[40:43]
	v_mfma_f32_16x16x32_bf16 v[28:31], v[152:155], v[184:187], v[28:31]
	v_mfma_f32_16x16x32_bf16 v[24:27], v[160:163], v[184:187], v[24:27]
	v_mfma_f32_16x16x32_bf16 v[16:19], v[152:155], v[192:195], v[16:19]
	v_mfma_f32_16x16x32_bf16 v[8:11], v[160:163], v[192:195], v[8:11]
	v_mfma_f32_16x16x32_bf16 v[52:55], v[196:199], v[164:167], v[52:55]
	v_mfma_f32_16x16x32_bf16 v[44:47], v[204:207], v[164:167], v[44:47]
	v_mfma_f32_16x16x32_bf16 v[36:39], v[196:199], v[172:175], v[36:39]
	v_mfma_f32_16x16x32_bf16 v[32:35], v[204:207], v[172:175], v[32:35]
	v_mfma_f32_16x16x32_bf16 v[20:23], v[196:199], v[180:183], v[20:23]
	v_mfma_f32_16x16x32_bf16 v[12:15], v[204:207], v[180:183], v[12:15]
	v_mfma_f32_16x16x32_bf16 v[4:7], v[196:199], v[188:191], v[4:7]
	v_mfma_f32_16x16x32_bf16 v[0:3], v[204:207], v[188:191], v[0:3]
	v_mfma_f32_16x16x32_bf16 v[52:55], v[200:203], v[168:171], v[52:55]
	v_mfma_f32_16x16x32_bf16 v[44:47], v[208:211], v[168:171], v[44:47]
	v_mfma_f32_16x16x32_bf16 v[36:39], v[200:203], v[176:179], v[36:39]
	v_mfma_f32_16x16x32_bf16 v[32:35], v[208:211], v[176:179], v[32:35]
	v_mfma_f32_16x16x32_bf16 v[20:23], v[200:203], v[184:187], v[20:23]
	v_mfma_f32_16x16x32_bf16 v[12:15], v[208:211], v[184:187], v[12:15]
	v_mfma_f32_16x16x32_bf16 v[4:7], v[200:203], v[192:195], v[4:7]
	v_mfma_f32_16x16x32_bf16 v[0:3], v[208:211], v[192:195], v[0:3]
	s_setprio 0
	s_add_i32 s69, 0, 0x18000
	v_add_u32_e32 v160, s69, v147
	s_barrier
	ds_read_b128 v[140:143], v160
	ds_read_b128 v[152:155], v160 offset:1024
	ds_read_b128 v[156:159], v160 offset:2048
	ds_read_b128 v[160:163], v160 offset:3072
	s_add_u32 s28, s36, 0xb0000
	s_addc_u32 s29, s37, 0
	s_mov_b32 m0, s38
	v_lshl_add_u64 v[196:197], s[28:29], 0, v[128:129]
	ds_read_b128 v[164:167], v150 offset:32768
	ds_read_b128 v[168:171], v150 offset:33792
	ds_read_b128 v[172:175], v150 offset:34816
	ds_read_b128 v[176:179], v150 offset:35840
	ds_read_b128 v[180:183], v150 offset:36864
	ds_read_b128 v[184:187], v150 offset:37888
	ds_read_b128 v[188:191], v150 offset:38912
	ds_read_b128 v[192:195], v150 offset:39936
	global_load_lds_dwordx4 v[196:197], off
	v_lshl_add_u64 v[196:197], s[28:29], 0, v[130:131]
	s_mov_b32 m0, s39
	s_nop 0
	global_load_lds_dwordx4 v[196:197], off
	s_add_i32 s36, 0, 0x1c000
	v_add_u32_e32 v208, s36, v147
	ds_read_b128 v[196:199], v208
	ds_read_b128 v[200:203], v208 offset:1024
	ds_read_b128 v[204:207], v208 offset:2048
	ds_read_b128 v[208:211], v208 offset:3072
	s_waitcnt lgkmcnt(0)
	s_barrier
	s_setprio 1
	v_mfma_f32_16x16x32_bf16 v[124:127], v[140:143], v[164:167], v[124:127]
	v_mfma_f32_16x16x32_bf16 v[120:123], v[156:159], v[164:167], v[120:123]
	v_mfma_f32_16x16x32_bf16 v[112:115], v[140:143], v[172:175], v[112:115]
	v_mfma_f32_16x16x32_bf16 v[104:107], v[156:159], v[172:175], v[104:107]
	v_mfma_f32_16x16x32_bf16 v[92:95], v[140:143], v[180:183], v[92:95]
	v_mfma_f32_16x16x32_bf16 v[88:91], v[156:159], v[180:183], v[88:91]
	v_mfma_f32_16x16x32_bf16 v[80:83], v[140:143], v[188:191], v[80:83]
	v_mfma_f32_16x16x32_bf16 v[72:75], v[156:159], v[188:191], v[72:75]
	v_mfma_f32_16x16x32_bf16 v[124:127], v[152:155], v[168:171], v[124:127]
	v_mfma_f32_16x16x32_bf16 v[120:123], v[160:163], v[168:171], v[120:123]
	v_mfma_f32_16x16x32_bf16 v[112:115], v[152:155], v[176:179], v[112:115]
	v_mfma_f32_16x16x32_bf16 v[104:107], v[160:163], v[176:179], v[104:107]
	v_mfma_f32_16x16x32_bf16 v[92:95], v[152:155], v[184:187], v[92:95]
	v_mfma_f32_16x16x32_bf16 v[88:91], v[160:163], v[184:187], v[88:91]
	v_mfma_f32_16x16x32_bf16 v[80:83], v[152:155], v[192:195], v[80:83]
	v_mfma_f32_16x16x32_bf16 v[72:75], v[160:163], v[192:195], v[72:75]
	v_mfma_f32_16x16x32_bf16 v[116:119], v[196:199], v[164:167], v[116:119]
	v_mfma_f32_16x16x32_bf16 v[108:111], v[204:207], v[164:167], v[108:111]
	v_mfma_f32_16x16x32_bf16 v[100:103], v[196:199], v[172:175], v[100:103]
	v_mfma_f32_16x16x32_bf16 v[96:99], v[204:207], v[172:175], v[96:99]
	v_mfma_f32_16x16x32_bf16 v[84:87], v[196:199], v[180:183], v[84:87]
	v_mfma_f32_16x16x32_bf16 v[76:79], v[204:207], v[180:183], v[76:79]
	v_mfma_f32_16x16x32_bf16 v[68:71], v[196:199], v[188:191], v[68:71]
	v_mfma_f32_16x16x32_bf16 v[64:67], v[204:207], v[188:191], v[64:67]
	v_mfma_f32_16x16x32_bf16 v[116:119], v[200:203], v[168:171], v[116:119]
	v_mfma_f32_16x16x32_bf16 v[108:111], v[208:211], v[168:171], v[108:111]
	v_mfma_f32_16x16x32_bf16 v[100:103], v[200:203], v[176:179], v[100:103]
	v_mfma_f32_16x16x32_bf16 v[96:99], v[208:211], v[176:179], v[96:99]
	v_mfma_f32_16x16x32_bf16 v[84:87], v[200:203], v[184:187], v[84:87]
	v_mfma_f32_16x16x32_bf16 v[76:79], v[208:211], v[184:187], v[76:79]
	v_mfma_f32_16x16x32_bf16 v[68:71], v[200:203], v[192:195], v[68:71]
	v_mfma_f32_16x16x32_bf16 v[64:67], v[208:211], v[192:195], v[64:67]
	s_setprio 0
	s_barrier
; #define PG8_STAGE(bufoff, gbase, voff) do { _Pragma("unroll") for (int _i = 0; _i < 2; ++_i) \
;         __builtin_amdgcn_global_load_lds((const unsigned*)((const char*)(gbase) + (voff)[_i]), (LAS unsigned*)(lds + (bufoff) + ldsw + _i * 8192), 16, 0, 0); } while (0)
; #define PG8_MMA(ai, bj, At, Bt) do { __builtin_amdgcn_s_setprio(1); _Pragma("unroll") for (int m = 0; m < 4; ++m) _Pragma("unroll") for (int n = 0; n < 2; ++n) _Pragma("unroll") for (int k = 0; k < 2; ++k) \
;         acc[ai][bj][m][n] = __builtin_amdgcn_mfma_f32_16x16x32_bf16(Bt[n][k], At[m][k], acc[ai][bj][m][n], 0, 0, 0); __builtin_amdgcn_s_setprio(0); } while (0)
; #define PG8_WAIT_V(n) asm volatile("s_waitcnt vmcnt(" #n ")" ::: "memory")
; #define PG8_WAIT_L(n) asm volatile("s_waitcnt lgkmcnt(" #n ")" ::: "memory")
; #define PG8_BAR __builtin_amdgcn_s_barrier()
; #define PG8_SCHED __builtin_amdgcn_sched_barrier(0)
; template <class Epi>
; __device__ __forceinline__ void gemm_phase(LAS unsigned char* lds, const Gemm g, const StaticOrder& S, const Epi& E) {
;     ...
;             PG8_BAR; PG8_WAIT_L(0); PG8_MMA(1, 0, At, B0); PG8_BAR; PG8_SCHED;
;             PG8_STAGE(PG8_SB(1, 1), b3 + hstepB, voffB);
;             PG8_WAIT_V(6); PG8_BAR; PG8_MMA(1, 1, At, B1); PG8_BAR;
;     __device__ __forceinline__ void operator()(AccRef acc, const Unit& u, int wr, int wc, int fr, int fq) const {
;         const int row0 = u.pm * 256 + wr * 64 + fr, col0 = u.pn * 256 + wc * 32 + 4 * fq;
;         f32x4 sv[2][2], bv[2][2];
; #pragma unroll
;         for (int bj = 0; bj < 2; ++bj)
; #pragma unroll
;             for (int n = 0; n < 2; ++n) {
;                 sv[bj][n] = scale ? *(const f32x4*)(scale + col0 + bj * 128 + n * 16) : (f32x4){1.f, 1.f, 1.f, 1.f};
;                 bv[bj][n] = bias ? *(const f32x4*)(bias + col0 + bj * 128 + n * 16) : (f32x4){0.f, 0.f, 0.f, 0.f}; }
; #pragma unroll
;         for (int ai = 0; ai < 2; ++ai)
; #pragma unroll
;             for (int mh = 0; mh < 2; ++mh) {
;                 f32x4 bs[2][2][2];
; #pragma unroll
;                 for (int m = 0; m < 2; ++m)
; #pragma unroll
;                     for (int bj = 0; bj < 2; ++bj)
; #pragma unroll
;                         for (int n = 0; n < 2; ++n) bs[m][bj][n] = *(const f32x4*)(base + (size_t)(row0 + ai * 128 + (2 * mh + m) * 16) * D + col0 + bj * 128 + n * 16);
	s_nop 1
	ds_read_b128 v[164:167], v150 offset:49152
	ds_read_b128 v[168:171], v150 offset:50176
	ds_read_b128 v[172:175], v150 offset:51200
	ds_read_b128 v[176:179], v150 offset:52224
	ds_read_b128 v[180:183], v150 offset:53248
	ds_read_b128 v[184:187], v150 offset:54272
	ds_read_b128 v[188:191], v150 offset:55296
	ds_read_b128 v[192:195], v150 offset:56320
	s_add_i32 s28, s69, s7
	v_lshl_add_u64 v[254:255], v[144:145], 0, s[20:21]
	s_mov_b32 m0, s28
	s_nop 0
	global_load_lds_dwordx4 v[254:255], off
	v_lshl_add_u64 v[254:255], v[212:213], 0, s[20:21]
	s_add_i32 m0, s28, 0x2000
	s_nop 0
	global_load_lds_dwordx4 v[254:255], off
	s_mov_b32 m0, s41
	v_lshl_add_u64 v[254:255], v[214:215], 0, s[20:21]
	global_load_lds_dwordx4 v[254:255], off
	v_lshl_add_u64 v[144:145], v[216:217], 0, s[20:21]
	s_mov_b32 m0, s42
	s_nop 0
	global_load_lds_dwordx4 v[144:145], off
	s_add_u32 s28, s34, 0xb0080
	s_addc_u32 s29, s35, 0
	s_add_i32 s34, s36, s7
	v_lshl_add_u64 v[254:255], s[28:29], 0, v[128:129]
	s_mov_b32 m0, s34
	s_nop 0
	global_load_lds_dwordx4 v[254:255], off
	v_lshl_add_u64 v[254:255], s[28:29], 0, v[130:131]
	s_add_i32 m0, s34, 0x2000
	s_nop 0
	global_load_lds_dwordx4 v[254:255], off
	s_waitcnt vmcnt(6)
	s_waitcnt lgkmcnt(0)
	s_barrier
	s_setprio 1
	v_mfma_f32_16x16x32_bf16 v[60:63], v[140:143], v[164:167], v[60:63]
	v_mfma_f32_16x16x32_bf16 v[56:59], v[156:159], v[164:167], v[56:59]
	v_mfma_f32_16x16x32_bf16 v[48:51], v[140:143], v[172:175], v[48:51]
	v_mfma_f32_16x16x32_bf16 v[40:43], v[156:159], v[172:175], v[40:43]
	v_mfma_f32_16x16x32_bf16 v[28:31], v[140:143], v[180:183], v[28:31]
	v_mfma_f32_16x16x32_bf16 v[24:27], v[156:159], v[180:183], v[24:27]
	v_mfma_f32_16x16x32_bf16 v[16:19], v[140:143], v[188:191], v[16:19]
	v_mfma_f32_16x16x32_bf16 v[8:11], v[156:159], v[188:191], v[8:11]
	v_mfma_f32_16x16x32_bf16 v[60:63], v[152:155], v[168:171], v[60:63]
	v_mfma_f32_16x16x32_bf16 v[56:59], v[160:163], v[168:171], v[56:59]
	v_mfma_f32_16x16x32_bf16 v[48:51], v[152:155], v[176:179], v[48:51]
	v_mfma_f32_16x16x32_bf16 v[40:43], v[160:163], v[176:179], v[40:43]
	v_mfma_f32_16x16x32_bf16 v[28:31], v[152:155], v[184:187], v[28:31]
	v_mfma_f32_16x16x32_bf16 v[24:27], v[160:163], v[184:187], v[24:27]
	v_mfma_f32_16x16x32_bf16 v[16:19], v[152:155], v[192:195], v[16:19]
	v_mfma_f32_16x16x32_bf16 v[8:11], v[160:163], v[192:195], v[8:11]
	v_mfma_f32_16x16x32_bf16 v[52:55], v[196:199], v[164:167], v[52:55]
	v_mfma_f32_16x16x32_bf16 v[44:47], v[204:207], v[164:167], v[44:47]
	v_mfma_f32_16x16x32_bf16 v[36:39], v[196:199], v[172:175], v[36:39]
	v_mfma_f32_16x16x32_bf16 v[32:35], v[204:207], v[172:175], v[32:35]
	v_mfma_f32_16x16x32_bf16 v[20:23], v[196:199], v[180:183], v[20:23]
	v_mfma_f32_16x16x32_bf16 v[12:15], v[204:207], v[180:183], v[12:15]
	v_mfma_f32_16x16x32_bf16 v[4:7], v[196:199], v[188:191], v[4:7]
	v_mfma_f32_16x16x32_bf16 v[0:3], v[204:207], v[188:191], v[0:3]
	v_mfma_f32_16x16x32_bf16 v[52:55], v[200:203], v[168:171], v[52:55]
	v_mfma_f32_16x16x32_bf16 v[44:47], v[208:211], v[168:171], v[44:47]
	v_mfma_f32_16x16x32_bf16 v[36:39], v[200:203], v[176:179], v[36:39]
	v_mfma_f32_16x16x32_bf16 v[32:35], v[208:211], v[176:179], v[32:35]
	v_mfma_f32_16x16x32_bf16 v[20:23], v[200:203], v[184:187], v[20:23]
	v_mfma_f32_16x16x32_bf16 v[12:15], v[208:211], v[184:187], v[12:15]
	v_mfma_f32_16x16x32_bf16 v[4:7], v[200:203], v[192:195], v[4:7]
	v_mfma_f32_16x16x32_bf16 v[0:3], v[208:211], v[192:195], v[0:3]
	s_setprio 0
	s_add_i32 s68, s68, 2
	s_add_u32 s49, s49, 0x100
	s_addc_u32 s63, s63, 0
	s_cmp_gt_u32 s68, 41
	s_mov_b64 s[28:29], s[30:31]
	s_barrier
	s_cbranch_scc0 .LBB0_860
	v_lshl_or_b32 v144, s47, 8, v148
	v_lshl_add_u32 v145, s48, 8, v146
	v_lshlrev_b32_e32 v144, 2, v144
	v_lshl_add_u32 v145, v145, 12, v144
	v_add_u32_e32 v216, 0x10000, v145
	v_add_u32_e32 v217, 0x20000, v145
	v_add_u32_e32 v218, 0x30000, v145
	v_add_u32_e32 v220, 0x80000, v145
	v_add_u32_e32 v221, 0x90000, v145
	v_add_u32_e32 v222, 0xa0000, v145
	v_add_u32_e32 v223, 0xb0000, v145
	v_and_b32_e32 v235, 8, v146
	v_cmp_ne_u32_e32 vcc, 0, v235
	v_mov_b32_e32 v232, 0xffff8040
	s_nop 0
	v_cndmask_b32_e32 v232, 0, v232, vcc
	v_mov_b32_e32 v233, 64
	v_mov_b32_e32 v235, 0x8000
	v_cndmask_b32_e32 v233, v235, v233, vcc
	v_add_u32_e32 v224, v145, v232
	v_add_u32_e32 v225, v216, v232
	v_add_u32_e32 v226, v217, v232
	v_add_u32_e32 v227, v218, v232
	v_add_u32_e32 v228, v220, v232
	v_add_u32_e32 v229, v221, v232
	v_add_u32_e32 v230, v222, v232
	v_add_u32_e32 v231, v223, v232
	s_and_b64 vcc, exec, s[10:11]
	s_mov_b32 s47, s45
	s_mov_b32 s48, s46
	s_mov_b64 s[30:31], s[14:15]
	s_mov_b64 s[28:29], s[12:13]
	global_load_dwordx4 v[140:143], v224, s[52:53]
	v_add_u32_e32 v144, v145, v233
	global_load_dwordx4 v[152:155], v144, s[52:53]
	global_load_dwordx4 v[156:159], v224, s[52:53] offset:512
	v_add_u32_e32 v144, v145, v233
	global_load_dwordx4 v[160:163], v144, s[52:53] offset:512
	global_load_dwordx4 v[164:167], v225, s[52:53]
	v_add_u32_e32 v144, v216, v233
	global_load_dwordx4 v[168:171], v144, s[52:53]
	global_load_dwordx4 v[172:175], v225, s[52:53] offset:512
	v_add_u32_e32 v144, v216, v233
	global_load_dwordx4 v[176:179], v144, s[52:53] offset:512
	global_load_dwordx4 v[180:183], v226, s[52:53]
	v_add_u32_e32 v144, v217, v233
	global_load_dwordx4 v[184:187], v144, s[52:53]
	global_load_dwordx4 v[188:191], v226, s[52:53] offset:512
	v_add_u32_e32 v144, v217, v233
	global_load_dwordx4 v[192:195], v144, s[52:53] offset:512
	global_load_dwordx4 v[196:199], v227, s[52:53]
	v_add_u32_e32 v144, v218, v233
	global_load_dwordx4 v[200:203], v144, s[52:53]
	global_load_dwordx4 v[204:207], v227, s[52:53] offset:512
	v_add_u32_e32 v144, v218, v233
	global_load_dwordx4 v[208:211], v144, s[52:53] offset:512
	s_barrier
;     __device__ __forceinline__ void operator()(AccRef acc, const Unit& u, int wr, int wc, int fr, int fq) const {
;     ...
;                 sv[bj][n] = scale ? *(const f32x4*)(scale + col0 + bj * 128 + n * 16) : (f32x4){1.f, 1.f, 1.f, 1.f};
;                 bv[bj][n] = bias ? *(const f32x4*)(bias + col0 + bj * 128 + n * 16) : (f32x4){0.f, 0.f, 0.f, 0.f}; }
; #pragma unroll
;         for (int ai = 0; ai < 2; ++ai)
; #pragma unroll
;             for (int mh = 0; mh < 2; ++mh) {
;                 f32x4 bs[2][2][2];
; #pragma unroll
;                 for (int m = 0; m < 2; ++m)
; #pragma unroll
;                     for (int bj = 0; bj < 2; ++bj)
; #pragma unroll
;                         for (int n = 0; n < 2; ++n) bs[m][bj][n] = *(const f32x4*)(base + (size_t)(row0 + ai * 128 + (2 * mh + m) * 16) * D + col0 + bj * 128 + n * 16);
; #pragma unroll
;                 for (int m = 0; m < 2; ++m)
; #pragma unroll
;                     for (int bj = 0; bj < 2; ++bj)
; #pragma unroll
;                         for (int n = 0; n < 2; ++n) *(f32x4*)(out + (size_t)(row0 + ai * 128 + (2 * mh + m) * 16) * D + col0 + bj * 128 + n * 16) = bs[m][bj][n] + sv[bj][n] * (acc[ai][bj][2 * mh + m][n] + bv[bj][n]);
	v_pk_add_f32 v[124:125], v[124:125], 0 op_sel_hi:[1,0]
	v_pk_add_f32 v[126:127], v[126:127], 0 op_sel_hi:[1,0]
	v_pk_add_f32 v[120:121], v[120:121], 0 op_sel_hi:[1,0]
	v_pk_add_f32 v[122:123], v[122:123], 0 op_sel_hi:[1,0]
	v_pk_add_f32 v[116:117], v[116:117], 0 op_sel_hi:[1,0]
	v_pk_add_f32 v[118:119], v[118:119], 0 op_sel_hi:[1,0]
	v_pk_add_f32 v[108:109], v[108:109], 0 op_sel_hi:[1,0]
	v_pk_add_f32 v[110:111], v[110:111], 0 op_sel_hi:[1,0]
	v_pk_add_f32 v[112:113], v[112:113], 0 op_sel_hi:[1,0]
	v_pk_add_f32 v[114:115], v[114:115], 0 op_sel_hi:[1,0]
	v_pk_add_f32 v[104:105], v[104:105], 0 op_sel_hi:[1,0]
	v_pk_add_f32 v[106:107], v[106:107], 0 op_sel_hi:[1,0]
	v_pk_add_f32 v[100:101], v[100:101], 0 op_sel_hi:[1,0]
	v_pk_add_f32 v[102:103], v[102:103], 0 op_sel_hi:[1,0]
	v_pk_add_f32 v[96:97], v[96:97], 0 op_sel_hi:[1,0]
	v_pk_add_f32 v[98:99], v[98:99], 0 op_sel_hi:[1,0]
	v_pk_add_f32 v[92:93], v[92:93], 0 op_sel_hi:[1,0]
	v_pk_add_f32 v[94:95], v[94:95], 0 op_sel_hi:[1,0]
	v_pk_add_f32 v[88:89], v[88:89], 0 op_sel_hi:[1,0]
	v_pk_add_f32 v[90:91], v[90:91], 0 op_sel_hi:[1,0]
	v_pk_add_f32 v[84:85], v[84:85], 0 op_sel_hi:[1,0]
	v_pk_add_f32 v[86:87], v[86:87], 0 op_sel_hi:[1,0]
	v_pk_add_f32 v[76:77], v[76:77], 0 op_sel_hi:[1,0]
	v_pk_add_f32 v[78:79], v[78:79], 0 op_sel_hi:[1,0]
	v_pk_add_f32 v[80:81], v[80:81], 0 op_sel_hi:[1,0]
	v_pk_add_f32 v[82:83], v[82:83], 0 op_sel_hi:[1,0]
	v_pk_add_f32 v[72:73], v[72:73], 0 op_sel_hi:[1,0]
	v_pk_add_f32 v[74:75], v[74:75], 0 op_sel_hi:[1,0]
	v_pk_add_f32 v[68:69], v[68:69], 0 op_sel_hi:[1,0]
	v_pk_add_f32 v[70:71], v[70:71], 0 op_sel_hi:[1,0]
	v_pk_add_f32 v[64:65], v[64:65], 0 op_sel_hi:[1,0]
	v_pk_add_f32 v[66:67], v[66:67], 0 op_sel_hi:[1,0]
	v_pk_add_f32 v[60:61], v[60:61], 0 op_sel_hi:[1,0]
	v_pk_add_f32 v[62:63], v[62:63], 0 op_sel_hi:[1,0]
	v_pk_add_f32 v[56:57], v[56:57], 0 op_sel_hi:[1,0]
	v_pk_add_f32 v[58:59], v[58:59], 0 op_sel_hi:[1,0]
	v_pk_add_f32 v[52:53], v[52:53], 0 op_sel_hi:[1,0]
	v_pk_add_f32 v[54:55], v[54:55], 0 op_sel_hi:[1,0]
	v_pk_add_f32 v[44:45], v[44:45], 0 op_sel_hi:[1,0]
	v_pk_add_f32 v[46:47], v[46:47], 0 op_sel_hi:[1,0]
	v_pk_add_f32 v[48:49], v[48:49], 0 op_sel_hi:[1,0]
	v_pk_add_f32 v[50:51], v[50:51], 0 op_sel_hi:[1,0]
	v_pk_add_f32 v[40:41], v[40:41], 0 op_sel_hi:[1,0]
	v_pk_add_f32 v[42:43], v[42:43], 0 op_sel_hi:[1,0]
	v_pk_add_f32 v[36:37], v[36:37], 0 op_sel_hi:[1,0]
	v_pk_add_f32 v[38:39], v[38:39], 0 op_sel_hi:[1,0]
	v_pk_add_f32 v[32:33], v[32:33], 0 op_sel_hi:[1,0]
	v_pk_add_f32 v[34:35], v[34:35], 0 op_sel_hi:[1,0]
	v_pk_add_f32 v[28:29], v[28:29], 0 op_sel_hi:[1,0]
	v_pk_add_f32 v[30:31], v[30:31], 0 op_sel_hi:[1,0]
	v_pk_add_f32 v[24:25], v[24:25], 0 op_sel_hi:[1,0]
	v_pk_add_f32 v[26:27], v[26:27], 0 op_sel_hi:[1,0]
	v_pk_add_f32 v[20:21], v[20:21], 0 op_sel_hi:[1,0]
	v_pk_add_f32 v[22:23], v[22:23], 0 op_sel_hi:[1,0]
	v_pk_add_f32 v[12:13], v[12:13], 0 op_sel_hi:[1,0]
	v_pk_add_f32 v[14:15], v[14:15], 0 op_sel_hi:[1,0]
	v_pk_add_f32 v[16:17], v[16:17], 0 op_sel_hi:[1,0]
	v_pk_add_f32 v[18:19], v[18:19], 0 op_sel_hi:[1,0]
	v_pk_add_f32 v[8:9], v[8:9], 0 op_sel_hi:[1,0]
	v_pk_add_f32 v[10:11], v[10:11], 0 op_sel_hi:[1,0]
	v_pk_add_f32 v[4:5], v[4:5], 0 op_sel_hi:[1,0]
	v_pk_add_f32 v[6:7], v[6:7], 0 op_sel_hi:[1,0]
	v_pk_add_f32 v[0:1], v[0:1], 0 op_sel_hi:[1,0]
	v_pk_add_f32 v[2:3], v[2:3], 0 op_sel_hi:[1,0]
	s_waitcnt vmcnt(8)
	v_mov_b32_e32 v212, v124
	v_mov_b32_e32 v213, v125
	v_mov_b32_e32 v214, v126
	v_mov_b32_e32 v215, v127
	s_nop 0
	v_mov_b32_dpp v124, v120 row_shr:8 row_mask:0xf bank_mask:0xc
	v_mov_b32_dpp v125, v121 row_shr:8 row_mask:0xf bank_mask:0xc
	v_mov_b32_dpp v126, v122 row_shr:8 row_mask:0xf bank_mask:0xc
	v_mov_b32_dpp v127, v123 row_shr:8 row_mask:0xf bank_mask:0xc
	v_mov_b32_dpp v120, v212 row_shl:8 row_mask:0xf bank_mask:0x3
	v_mov_b32_dpp v121, v213 row_shl:8 row_mask:0xf bank_mask:0x3
	v_mov_b32_dpp v122, v214 row_shl:8 row_mask:0xf bank_mask:0x3
	v_mov_b32_dpp v123, v215 row_shl:8 row_mask:0xf bank_mask:0x3
	v_mov_b32_e32 v212, v116
	v_mov_b32_e32 v213, v117
	v_mov_b32_e32 v214, v118
	v_mov_b32_e32 v215, v119
	s_nop 0
	v_mov_b32_dpp v116, v108 row_shr:8 row_mask:0xf bank_mask:0xc
	v_mov_b32_dpp v117, v109 row_shr:8 row_mask:0xf bank_mask:0xc
	v_mov_b32_dpp v118, v110 row_shr:8 row_mask:0xf bank_mask:0xc
	v_mov_b32_dpp v119, v111 row_shr:8 row_mask:0xf bank_mask:0xc
	v_mov_b32_dpp v108, v212 row_shl:8 row_mask:0xf bank_mask:0x3
	v_mov_b32_dpp v109, v213 row_shl:8 row_mask:0xf bank_mask:0x3
	v_mov_b32_dpp v110, v214 row_shl:8 row_mask:0xf bank_mask:0x3
	v_mov_b32_dpp v111, v215 row_shl:8 row_mask:0xf bank_mask:0x3
	v_mov_b32_e32 v212, v112
	v_mov_b32_e32 v213, v113
	v_mov_b32_e32 v214, v114
	v_mov_b32_e32 v215, v115
	s_nop 0
	v_mov_b32_dpp v112, v104 row_shr:8 row_mask:0xf bank_mask:0xc
	v_mov_b32_dpp v113, v105 row_shr:8 row_mask:0xf bank_mask:0xc
	v_mov_b32_dpp v114, v106 row_shr:8 row_mask:0xf bank_mask:0xc
	v_mov_b32_dpp v115, v107 row_shr:8 row_mask:0xf bank_mask:0xc
	v_mov_b32_dpp v104, v212 row_shl:8 row_mask:0xf bank_mask:0x3
	v_mov_b32_dpp v105, v213 row_shl:8 row_mask:0xf bank_mask:0x3
	v_mov_b32_dpp v106, v214 row_shl:8 row_mask:0xf bank_mask:0x3
	v_mov_b32_dpp v107, v215 row_shl:8 row_mask:0xf bank_mask:0x3
	v_mov_b32_e32 v212, v100
	v_mov_b32_e32 v213, v101
	v_mov_b32_e32 v214, v102
	v_mov_b32_e32 v215, v103
	s_nop 0
	v_mov_b32_dpp v100, v96 row_shr:8 row_mask:0xf bank_mask:0xc
	v_mov_b32_dpp v101, v97 row_shr:8 row_mask:0xf bank_mask:0xc
	v_mov_b32_dpp v102, v98 row_shr:8 row_mask:0xf bank_mask:0xc
	v_mov_b32_dpp v103, v99 row_shr:8 row_mask:0xf bank_mask:0xc
	v_mov_b32_dpp v96, v212 row_shl:8 row_mask:0xf bank_mask:0x3
;     __device__ __forceinline__ void operator()(AccRef acc, const Unit& u, int wr, int wc, int fr, int fq) const {
;     ...
;                         for (int n = 0; n < 2; ++n) bs[m][bj][n] = *(const f32x4*)(base + (size_t)(row0 + ai * 128 + (2 * mh + m) * 16) * D + col0 + bj * 128 + n * 16);
; #pragma unroll
;                 for (int m = 0; m < 2; ++m)
; #pragma unroll
;                     for (int bj = 0; bj < 2; ++bj)
; #pragma unroll
;                         for (int n = 0; n < 2; ++n) *(f32x4*)(out + (size_t)(row0 + ai * 128 + (2 * mh + m) * 16) * D + col0 + bj * 128 + n * 16) = bs[m][bj][n] + sv[bj][n] * (acc[ai][bj][2 * mh + m][n] + bv[bj][n]);
;                 asm volatile("" ::: "memory"); }
	v_mov_b32_dpp v97, v213 row_shl:8 row_mask:0xf bank_mask:0x3
	v_mov_b32_dpp v98, v214 row_shl:8 row_mask:0xf bank_mask:0x3
	v_mov_b32_dpp v99, v215 row_shl:8 row_mask:0xf bank_mask:0x3
	v_pk_add_f32 v[124:125], v[124:125], v[140:141]
	v_pk_add_f32 v[126:127], v[126:127], v[142:143]
	v_pk_add_f32 v[120:121], v[120:121], v[152:153]
	v_pk_add_f32 v[122:123], v[122:123], v[154:155]
	v_pk_add_f32 v[116:117], v[116:117], v[156:157]
	v_pk_add_f32 v[118:119], v[118:119], v[158:159]
	v_pk_add_f32 v[108:109], v[108:109], v[160:161]
	v_pk_add_f32 v[110:111], v[110:111], v[162:163]
	v_pk_add_f32 v[112:113], v[112:113], v[164:165]
	v_pk_add_f32 v[114:115], v[114:115], v[166:167]
	v_pk_add_f32 v[104:105], v[104:105], v[168:169]
	v_pk_add_f32 v[106:107], v[106:107], v[170:171]
	v_pk_add_f32 v[100:101], v[100:101], v[172:173]
	v_pk_add_f32 v[102:103], v[102:103], v[174:175]
	v_pk_add_f32 v[96:97], v[96:97], v[176:177]
	v_pk_add_f32 v[98:99], v[98:99], v[178:179]
	global_store_dwordx4 v224, v[124:127], s[52:53]
	v_add_u32_e32 v144, v145, v233
	global_store_dwordx4 v144, v[120:123], s[52:53]
	global_store_dwordx4 v224, v[116:119], s[52:53] offset:512
	v_add_u32_e32 v144, v145, v233
	global_store_dwordx4 v144, v[108:111], s[52:53] offset:512
	global_store_dwordx4 v225, v[112:115], s[52:53]
	v_add_u32_e32 v144, v216, v233
	global_store_dwordx4 v144, v[104:107], s[52:53]
	global_store_dwordx4 v225, v[100:103], s[52:53] offset:512
	v_add_u32_e32 v144, v216, v233
	global_store_dwordx4 v144, v[96:99], s[52:53] offset:512
	global_load_dwordx4 v[140:143], v228, s[52:53]
	v_add_u32_e32 v144, v220, v233
	global_load_dwordx4 v[152:155], v144, s[52:53]
	global_load_dwordx4 v[156:159], v228, s[52:53] offset:512
	v_add_u32_e32 v144, v220, v233
	global_load_dwordx4 v[160:163], v144, s[52:53] offset:512
	global_load_dwordx4 v[164:167], v229, s[52:53]
	v_add_u32_e32 v144, v221, v233
	global_load_dwordx4 v[168:171], v144, s[52:53]
	global_load_dwordx4 v[172:175], v229, s[52:53] offset:512
	v_add_u32_e32 v144, v221, v233
	global_load_dwordx4 v[176:179], v144, s[52:53] offset:512
	s_waitcnt vmcnt(16)
	v_mov_b32_e32 v212, v92
	v_mov_b32_e32 v213, v93
	v_mov_b32_e32 v214, v94
	v_mov_b32_e32 v215, v95
	s_nop 0
	v_mov_b32_dpp v92, v88 row_shr:8 row_mask:0xf bank_mask:0xc
	v_mov_b32_dpp v93, v89 row_shr:8 row_mask:0xf bank_mask:0xc
	v_mov_b32_dpp v94, v90 row_shr:8 row_mask:0xf bank_mask:0xc
	v_mov_b32_dpp v95, v91 row_shr:8 row_mask:0xf bank_mask:0xc
	v_mov_b32_dpp v88, v212 row_shl:8 row_mask:0xf bank_mask:0x3
	v_mov_b32_dpp v89, v213 row_shl:8 row_mask:0xf bank_mask:0x3
	v_mov_b32_dpp v90, v214 row_shl:8 row_mask:0xf bank_mask:0x3
	v_mov_b32_dpp v91, v215 row_shl:8 row_mask:0xf bank_mask:0x3
	v_mov_b32_e32 v212, v84
	v_mov_b32_e32 v213, v85
	v_mov_b32_e32 v214, v86
	v_mov_b32_e32 v215, v87
	s_nop 0
	v_mov_b32_dpp v84, v76 row_shr:8 row_mask:0xf bank_mask:0xc
	v_mov_b32_dpp v85, v77 row_shr:8 row_mask:0xf bank_mask:0xc
	v_mov_b32_dpp v86, v78 row_shr:8 row_mask:0xf bank_mask:0xc
	v_mov_b32_dpp v87, v79 row_shr:8 row_mask:0xf bank_mask:0xc
	v_mov_b32_dpp v76, v212 row_shl:8 row_mask:0xf bank_mask:0x3
	v_mov_b32_dpp v77, v213 row_shl:8 row_mask:0xf bank_mask:0x3
	v_mov_b32_dpp v78, v214 row_shl:8 row_mask:0xf bank_mask:0x3
	v_mov_b32_dpp v79, v215 row_shl:8 row_mask:0xf bank_mask:0x3
	v_mov_b32_e32 v212, v80
	v_mov_b32_e32 v213, v81
	v_mov_b32_e32 v214, v82
	v_mov_b32_e32 v215, v83
	s_nop 0
	v_mov_b32_dpp v80, v72 row_shr:8 row_mask:0xf bank_mask:0xc
	v_mov_b32_dpp v81, v73 row_shr:8 row_mask:0xf bank_mask:0xc
	v_mov_b32_dpp v82, v74 row_shr:8 row_mask:0xf bank_mask:0xc
	v_mov_b32_dpp v83, v75 row_shr:8 row_mask:0xf bank_mask:0xc
	v_mov_b32_dpp v72, v212 row_shl:8 row_mask:0xf bank_mask:0x3
	v_mov_b32_dpp v73, v213 row_shl:8 row_mask:0xf bank_mask:0x3
	v_mov_b32_dpp v74, v214 row_shl:8 row_mask:0xf bank_mask:0x3
	v_mov_b32_dpp v75, v215 row_shl:8 row_mask:0xf bank_mask:0x3
	v_mov_b32_e32 v212, v68
	v_mov_b32_e32 v213, v69
	v_mov_b32_e32 v214, v70
	v_mov_b32_e32 v215, v71
	s_nop 0
	v_mov_b32_dpp v68, v64 row_shr:8 row_mask:0xf bank_mask:0xc
	v_mov_b32_dpp v69, v65 row_shr:8 row_mask:0xf bank_mask:0xc
	v_mov_b32_dpp v70, v66 row_shr:8 row_mask:0xf bank_mask:0xc
	v_mov_b32_dpp v71, v67 row_shr:8 row_mask:0xf bank_mask:0xc
	v_mov_b32_dpp v64, v212 row_shl:8 row_mask:0xf bank_mask:0x3
	v_mov_b32_dpp v65, v213 row_shl:8 row_mask:0xf bank_mask:0x3
	v_mov_b32_dpp v66, v214 row_shl:8 row_mask:0xf bank_mask:0x3
	v_mov_b32_dpp v67, v215 row_shl:8 row_mask:0xf bank_mask:0x3
	v_pk_add_f32 v[92:93], v[92:93], v[180:181]
	v_pk_add_f32 v[94:95], v[94:95], v[182:183]
	v_pk_add_f32 v[88:89], v[88:89], v[184:185]
	v_pk_add_f32 v[90:91], v[90:91], v[186:187]
	v_pk_add_f32 v[84:85], v[84:85], v[188:189]
	v_pk_add_f32 v[86:87], v[86:87], v[190:191]
	v_pk_add_f32 v[76:77], v[76:77], v[192:193]
	v_pk_add_f32 v[78:79], v[78:79], v[194:195]
	v_pk_add_f32 v[80:81], v[80:81], v[196:197]
	v_pk_add_f32 v[82:83], v[82:83], v[198:199]
	v_pk_add_f32 v[72:73], v[72:73], v[200:201]
	v_pk_add_f32 v[74:75], v[74:75], v[202:203]
	v_pk_add_f32 v[68:69], v[68:69], v[204:205]
	v_pk_add_f32 v[70:71], v[70:71], v[206:207]
	v_pk_add_f32 v[64:65], v[64:65], v[208:209]
	v_pk_add_f32 v[66:67], v[66:67], v[210:211]
	global_store_dwordx4 v226, v[92:95], s[52:53]
	v_add_u32_e32 v144, v217, v233
	global_store_dwordx4 v144, v[88:91], s[52:53]
	global_store_dwordx4 v226, v[84:87], s[52:53] offset:512
	v_add_u32_e32 v144, v217, v233
	global_store_dwordx4 v144, v[76:79], s[52:53] offset:512
	global_store_dwordx4 v227, v[80:83], s[52:53]
	v_add_u32_e32 v144, v218, v233
	global_store_dwordx4 v144, v[72:75], s[52:53]
	global_store_dwordx4 v227, v[68:71], s[52:53] offset:512
	v_add_u32_e32 v144, v218, v233
	global_store_dwordx4 v144, v[64:67], s[52:53] offset:512
	global_load_dwordx4 v[180:183], v230, s[52:53]
	v_add_u32_e32 v144, v222, v233
	global_load_dwordx4 v[184:187], v144, s[52:53]
	global_load_dwordx4 v[188:191], v230, s[52:53] offset:512
	v_add_u32_e32 v144, v222, v233
	global_load_dwordx4 v[192:195], v144, s[52:53] offset:512
	global_load_dwordx4 v[196:199], v231, s[52:53]
	v_add_u32_e32 v144, v223, v233
	global_load_dwordx4 v[200:203], v144, s[52:53]
	global_load_dwordx4 v[204:207], v231, s[52:53] offset:512
	v_add_u32_e32 v144, v223, v233
	global_load_dwordx4 v[208:211], v144, s[52:53] offset:512
	s_waitcnt vmcnt(16)
;     __device__ __forceinline__ void operator()(AccRef acc, const Unit& u, int wr, int wc, int fr, int fq) const {
;     ...
;                         for (int n = 0; n < 2; ++n) bs[m][bj][n] = *(const f32x4*)(base + (size_t)(row0 + ai * 128 + (2 * mh + m) * 16) * D + col0 + bj * 128 + n * 16);
; #pragma unroll
;                 for (int m = 0; m < 2; ++m)
; #pragma unroll
;                     for (int bj = 0; bj < 2; ++bj)
; #pragma unroll
;                         for (int n = 0; n < 2; ++n) *(f32x4*)(out + (size_t)(row0 + ai * 128 + (2 * mh + m) * 16) * D + col0 + bj * 128 + n * 16) = bs[m][bj][n] + sv[bj][n] * (acc[ai][bj][2 * mh + m][n] + bv[bj][n]);
;                 asm volatile("" ::: "memory"); }
	v_mov_b32_e32 v212, v60
	v_mov_b32_e32 v213, v61
	v_mov_b32_e32 v214, v62
	v_mov_b32_e32 v215, v63
	s_nop 0
	v_mov_b32_dpp v60, v56 row_shr:8 row_mask:0xf bank_mask:0xc
	v_mov_b32_dpp v61, v57 row_shr:8 row_mask:0xf bank_mask:0xc
	v_mov_b32_dpp v62, v58 row_shr:8 row_mask:0xf bank_mask:0xc
	v_mov_b32_dpp v63, v59 row_shr:8 row_mask:0xf bank_mask:0xc
	v_mov_b32_dpp v56, v212 row_shl:8 row_mask:0xf bank_mask:0x3
	v_mov_b32_dpp v57, v213 row_shl:8 row_mask:0xf bank_mask:0x3
	v_mov_b32_dpp v58, v214 row_shl:8 row_mask:0xf bank_mask:0x3
	v_mov_b32_dpp v59, v215 row_shl:8 row_mask:0xf bank_mask:0x3
	v_mov_b32_e32 v212, v52
	v_mov_b32_e32 v213, v53
	v_mov_b32_e32 v214, v54
	v_mov_b32_e32 v215, v55
	s_nop 0
	v_mov_b32_dpp v52, v44 row_shr:8 row_mask:0xf bank_mask:0xc
	v_mov_b32_dpp v53, v45 row_shr:8 row_mask:0xf bank_mask:0xc
	v_mov_b32_dpp v54, v46 row_shr:8 row_mask:0xf bank_mask:0xc
	v_mov_b32_dpp v55, v47 row_shr:8 row_mask:0xf bank_mask:0xc
	v_mov_b32_dpp v44, v212 row_shl:8 row_mask:0xf bank_mask:0x3
	v_mov_b32_dpp v45, v213 row_shl:8 row_mask:0xf bank_mask:0x3
	v_mov_b32_dpp v46, v214 row_shl:8 row_mask:0xf bank_mask:0x3
	v_mov_b32_dpp v47, v215 row_shl:8 row_mask:0xf bank_mask:0x3
	v_mov_b32_e32 v212, v48
	v_mov_b32_e32 v213, v49
	v_mov_b32_e32 v214, v50
	v_mov_b32_e32 v215, v51
	s_nop 0
	v_mov_b32_dpp v48, v40 row_shr:8 row_mask:0xf bank_mask:0xc
	v_mov_b32_dpp v49, v41 row_shr:8 row_mask:0xf bank_mask:0xc
	v_mov_b32_dpp v50, v42 row_shr:8 row_mask:0xf bank_mask:0xc
	v_mov_b32_dpp v51, v43 row_shr:8 row_mask:0xf bank_mask:0xc
	v_mov_b32_dpp v40, v212 row_shl:8 row_mask:0xf bank_mask:0x3
	v_mov_b32_dpp v41, v213 row_shl:8 row_mask:0xf bank_mask:0x3
	v_mov_b32_dpp v42, v214 row_shl:8 row_mask:0xf bank_mask:0x3
	v_mov_b32_dpp v43, v215 row_shl:8 row_mask:0xf bank_mask:0x3
	v_mov_b32_e32 v212, v36
	v_mov_b32_e32 v213, v37
	v_mov_b32_e32 v214, v38
	v_mov_b32_e32 v215, v39
	s_nop 0
	v_mov_b32_dpp v36, v32 row_shr:8 row_mask:0xf bank_mask:0xc
	v_mov_b32_dpp v37, v33 row_shr:8 row_mask:0xf bank_mask:0xc
	v_mov_b32_dpp v38, v34 row_shr:8 row_mask:0xf bank_mask:0xc
	v_mov_b32_dpp v39, v35 row_shr:8 row_mask:0xf bank_mask:0xc
	v_mov_b32_dpp v32, v212 row_shl:8 row_mask:0xf bank_mask:0x3
	v_mov_b32_dpp v33, v213 row_shl:8 row_mask:0xf bank_mask:0x3
	v_mov_b32_dpp v34, v214 row_shl:8 row_mask:0xf bank_mask:0x3
	v_mov_b32_dpp v35, v215 row_shl:8 row_mask:0xf bank_mask:0x3
	v_pk_add_f32 v[60:61], v[60:61], v[140:141]
	v_pk_add_f32 v[62:63], v[62:63], v[142:143]
	v_pk_add_f32 v[56:57], v[56:57], v[152:153]
	v_pk_add_f32 v[58:59], v[58:59], v[154:155]
	v_pk_add_f32 v[52:53], v[52:53], v[156:157]
	v_pk_add_f32 v[54:55], v[54:55], v[158:159]
	v_pk_add_f32 v[44:45], v[44:45], v[160:161]
	v_pk_add_f32 v[46:47], v[46:47], v[162:163]
	v_pk_add_f32 v[48:49], v[48:49], v[164:165]
	v_pk_add_f32 v[50:51], v[50:51], v[166:167]
	v_pk_add_f32 v[40:41], v[40:41], v[168:169]
	v_pk_add_f32 v[42:43], v[42:43], v[170:171]
	v_pk_add_f32 v[36:37], v[36:37], v[172:173]
	v_pk_add_f32 v[38:39], v[38:39], v[174:175]
	v_pk_add_f32 v[32:33], v[32:33], v[176:177]
	v_pk_add_f32 v[34:35], v[34:35], v[178:179]
	global_store_dwordx4 v228, v[60:63], s[52:53]
	v_add_u32_e32 v144, v220, v233
	global_store_dwordx4 v144, v[56:59], s[52:53]
	global_store_dwordx4 v228, v[52:55], s[52:53] offset:512
	v_add_u32_e32 v144, v220, v233
	global_store_dwordx4 v144, v[44:47], s[52:53] offset:512
	global_store_dwordx4 v229, v[48:51], s[52:53]
	v_add_u32_e32 v144, v221, v233
	global_store_dwordx4 v144, v[40:43], s[52:53]
	global_store_dwordx4 v229, v[36:39], s[52:53] offset:512
	v_add_u32_e32 v144, v221, v233
	global_store_dwordx4 v144, v[32:35], s[52:53] offset:512
	s_waitcnt vmcnt(8)
; #define PG8_WAIT_V(n) asm volatile("s_waitcnt vmcnt(" #n ")" ::: "memory")
; #define PG8_BAR __builtin_amdgcn_s_barrier()
; template <class Epi>
; __device__ __forceinline__ void gemm_phase(LAS unsigned char* lds, const Gemm g, const StaticOrder& S, const Epi& E) {
;     ...
;     PG8_WAIT_V(0);
;     if (wr == 0) PG8_BAR;
;     PG8_BAR;
;     __device__ __forceinline__ void operator()(AccRef acc, const Unit& u, int wr, int wc, int fr, int fq) const {
;     ...
;                         for (int n = 0; n < 2; ++n) bs[m][bj][n] = *(const f32x4*)(base + (size_t)(row0 + ai * 128 + (2 * mh + m) * 16) * D + col0 + bj * 128 + n * 16);
; #pragma unroll
;                 for (int m = 0; m < 2; ++m)
; #pragma unroll
;                     for (int bj = 0; bj < 2; ++bj)
; #pragma unroll
;                         for (int n = 0; n < 2; ++n) *(f32x4*)(out + (size_t)(row0 + ai * 128 + (2 * mh + m) * 16) * D + col0 + bj * 128 + n * 16) = bs[m][bj][n] + sv[bj][n] * (acc[ai][bj][2 * mh + m][n] + bv[bj][n]);
;                 asm volatile("" ::: "memory"); }
	v_mov_b32_e32 v212, v28
	v_mov_b32_e32 v213, v29
	v_mov_b32_e32 v214, v30
	v_mov_b32_e32 v215, v31
	s_nop 0
	v_mov_b32_dpp v28, v24 row_shr:8 row_mask:0xf bank_mask:0xc
	v_mov_b32_dpp v29, v25 row_shr:8 row_mask:0xf bank_mask:0xc
	v_mov_b32_dpp v30, v26 row_shr:8 row_mask:0xf bank_mask:0xc
	v_mov_b32_dpp v31, v27 row_shr:8 row_mask:0xf bank_mask:0xc
	v_mov_b32_dpp v24, v212 row_shl:8 row_mask:0xf bank_mask:0x3
	v_mov_b32_dpp v25, v213 row_shl:8 row_mask:0xf bank_mask:0x3
	v_mov_b32_dpp v26, v214 row_shl:8 row_mask:0xf bank_mask:0x3
	v_mov_b32_dpp v27, v215 row_shl:8 row_mask:0xf bank_mask:0x3
	v_mov_b32_e32 v212, v20
	v_mov_b32_e32 v213, v21
	v_mov_b32_e32 v214, v22
	v_mov_b32_e32 v215, v23
	s_nop 0
	v_mov_b32_dpp v20, v12 row_shr:8 row_mask:0xf bank_mask:0xc
	v_mov_b32_dpp v21, v13 row_shr:8 row_mask:0xf bank_mask:0xc
	v_mov_b32_dpp v22, v14 row_shr:8 row_mask:0xf bank_mask:0xc
	v_mov_b32_dpp v23, v15 row_shr:8 row_mask:0xf bank_mask:0xc
	v_mov_b32_dpp v12, v212 row_shl:8 row_mask:0xf bank_mask:0x3
	v_mov_b32_dpp v13, v213 row_shl:8 row_mask:0xf bank_mask:0x3
	v_mov_b32_dpp v14, v214 row_shl:8 row_mask:0xf bank_mask:0x3
	v_mov_b32_dpp v15, v215 row_shl:8 row_mask:0xf bank_mask:0x3
	v_mov_b32_e32 v212, v16
	v_mov_b32_e32 v213, v17
	v_mov_b32_e32 v214, v18
	v_mov_b32_e32 v215, v19
	s_nop 0
	v_mov_b32_dpp v16, v8 row_shr:8 row_mask:0xf bank_mask:0xc
	v_mov_b32_dpp v17, v9 row_shr:8 row_mask:0xf bank_mask:0xc
	v_mov_b32_dpp v18, v10 row_shr:8 row_mask:0xf bank_mask:0xc
	v_mov_b32_dpp v19, v11 row_shr:8 row_mask:0xf bank_mask:0xc
	v_mov_b32_dpp v8, v212 row_shl:8 row_mask:0xf bank_mask:0x3
	v_mov_b32_dpp v9, v213 row_shl:8 row_mask:0xf bank_mask:0x3
	v_mov_b32_dpp v10, v214 row_shl:8 row_mask:0xf bank_mask:0x3
	v_mov_b32_dpp v11, v215 row_shl:8 row_mask:0xf bank_mask:0x3
	v_mov_b32_e32 v212, v4
	v_mov_b32_e32 v213, v5
	v_mov_b32_e32 v214, v6
	v_mov_b32_e32 v215, v7
	s_nop 0
	v_mov_b32_dpp v4, v0 row_shr:8 row_mask:0xf bank_mask:0xc
	v_mov_b32_dpp v5, v1 row_shr:8 row_mask:0xf bank_mask:0xc
	v_mov_b32_dpp v6, v2 row_shr:8 row_mask:0xf bank_mask:0xc
	v_mov_b32_dpp v7, v3 row_shr:8 row_mask:0xf bank_mask:0xc
	v_mov_b32_dpp v0, v212 row_shl:8 row_mask:0xf bank_mask:0x3
	v_mov_b32_dpp v1, v213 row_shl:8 row_mask:0xf bank_mask:0x3
	v_mov_b32_dpp v2, v214 row_shl:8 row_mask:0xf bank_mask:0x3
	v_mov_b32_dpp v3, v215 row_shl:8 row_mask:0xf bank_mask:0x3
	v_pk_add_f32 v[28:29], v[28:29], v[180:181]
	v_pk_add_f32 v[30:31], v[30:31], v[182:183]
	v_pk_add_f32 v[24:25], v[24:25], v[184:185]
	v_pk_add_f32 v[26:27], v[26:27], v[186:187]
	v_pk_add_f32 v[20:21], v[20:21], v[188:189]
	v_pk_add_f32 v[22:23], v[22:23], v[190:191]
	v_pk_add_f32 v[12:13], v[12:13], v[192:193]
	v_pk_add_f32 v[14:15], v[14:15], v[194:195]
	v_pk_add_f32 v[16:17], v[16:17], v[196:197]
	v_pk_add_f32 v[18:19], v[18:19], v[198:199]
	v_pk_add_f32 v[8:9], v[8:9], v[200:201]
	v_pk_add_f32 v[10:11], v[10:11], v[202:203]
	v_pk_add_f32 v[4:5], v[4:5], v[204:205]
	v_pk_add_f32 v[6:7], v[6:7], v[206:207]
	v_pk_add_f32 v[0:1], v[0:1], v[208:209]
	v_pk_add_f32 v[2:3], v[2:3], v[210:211]
	global_store_dwordx4 v230, v[28:31], s[52:53]
	v_add_u32_e32 v144, v222, v233
	global_store_dwordx4 v144, v[24:27], s[52:53]
	global_store_dwordx4 v230, v[20:23], s[52:53] offset:512
	v_add_u32_e32 v144, v222, v233
	global_store_dwordx4 v144, v[12:15], s[52:53] offset:512
	global_store_dwordx4 v231, v[16:19], s[52:53]
	v_add_u32_e32 v144, v223, v233
	global_store_dwordx4 v144, v[8:11], s[52:53]
	global_store_dwordx4 v231, v[4:7], s[52:53] offset:512
	v_add_u32_e32 v144, v223, v233
	global_store_dwordx4 v144, v[0:3], s[52:53] offset:512
	s_cbranch_vccz .LBB0_849
	s_waitcnt vmcnt(0)
	s_cmpk_gt_u32 s4, 0xff
	s_cbranch_scc1 .LBB0_864
	s_barrier

; #define PG8_STAGE(bufoff, gbase, voff) do { _Pragma("unroll") for (int _i = 0; _i < 2; ++_i) \
;         __builtin_amdgcn_global_load_lds((const unsigned*)((const char*)(gbase) + (voff)[_i]), (LAS unsigned*)(lds + (bufoff) + ldsw + _i * 8192), 16, 0, 0); } while (0)
; #define PG8_LDA(dst, b, h) do { _Pragma("unroll") for (int m = 0; m < 4; ++m) _Pragma("unroll") for (int k = 0; k < 2; ++k) dst[m][k] = *(const LAS bf16x8*)(lds + PG8_SA(b, h) + aoff + m * 2048 + k * 1024); } while (0)
; #define PG8_LDB(dst, b, h) do { _Pragma("unroll") for (int n = 0; n < 2; ++n) _Pragma("unroll") for (int k = 0; k < 2; ++k) dst[n][k] = *(const LAS bf16x8*)(lds + PG8_SB(b, h) + boff + n * 2048 + k * 1024); } while (0)
; #define PG8_MMA(ai, bj, At, Bt) do { __builtin_amdgcn_s_setprio(1); _Pragma("unroll") for (int m = 0; m < 4; ++m) _Pragma("unroll") for (int n = 0; n < 2; ++n) _Pragma("unroll") for (int k = 0; k < 2; ++k) \
;         acc[ai][bj][m][n] = __builtin_amdgcn_mfma_f32_16x16x32_bf16(Bt[n][k], At[m][k], acc[ai][bj][m][n], 0, 0, 0); __builtin_amdgcn_s_setprio(0); } while (0)
; #define PG8_WAIT_V(n) asm volatile("s_waitcnt vmcnt(" #n ")" ::: "memory")
; #define PG8_WAIT_L(n) asm volatile("s_waitcnt lgkmcnt(" #n ")" ::: "memory")
; #define PG8_BAR __builtin_amdgcn_s_barrier()
; #define PG8_SCHED __builtin_amdgcn_sched_barrier(0)
; template <class Epi>
; __device__ __forceinline__ void gemm_phase(LAS unsigned char* lds, const Gemm g, const StaticOrder& S, const Epi& E) {
;     ...
;             PG8_LDB(B0, 0, 0); PG8_SCHED; PG8_LDA(At, 0, 0); PG8_STAGE(PG8_SA(1, 1), a1 + hstepA, voffA);
;             PG8_WAIT_L(8); PG8_BAR; PG8_WAIT_L(0); PG8_MMA(0, 0, At, B0); PG8_BAR; PG8_SCHED;
;             PG8_LDB(B1, 0, 1); PG8_STAGE(PG8_SB(0, 0), b2, voffB);
;             PG8_BAR; PG8_WAIT_L(0); PG8_MMA(0, 1, At, B1); PG8_BAR;
;             PG8_LDA(At, 0, 1); PG8_STAGE(PG8_SA(0, 0), a2, voffA);
;             PG8_BAR; PG8_WAIT_L(0); PG8_MMA(1, 0, At, B0); PG8_BAR; PG8_SCHED;
;             PG8_STAGE(PG8_SB(0, 1), b2 + hstepB, voffB);
;             PG8_WAIT_V(6); PG8_BAR; PG8_MMA(1, 1, At, B1); PG8_BAR;
.LBB0_1239:
	ds_read_b128 v[140:143], v149
	ds_read_b128 v[152:155], v149 offset:1024
	ds_read_b128 v[156:159], v149 offset:2048
	ds_read_b128 v[160:163], v149 offset:3072
	s_add_u32 s40, s38, 0xfffc0080
	s_addc_u32 s41, s39, -1
	s_cmp_eq_u32 s76, 12
	s_cselect_b32 s43, s29, s41
	s_cselect_b32 s42, s72, s40
	s_cselect_b32 s41, s27, s75
	s_cselect_b32 s40, s73, s74
	v_lshl_add_u64 v[144:145], s[38:39], 0, v[132:133]
	s_add_i32 m0, s8, 0xc000
	ds_read_b128 v[164:167], v150
	ds_read_b128 v[168:171], v150 offset:1024
	ds_read_b128 v[172:175], v150 offset:2048
	ds_read_b128 v[176:179], v150 offset:3072
	ds_read_b128 v[180:183], v150 offset:4096
	ds_read_b128 v[184:187], v150 offset:5120
	ds_read_b128 v[188:191], v150 offset:6144
	ds_read_b128 v[192:195], v150 offset:7168
	global_load_lds_dwordx4 v[144:145], off
	v_lshl_add_u64 v[144:145], s[38:39], 0, v[134:135]
	s_add_i32 m0, s8, 0xe000
	s_nop 0
	global_load_lds_dwordx4 v[144:145], off
	ds_read_b128 v[196:199], v151
	ds_read_b128 v[200:203], v151 offset:1024
	ds_read_b128 v[204:207], v151 offset:2048
	ds_read_b128 v[208:211], v151 offset:3072
	s_waitcnt lgkmcnt(0)
	s_barrier
	s_setprio 1
	v_mfma_f32_16x16x32_bf16 v[124:127], v[140:143], v[164:167], v[124:127]
	v_mfma_f32_16x16x32_bf16 v[120:123], v[156:159], v[164:167], v[120:123]
	v_mfma_f32_16x16x32_bf16 v[112:115], v[140:143], v[172:175], v[112:115]
	v_mfma_f32_16x16x32_bf16 v[104:107], v[156:159], v[172:175], v[104:107]
	v_mfma_f32_16x16x32_bf16 v[92:95], v[140:143], v[180:183], v[92:95]
	v_mfma_f32_16x16x32_bf16 v[88:91], v[156:159], v[180:183], v[88:91]
	v_mfma_f32_16x16x32_bf16 v[80:83], v[140:143], v[188:191], v[80:83]
	v_mfma_f32_16x16x32_bf16 v[72:75], v[156:159], v[188:191], v[72:75]
	v_mfma_f32_16x16x32_bf16 v[124:127], v[152:155], v[168:171], v[124:127]
	v_mfma_f32_16x16x32_bf16 v[120:123], v[160:163], v[168:171], v[120:123]
	v_mfma_f32_16x16x32_bf16 v[112:115], v[152:155], v[176:179], v[112:115]
	v_mfma_f32_16x16x32_bf16 v[104:107], v[160:163], v[176:179], v[104:107]
	v_mfma_f32_16x16x32_bf16 v[92:95], v[152:155], v[184:187], v[92:95]
	v_mfma_f32_16x16x32_bf16 v[88:91], v[160:163], v[184:187], v[88:91]
	v_mfma_f32_16x16x32_bf16 v[80:83], v[152:155], v[192:195], v[80:83]
	v_mfma_f32_16x16x32_bf16 v[72:75], v[160:163], v[192:195], v[72:75]
	v_mfma_f32_16x16x32_bf16 v[116:119], v[196:199], v[164:167], v[116:119]
	v_mfma_f32_16x16x32_bf16 v[108:111], v[204:207], v[164:167], v[108:111]
	v_mfma_f32_16x16x32_bf16 v[100:103], v[196:199], v[172:175], v[100:103]
	v_mfma_f32_16x16x32_bf16 v[96:99], v[204:207], v[172:175], v[96:99]
	v_mfma_f32_16x16x32_bf16 v[84:87], v[196:199], v[180:183], v[84:87]
	v_mfma_f32_16x16x32_bf16 v[76:79], v[204:207], v[180:183], v[76:79]
	v_mfma_f32_16x16x32_bf16 v[68:71], v[196:199], v[188:191], v[68:71]
	v_mfma_f32_16x16x32_bf16 v[64:67], v[204:207], v[188:191], v[64:67]
	v_mfma_f32_16x16x32_bf16 v[116:119], v[200:203], v[168:171], v[116:119]
	v_mfma_f32_16x16x32_bf16 v[108:111], v[208:211], v[168:171], v[108:111]
	v_mfma_f32_16x16x32_bf16 v[100:103], v[200:203], v[176:179], v[100:103]
	v_mfma_f32_16x16x32_bf16 v[96:99], v[208:211], v[176:179], v[96:99]
	v_mfma_f32_16x16x32_bf16 v[84:87], v[200:203], v[184:187], v[84:87]
	v_mfma_f32_16x16x32_bf16 v[76:79], v[208:211], v[184:187], v[76:79]
	v_mfma_f32_16x16x32_bf16 v[68:71], v[200:203], v[192:195], v[68:71]
	v_mfma_f32_16x16x32_bf16 v[64:67], v[208:211], v[192:195], v[64:67]
	s_setprio 0
	s_barrier
	s_nop 1
	ds_read_b128 v[164:167], v150 offset:16384
	ds_read_b128 v[168:171], v150 offset:17408
	ds_read_b128 v[172:175], v150 offset:18432
	ds_read_b128 v[176:179], v150 offset:19456
	ds_read_b128 v[180:183], v150 offset:20480
	ds_read_b128 v[184:187], v150 offset:21504
	ds_read_b128 v[188:191], v150 offset:22528
	ds_read_b128 v[192:195], v150 offset:23552
	s_add_i32 s77, s48, s7
	v_lshl_add_u64 v[144:145], s[40:41], 0, v[128:129]
	s_mov_b32 m0, s77
	s_nop 0
	global_load_lds_dwordx4 v[144:145], off
	v_lshl_add_u64 v[212:213], s[40:41], 0, v[130:131]
	s_add_i32 m0, s77, 0x2000
	s_nop 0
	global_load_lds_dwordx4 v[212:213], off
	s_mov_b32 m0, s8
	v_lshl_add_u64 v[214:215], s[42:43], 0, v[128:129]
	global_load_lds_dwordx4 v[214:215], off
	v_lshl_add_u64 v[216:217], s[42:43], 0, v[130:131]
	s_mov_b32 m0, s9
	s_nop 0
	global_load_lds_dwordx4 v[216:217], off
	s_add_u32 s78, s40, 0x40000
	s_addc_u32 s79, s41, 0
	s_add_i32 s77, s49, s7
	v_lshl_add_u64 v[254:255], s[78:79], 0, v[128:129]
	s_mov_b32 m0, s77
	s_nop 0
	global_load_lds_dwordx4 v[254:255], off
	v_lshl_add_u64 v[254:255], s[78:79], 0, v[130:131]
	s_add_i32 m0, s77, 0x2000
	s_nop 0
	global_load_lds_dwordx4 v[254:255], off
	s_waitcnt vmcnt(6)
	s_waitcnt lgkmcnt(0)
	s_barrier
; #define PG8_STAGE(bufoff, gbase, voff) do { _Pragma("unroll") for (int _i = 0; _i < 2; ++_i) \
;         __builtin_amdgcn_global_load_lds((const unsigned*)((const char*)(gbase) + (voff)[_i]), (LAS unsigned*)(lds + (bufoff) + ldsw + _i * 8192), 16, 0, 0); } while (0)
; #define PG8_LDA(dst, b, h) do { _Pragma("unroll") for (int m = 0; m < 4; ++m) _Pragma("unroll") for (int k = 0; k < 2; ++k) dst[m][k] = *(const LAS bf16x8*)(lds + PG8_SA(b, h) + aoff + m * 2048 + k * 1024); } while (0)
; #define PG8_LDB(dst, b, h) do { _Pragma("unroll") for (int n = 0; n < 2; ++n) _Pragma("unroll") for (int k = 0; k < 2; ++k) dst[n][k] = *(const LAS bf16x8*)(lds + PG8_SB(b, h) + boff + n * 2048 + k * 1024); } while (0)
; #define PG8_MMA(ai, bj, At, Bt) do { __builtin_amdgcn_s_setprio(1); _Pragma("unroll") for (int m = 0; m < 4; ++m) _Pragma("unroll") for (int n = 0; n < 2; ++n) _Pragma("unroll") for (int k = 0; k < 2; ++k) \
;         acc[ai][bj][m][n] = __builtin_amdgcn_mfma_f32_16x16x32_bf16(Bt[n][k], At[m][k], acc[ai][bj][m][n], 0, 0, 0); __builtin_amdgcn_s_setprio(0); } while (0)
; #define PG8_WAIT_V(n) asm volatile("s_waitcnt vmcnt(" #n ")" ::: "memory")
; #define PG8_WAIT_L(n) asm volatile("s_waitcnt lgkmcnt(" #n ")" ::: "memory")
; #define PG8_BAR __builtin_amdgcn_s_barrier()
; #define PG8_SCHED __builtin_amdgcn_sched_barrier(0)
; template <class Epi>
; __device__ __forceinline__ void gemm_phase(LAS unsigned char* lds, const Gemm g, const StaticOrder& S, const Epi& E) {
;     ...
;             PG8_WAIT_V(6); PG8_BAR; PG8_MMA(1, 1, At, B1); PG8_BAR;
;             PG8_LDB(B0, 1, 0); PG8_SCHED; PG8_LDA(At, 1, 0); PG8_STAGE(PG8_SA(0, 1), a2 + hstepA, voffA);
;             PG8_WAIT_L(8); PG8_BAR; PG8_WAIT_L(0); PG8_MMA(0, 0, At, B0); PG8_BAR; PG8_SCHED;
;             PG8_LDB(B1, 1, 1); PG8_STAGE(PG8_SB(1, 0), b3, voffB);
;             PG8_BAR; PG8_WAIT_L(0); PG8_MMA(0, 1, At, B1); PG8_BAR;
;             PG8_LDA(At, 1, 1); PG8_STAGE(PG8_SA(1, 0), a3, voffA);
;             PG8_BAR; PG8_WAIT_L(0); PG8_MMA(1, 0, At, B0); PG8_BAR; PG8_SCHED;
	s_setprio 1
	v_mfma_f32_16x16x32_bf16 v[60:63], v[140:143], v[164:167], v[60:63]
	v_mfma_f32_16x16x32_bf16 v[56:59], v[156:159], v[164:167], v[56:59]
	v_mfma_f32_16x16x32_bf16 v[48:51], v[140:143], v[172:175], v[48:51]
	v_mfma_f32_16x16x32_bf16 v[40:43], v[156:159], v[172:175], v[40:43]
	v_mfma_f32_16x16x32_bf16 v[28:31], v[140:143], v[180:183], v[28:31]
	v_mfma_f32_16x16x32_bf16 v[24:27], v[156:159], v[180:183], v[24:27]
	v_mfma_f32_16x16x32_bf16 v[16:19], v[140:143], v[188:191], v[16:19]
	v_mfma_f32_16x16x32_bf16 v[8:11], v[156:159], v[188:191], v[8:11]
	v_mfma_f32_16x16x32_bf16 v[60:63], v[152:155], v[168:171], v[60:63]
	v_mfma_f32_16x16x32_bf16 v[56:59], v[160:163], v[168:171], v[56:59]
	v_mfma_f32_16x16x32_bf16 v[48:51], v[152:155], v[176:179], v[48:51]
	v_mfma_f32_16x16x32_bf16 v[40:43], v[160:163], v[176:179], v[40:43]
	v_mfma_f32_16x16x32_bf16 v[28:31], v[152:155], v[184:187], v[28:31]
	v_mfma_f32_16x16x32_bf16 v[24:27], v[160:163], v[184:187], v[24:27]
	v_mfma_f32_16x16x32_bf16 v[16:19], v[152:155], v[192:195], v[16:19]
	v_mfma_f32_16x16x32_bf16 v[8:11], v[160:163], v[192:195], v[8:11]
	v_mfma_f32_16x16x32_bf16 v[52:55], v[196:199], v[164:167], v[52:55]
	v_mfma_f32_16x16x32_bf16 v[44:47], v[204:207], v[164:167], v[44:47]
	v_mfma_f32_16x16x32_bf16 v[36:39], v[196:199], v[172:175], v[36:39]
	v_mfma_f32_16x16x32_bf16 v[32:35], v[204:207], v[172:175], v[32:35]
	v_mfma_f32_16x16x32_bf16 v[20:23], v[196:199], v[180:183], v[20:23]
	v_mfma_f32_16x16x32_bf16 v[12:15], v[204:207], v[180:183], v[12:15]
	v_mfma_f32_16x16x32_bf16 v[4:7], v[196:199], v[188:191], v[4:7]
	v_mfma_f32_16x16x32_bf16 v[0:3], v[204:207], v[188:191], v[0:3]
	v_mfma_f32_16x16x32_bf16 v[52:55], v[200:203], v[168:171], v[52:55]
	v_mfma_f32_16x16x32_bf16 v[44:47], v[208:211], v[168:171], v[44:47]
	v_mfma_f32_16x16x32_bf16 v[36:39], v[200:203], v[176:179], v[36:39]
	v_mfma_f32_16x16x32_bf16 v[32:35], v[208:211], v[176:179], v[32:35]
	v_mfma_f32_16x16x32_bf16 v[20:23], v[200:203], v[184:187], v[20:23]
	v_mfma_f32_16x16x32_bf16 v[12:15], v[208:211], v[184:187], v[12:15]
	v_mfma_f32_16x16x32_bf16 v[4:7], v[200:203], v[192:195], v[4:7]
	v_mfma_f32_16x16x32_bf16 v[0:3], v[208:211], v[192:195], v[0:3]
	s_setprio 0
	s_add_i32 s77, 0, 0x18000
	v_add_u32_e32 v160, s77, v147
	s_barrier
	ds_read_b128 v[140:143], v160
	ds_read_b128 v[152:155], v160 offset:1024
	ds_read_b128 v[156:159], v160 offset:2048
	ds_read_b128 v[160:163], v160 offset:3072
	s_add_u32 s42, s42, 0x40000
	s_addc_u32 s43, s43, 0
	s_mov_b32 m0, s37
	v_lshl_add_u64 v[196:197], s[42:43], 0, v[128:129]
	ds_read_b128 v[164:167], v150 offset:32768
	ds_read_b128 v[168:171], v150 offset:33792
	ds_read_b128 v[172:175], v150 offset:34816
	ds_read_b128 v[176:179], v150 offset:35840
	ds_read_b128 v[180:183], v150 offset:36864
	ds_read_b128 v[184:187], v150 offset:37888
	ds_read_b128 v[188:191], v150 offset:38912
	ds_read_b128 v[192:195], v150 offset:39936
	global_load_lds_dwordx4 v[196:197], off
	v_lshl_add_u64 v[196:197], s[42:43], 0, v[130:131]
	s_mov_b32 m0, s44
	s_nop 0
	global_load_lds_dwordx4 v[196:197], off
	s_add_i32 s42, 0, 0x1c000
	v_add_u32_e32 v208, s42, v147
	ds_read_b128 v[196:199], v208
	ds_read_b128 v[200:203], v208 offset:1024
	ds_read_b128 v[204:207], v208 offset:2048
	ds_read_b128 v[208:211], v208 offset:3072
	s_waitcnt lgkmcnt(0)
	s_barrier
	s_setprio 1
	v_mfma_f32_16x16x32_bf16 v[124:127], v[140:143], v[164:167], v[124:127]
	v_mfma_f32_16x16x32_bf16 v[120:123], v[156:159], v[164:167], v[120:123]
	v_mfma_f32_16x16x32_bf16 v[112:115], v[140:143], v[172:175], v[112:115]
	v_mfma_f32_16x16x32_bf16 v[104:107], v[156:159], v[172:175], v[104:107]
	v_mfma_f32_16x16x32_bf16 v[92:95], v[140:143], v[180:183], v[92:95]
	v_mfma_f32_16x16x32_bf16 v[88:91], v[156:159], v[180:183], v[88:91]
	v_mfma_f32_16x16x32_bf16 v[80:83], v[140:143], v[188:191], v[80:83]
	v_mfma_f32_16x16x32_bf16 v[72:75], v[156:159], v[188:191], v[72:75]
	v_mfma_f32_16x16x32_bf16 v[124:127], v[152:155], v[168:171], v[124:127]
	v_mfma_f32_16x16x32_bf16 v[120:123], v[160:163], v[168:171], v[120:123]
	v_mfma_f32_16x16x32_bf16 v[112:115], v[152:155], v[176:179], v[112:115]
	v_mfma_f32_16x16x32_bf16 v[104:107], v[160:163], v[176:179], v[104:107]
	v_mfma_f32_16x16x32_bf16 v[92:95], v[152:155], v[184:187], v[92:95]
	v_mfma_f32_16x16x32_bf16 v[88:91], v[160:163], v[184:187], v[88:91]
	v_mfma_f32_16x16x32_bf16 v[80:83], v[152:155], v[192:195], v[80:83]
	v_mfma_f32_16x16x32_bf16 v[72:75], v[160:163], v[192:195], v[72:75]
	v_mfma_f32_16x16x32_bf16 v[116:119], v[196:199], v[164:167], v[116:119]
	v_mfma_f32_16x16x32_bf16 v[108:111], v[204:207], v[164:167], v[108:111]
	v_mfma_f32_16x16x32_bf16 v[100:103], v[196:199], v[172:175], v[100:103]
	v_mfma_f32_16x16x32_bf16 v[96:99], v[204:207], v[172:175], v[96:99]
	v_mfma_f32_16x16x32_bf16 v[84:87], v[196:199], v[180:183], v[84:87]
	v_mfma_f32_16x16x32_bf16 v[76:79], v[204:207], v[180:183], v[76:79]
	v_mfma_f32_16x16x32_bf16 v[68:71], v[196:199], v[188:191], v[68:71]
	v_mfma_f32_16x16x32_bf16 v[64:67], v[204:207], v[188:191], v[64:67]
	v_mfma_f32_16x16x32_bf16 v[116:119], v[200:203], v[168:171], v[116:119]
	v_mfma_f32_16x16x32_bf16 v[108:111], v[208:211], v[168:171], v[108:111]
	v_mfma_f32_16x16x32_bf16 v[100:103], v[200:203], v[176:179], v[100:103]
	v_mfma_f32_16x16x32_bf16 v[96:99], v[208:211], v[176:179], v[96:99]
	v_mfma_f32_16x16x32_bf16 v[84:87], v[200:203], v[184:187], v[84:87]
	v_mfma_f32_16x16x32_bf16 v[76:79], v[208:211], v[184:187], v[76:79]
	v_mfma_f32_16x16x32_bf16 v[68:71], v[200:203], v[192:195], v[68:71]
	v_mfma_f32_16x16x32_bf16 v[64:67], v[208:211], v[192:195], v[64:67]
	s_setprio 0
	s_barrier
; #define PG8_STAGE(bufoff, gbase, voff) do { _Pragma("unroll") for (int _i = 0; _i < 2; ++_i) \
;         __builtin_amdgcn_global_load_lds((const unsigned*)((const char*)(gbase) + (voff)[_i]), (LAS unsigned*)(lds + (bufoff) + ldsw + _i * 8192), 16, 0, 0); } while (0)
; #define PG8_LDA(dst, b, h) do { _Pragma("unroll") for (int m = 0; m < 4; ++m) _Pragma("unroll") for (int k = 0; k < 2; ++k) dst[m][k] = *(const LAS bf16x8*)(lds + PG8_SA(b, h) + aoff + m * 2048 + k * 1024); } while (0)
; #define PG8_MMA(ai, bj, At, Bt) do { __builtin_amdgcn_s_setprio(1); _Pragma("unroll") for (int m = 0; m < 4; ++m) _Pragma("unroll") for (int n = 0; n < 2; ++n) _Pragma("unroll") for (int k = 0; k < 2; ++k) \
;         acc[ai][bj][m][n] = __builtin_amdgcn_mfma_f32_16x16x32_bf16(Bt[n][k], At[m][k], acc[ai][bj][m][n], 0, 0, 0); __builtin_amdgcn_s_setprio(0); } while (0)
; template <class Epi>
; __device__ __forceinline__ void gemm_phase(LAS unsigned char* lds, const Gemm g, const StaticOrder& S, const Epi& E) {
;     ...
;             PG8_LDA(At, 1, 1); PG8_STAGE(PG8_SA(1, 0), a3, voffA);
;             PG8_BAR; PG8_WAIT_L(0); PG8_MMA(1, 0, At, B0); PG8_BAR; PG8_SCHED;
;             PG8_STAGE(PG8_SB(1, 1), b3 + hstepB, voffB);
;             PG8_WAIT_V(6); PG8_BAR; PG8_MMA(1, 1, At, B1); PG8_BAR;
;         }
;     __device__ __forceinline__ void operator()(AccRef acc, const Unit& u, int wr, int wc, int fr, int fq) const {
;         const int row0 = u.pm * 256 + wr * 64 + fr, col0 = u.pn * 256 + wc * 32 + 4 * fq;
;         f32x4 sv[2][2], bv[2][2];
; #pragma unroll
;         for (int bj = 0; bj < 2; ++bj)
; #pragma unroll
;             for (int n = 0; n < 2; ++n) {
;                 sv[bj][n] = scale ? *(const f32x4*)(scale + col0 + bj * 128 + n * 16) : (f32x4){1.f, 1.f, 1.f, 1.f};
;                 bv[bj][n] = bias ? *(const f32x4*)(bias + col0 + bj * 128 + n * 16) : (f32x4){0.f, 0.f, 0.f, 0.f}; }
; #pragma unroll
;         for (int ai = 0; ai < 2; ++ai)
; #pragma unroll
;             for (int mh = 0; mh < 2; ++mh) {
;                 f32x4 bs[2][2][2];
; #pragma unroll
;                 for (int m = 0; m < 2; ++m)
; #pragma unroll
;                     for (int bj = 0; bj < 2; ++bj)
; #pragma unroll
;                         for (int n = 0; n < 2; ++n) bs[m][bj][n] = *(const f32x4*)(base + (size_t)(row0 + ai * 128 + (2 * mh + m) * 16) * D + col0 + bj * 128 + n * 16);
	s_nop 1
	ds_read_b128 v[164:167], v150 offset:49152
	ds_read_b128 v[168:171], v150 offset:50176
	ds_read_b128 v[172:175], v150 offset:51200
	ds_read_b128 v[176:179], v150 offset:52224
	ds_read_b128 v[180:183], v150 offset:53248
	ds_read_b128 v[184:187], v150 offset:54272
	ds_read_b128 v[188:191], v150 offset:55296
	ds_read_b128 v[192:195], v150 offset:56320
	s_add_i32 s43, s77, s7
	v_lshl_add_u64 v[254:255], v[144:145], 0, s[12:13]
	s_mov_b32 m0, s43
	s_nop 0
	global_load_lds_dwordx4 v[254:255], off
	v_lshl_add_u64 v[254:255], v[212:213], 0, s[12:13]
	s_add_i32 m0, s43, 0x2000
	s_nop 0
	global_load_lds_dwordx4 v[254:255], off
	s_mov_b32 m0, s46
	v_lshl_add_u64 v[254:255], v[214:215], 0, s[12:13]
	global_load_lds_dwordx4 v[254:255], off
	v_lshl_add_u64 v[144:145], v[216:217], 0, s[12:13]
	s_mov_b32 m0, s47
	s_nop 0
	global_load_lds_dwordx4 v[144:145], off
	s_add_u32 s40, s40, 0x40080
	s_addc_u32 s41, s41, 0
	s_add_i32 s42, s42, s7
	v_lshl_add_u64 v[254:255], s[40:41], 0, v[128:129]
	s_mov_b32 m0, s42
	s_nop 0
	global_load_lds_dwordx4 v[254:255], off
	v_lshl_add_u64 v[254:255], s[40:41], 0, v[130:131]
	s_add_i32 m0, s42, 0x2000
	s_nop 0
	global_load_lds_dwordx4 v[254:255], off
	s_waitcnt vmcnt(6)
	s_waitcnt lgkmcnt(0)
	s_barrier
	s_setprio 1
	v_mfma_f32_16x16x32_bf16 v[60:63], v[140:143], v[164:167], v[60:63]
	v_mfma_f32_16x16x32_bf16 v[56:59], v[156:159], v[164:167], v[56:59]
	v_mfma_f32_16x16x32_bf16 v[48:51], v[140:143], v[172:175], v[48:51]
	v_mfma_f32_16x16x32_bf16 v[40:43], v[156:159], v[172:175], v[40:43]
	v_mfma_f32_16x16x32_bf16 v[28:31], v[140:143], v[180:183], v[28:31]
	v_mfma_f32_16x16x32_bf16 v[24:27], v[156:159], v[180:183], v[24:27]
	v_mfma_f32_16x16x32_bf16 v[16:19], v[140:143], v[188:191], v[16:19]
	v_mfma_f32_16x16x32_bf16 v[8:11], v[156:159], v[188:191], v[8:11]
	v_mfma_f32_16x16x32_bf16 v[60:63], v[152:155], v[168:171], v[60:63]
	v_mfma_f32_16x16x32_bf16 v[56:59], v[160:163], v[168:171], v[56:59]
	v_mfma_f32_16x16x32_bf16 v[48:51], v[152:155], v[176:179], v[48:51]
	v_mfma_f32_16x16x32_bf16 v[40:43], v[160:163], v[176:179], v[40:43]
	v_mfma_f32_16x16x32_bf16 v[28:31], v[152:155], v[184:187], v[28:31]
	v_mfma_f32_16x16x32_bf16 v[24:27], v[160:163], v[184:187], v[24:27]
	v_mfma_f32_16x16x32_bf16 v[16:19], v[152:155], v[192:195], v[16:19]
	v_mfma_f32_16x16x32_bf16 v[8:11], v[160:163], v[192:195], v[8:11]
	v_mfma_f32_16x16x32_bf16 v[52:55], v[196:199], v[164:167], v[52:55]
	v_mfma_f32_16x16x32_bf16 v[44:47], v[204:207], v[164:167], v[44:47]
	v_mfma_f32_16x16x32_bf16 v[36:39], v[196:199], v[172:175], v[36:39]
	v_mfma_f32_16x16x32_bf16 v[32:35], v[204:207], v[172:175], v[32:35]
	v_mfma_f32_16x16x32_bf16 v[20:23], v[196:199], v[180:183], v[20:23]
	v_mfma_f32_16x16x32_bf16 v[12:15], v[204:207], v[180:183], v[12:15]
	v_mfma_f32_16x16x32_bf16 v[4:7], v[196:199], v[188:191], v[4:7]
	v_mfma_f32_16x16x32_bf16 v[0:3], v[204:207], v[188:191], v[0:3]
	v_mfma_f32_16x16x32_bf16 v[52:55], v[200:203], v[168:171], v[52:55]
	v_mfma_f32_16x16x32_bf16 v[44:47], v[208:211], v[168:171], v[44:47]
	v_mfma_f32_16x16x32_bf16 v[36:39], v[200:203], v[176:179], v[36:39]
	v_mfma_f32_16x16x32_bf16 v[32:35], v[208:211], v[176:179], v[32:35]
	v_mfma_f32_16x16x32_bf16 v[20:23], v[200:203], v[184:187], v[20:23]
	v_mfma_f32_16x16x32_bf16 v[12:15], v[208:211], v[184:187], v[12:15]
	v_mfma_f32_16x16x32_bf16 v[4:7], v[200:203], v[192:195], v[4:7]
	v_mfma_f32_16x16x32_bf16 v[0:3], v[208:211], v[192:195], v[0:3]
	s_setprio 0
	s_add_i32 s76, s76, 2
	s_add_u32 s38, s38, 0x100
	s_addc_u32 s39, s39, 0
	s_add_u32 s74, s74, 0x100
	s_addc_u32 s75, s75, 0
	s_cmp_gt_u32 s76, 13
	s_barrier
	s_cbranch_scc0 .LBB0_1239
	v_lshl_or_b32 v144, s63, 8, v148
	v_lshl_add_u32 v145, s36, 8, v146
	v_lshlrev_b32_e32 v144, 2, v144
	v_lshl_add_u32 v145, v145, 12, v144
	v_add_u32_e32 v216, 0x10000, v145
	v_add_u32_e32 v217, 0x20000, v145
	v_add_u32_e32 v218, 0x30000, v145
	v_add_u32_e32 v220, 0x80000, v145
	v_add_u32_e32 v221, 0x90000, v145
	v_add_u32_e32 v222, 0xa0000, v145
	v_add_u32_e32 v223, 0xb0000, v145
	v_and_b32_e32 v235, 8, v146
	v_cmp_ne_u32_e32 vcc, 0, v235
	v_mov_b32_e32 v232, 0xffff8040
	s_nop 0
	v_cndmask_b32_e32 v232, 0, v232, vcc
	v_mov_b32_e32 v233, 64
	v_mov_b32_e32 v235, 0x8000
	v_cndmask_b32_e32 v233, v235, v233, vcc
	v_add_u32_e32 v224, v145, v232
	v_add_u32_e32 v225, v216, v232
	v_add_u32_e32 v226, v217, v232
	v_add_u32_e32 v227, v218, v232
	v_add_u32_e32 v228, v220, v232
	v_add_u32_e32 v229, v221, v232
	v_add_u32_e32 v230, v222, v232
	v_add_u32_e32 v231, v223, v232
	s_and_b64 vcc, exec, s[10:11]
	s_mov_b32 s63, s26
	s_mov_b32 s36, s28
	s_mov_b64 s[40:41], s[34:35]
	s_mov_b64 s[38:39], s[30:31]
	global_load_dwordx4 v[140:143], v224, s[52:53]
	v_add_u32_e32 v144, v145, v233
	global_load_dwordx4 v[152:155], v144, s[52:53]
	global_load_dwordx4 v[156:159], v224, s[52:53] offset:512
	v_add_u32_e32 v144, v145, v233
	global_load_dwordx4 v[160:163], v144, s[52:53] offset:512
	global_load_dwordx4 v[164:167], v225, s[52:53]
	v_add_u32_e32 v144, v216, v233
	global_load_dwordx4 v[168:171], v144, s[52:53]
	global_load_dwordx4 v[172:175], v225, s[52:53] offset:512
	v_add_u32_e32 v144, v216, v233
	global_load_dwordx4 v[176:179], v144, s[52:53] offset:512
	global_load_dwordx4 v[180:183], v226, s[52:53]
	v_add_u32_e32 v144, v217, v233
	global_load_dwordx4 v[184:187], v144, s[52:53]
	global_load_dwordx4 v[188:191], v226, s[52:53] offset:512
	v_add_u32_e32 v144, v217, v233
	global_load_dwordx4 v[192:195], v144, s[52:53] offset:512
	global_load_dwordx4 v[196:199], v227, s[52:53]
	v_add_u32_e32 v144, v218, v233
	global_load_dwordx4 v[200:203], v144, s[52:53]
	global_load_dwordx4 v[204:207], v227, s[52:53] offset:512
	v_add_u32_e32 v144, v218, v233
	global_load_dwordx4 v[208:211], v144, s[52:53] offset:512
	s_barrier
;     __device__ __forceinline__ void operator()(AccRef acc, const Unit& u, int wr, int wc, int fr, int fq) const {
;     ...
;                         for (int n = 0; n < 2; ++n) bs[m][bj][n] = *(const f32x4*)(base + (size_t)(row0 + ai * 128 + (2 * mh + m) * 16) * D + col0 + bj * 128 + n * 16);
; #pragma unroll
;                 for (int m = 0; m < 2; ++m)
; #pragma unroll
;                     for (int bj = 0; bj < 2; ++bj)
; #pragma unroll
;                         for (int n = 0; n < 2; ++n) *(f32x4*)(out + (size_t)(row0 + ai * 128 + (2 * mh + m) * 16) * D + col0 + bj * 128 + n * 16) = bs[m][bj][n] + sv[bj][n] * (acc[ai][bj][2 * mh + m][n] + bv[bj][n]);
	v_pk_add_f32 v[124:125], v[124:125], 0 op_sel_hi:[1,0]
	v_pk_add_f32 v[126:127], v[126:127], 0 op_sel_hi:[1,0]
	v_pk_add_f32 v[120:121], v[120:121], 0 op_sel_hi:[1,0]
	v_pk_add_f32 v[122:123], v[122:123], 0 op_sel_hi:[1,0]
	v_pk_add_f32 v[116:117], v[116:117], 0 op_sel_hi:[1,0]
	v_pk_add_f32 v[118:119], v[118:119], 0 op_sel_hi:[1,0]
	v_pk_add_f32 v[108:109], v[108:109], 0 op_sel_hi:[1,0]
	v_pk_add_f32 v[110:111], v[110:111], 0 op_sel_hi:[1,0]
	v_pk_add_f32 v[112:113], v[112:113], 0 op_sel_hi:[1,0]
	v_pk_add_f32 v[114:115], v[114:115], 0 op_sel_hi:[1,0]
	v_pk_add_f32 v[104:105], v[104:105], 0 op_sel_hi:[1,0]
	v_pk_add_f32 v[106:107], v[106:107], 0 op_sel_hi:[1,0]
	v_pk_add_f32 v[100:101], v[100:101], 0 op_sel_hi:[1,0]
	v_pk_add_f32 v[102:103], v[102:103], 0 op_sel_hi:[1,0]
	v_pk_add_f32 v[96:97], v[96:97], 0 op_sel_hi:[1,0]
	v_pk_add_f32 v[98:99], v[98:99], 0 op_sel_hi:[1,0]
	v_pk_add_f32 v[92:93], v[92:93], 0 op_sel_hi:[1,0]
	v_pk_add_f32 v[94:95], v[94:95], 0 op_sel_hi:[1,0]
	v_pk_add_f32 v[88:89], v[88:89], 0 op_sel_hi:[1,0]
	v_pk_add_f32 v[90:91], v[90:91], 0 op_sel_hi:[1,0]
	v_pk_add_f32 v[84:85], v[84:85], 0 op_sel_hi:[1,0]
	v_pk_add_f32 v[86:87], v[86:87], 0 op_sel_hi:[1,0]
	v_pk_add_f32 v[76:77], v[76:77], 0 op_sel_hi:[1,0]
	v_pk_add_f32 v[78:79], v[78:79], 0 op_sel_hi:[1,0]
	v_pk_add_f32 v[80:81], v[80:81], 0 op_sel_hi:[1,0]
	v_pk_add_f32 v[82:83], v[82:83], 0 op_sel_hi:[1,0]
	v_pk_add_f32 v[72:73], v[72:73], 0 op_sel_hi:[1,0]
	v_pk_add_f32 v[74:75], v[74:75], 0 op_sel_hi:[1,0]
	v_pk_add_f32 v[68:69], v[68:69], 0 op_sel_hi:[1,0]
	v_pk_add_f32 v[70:71], v[70:71], 0 op_sel_hi:[1,0]
	v_pk_add_f32 v[64:65], v[64:65], 0 op_sel_hi:[1,0]
	v_pk_add_f32 v[66:67], v[66:67], 0 op_sel_hi:[1,0]
	v_pk_add_f32 v[60:61], v[60:61], 0 op_sel_hi:[1,0]
	v_pk_add_f32 v[62:63], v[62:63], 0 op_sel_hi:[1,0]
	v_pk_add_f32 v[56:57], v[56:57], 0 op_sel_hi:[1,0]
	v_pk_add_f32 v[58:59], v[58:59], 0 op_sel_hi:[1,0]
	v_pk_add_f32 v[52:53], v[52:53], 0 op_sel_hi:[1,0]
	v_pk_add_f32 v[54:55], v[54:55], 0 op_sel_hi:[1,0]
	v_pk_add_f32 v[44:45], v[44:45], 0 op_sel_hi:[1,0]
	v_pk_add_f32 v[46:47], v[46:47], 0 op_sel_hi:[1,0]
	v_pk_add_f32 v[48:49], v[48:49], 0 op_sel_hi:[1,0]
	v_pk_add_f32 v[50:51], v[50:51], 0 op_sel_hi:[1,0]
	v_pk_add_f32 v[40:41], v[40:41], 0 op_sel_hi:[1,0]
	v_pk_add_f32 v[42:43], v[42:43], 0 op_sel_hi:[1,0]
	v_pk_add_f32 v[36:37], v[36:37], 0 op_sel_hi:[1,0]
	v_pk_add_f32 v[38:39], v[38:39], 0 op_sel_hi:[1,0]
	v_pk_add_f32 v[32:33], v[32:33], 0 op_sel_hi:[1,0]
	v_pk_add_f32 v[34:35], v[34:35], 0 op_sel_hi:[1,0]
	v_pk_add_f32 v[28:29], v[28:29], 0 op_sel_hi:[1,0]
	v_pk_add_f32 v[30:31], v[30:31], 0 op_sel_hi:[1,0]
	v_pk_add_f32 v[24:25], v[24:25], 0 op_sel_hi:[1,0]
	v_pk_add_f32 v[26:27], v[26:27], 0 op_sel_hi:[1,0]
	v_pk_add_f32 v[20:21], v[20:21], 0 op_sel_hi:[1,0]
	v_pk_add_f32 v[22:23], v[22:23], 0 op_sel_hi:[1,0]
	v_pk_add_f32 v[12:13], v[12:13], 0 op_sel_hi:[1,0]
	v_pk_add_f32 v[14:15], v[14:15], 0 op_sel_hi:[1,0]
	v_pk_add_f32 v[16:17], v[16:17], 0 op_sel_hi:[1,0]
	v_pk_add_f32 v[18:19], v[18:19], 0 op_sel_hi:[1,0]
	v_pk_add_f32 v[8:9], v[8:9], 0 op_sel_hi:[1,0]
	v_pk_add_f32 v[10:11], v[10:11], 0 op_sel_hi:[1,0]
	v_pk_add_f32 v[4:5], v[4:5], 0 op_sel_hi:[1,0]
	v_pk_add_f32 v[6:7], v[6:7], 0 op_sel_hi:[1,0]
	v_pk_add_f32 v[0:1], v[0:1], 0 op_sel_hi:[1,0]
	v_pk_add_f32 v[2:3], v[2:3], 0 op_sel_hi:[1,0]
	s_waitcnt vmcnt(8)
	v_mov_b32_e32 v212, v124
	v_mov_b32_e32 v213, v125
	v_mov_b32_e32 v214, v126
	v_mov_b32_e32 v215, v127
	s_nop 0
	v_mov_b32_dpp v124, v120 row_shr:8 row_mask:0xf bank_mask:0xc
	v_mov_b32_dpp v125, v121 row_shr:8 row_mask:0xf bank_mask:0xc
	v_mov_b32_dpp v126, v122 row_shr:8 row_mask:0xf bank_mask:0xc
	v_mov_b32_dpp v127, v123 row_shr:8 row_mask:0xf bank_mask:0xc
	v_mov_b32_dpp v120, v212 row_shl:8 row_mask:0xf bank_mask:0x3
	v_mov_b32_dpp v121, v213 row_shl:8 row_mask:0xf bank_mask:0x3
	v_mov_b32_dpp v122, v214 row_shl:8 row_mask:0xf bank_mask:0x3
	v_mov_b32_dpp v123, v215 row_shl:8 row_mask:0xf bank_mask:0x3
	v_mov_b32_e32 v212, v116
	v_mov_b32_e32 v213, v117
	v_mov_b32_e32 v214, v118
	v_mov_b32_e32 v215, v119
	s_nop 0
	v_mov_b32_dpp v116, v108 row_shr:8 row_mask:0xf bank_mask:0xc
	v_mov_b32_dpp v117, v109 row_shr:8 row_mask:0xf bank_mask:0xc
	v_mov_b32_dpp v118, v110 row_shr:8 row_mask:0xf bank_mask:0xc
	v_mov_b32_dpp v119, v111 row_shr:8 row_mask:0xf bank_mask:0xc
	v_mov_b32_dpp v108, v212 row_shl:8 row_mask:0xf bank_mask:0x3
	v_mov_b32_dpp v109, v213 row_shl:8 row_mask:0xf bank_mask:0x3
	v_mov_b32_dpp v110, v214 row_shl:8 row_mask:0xf bank_mask:0x3
	v_mov_b32_dpp v111, v215 row_shl:8 row_mask:0xf bank_mask:0x3
	v_mov_b32_e32 v212, v112
	v_mov_b32_e32 v213, v113
	v_mov_b32_e32 v214, v114
	v_mov_b32_e32 v215, v115
	s_nop 0
	v_mov_b32_dpp v112, v104 row_shr:8 row_mask:0xf bank_mask:0xc
	v_mov_b32_dpp v113, v105 row_shr:8 row_mask:0xf bank_mask:0xc
	v_mov_b32_dpp v114, v106 row_shr:8 row_mask:0xf bank_mask:0xc
	v_mov_b32_dpp v115, v107 row_shr:8 row_mask:0xf bank_mask:0xc
	v_mov_b32_dpp v104, v212 row_shl:8 row_mask:0xf bank_mask:0x3
	v_mov_b32_dpp v105, v213 row_shl:8 row_mask:0xf bank_mask:0x3
	v_mov_b32_dpp v106, v214 row_shl:8 row_mask:0xf bank_mask:0x3
	v_mov_b32_dpp v107, v215 row_shl:8 row_mask:0xf bank_mask:0x3
	v_mov_b32_e32 v212, v100
	v_mov_b32_e32 v213, v101
	v_mov_b32_e32 v214, v102
	v_mov_b32_e32 v215, v103
	s_nop 0
	v_mov_b32_dpp v100, v96 row_shr:8 row_mask:0xf bank_mask:0xc
	v_mov_b32_dpp v101, v97 row_shr:8 row_mask:0xf bank_mask:0xc
	v_mov_b32_dpp v102, v98 row_shr:8 row_mask:0xf bank_mask:0xc
	v_mov_b32_dpp v103, v99 row_shr:8 row_mask:0xf bank_mask:0xc
	v_mov_b32_dpp v96, v212 row_shl:8 row_mask:0xf bank_mask:0x3
;     __device__ __forceinline__ void operator()(AccRef acc, const Unit& u, int wr, int wc, int fr, int fq) const {
;     ...
;                         for (int n = 0; n < 2; ++n) bs[m][bj][n] = *(const f32x4*)(base + (size_t)(row0 + ai * 128 + (2 * mh + m) * 16) * D + col0 + bj * 128 + n * 16);
; #pragma unroll
;                 for (int m = 0; m < 2; ++m)
; #pragma unroll
;                     for (int bj = 0; bj < 2; ++bj)
; #pragma unroll
;                         for (int n = 0; n < 2; ++n) *(f32x4*)(out + (size_t)(row0 + ai * 128 + (2 * mh + m) * 16) * D + col0 + bj * 128 + n * 16) = bs[m][bj][n] + sv[bj][n] * (acc[ai][bj][2 * mh + m][n] + bv[bj][n]);
;                 asm volatile("" ::: "memory"); }
	v_mov_b32_dpp v97, v213 row_shl:8 row_mask:0xf bank_mask:0x3
	v_mov_b32_dpp v98, v214 row_shl:8 row_mask:0xf bank_mask:0x3
	v_mov_b32_dpp v99, v215 row_shl:8 row_mask:0xf bank_mask:0x3
	v_pk_add_f32 v[124:125], v[124:125], v[140:141]
	v_pk_add_f32 v[126:127], v[126:127], v[142:143]
	v_pk_add_f32 v[120:121], v[120:121], v[152:153]
	v_pk_add_f32 v[122:123], v[122:123], v[154:155]
	v_pk_add_f32 v[116:117], v[116:117], v[156:157]
	v_pk_add_f32 v[118:119], v[118:119], v[158:159]
	v_pk_add_f32 v[108:109], v[108:109], v[160:161]
	v_pk_add_f32 v[110:111], v[110:111], v[162:163]
	v_pk_add_f32 v[112:113], v[112:113], v[164:165]
	v_pk_add_f32 v[114:115], v[114:115], v[166:167]
	v_pk_add_f32 v[104:105], v[104:105], v[168:169]
	v_pk_add_f32 v[106:107], v[106:107], v[170:171]
	v_pk_add_f32 v[100:101], v[100:101], v[172:173]
	v_pk_add_f32 v[102:103], v[102:103], v[174:175]
	v_pk_add_f32 v[96:97], v[96:97], v[176:177]
	v_pk_add_f32 v[98:99], v[98:99], v[178:179]
	global_store_dwordx4 v224, v[124:127], s[52:53]
	v_add_u32_e32 v144, v145, v233
	global_store_dwordx4 v144, v[120:123], s[52:53]
	global_store_dwordx4 v224, v[116:119], s[52:53] offset:512
	v_add_u32_e32 v144, v145, v233
	global_store_dwordx4 v144, v[108:111], s[52:53] offset:512
	global_store_dwordx4 v225, v[112:115], s[52:53]
	v_add_u32_e32 v144, v216, v233
	global_store_dwordx4 v144, v[104:107], s[52:53]
	global_store_dwordx4 v225, v[100:103], s[52:53] offset:512
	v_add_u32_e32 v144, v216, v233
	global_store_dwordx4 v144, v[96:99], s[52:53] offset:512
	global_load_dwordx4 v[140:143], v228, s[52:53]
	v_add_u32_e32 v144, v220, v233
	global_load_dwordx4 v[152:155], v144, s[52:53]
	global_load_dwordx4 v[156:159], v228, s[52:53] offset:512
	v_add_u32_e32 v144, v220, v233
	global_load_dwordx4 v[160:163], v144, s[52:53] offset:512
	global_load_dwordx4 v[164:167], v229, s[52:53]
	v_add_u32_e32 v144, v221, v233
	global_load_dwordx4 v[168:171], v144, s[52:53]
	global_load_dwordx4 v[172:175], v229, s[52:53] offset:512
	v_add_u32_e32 v144, v221, v233
	global_load_dwordx4 v[176:179], v144, s[52:53] offset:512
	s_waitcnt vmcnt(16)
	v_mov_b32_e32 v212, v92
	v_mov_b32_e32 v213, v93
	v_mov_b32_e32 v214, v94
	v_mov_b32_e32 v215, v95
	s_nop 0
	v_mov_b32_dpp v92, v88 row_shr:8 row_mask:0xf bank_mask:0xc
	v_mov_b32_dpp v93, v89 row_shr:8 row_mask:0xf bank_mask:0xc
	v_mov_b32_dpp v94, v90 row_shr:8 row_mask:0xf bank_mask:0xc
	v_mov_b32_dpp v95, v91 row_shr:8 row_mask:0xf bank_mask:0xc
	v_mov_b32_dpp v88, v212 row_shl:8 row_mask:0xf bank_mask:0x3
	v_mov_b32_dpp v89, v213 row_shl:8 row_mask:0xf bank_mask:0x3
	v_mov_b32_dpp v90, v214 row_shl:8 row_mask:0xf bank_mask:0x3
	v_mov_b32_dpp v91, v215 row_shl:8 row_mask:0xf bank_mask:0x3
	v_mov_b32_e32 v212, v84
	v_mov_b32_e32 v213, v85
	v_mov_b32_e32 v214, v86
	v_mov_b32_e32 v215, v87
	s_nop 0
	v_mov_b32_dpp v84, v76 row_shr:8 row_mask:0xf bank_mask:0xc
	v_mov_b32_dpp v85, v77 row_shr:8 row_mask:0xf bank_mask:0xc
	v_mov_b32_dpp v86, v78 row_shr:8 row_mask:0xf bank_mask:0xc
	v_mov_b32_dpp v87, v79 row_shr:8 row_mask:0xf bank_mask:0xc
	v_mov_b32_dpp v76, v212 row_shl:8 row_mask:0xf bank_mask:0x3
	v_mov_b32_dpp v77, v213 row_shl:8 row_mask:0xf bank_mask:0x3
	v_mov_b32_dpp v78, v214 row_shl:8 row_mask:0xf bank_mask:0x3
	v_mov_b32_dpp v79, v215 row_shl:8 row_mask:0xf bank_mask:0x3
	v_mov_b32_e32 v212, v80
	v_mov_b32_e32 v213, v81
	v_mov_b32_e32 v214, v82
	v_mov_b32_e32 v215, v83
	s_nop 0
	v_mov_b32_dpp v80, v72 row_shr:8 row_mask:0xf bank_mask:0xc
	v_mov_b32_dpp v81, v73 row_shr:8 row_mask:0xf bank_mask:0xc
	v_mov_b32_dpp v82, v74 row_shr:8 row_mask:0xf bank_mask:0xc
	v_mov_b32_dpp v83, v75 row_shr:8 row_mask:0xf bank_mask:0xc
	v_mov_b32_dpp v72, v212 row_shl:8 row_mask:0xf bank_mask:0x3
	v_mov_b32_dpp v73, v213 row_shl:8 row_mask:0xf bank_mask:0x3
	v_mov_b32_dpp v74, v214 row_shl:8 row_mask:0xf bank_mask:0x3
	v_mov_b32_dpp v75, v215 row_shl:8 row_mask:0xf bank_mask:0x3
	v_mov_b32_e32 v212, v68
	v_mov_b32_e32 v213, v69
	v_mov_b32_e32 v214, v70
	v_mov_b32_e32 v215, v71
	s_nop 0
	v_mov_b32_dpp v68, v64 row_shr:8 row_mask:0xf bank_mask:0xc
	v_mov_b32_dpp v69, v65 row_shr:8 row_mask:0xf bank_mask:0xc
	v_mov_b32_dpp v70, v66 row_shr:8 row_mask:0xf bank_mask:0xc
	v_mov_b32_dpp v71, v67 row_shr:8 row_mask:0xf bank_mask:0xc
	v_mov_b32_dpp v64, v212 row_shl:8 row_mask:0xf bank_mask:0x3
	v_mov_b32_dpp v65, v213 row_shl:8 row_mask:0xf bank_mask:0x3
	v_mov_b32_dpp v66, v214 row_shl:8 row_mask:0xf bank_mask:0x3
	v_mov_b32_dpp v67, v215 row_shl:8 row_mask:0xf bank_mask:0x3
	v_pk_add_f32 v[92:93], v[92:93], v[180:181]
	v_pk_add_f32 v[94:95], v[94:95], v[182:183]
	v_pk_add_f32 v[88:89], v[88:89], v[184:185]
	v_pk_add_f32 v[90:91], v[90:91], v[186:187]
	v_pk_add_f32 v[84:85], v[84:85], v[188:189]
	v_pk_add_f32 v[86:87], v[86:87], v[190:191]
	v_pk_add_f32 v[76:77], v[76:77], v[192:193]
	v_pk_add_f32 v[78:79], v[78:79], v[194:195]
	v_pk_add_f32 v[80:81], v[80:81], v[196:197]
	v_pk_add_f32 v[82:83], v[82:83], v[198:199]
	v_pk_add_f32 v[72:73], v[72:73], v[200:201]
	v_pk_add_f32 v[74:75], v[74:75], v[202:203]
	v_pk_add_f32 v[68:69], v[68:69], v[204:205]
	v_pk_add_f32 v[70:71], v[70:71], v[206:207]
	v_pk_add_f32 v[64:65], v[64:65], v[208:209]
	v_pk_add_f32 v[66:67], v[66:67], v[210:211]
	global_store_dwordx4 v226, v[92:95], s[52:53]
	v_add_u32_e32 v144, v217, v233
	global_store_dwordx4 v144, v[88:91], s[52:53]
	global_store_dwordx4 v226, v[84:87], s[52:53] offset:512
	v_add_u32_e32 v144, v217, v233
	global_store_dwordx4 v144, v[76:79], s[52:53] offset:512
	global_store_dwordx4 v227, v[80:83], s[52:53]
	v_add_u32_e32 v144, v218, v233
	global_store_dwordx4 v144, v[72:75], s[52:53]
	global_store_dwordx4 v227, v[68:71], s[52:53] offset:512
	v_add_u32_e32 v144, v218, v233
	global_store_dwordx4 v144, v[64:67], s[52:53] offset:512
	global_load_dwordx4 v[180:183], v230, s[52:53]
	v_add_u32_e32 v144, v222, v233
	global_load_dwordx4 v[184:187], v144, s[52:53]
	global_load_dwordx4 v[188:191], v230, s[52:53] offset:512
	v_add_u32_e32 v144, v222, v233
	global_load_dwordx4 v[192:195], v144, s[52:53] offset:512
	global_load_dwordx4 v[196:199], v231, s[52:53]
	v_add_u32_e32 v144, v223, v233
	global_load_dwordx4 v[200:203], v144, s[52:53]
	global_load_dwordx4 v[204:207], v231, s[52:53] offset:512
	v_add_u32_e32 v144, v223, v233
	global_load_dwordx4 v[208:211], v144, s[52:53] offset:512
	s_waitcnt vmcnt(16)
;     __device__ __forceinline__ void operator()(AccRef acc, const Unit& u, int wr, int wc, int fr, int fq) const {
;     ...
;                         for (int n = 0; n < 2; ++n) bs[m][bj][n] = *(const f32x4*)(base + (size_t)(row0 + ai * 128 + (2 * mh + m) * 16) * D + col0 + bj * 128 + n * 16);
; #pragma unroll
;                 for (int m = 0; m < 2; ++m)
; #pragma unroll
;                     for (int bj = 0; bj < 2; ++bj)
; #pragma unroll
;                         for (int n = 0; n < 2; ++n) *(f32x4*)(out + (size_t)(row0 + ai * 128 + (2 * mh + m) * 16) * D + col0 + bj * 128 + n * 16) = bs[m][bj][n] + sv[bj][n] * (acc[ai][bj][2 * mh + m][n] + bv[bj][n]);
;                 asm volatile("" ::: "memory"); }
	v_mov_b32_e32 v212, v60
	v_mov_b32_e32 v213, v61
	v_mov_b32_e32 v214, v62
	v_mov_b32_e32 v215, v63
	s_nop 0
	v_mov_b32_dpp v60, v56 row_shr:8 row_mask:0xf bank_mask:0xc
	v_mov_b32_dpp v61, v57 row_shr:8 row_mask:0xf bank_mask:0xc
	v_mov_b32_dpp v62, v58 row_shr:8 row_mask:0xf bank_mask:0xc
	v_mov_b32_dpp v63, v59 row_shr:8 row_mask:0xf bank_mask:0xc
	v_mov_b32_dpp v56, v212 row_shl:8 row_mask:0xf bank_mask:0x3
	v_mov_b32_dpp v57, v213 row_shl:8 row_mask:0xf bank_mask:0x3
	v_mov_b32_dpp v58, v214 row_shl:8 row_mask:0xf bank_mask:0x3
	v_mov_b32_dpp v59, v215 row_shl:8 row_mask:0xf bank_mask:0x3
	v_mov_b32_e32 v212, v52
	v_mov_b32_e32 v213, v53
	v_mov_b32_e32 v214, v54
	v_mov_b32_e32 v215, v55
	s_nop 0
	v_mov_b32_dpp v52, v44 row_shr:8 row_mask:0xf bank_mask:0xc
	v_mov_b32_dpp v53, v45 row_shr:8 row_mask:0xf bank_mask:0xc
	v_mov_b32_dpp v54, v46 row_shr:8 row_mask:0xf bank_mask:0xc
	v_mov_b32_dpp v55, v47 row_shr:8 row_mask:0xf bank_mask:0xc
	v_mov_b32_dpp v44, v212 row_shl:8 row_mask:0xf bank_mask:0x3
	v_mov_b32_dpp v45, v213 row_shl:8 row_mask:0xf bank_mask:0x3
	v_mov_b32_dpp v46, v214 row_shl:8 row_mask:0xf bank_mask:0x3
	v_mov_b32_dpp v47, v215 row_shl:8 row_mask:0xf bank_mask:0x3
	v_mov_b32_e32 v212, v48
	v_mov_b32_e32 v213, v49
	v_mov_b32_e32 v214, v50
	v_mov_b32_e32 v215, v51
	s_nop 0
	v_mov_b32_dpp v48, v40 row_shr:8 row_mask:0xf bank_mask:0xc
	v_mov_b32_dpp v49, v41 row_shr:8 row_mask:0xf bank_mask:0xc
	v_mov_b32_dpp v50, v42 row_shr:8 row_mask:0xf bank_mask:0xc
	v_mov_b32_dpp v51, v43 row_shr:8 row_mask:0xf bank_mask:0xc
	v_mov_b32_dpp v40, v212 row_shl:8 row_mask:0xf bank_mask:0x3
	v_mov_b32_dpp v41, v213 row_shl:8 row_mask:0xf bank_mask:0x3
	v_mov_b32_dpp v42, v214 row_shl:8 row_mask:0xf bank_mask:0x3
	v_mov_b32_dpp v43, v215 row_shl:8 row_mask:0xf bank_mask:0x3
	v_mov_b32_e32 v212, v36
	v_mov_b32_e32 v213, v37
	v_mov_b32_e32 v214, v38
	v_mov_b32_e32 v215, v39
	s_nop 0
	v_mov_b32_dpp v36, v32 row_shr:8 row_mask:0xf bank_mask:0xc
	v_mov_b32_dpp v37, v33 row_shr:8 row_mask:0xf bank_mask:0xc
	v_mov_b32_dpp v38, v34 row_shr:8 row_mask:0xf bank_mask:0xc
	v_mov_b32_dpp v39, v35 row_shr:8 row_mask:0xf bank_mask:0xc
	v_mov_b32_dpp v32, v212 row_shl:8 row_mask:0xf bank_mask:0x3
	v_mov_b32_dpp v33, v213 row_shl:8 row_mask:0xf bank_mask:0x3
	v_mov_b32_dpp v34, v214 row_shl:8 row_mask:0xf bank_mask:0x3
	v_mov_b32_dpp v35, v215 row_shl:8 row_mask:0xf bank_mask:0x3
	v_pk_add_f32 v[60:61], v[60:61], v[140:141]
	v_pk_add_f32 v[62:63], v[62:63], v[142:143]
	v_pk_add_f32 v[56:57], v[56:57], v[152:153]
	v_pk_add_f32 v[58:59], v[58:59], v[154:155]
	v_pk_add_f32 v[52:53], v[52:53], v[156:157]
	v_pk_add_f32 v[54:55], v[54:55], v[158:159]
	v_pk_add_f32 v[44:45], v[44:45], v[160:161]
	v_pk_add_f32 v[46:47], v[46:47], v[162:163]
	v_pk_add_f32 v[48:49], v[48:49], v[164:165]
	v_pk_add_f32 v[50:51], v[50:51], v[166:167]
	v_pk_add_f32 v[40:41], v[40:41], v[168:169]
	v_pk_add_f32 v[42:43], v[42:43], v[170:171]
	v_pk_add_f32 v[36:37], v[36:37], v[172:173]
	v_pk_add_f32 v[38:39], v[38:39], v[174:175]
	v_pk_add_f32 v[32:33], v[32:33], v[176:177]
	v_pk_add_f32 v[34:35], v[34:35], v[178:179]
	global_store_dwordx4 v228, v[60:63], s[52:53]
	v_add_u32_e32 v144, v220, v233
	global_store_dwordx4 v144, v[56:59], s[52:53]
	global_store_dwordx4 v228, v[52:55], s[52:53] offset:512
	v_add_u32_e32 v144, v220, v233
	global_store_dwordx4 v144, v[44:47], s[52:53] offset:512
	global_store_dwordx4 v229, v[48:51], s[52:53]
	v_add_u32_e32 v144, v221, v233
	global_store_dwordx4 v144, v[40:43], s[52:53]
	global_store_dwordx4 v229, v[36:39], s[52:53] offset:512
	v_add_u32_e32 v144, v221, v233
	global_store_dwordx4 v144, v[32:35], s[52:53] offset:512
	s_waitcnt vmcnt(8)
; #define PG8_WAIT_V(n) asm volatile("s_waitcnt vmcnt(" #n ")" ::: "memory")
; #define PG8_BAR __builtin_amdgcn_s_barrier()
; template <class Epi>
; __device__ __forceinline__ void gemm_phase(LAS unsigned char* lds, const Gemm g, const StaticOrder& S, const Epi& E) {
;     ...
;         if (!has_next) break;
;         {
; #pragma unroll
;         for (int a = 0; a < 2; ++a)
; #pragma unroll
;             for (int b = 0; b < 2; ++b)
; #pragma unroll
;                 for (int m = 0; m < 4; ++m)
; #pragma unroll
;                     for (int n = 0; n < 2; ++n) acc[a][b][m][n] = (f32x4){0.f, 0.f, 0.f, 0.f};
;         }
;         cur = nxt; cA = nA; cB = nB; ++ui;
;     }
;     PG8_WAIT_V(0);
;     if (wr == 0) PG8_BAR;
;     __device__ __forceinline__ void operator()(AccRef acc, const Unit& u, int wr, int wc, int fr, int fq) const {
;     ...
;                         for (int n = 0; n < 2; ++n) bs[m][bj][n] = *(const f32x4*)(base + (size_t)(row0 + ai * 128 + (2 * mh + m) * 16) * D + col0 + bj * 128 + n * 16);
; #pragma unroll
;                 for (int m = 0; m < 2; ++m)
; #pragma unroll
;                     for (int bj = 0; bj < 2; ++bj)
; #pragma unroll
;                         for (int n = 0; n < 2; ++n) *(f32x4*)(out + (size_t)(row0 + ai * 128 + (2 * mh + m) * 16) * D + col0 + bj * 128 + n * 16) = bs[m][bj][n] + sv[bj][n] * (acc[ai][bj][2 * mh + m][n] + bv[bj][n]);
;                 asm volatile("" ::: "memory"); }
	v_mov_b32_e32 v212, v28
	v_mov_b32_e32 v213, v29
	v_mov_b32_e32 v214, v30
	v_mov_b32_e32 v215, v31
	s_nop 0
	v_mov_b32_dpp v28, v24 row_shr:8 row_mask:0xf bank_mask:0xc
	v_mov_b32_dpp v29, v25 row_shr:8 row_mask:0xf bank_mask:0xc
	v_mov_b32_dpp v30, v26 row_shr:8 row_mask:0xf bank_mask:0xc
	v_mov_b32_dpp v31, v27 row_shr:8 row_mask:0xf bank_mask:0xc
	v_mov_b32_dpp v24, v212 row_shl:8 row_mask:0xf bank_mask:0x3
	v_mov_b32_dpp v25, v213 row_shl:8 row_mask:0xf bank_mask:0x3
	v_mov_b32_dpp v26, v214 row_shl:8 row_mask:0xf bank_mask:0x3
	v_mov_b32_dpp v27, v215 row_shl:8 row_mask:0xf bank_mask:0x3
	v_mov_b32_e32 v212, v20
	v_mov_b32_e32 v213, v21
	v_mov_b32_e32 v214, v22
	v_mov_b32_e32 v215, v23
	s_nop 0
	v_mov_b32_dpp v20, v12 row_shr:8 row_mask:0xf bank_mask:0xc
	v_mov_b32_dpp v21, v13 row_shr:8 row_mask:0xf bank_mask:0xc
	v_mov_b32_dpp v22, v14 row_shr:8 row_mask:0xf bank_mask:0xc
	v_mov_b32_dpp v23, v15 row_shr:8 row_mask:0xf bank_mask:0xc
	v_mov_b32_dpp v12, v212 row_shl:8 row_mask:0xf bank_mask:0x3
	v_mov_b32_dpp v13, v213 row_shl:8 row_mask:0xf bank_mask:0x3
	v_mov_b32_dpp v14, v214 row_shl:8 row_mask:0xf bank_mask:0x3
	v_mov_b32_dpp v15, v215 row_shl:8 row_mask:0xf bank_mask:0x3
	v_mov_b32_e32 v212, v16
	v_mov_b32_e32 v213, v17
	v_mov_b32_e32 v214, v18
	v_mov_b32_e32 v215, v19
	s_nop 0
	v_mov_b32_dpp v16, v8 row_shr:8 row_mask:0xf bank_mask:0xc
	v_mov_b32_dpp v17, v9 row_shr:8 row_mask:0xf bank_mask:0xc
	v_mov_b32_dpp v18, v10 row_shr:8 row_mask:0xf bank_mask:0xc
	v_mov_b32_dpp v19, v11 row_shr:8 row_mask:0xf bank_mask:0xc
	v_mov_b32_dpp v8, v212 row_shl:8 row_mask:0xf bank_mask:0x3
	v_mov_b32_dpp v9, v213 row_shl:8 row_mask:0xf bank_mask:0x3
	v_mov_b32_dpp v10, v214 row_shl:8 row_mask:0xf bank_mask:0x3
	v_mov_b32_dpp v11, v215 row_shl:8 row_mask:0xf bank_mask:0x3
	v_mov_b32_e32 v212, v4
	v_mov_b32_e32 v213, v5
	v_mov_b32_e32 v214, v6
	v_mov_b32_e32 v215, v7
	s_nop 0
	v_mov_b32_dpp v4, v0 row_shr:8 row_mask:0xf bank_mask:0xc
	v_mov_b32_dpp v5, v1 row_shr:8 row_mask:0xf bank_mask:0xc
	v_mov_b32_dpp v6, v2 row_shr:8 row_mask:0xf bank_mask:0xc
	v_mov_b32_dpp v7, v3 row_shr:8 row_mask:0xf bank_mask:0xc
	v_mov_b32_dpp v0, v212 row_shl:8 row_mask:0xf bank_mask:0x3
	v_mov_b32_dpp v1, v213 row_shl:8 row_mask:0xf bank_mask:0x3
	v_mov_b32_dpp v2, v214 row_shl:8 row_mask:0xf bank_mask:0x3
	v_mov_b32_dpp v3, v215 row_shl:8 row_mask:0xf bank_mask:0x3
	v_pk_add_f32 v[28:29], v[28:29], v[180:181]
	v_pk_add_f32 v[30:31], v[30:31], v[182:183]
	v_pk_add_f32 v[24:25], v[24:25], v[184:185]
	v_pk_add_f32 v[26:27], v[26:27], v[186:187]
	v_pk_add_f32 v[20:21], v[20:21], v[188:189]
	v_pk_add_f32 v[22:23], v[22:23], v[190:191]
	v_pk_add_f32 v[12:13], v[12:13], v[192:193]
	v_pk_add_f32 v[14:15], v[14:15], v[194:195]
	v_pk_add_f32 v[16:17], v[16:17], v[196:197]
	v_pk_add_f32 v[18:19], v[18:19], v[198:199]
	v_pk_add_f32 v[8:9], v[8:9], v[200:201]
	v_pk_add_f32 v[10:11], v[10:11], v[202:203]
	v_pk_add_f32 v[4:5], v[4:5], v[204:205]
	v_pk_add_f32 v[6:7], v[6:7], v[206:207]
	v_pk_add_f32 v[0:1], v[0:1], v[208:209]
	v_pk_add_f32 v[2:3], v[2:3], v[210:211]
	global_store_dwordx4 v230, v[28:31], s[52:53]
	v_add_u32_e32 v144, v222, v233
	global_store_dwordx4 v144, v[24:27], s[52:53]
	global_store_dwordx4 v230, v[20:23], s[52:53] offset:512
	v_add_u32_e32 v144, v222, v233
	global_store_dwordx4 v144, v[12:15], s[52:53] offset:512
	global_store_dwordx4 v231, v[16:19], s[52:53]
	v_add_u32_e32 v144, v223, v233
	global_store_dwordx4 v144, v[8:11], s[52:53]
	global_store_dwordx4 v231, v[4:7], s[52:53] offset:512
	v_add_u32_e32 v144, v223, v233
	global_store_dwordx4 v144, v[0:3], s[52:53] offset:512
	s_cbranch_vccz .LBB0_1232
	s_waitcnt vmcnt(0)
	s_cmpk_gt_u32 s4, 0xff
	s_cbranch_scc1 .LBB0_1243
	s_barrier

; #define PG8_STAGE(bufoff, gbase, voff) do { _Pragma("unroll") for (int _i = 0; _i < 2; ++_i) \
;         __builtin_amdgcn_global_load_lds((const unsigned*)((const char*)(gbase) + (voff)[_i]), (LAS unsigned*)(lds + (bufoff) + ldsw + _i * 8192), 16, 0, 0); } while (0)
; #define PG8_LDA(dst, b, h) do { _Pragma("unroll") for (int m = 0; m < 4; ++m) _Pragma("unroll") for (int k = 0; k < 2; ++k) dst[m][k] = *(const LAS bf16x8*)(lds + PG8_SA(b, h) + aoff + m * 2048 + k * 1024); } while (0)
; #define PG8_LDB(dst, b, h) do { _Pragma("unroll") for (int n = 0; n < 2; ++n) _Pragma("unroll") for (int k = 0; k < 2; ++k) dst[n][k] = *(const LAS bf16x8*)(lds + PG8_SB(b, h) + boff + n * 2048 + k * 1024); } while (0)
; #define PG8_MMA(ai, bj, At, Bt) do { __builtin_amdgcn_s_setprio(1); _Pragma("unroll") for (int m = 0; m < 4; ++m) _Pragma("unroll") for (int n = 0; n < 2; ++n) _Pragma("unroll") for (int k = 0; k < 2; ++k) \
;         acc[ai][bj][m][n] = __builtin_amdgcn_mfma_f32_16x16x32_bf16(Bt[n][k], At[m][k], acc[ai][bj][m][n], 0, 0, 0); __builtin_amdgcn_s_setprio(0); } while (0)
; #define PG8_WAIT_V(n) asm volatile("s_waitcnt vmcnt(" #n ")" ::: "memory")
; #define PG8_WAIT_L(n) asm volatile("s_waitcnt lgkmcnt(" #n ")" ::: "memory")
; template <class Epi>
; __device__ __forceinline__ void gemm_phase(LAS unsigned char* lds, const Gemm g, const StaticOrder& S, const Epi& E) {
;     ...
;         for (int t = 0; t < nt; t += 2) {
;             const bool last = (t == nt - 2);
;             const char* a1 = cA + (size_t)(t + 1) * kstep;
;             const char* a2 = last ? nA : cA + (size_t)(t + 2) * kstep; const char* b2 = last ? nB : cB + (size_t)(t + 2) * kstep;
;             const char* a3 = a2 + kstep; const char* b3 = b2 + kstep;
;             PG8_LDB(B0, 0, 0); PG8_SCHED; PG8_LDA(At, 0, 0); PG8_STAGE(PG8_SA(1, 1), a1 + hstepA, voffA);
;             PG8_WAIT_L(8); PG8_BAR; PG8_WAIT_L(0); PG8_MMA(0, 0, At, B0); PG8_BAR; PG8_SCHED;
;             PG8_LDB(B1, 0, 1); PG8_STAGE(PG8_SB(0, 0), b2, voffB);
;             PG8_BAR; PG8_WAIT_L(0); PG8_MMA(0, 1, At, B1); PG8_BAR;
;             PG8_LDA(At, 0, 1); PG8_STAGE(PG8_SA(0, 0), a2, voffA);
;             PG8_BAR; PG8_WAIT_L(0); PG8_MMA(1, 0, At, B0); PG8_BAR; PG8_SCHED;
;             PG8_STAGE(PG8_SB(0, 1), b2 + hstepB, voffB);
;             PG8_WAIT_V(6); PG8_BAR; PG8_MMA(1, 1, At, B1); PG8_BAR;
.LBB0_1461:
	ds_read_b128 v[140:143], v149
	ds_read_b128 v[152:155], v149 offset:1024
	ds_read_b128 v[156:159], v149 offset:2048
	ds_read_b128 v[160:163], v149 offset:3072
	s_add_u32 s34, s30, 0x100
	s_addc_u32 s35, s31, 0
	s_cmp_eq_u32 s74, 40
	s_cselect_b32 s39, s13, s35
	s_cselect_b32 s38, s12, s34
	s_cselect_b32 s37, s15, s73
	s_cselect_b32 s36, s14, s72
	v_lshl_add_u64 v[144:145], s[30:31], 0, v[132:133]
	s_add_i32 m0, s8, 0xc000
	ds_read_b128 v[164:167], v150
	ds_read_b128 v[168:171], v150 offset:1024
	ds_read_b128 v[172:175], v150 offset:2048
	ds_read_b128 v[176:179], v150 offset:3072
	ds_read_b128 v[180:183], v150 offset:4096
	ds_read_b128 v[184:187], v150 offset:5120
	ds_read_b128 v[188:191], v150 offset:6144
	ds_read_b128 v[192:195], v150 offset:7168
	global_load_lds_dwordx4 v[144:145], off
	v_lshl_add_u64 v[144:145], s[30:31], 0, v[134:135]
	s_add_i32 m0, s8, 0xe000
	s_nop 0
	global_load_lds_dwordx4 v[144:145], off
	ds_read_b128 v[196:199], v151
	ds_read_b128 v[200:203], v151 offset:1024
	ds_read_b128 v[204:207], v151 offset:2048
	ds_read_b128 v[208:211], v151 offset:3072
	s_waitcnt lgkmcnt(0)
	s_barrier
	s_setprio 1
	v_mfma_f32_16x16x32_bf16 v[124:127], v[140:143], v[164:167], v[124:127]
	v_mfma_f32_16x16x32_bf16 v[120:123], v[156:159], v[164:167], v[120:123]
	v_mfma_f32_16x16x32_bf16 v[112:115], v[140:143], v[172:175], v[112:115]
	v_mfma_f32_16x16x32_bf16 v[104:107], v[156:159], v[172:175], v[104:107]
	v_mfma_f32_16x16x32_bf16 v[92:95], v[140:143], v[180:183], v[92:95]
	v_mfma_f32_16x16x32_bf16 v[88:91], v[156:159], v[180:183], v[88:91]
	v_mfma_f32_16x16x32_bf16 v[80:83], v[140:143], v[188:191], v[80:83]
	v_mfma_f32_16x16x32_bf16 v[72:75], v[156:159], v[188:191], v[72:75]
	v_mfma_f32_16x16x32_bf16 v[124:127], v[152:155], v[168:171], v[124:127]
	v_mfma_f32_16x16x32_bf16 v[120:123], v[160:163], v[168:171], v[120:123]
	v_mfma_f32_16x16x32_bf16 v[112:115], v[152:155], v[176:179], v[112:115]
	v_mfma_f32_16x16x32_bf16 v[104:107], v[160:163], v[176:179], v[104:107]
	v_mfma_f32_16x16x32_bf16 v[92:95], v[152:155], v[184:187], v[92:95]
	v_mfma_f32_16x16x32_bf16 v[88:91], v[160:163], v[184:187], v[88:91]
	v_mfma_f32_16x16x32_bf16 v[80:83], v[152:155], v[192:195], v[80:83]
	v_mfma_f32_16x16x32_bf16 v[72:75], v[160:163], v[192:195], v[72:75]
	v_mfma_f32_16x16x32_bf16 v[116:119], v[196:199], v[164:167], v[116:119]
	v_mfma_f32_16x16x32_bf16 v[108:111], v[204:207], v[164:167], v[108:111]
	v_mfma_f32_16x16x32_bf16 v[100:103], v[196:199], v[172:175], v[100:103]
	v_mfma_f32_16x16x32_bf16 v[96:99], v[204:207], v[172:175], v[96:99]
	v_mfma_f32_16x16x32_bf16 v[84:87], v[196:199], v[180:183], v[84:87]
	v_mfma_f32_16x16x32_bf16 v[76:79], v[204:207], v[180:183], v[76:79]
	v_mfma_f32_16x16x32_bf16 v[68:71], v[196:199], v[188:191], v[68:71]
	v_mfma_f32_16x16x32_bf16 v[64:67], v[204:207], v[188:191], v[64:67]
	v_mfma_f32_16x16x32_bf16 v[116:119], v[200:203], v[168:171], v[116:119]
	v_mfma_f32_16x16x32_bf16 v[108:111], v[208:211], v[168:171], v[108:111]
	v_mfma_f32_16x16x32_bf16 v[100:103], v[200:203], v[176:179], v[100:103]
	v_mfma_f32_16x16x32_bf16 v[96:99], v[208:211], v[176:179], v[96:99]
	v_mfma_f32_16x16x32_bf16 v[84:87], v[200:203], v[184:187], v[84:87]
	v_mfma_f32_16x16x32_bf16 v[76:79], v[208:211], v[184:187], v[76:79]
	v_mfma_f32_16x16x32_bf16 v[68:71], v[200:203], v[192:195], v[68:71]
	v_mfma_f32_16x16x32_bf16 v[64:67], v[208:211], v[192:195], v[64:67]
	s_setprio 0
	s_barrier
	s_nop 1
	ds_read_b128 v[164:167], v150 offset:16384
	ds_read_b128 v[168:171], v150 offset:17408
	ds_read_b128 v[172:175], v150 offset:18432
	ds_read_b128 v[176:179], v150 offset:19456
	ds_read_b128 v[180:183], v150 offset:20480
	ds_read_b128 v[184:187], v150 offset:21504
	ds_read_b128 v[188:191], v150 offset:22528
	ds_read_b128 v[192:195], v150 offset:23552
	s_add_i32 s30, s45, s7
	v_lshl_add_u64 v[144:145], s[36:37], 0, v[128:129]
	s_mov_b32 m0, s30
	s_nop 0
	global_load_lds_dwordx4 v[144:145], off
	v_lshl_add_u64 v[212:213], s[36:37], 0, v[130:131]
	s_add_i32 m0, s30, 0x2000
	s_nop 0
	global_load_lds_dwordx4 v[212:213], off
	s_mov_b32 m0, s8
	v_lshl_add_u64 v[214:215], s[38:39], 0, v[128:129]
	global_load_lds_dwordx4 v[214:215], off
	v_lshl_add_u64 v[216:217], s[38:39], 0, v[130:131]
	s_mov_b32 m0, s9
	s_nop 0
	global_load_lds_dwordx4 v[216:217], off
	s_add_u32 s30, s36, 0xb0000
	s_addc_u32 s31, s37, 0
	s_add_i32 s75, s46, s7
	v_lshl_add_u64 v[254:255], s[30:31], 0, v[128:129]
	s_mov_b32 m0, s75
	s_nop 0
	global_load_lds_dwordx4 v[254:255], off
	v_lshl_add_u64 v[254:255], s[30:31], 0, v[130:131]
	s_add_i32 m0, s75, 0x2000
	s_nop 0
	global_load_lds_dwordx4 v[254:255], off
	s_waitcnt vmcnt(6)
	s_waitcnt lgkmcnt(0)
	s_barrier
; #define PG8_STAGE(bufoff, gbase, voff) do { _Pragma("unroll") for (int _i = 0; _i < 2; ++_i) \
;         __builtin_amdgcn_global_load_lds((const unsigned*)((const char*)(gbase) + (voff)[_i]), (LAS unsigned*)(lds + (bufoff) + ldsw + _i * 8192), 16, 0, 0); } while (0)
; #define PG8_LDA(dst, b, h) do { _Pragma("unroll") for (int m = 0; m < 4; ++m) _Pragma("unroll") for (int k = 0; k < 2; ++k) dst[m][k] = *(const LAS bf16x8*)(lds + PG8_SA(b, h) + aoff + m * 2048 + k * 1024); } while (0)
; #define PG8_LDB(dst, b, h) do { _Pragma("unroll") for (int n = 0; n < 2; ++n) _Pragma("unroll") for (int k = 0; k < 2; ++k) dst[n][k] = *(const LAS bf16x8*)(lds + PG8_SB(b, h) + boff + n * 2048 + k * 1024); } while (0)
; #define PG8_MMA(ai, bj, At, Bt) do { __builtin_amdgcn_s_setprio(1); _Pragma("unroll") for (int m = 0; m < 4; ++m) _Pragma("unroll") for (int n = 0; n < 2; ++n) _Pragma("unroll") for (int k = 0; k < 2; ++k) \
;         acc[ai][bj][m][n] = __builtin_amdgcn_mfma_f32_16x16x32_bf16(Bt[n][k], At[m][k], acc[ai][bj][m][n], 0, 0, 0); __builtin_amdgcn_s_setprio(0); } while (0)
; #define PG8_WAIT_V(n) asm volatile("s_waitcnt vmcnt(" #n ")" ::: "memory")
; #define PG8_WAIT_L(n) asm volatile("s_waitcnt lgkmcnt(" #n ")" ::: "memory")
; #define PG8_BAR __builtin_amdgcn_s_barrier()
; #define PG8_SCHED __builtin_amdgcn_sched_barrier(0)
; template <class Epi>
; __device__ __forceinline__ void gemm_phase(LAS unsigned char* lds, const Gemm g, const StaticOrder& S, const Epi& E) {
;     ...
;             PG8_WAIT_V(6); PG8_BAR; PG8_MMA(1, 1, At, B1); PG8_BAR;
;             PG8_LDB(B0, 1, 0); PG8_SCHED; PG8_LDA(At, 1, 0); PG8_STAGE(PG8_SA(0, 1), a2 + hstepA, voffA);
;             PG8_WAIT_L(8); PG8_BAR; PG8_WAIT_L(0); PG8_MMA(0, 0, At, B0); PG8_BAR; PG8_SCHED;
;             PG8_LDB(B1, 1, 1); PG8_STAGE(PG8_SB(1, 0), b3, voffB);
;             PG8_BAR; PG8_WAIT_L(0); PG8_MMA(0, 1, At, B1); PG8_BAR;
;             PG8_LDA(At, 1, 1); PG8_STAGE(PG8_SA(1, 0), a3, voffA);
;             PG8_BAR; PG8_WAIT_L(0); PG8_MMA(1, 0, At, B0); PG8_BAR; PG8_SCHED;
	s_setprio 1
	v_mfma_f32_16x16x32_bf16 v[60:63], v[140:143], v[164:167], v[60:63]
	v_mfma_f32_16x16x32_bf16 v[56:59], v[156:159], v[164:167], v[56:59]
	v_mfma_f32_16x16x32_bf16 v[48:51], v[140:143], v[172:175], v[48:51]
	v_mfma_f32_16x16x32_bf16 v[40:43], v[156:159], v[172:175], v[40:43]
	v_mfma_f32_16x16x32_bf16 v[28:31], v[140:143], v[180:183], v[28:31]
	v_mfma_f32_16x16x32_bf16 v[24:27], v[156:159], v[180:183], v[24:27]
	v_mfma_f32_16x16x32_bf16 v[16:19], v[140:143], v[188:191], v[16:19]
	v_mfma_f32_16x16x32_bf16 v[8:11], v[156:159], v[188:191], v[8:11]
	v_mfma_f32_16x16x32_bf16 v[60:63], v[152:155], v[168:171], v[60:63]
	v_mfma_f32_16x16x32_bf16 v[56:59], v[160:163], v[168:171], v[56:59]
	v_mfma_f32_16x16x32_bf16 v[48:51], v[152:155], v[176:179], v[48:51]
	v_mfma_f32_16x16x32_bf16 v[40:43], v[160:163], v[176:179], v[40:43]
	v_mfma_f32_16x16x32_bf16 v[28:31], v[152:155], v[184:187], v[28:31]
	v_mfma_f32_16x16x32_bf16 v[24:27], v[160:163], v[184:187], v[24:27]
	v_mfma_f32_16x16x32_bf16 v[16:19], v[152:155], v[192:195], v[16:19]
	v_mfma_f32_16x16x32_bf16 v[8:11], v[160:163], v[192:195], v[8:11]
	v_mfma_f32_16x16x32_bf16 v[52:55], v[196:199], v[164:167], v[52:55]
	v_mfma_f32_16x16x32_bf16 v[44:47], v[204:207], v[164:167], v[44:47]
	v_mfma_f32_16x16x32_bf16 v[36:39], v[196:199], v[172:175], v[36:39]
	v_mfma_f32_16x16x32_bf16 v[32:35], v[204:207], v[172:175], v[32:35]
	v_mfma_f32_16x16x32_bf16 v[20:23], v[196:199], v[180:183], v[20:23]
	v_mfma_f32_16x16x32_bf16 v[12:15], v[204:207], v[180:183], v[12:15]
	v_mfma_f32_16x16x32_bf16 v[4:7], v[196:199], v[188:191], v[4:7]
	v_mfma_f32_16x16x32_bf16 v[0:3], v[204:207], v[188:191], v[0:3]
	v_mfma_f32_16x16x32_bf16 v[52:55], v[200:203], v[168:171], v[52:55]
	v_mfma_f32_16x16x32_bf16 v[44:47], v[208:211], v[168:171], v[44:47]
	v_mfma_f32_16x16x32_bf16 v[36:39], v[200:203], v[176:179], v[36:39]
	v_mfma_f32_16x16x32_bf16 v[32:35], v[208:211], v[176:179], v[32:35]
	v_mfma_f32_16x16x32_bf16 v[20:23], v[200:203], v[184:187], v[20:23]
	v_mfma_f32_16x16x32_bf16 v[12:15], v[208:211], v[184:187], v[12:15]
	v_mfma_f32_16x16x32_bf16 v[4:7], v[200:203], v[192:195], v[4:7]
	v_mfma_f32_16x16x32_bf16 v[0:3], v[208:211], v[192:195], v[0:3]
	s_setprio 0
	s_add_i32 s75, 0, 0x18000
	v_add_u32_e32 v160, s75, v147
	s_barrier
	ds_read_b128 v[140:143], v160
	ds_read_b128 v[152:155], v160 offset:1024
	ds_read_b128 v[156:159], v160 offset:2048
	ds_read_b128 v[160:163], v160 offset:3072
	s_add_u32 s30, s38, 0xb0000
	s_addc_u32 s31, s39, 0
	s_mov_b32 m0, s40
	v_lshl_add_u64 v[196:197], s[30:31], 0, v[128:129]
	ds_read_b128 v[164:167], v150 offset:32768
	ds_read_b128 v[168:171], v150 offset:33792
	ds_read_b128 v[172:175], v150 offset:34816
	ds_read_b128 v[176:179], v150 offset:35840
	ds_read_b128 v[180:183], v150 offset:36864
	ds_read_b128 v[184:187], v150 offset:37888
	ds_read_b128 v[188:191], v150 offset:38912
	ds_read_b128 v[192:195], v150 offset:39936
	global_load_lds_dwordx4 v[196:197], off
	v_lshl_add_u64 v[196:197], s[30:31], 0, v[130:131]
	s_mov_b32 m0, s41
	s_nop 0
	global_load_lds_dwordx4 v[196:197], off
	s_add_i32 s38, 0, 0x1c000
	v_add_u32_e32 v208, s38, v147
	ds_read_b128 v[196:199], v208
	ds_read_b128 v[200:203], v208 offset:1024
	ds_read_b128 v[204:207], v208 offset:2048
	ds_read_b128 v[208:211], v208 offset:3072
	s_waitcnt lgkmcnt(0)
	s_barrier
	s_setprio 1
	v_mfma_f32_16x16x32_bf16 v[124:127], v[140:143], v[164:167], v[124:127]
	v_mfma_f32_16x16x32_bf16 v[120:123], v[156:159], v[164:167], v[120:123]
	v_mfma_f32_16x16x32_bf16 v[112:115], v[140:143], v[172:175], v[112:115]
	v_mfma_f32_16x16x32_bf16 v[104:107], v[156:159], v[172:175], v[104:107]
	v_mfma_f32_16x16x32_bf16 v[92:95], v[140:143], v[180:183], v[92:95]
	v_mfma_f32_16x16x32_bf16 v[88:91], v[156:159], v[180:183], v[88:91]
	v_mfma_f32_16x16x32_bf16 v[80:83], v[140:143], v[188:191], v[80:83]
	v_mfma_f32_16x16x32_bf16 v[72:75], v[156:159], v[188:191], v[72:75]
	v_mfma_f32_16x16x32_bf16 v[124:127], v[152:155], v[168:171], v[124:127]
	v_mfma_f32_16x16x32_bf16 v[120:123], v[160:163], v[168:171], v[120:123]
	v_mfma_f32_16x16x32_bf16 v[112:115], v[152:155], v[176:179], v[112:115]
	v_mfma_f32_16x16x32_bf16 v[104:107], v[160:163], v[176:179], v[104:107]
	v_mfma_f32_16x16x32_bf16 v[92:95], v[152:155], v[184:187], v[92:95]
	v_mfma_f32_16x16x32_bf16 v[88:91], v[160:163], v[184:187], v[88:91]
	v_mfma_f32_16x16x32_bf16 v[80:83], v[152:155], v[192:195], v[80:83]
	v_mfma_f32_16x16x32_bf16 v[72:75], v[160:163], v[192:195], v[72:75]
	v_mfma_f32_16x16x32_bf16 v[116:119], v[196:199], v[164:167], v[116:119]
	v_mfma_f32_16x16x32_bf16 v[108:111], v[204:207], v[164:167], v[108:111]
	v_mfma_f32_16x16x32_bf16 v[100:103], v[196:199], v[172:175], v[100:103]
	v_mfma_f32_16x16x32_bf16 v[96:99], v[204:207], v[172:175], v[96:99]
	v_mfma_f32_16x16x32_bf16 v[84:87], v[196:199], v[180:183], v[84:87]
	v_mfma_f32_16x16x32_bf16 v[76:79], v[204:207], v[180:183], v[76:79]
	v_mfma_f32_16x16x32_bf16 v[68:71], v[196:199], v[188:191], v[68:71]
	v_mfma_f32_16x16x32_bf16 v[64:67], v[204:207], v[188:191], v[64:67]
	v_mfma_f32_16x16x32_bf16 v[116:119], v[200:203], v[168:171], v[116:119]
	v_mfma_f32_16x16x32_bf16 v[108:111], v[208:211], v[168:171], v[108:111]
	v_mfma_f32_16x16x32_bf16 v[100:103], v[200:203], v[176:179], v[100:103]
	v_mfma_f32_16x16x32_bf16 v[96:99], v[208:211], v[176:179], v[96:99]
	v_mfma_f32_16x16x32_bf16 v[84:87], v[200:203], v[184:187], v[84:87]
	v_mfma_f32_16x16x32_bf16 v[76:79], v[208:211], v[184:187], v[76:79]
	v_mfma_f32_16x16x32_bf16 v[68:71], v[200:203], v[192:195], v[68:71]
	v_mfma_f32_16x16x32_bf16 v[64:67], v[208:211], v[192:195], v[64:67]
	s_setprio 0
	s_barrier
; #define PG8_STAGE(bufoff, gbase, voff) do { _Pragma("unroll") for (int _i = 0; _i < 2; ++_i) \
;         __builtin_amdgcn_global_load_lds((const unsigned*)((const char*)(gbase) + (voff)[_i]), (LAS unsigned*)(lds + (bufoff) + ldsw + _i * 8192), 16, 0, 0); } while (0)
; #define PG8_LDA(dst, b, h) do { _Pragma("unroll") for (int m = 0; m < 4; ++m) _Pragma("unroll") for (int k = 0; k < 2; ++k) dst[m][k] = *(const LAS bf16x8*)(lds + PG8_SA(b, h) + aoff + m * 2048 + k * 1024); } while (0)
; #define PG8_MMA(ai, bj, At, Bt) do { __builtin_amdgcn_s_setprio(1); _Pragma("unroll") for (int m = 0; m < 4; ++m) _Pragma("unroll") for (int n = 0; n < 2; ++n) _Pragma("unroll") for (int k = 0; k < 2; ++k) \
;         acc[ai][bj][m][n] = __builtin_amdgcn_mfma_f32_16x16x32_bf16(Bt[n][k], At[m][k], acc[ai][bj][m][n], 0, 0, 0); __builtin_amdgcn_s_setprio(0); } while (0)
; template <class Epi>
; __device__ __forceinline__ void gemm_phase(LAS unsigned char* lds, const Gemm g, const StaticOrder& S, const Epi& E) {
;     ...
;             PG8_LDA(At, 1, 1); PG8_STAGE(PG8_SA(1, 0), a3, voffA);
;             PG8_BAR; PG8_WAIT_L(0); PG8_MMA(1, 0, At, B0); PG8_BAR; PG8_SCHED;
;             PG8_STAGE(PG8_SB(1, 1), b3 + hstepB, voffB);
;             PG8_WAIT_V(6); PG8_BAR; PG8_MMA(1, 1, At, B1); PG8_BAR;
;         }
;     __device__ __forceinline__ void operator()(AccRef acc, const Unit& u, int wr, int wc, int fr, int fq) const {
;         const int row0 = u.pm * 256 + wr * 64 + fr, col0 = u.pn * 256 + wc * 32 + 4 * fq;
;         f32x4 sv[2][2], bv[2][2];
; #pragma unroll
;         for (int bj = 0; bj < 2; ++bj)
; #pragma unroll
;             for (int n = 0; n < 2; ++n) {
;                 sv[bj][n] = scale ? *(const f32x4*)(scale + col0 + bj * 128 + n * 16) : (f32x4){1.f, 1.f, 1.f, 1.f};
;                 bv[bj][n] = bias ? *(const f32x4*)(bias + col0 + bj * 128 + n * 16) : (f32x4){0.f, 0.f, 0.f, 0.f}; }
; #pragma unroll
;         for (int ai = 0; ai < 2; ++ai)
; #pragma unroll
;             for (int mh = 0; mh < 2; ++mh) {
;                 f32x4 bs[2][2][2];
; #pragma unroll
;                 for (int m = 0; m < 2; ++m)
; #pragma unroll
;                     for (int bj = 0; bj < 2; ++bj)
; #pragma unroll
;                         for (int n = 0; n < 2; ++n) bs[m][bj][n] = *(const f32x4*)(base + (size_t)(row0 + ai * 128 + (2 * mh + m) * 16) * D + col0 + bj * 128 + n * 16);
	s_nop 1
	ds_read_b128 v[164:167], v150 offset:49152
	ds_read_b128 v[168:171], v150 offset:50176
	ds_read_b128 v[172:175], v150 offset:51200
	ds_read_b128 v[176:179], v150 offset:52224
	ds_read_b128 v[180:183], v150 offset:53248
	ds_read_b128 v[184:187], v150 offset:54272
	ds_read_b128 v[188:191], v150 offset:55296
	ds_read_b128 v[192:195], v150 offset:56320
	s_add_i32 s30, s75, s7
	v_lshl_add_u64 v[254:255], v[144:145], 0, s[22:23]
	s_mov_b32 m0, s30
	s_nop 0
	global_load_lds_dwordx4 v[254:255], off
	v_lshl_add_u64 v[254:255], v[212:213], 0, s[22:23]
	s_add_i32 m0, s30, 0x2000
	s_nop 0
	global_load_lds_dwordx4 v[254:255], off
	s_mov_b32 m0, s43
	v_lshl_add_u64 v[254:255], v[214:215], 0, s[22:23]
	global_load_lds_dwordx4 v[254:255], off
	v_lshl_add_u64 v[144:145], v[216:217], 0, s[22:23]
	s_mov_b32 m0, s44
	s_nop 0
	global_load_lds_dwordx4 v[144:145], off
	s_add_u32 s30, s36, 0xb0080
	s_addc_u32 s31, s37, 0
	s_add_i32 s36, s38, s7
	v_lshl_add_u64 v[254:255], s[30:31], 0, v[128:129]
	s_mov_b32 m0, s36
	s_nop 0
	global_load_lds_dwordx4 v[254:255], off
	v_lshl_add_u64 v[254:255], s[30:31], 0, v[130:131]
	s_add_i32 m0, s36, 0x2000
	s_nop 0
	global_load_lds_dwordx4 v[254:255], off
	s_waitcnt vmcnt(6)
	s_waitcnt lgkmcnt(0)
	s_barrier
	s_setprio 1
	v_mfma_f32_16x16x32_bf16 v[60:63], v[140:143], v[164:167], v[60:63]
	v_mfma_f32_16x16x32_bf16 v[56:59], v[156:159], v[164:167], v[56:59]
	v_mfma_f32_16x16x32_bf16 v[48:51], v[140:143], v[172:175], v[48:51]
	v_mfma_f32_16x16x32_bf16 v[40:43], v[156:159], v[172:175], v[40:43]
	v_mfma_f32_16x16x32_bf16 v[28:31], v[140:143], v[180:183], v[28:31]
	v_mfma_f32_16x16x32_bf16 v[24:27], v[156:159], v[180:183], v[24:27]
	v_mfma_f32_16x16x32_bf16 v[16:19], v[140:143], v[188:191], v[16:19]
	v_mfma_f32_16x16x32_bf16 v[8:11], v[156:159], v[188:191], v[8:11]
	v_mfma_f32_16x16x32_bf16 v[60:63], v[152:155], v[168:171], v[60:63]
	v_mfma_f32_16x16x32_bf16 v[56:59], v[160:163], v[168:171], v[56:59]
	v_mfma_f32_16x16x32_bf16 v[48:51], v[152:155], v[176:179], v[48:51]
	v_mfma_f32_16x16x32_bf16 v[40:43], v[160:163], v[176:179], v[40:43]
	v_mfma_f32_16x16x32_bf16 v[28:31], v[152:155], v[184:187], v[28:31]
	v_mfma_f32_16x16x32_bf16 v[24:27], v[160:163], v[184:187], v[24:27]
	v_mfma_f32_16x16x32_bf16 v[16:19], v[152:155], v[192:195], v[16:19]
	v_mfma_f32_16x16x32_bf16 v[8:11], v[160:163], v[192:195], v[8:11]
	v_mfma_f32_16x16x32_bf16 v[52:55], v[196:199], v[164:167], v[52:55]
	v_mfma_f32_16x16x32_bf16 v[44:47], v[204:207], v[164:167], v[44:47]
	v_mfma_f32_16x16x32_bf16 v[36:39], v[196:199], v[172:175], v[36:39]
	v_mfma_f32_16x16x32_bf16 v[32:35], v[204:207], v[172:175], v[32:35]
	v_mfma_f32_16x16x32_bf16 v[20:23], v[196:199], v[180:183], v[20:23]
	v_mfma_f32_16x16x32_bf16 v[12:15], v[204:207], v[180:183], v[12:15]
	v_mfma_f32_16x16x32_bf16 v[4:7], v[196:199], v[188:191], v[4:7]
	v_mfma_f32_16x16x32_bf16 v[0:3], v[204:207], v[188:191], v[0:3]
	v_mfma_f32_16x16x32_bf16 v[52:55], v[200:203], v[168:171], v[52:55]
	v_mfma_f32_16x16x32_bf16 v[44:47], v[208:211], v[168:171], v[44:47]
	v_mfma_f32_16x16x32_bf16 v[36:39], v[200:203], v[176:179], v[36:39]
	v_mfma_f32_16x16x32_bf16 v[32:35], v[208:211], v[176:179], v[32:35]
	v_mfma_f32_16x16x32_bf16 v[20:23], v[200:203], v[184:187], v[20:23]
	v_mfma_f32_16x16x32_bf16 v[12:15], v[208:211], v[184:187], v[12:15]
	v_mfma_f32_16x16x32_bf16 v[4:7], v[200:203], v[192:195], v[4:7]
	v_mfma_f32_16x16x32_bf16 v[0:3], v[208:211], v[192:195], v[0:3]
	s_setprio 0
	s_add_i32 s74, s74, 2
	s_add_u32 s72, s72, 0x100
	s_addc_u32 s73, s73, 0
	s_cmp_gt_u32 s74, 41
	s_mov_b64 s[30:31], s[34:35]
	s_barrier
	s_cbranch_scc0 .LBB0_1461
	v_lshl_or_b32 v144, s49, 8, v148
	v_lshl_add_u32 v145, s63, 8, v146
	v_lshlrev_b32_e32 v144, 2, v144
	v_lshl_add_u32 v145, v145, 12, v144
	v_add_u32_e32 v216, 0x10000, v145
	v_add_u32_e32 v217, 0x20000, v145
	v_add_u32_e32 v218, 0x30000, v145
	v_add_u32_e32 v220, 0x80000, v145
	v_add_u32_e32 v221, 0x90000, v145
	v_add_u32_e32 v222, 0xa0000, v145
	v_add_u32_e32 v223, 0xb0000, v145
	v_and_b32_e32 v235, 8, v146
	v_cmp_ne_u32_e32 vcc, 0, v235
	v_mov_b32_e32 v232, 0xffff8040
	s_nop 0
	v_cndmask_b32_e32 v232, 0, v232, vcc
	v_mov_b32_e32 v233, 64
	v_mov_b32_e32 v235, 0x8000
	v_cndmask_b32_e32 v233, v235, v233, vcc
	v_add_u32_e32 v224, v145, v232
	v_add_u32_e32 v225, v216, v232
	v_add_u32_e32 v226, v217, v232
	v_add_u32_e32 v227, v218, v232
	v_add_u32_e32 v228, v220, v232
	v_add_u32_e32 v229, v221, v232
	v_add_u32_e32 v230, v222, v232
	v_add_u32_e32 v231, v223, v232
	s_and_b64 vcc, exec, s[10:11]
	s_mov_b32 s49, s47
	s_mov_b32 s63, s48
	s_mov_b64 s[34:35], s[14:15]
	s_mov_b64 s[30:31], s[12:13]
	global_load_dwordx4 v[140:143], v224, s[52:53]
	v_add_u32_e32 v144, v145, v233
	global_load_dwordx4 v[152:155], v144, s[52:53]
	global_load_dwordx4 v[156:159], v224, s[52:53] offset:512
	v_add_u32_e32 v144, v145, v233
	global_load_dwordx4 v[160:163], v144, s[52:53] offset:512
	global_load_dwordx4 v[164:167], v225, s[52:53]
	v_add_u32_e32 v144, v216, v233
	global_load_dwordx4 v[168:171], v144, s[52:53]
	global_load_dwordx4 v[172:175], v225, s[52:53] offset:512
	v_add_u32_e32 v144, v216, v233
	global_load_dwordx4 v[176:179], v144, s[52:53] offset:512
	global_load_dwordx4 v[180:183], v226, s[52:53]
	v_add_u32_e32 v144, v217, v233
	global_load_dwordx4 v[184:187], v144, s[52:53]
	global_load_dwordx4 v[188:191], v226, s[52:53] offset:512
	v_add_u32_e32 v144, v217, v233
	global_load_dwordx4 v[192:195], v144, s[52:53] offset:512
	global_load_dwordx4 v[196:199], v227, s[52:53]
	v_add_u32_e32 v144, v218, v233
	global_load_dwordx4 v[200:203], v144, s[52:53]
	global_load_dwordx4 v[204:207], v227, s[52:53] offset:512
	v_add_u32_e32 v144, v218, v233
	global_load_dwordx4 v[208:211], v144, s[52:53] offset:512
	s_barrier
;     __device__ __forceinline__ void operator()(AccRef acc, const Unit& u, int wr, int wc, int fr, int fq) const {
;     ...
;                         for (int n = 0; n < 2; ++n) bs[m][bj][n] = *(const f32x4*)(base + (size_t)(row0 + ai * 128 + (2 * mh + m) * 16) * D + col0 + bj * 128 + n * 16);
; #pragma unroll
;                 for (int m = 0; m < 2; ++m)
; #pragma unroll
;                     for (int bj = 0; bj < 2; ++bj)
; #pragma unroll
;                         for (int n = 0; n < 2; ++n) *(f32x4*)(out + (size_t)(row0 + ai * 128 + (2 * mh + m) * 16) * D + col0 + bj * 128 + n * 16) = bs[m][bj][n] + sv[bj][n] * (acc[ai][bj][2 * mh + m][n] + bv[bj][n]);
	v_pk_add_f32 v[124:125], v[124:125], 0 op_sel_hi:[1,0]
	v_pk_add_f32 v[126:127], v[126:127], 0 op_sel_hi:[1,0]
	v_pk_add_f32 v[120:121], v[120:121], 0 op_sel_hi:[1,0]
	v_pk_add_f32 v[122:123], v[122:123], 0 op_sel_hi:[1,0]
	v_pk_add_f32 v[116:117], v[116:117], 0 op_sel_hi:[1,0]
	v_pk_add_f32 v[118:119], v[118:119], 0 op_sel_hi:[1,0]
	v_pk_add_f32 v[108:109], v[108:109], 0 op_sel_hi:[1,0]
	v_pk_add_f32 v[110:111], v[110:111], 0 op_sel_hi:[1,0]
	v_pk_add_f32 v[112:113], v[112:113], 0 op_sel_hi:[1,0]
	v_pk_add_f32 v[114:115], v[114:115], 0 op_sel_hi:[1,0]
	v_pk_add_f32 v[104:105], v[104:105], 0 op_sel_hi:[1,0]
	v_pk_add_f32 v[106:107], v[106:107], 0 op_sel_hi:[1,0]
	v_pk_add_f32 v[100:101], v[100:101], 0 op_sel_hi:[1,0]
	v_pk_add_f32 v[102:103], v[102:103], 0 op_sel_hi:[1,0]
	v_pk_add_f32 v[96:97], v[96:97], 0 op_sel_hi:[1,0]
	v_pk_add_f32 v[98:99], v[98:99], 0 op_sel_hi:[1,0]
	v_pk_add_f32 v[92:93], v[92:93], 0 op_sel_hi:[1,0]
	v_pk_add_f32 v[94:95], v[94:95], 0 op_sel_hi:[1,0]
	v_pk_add_f32 v[88:89], v[88:89], 0 op_sel_hi:[1,0]
	v_pk_add_f32 v[90:91], v[90:91], 0 op_sel_hi:[1,0]
	v_pk_add_f32 v[84:85], v[84:85], 0 op_sel_hi:[1,0]
	v_pk_add_f32 v[86:87], v[86:87], 0 op_sel_hi:[1,0]
	v_pk_add_f32 v[76:77], v[76:77], 0 op_sel_hi:[1,0]
	v_pk_add_f32 v[78:79], v[78:79], 0 op_sel_hi:[1,0]
	v_pk_add_f32 v[80:81], v[80:81], 0 op_sel_hi:[1,0]
	v_pk_add_f32 v[82:83], v[82:83], 0 op_sel_hi:[1,0]
	v_pk_add_f32 v[72:73], v[72:73], 0 op_sel_hi:[1,0]
	v_pk_add_f32 v[74:75], v[74:75], 0 op_sel_hi:[1,0]
	v_pk_add_f32 v[68:69], v[68:69], 0 op_sel_hi:[1,0]
	v_pk_add_f32 v[70:71], v[70:71], 0 op_sel_hi:[1,0]
	v_pk_add_f32 v[64:65], v[64:65], 0 op_sel_hi:[1,0]
	v_pk_add_f32 v[66:67], v[66:67], 0 op_sel_hi:[1,0]
	v_pk_add_f32 v[60:61], v[60:61], 0 op_sel_hi:[1,0]
	v_pk_add_f32 v[62:63], v[62:63], 0 op_sel_hi:[1,0]
	v_pk_add_f32 v[56:57], v[56:57], 0 op_sel_hi:[1,0]
	v_pk_add_f32 v[58:59], v[58:59], 0 op_sel_hi:[1,0]
	v_pk_add_f32 v[52:53], v[52:53], 0 op_sel_hi:[1,0]
	v_pk_add_f32 v[54:55], v[54:55], 0 op_sel_hi:[1,0]
	v_pk_add_f32 v[44:45], v[44:45], 0 op_sel_hi:[1,0]
	v_pk_add_f32 v[46:47], v[46:47], 0 op_sel_hi:[1,0]
	v_pk_add_f32 v[48:49], v[48:49], 0 op_sel_hi:[1,0]
	v_pk_add_f32 v[50:51], v[50:51], 0 op_sel_hi:[1,0]
	v_pk_add_f32 v[40:41], v[40:41], 0 op_sel_hi:[1,0]
	v_pk_add_f32 v[42:43], v[42:43], 0 op_sel_hi:[1,0]
	v_pk_add_f32 v[36:37], v[36:37], 0 op_sel_hi:[1,0]
	v_pk_add_f32 v[38:39], v[38:39], 0 op_sel_hi:[1,0]
	v_pk_add_f32 v[32:33], v[32:33], 0 op_sel_hi:[1,0]
	v_pk_add_f32 v[34:35], v[34:35], 0 op_sel_hi:[1,0]
	v_pk_add_f32 v[28:29], v[28:29], 0 op_sel_hi:[1,0]
	v_pk_add_f32 v[30:31], v[30:31], 0 op_sel_hi:[1,0]
	v_pk_add_f32 v[24:25], v[24:25], 0 op_sel_hi:[1,0]
	v_pk_add_f32 v[26:27], v[26:27], 0 op_sel_hi:[1,0]
	v_pk_add_f32 v[20:21], v[20:21], 0 op_sel_hi:[1,0]
	v_pk_add_f32 v[22:23], v[22:23], 0 op_sel_hi:[1,0]
	v_pk_add_f32 v[12:13], v[12:13], 0 op_sel_hi:[1,0]
	v_pk_add_f32 v[14:15], v[14:15], 0 op_sel_hi:[1,0]
	v_pk_add_f32 v[16:17], v[16:17], 0 op_sel_hi:[1,0]
	v_pk_add_f32 v[18:19], v[18:19], 0 op_sel_hi:[1,0]
	v_pk_add_f32 v[8:9], v[8:9], 0 op_sel_hi:[1,0]
	v_pk_add_f32 v[10:11], v[10:11], 0 op_sel_hi:[1,0]
	v_pk_add_f32 v[4:5], v[4:5], 0 op_sel_hi:[1,0]
	v_pk_add_f32 v[6:7], v[6:7], 0 op_sel_hi:[1,0]
	v_pk_add_f32 v[0:1], v[0:1], 0 op_sel_hi:[1,0]
	v_pk_add_f32 v[2:3], v[2:3], 0 op_sel_hi:[1,0]
	s_waitcnt vmcnt(8)
	v_mov_b32_e32 v212, v124
	v_mov_b32_e32 v213, v125
	v_mov_b32_e32 v214, v126
	v_mov_b32_e32 v215, v127
	s_nop 0
	v_mov_b32_dpp v124, v120 row_shr:8 row_mask:0xf bank_mask:0xc
	v_mov_b32_dpp v125, v121 row_shr:8 row_mask:0xf bank_mask:0xc
	v_mov_b32_dpp v126, v122 row_shr:8 row_mask:0xf bank_mask:0xc
	v_mov_b32_dpp v127, v123 row_shr:8 row_mask:0xf bank_mask:0xc
	v_mov_b32_dpp v120, v212 row_shl:8 row_mask:0xf bank_mask:0x3
	v_mov_b32_dpp v121, v213 row_shl:8 row_mask:0xf bank_mask:0x3
	v_mov_b32_dpp v122, v214 row_shl:8 row_mask:0xf bank_mask:0x3
	v_mov_b32_dpp v123, v215 row_shl:8 row_mask:0xf bank_mask:0x3
	v_mov_b32_e32 v212, v116
	v_mov_b32_e32 v213, v117
	v_mov_b32_e32 v214, v118
	v_mov_b32_e32 v215, v119
	s_nop 0
	v_mov_b32_dpp v116, v108 row_shr:8 row_mask:0xf bank_mask:0xc
	v_mov_b32_dpp v117, v109 row_shr:8 row_mask:0xf bank_mask:0xc
	v_mov_b32_dpp v118, v110 row_shr:8 row_mask:0xf bank_mask:0xc
	v_mov_b32_dpp v119, v111 row_shr:8 row_mask:0xf bank_mask:0xc
	v_mov_b32_dpp v108, v212 row_shl:8 row_mask:0xf bank_mask:0x3
	v_mov_b32_dpp v109, v213 row_shl:8 row_mask:0xf bank_mask:0x3
	v_mov_b32_dpp v110, v214 row_shl:8 row_mask:0xf bank_mask:0x3
	v_mov_b32_dpp v111, v215 row_shl:8 row_mask:0xf bank_mask:0x3
	v_mov_b32_e32 v212, v112
	v_mov_b32_e32 v213, v113
	v_mov_b32_e32 v214, v114
	v_mov_b32_e32 v215, v115
	s_nop 0
	v_mov_b32_dpp v112, v104 row_shr:8 row_mask:0xf bank_mask:0xc
	v_mov_b32_dpp v113, v105 row_shr:8 row_mask:0xf bank_mask:0xc
	v_mov_b32_dpp v114, v106 row_shr:8 row_mask:0xf bank_mask:0xc
	v_mov_b32_dpp v115, v107 row_shr:8 row_mask:0xf bank_mask:0xc
	v_mov_b32_dpp v104, v212 row_shl:8 row_mask:0xf bank_mask:0x3
	v_mov_b32_dpp v105, v213 row_shl:8 row_mask:0xf bank_mask:0x3
	v_mov_b32_dpp v106, v214 row_shl:8 row_mask:0xf bank_mask:0x3
	v_mov_b32_dpp v107, v215 row_shl:8 row_mask:0xf bank_mask:0x3
	v_mov_b32_e32 v212, v100
	v_mov_b32_e32 v213, v101
	v_mov_b32_e32 v214, v102
	v_mov_b32_e32 v215, v103
	s_nop 0
	v_mov_b32_dpp v100, v96 row_shr:8 row_mask:0xf bank_mask:0xc
	v_mov_b32_dpp v101, v97 row_shr:8 row_mask:0xf bank_mask:0xc
	v_mov_b32_dpp v102, v98 row_shr:8 row_mask:0xf bank_mask:0xc
	v_mov_b32_dpp v103, v99 row_shr:8 row_mask:0xf bank_mask:0xc
	v_mov_b32_dpp v96, v212 row_shl:8 row_mask:0xf bank_mask:0x3
;     __device__ __forceinline__ void operator()(AccRef acc, const Unit& u, int wr, int wc, int fr, int fq) const {
;     ...
;                         for (int n = 0; n < 2; ++n) bs[m][bj][n] = *(const f32x4*)(base + (size_t)(row0 + ai * 128 + (2 * mh + m) * 16) * D + col0 + bj * 128 + n * 16);
; #pragma unroll
;                 for (int m = 0; m < 2; ++m)
; #pragma unroll
;                     for (int bj = 0; bj < 2; ++bj)
; #pragma unroll
;                         for (int n = 0; n < 2; ++n) *(f32x4*)(out + (size_t)(row0 + ai * 128 + (2 * mh + m) * 16) * D + col0 + bj * 128 + n * 16) = bs[m][bj][n] + sv[bj][n] * (acc[ai][bj][2 * mh + m][n] + bv[bj][n]);
;                 asm volatile("" ::: "memory"); }
	v_mov_b32_dpp v97, v213 row_shl:8 row_mask:0xf bank_mask:0x3
	v_mov_b32_dpp v98, v214 row_shl:8 row_mask:0xf bank_mask:0x3
	v_mov_b32_dpp v99, v215 row_shl:8 row_mask:0xf bank_mask:0x3
	v_pk_add_f32 v[124:125], v[124:125], v[140:141]
	v_pk_add_f32 v[126:127], v[126:127], v[142:143]
	v_pk_add_f32 v[120:121], v[120:121], v[152:153]
	v_pk_add_f32 v[122:123], v[122:123], v[154:155]
	v_pk_add_f32 v[116:117], v[116:117], v[156:157]
	v_pk_add_f32 v[118:119], v[118:119], v[158:159]
	v_pk_add_f32 v[108:109], v[108:109], v[160:161]
	v_pk_add_f32 v[110:111], v[110:111], v[162:163]
	v_pk_add_f32 v[112:113], v[112:113], v[164:165]
	v_pk_add_f32 v[114:115], v[114:115], v[166:167]
	v_pk_add_f32 v[104:105], v[104:105], v[168:169]
	v_pk_add_f32 v[106:107], v[106:107], v[170:171]
	v_pk_add_f32 v[100:101], v[100:101], v[172:173]
	v_pk_add_f32 v[102:103], v[102:103], v[174:175]
	v_pk_add_f32 v[96:97], v[96:97], v[176:177]
	v_pk_add_f32 v[98:99], v[98:99], v[178:179]
	global_store_dwordx4 v224, v[124:127], s[52:53]
	v_add_u32_e32 v144, v145, v233
	global_store_dwordx4 v144, v[120:123], s[52:53]
	global_store_dwordx4 v224, v[116:119], s[52:53] offset:512
	v_add_u32_e32 v144, v145, v233
	global_store_dwordx4 v144, v[108:111], s[52:53] offset:512
	global_store_dwordx4 v225, v[112:115], s[52:53]
	v_add_u32_e32 v144, v216, v233
	global_store_dwordx4 v144, v[104:107], s[52:53]
	global_store_dwordx4 v225, v[100:103], s[52:53] offset:512
	v_add_u32_e32 v144, v216, v233
	global_store_dwordx4 v144, v[96:99], s[52:53] offset:512
	global_load_dwordx4 v[140:143], v228, s[52:53]
	v_add_u32_e32 v144, v220, v233
	global_load_dwordx4 v[152:155], v144, s[52:53]
	global_load_dwordx4 v[156:159], v228, s[52:53] offset:512
	v_add_u32_e32 v144, v220, v233
	global_load_dwordx4 v[160:163], v144, s[52:53] offset:512
	global_load_dwordx4 v[164:167], v229, s[52:53]
	v_add_u32_e32 v144, v221, v233
	global_load_dwordx4 v[168:171], v144, s[52:53]
	global_load_dwordx4 v[172:175], v229, s[52:53] offset:512
	v_add_u32_e32 v144, v221, v233
	global_load_dwordx4 v[176:179], v144, s[52:53] offset:512
	s_waitcnt vmcnt(16)
	v_mov_b32_e32 v212, v92
	v_mov_b32_e32 v213, v93
	v_mov_b32_e32 v214, v94
	v_mov_b32_e32 v215, v95
	s_nop 0
	v_mov_b32_dpp v92, v88 row_shr:8 row_mask:0xf bank_mask:0xc
	v_mov_b32_dpp v93, v89 row_shr:8 row_mask:0xf bank_mask:0xc
	v_mov_b32_dpp v94, v90 row_shr:8 row_mask:0xf bank_mask:0xc
	v_mov_b32_dpp v95, v91 row_shr:8 row_mask:0xf bank_mask:0xc
	v_mov_b32_dpp v88, v212 row_shl:8 row_mask:0xf bank_mask:0x3
	v_mov_b32_dpp v89, v213 row_shl:8 row_mask:0xf bank_mask:0x3
	v_mov_b32_dpp v90, v214 row_shl:8 row_mask:0xf bank_mask:0x3
	v_mov_b32_dpp v91, v215 row_shl:8 row_mask:0xf bank_mask:0x3
	v_mov_b32_e32 v212, v84
	v_mov_b32_e32 v213, v85
	v_mov_b32_e32 v214, v86
	v_mov_b32_e32 v215, v87
	s_nop 0
	v_mov_b32_dpp v84, v76 row_shr:8 row_mask:0xf bank_mask:0xc
	v_mov_b32_dpp v85, v77 row_shr:8 row_mask:0xf bank_mask:0xc
	v_mov_b32_dpp v86, v78 row_shr:8 row_mask:0xf bank_mask:0xc
	v_mov_b32_dpp v87, v79 row_shr:8 row_mask:0xf bank_mask:0xc
	v_mov_b32_dpp v76, v212 row_shl:8 row_mask:0xf bank_mask:0x3
	v_mov_b32_dpp v77, v213 row_shl:8 row_mask:0xf bank_mask:0x3
	v_mov_b32_dpp v78, v214 row_shl:8 row_mask:0xf bank_mask:0x3
	v_mov_b32_dpp v79, v215 row_shl:8 row_mask:0xf bank_mask:0x3
	v_mov_b32_e32 v212, v80
	v_mov_b32_e32 v213, v81
	v_mov_b32_e32 v214, v82
	v_mov_b32_e32 v215, v83
	s_nop 0
	v_mov_b32_dpp v80, v72 row_shr:8 row_mask:0xf bank_mask:0xc
	v_mov_b32_dpp v81, v73 row_shr:8 row_mask:0xf bank_mask:0xc
	v_mov_b32_dpp v82, v74 row_shr:8 row_mask:0xf bank_mask:0xc
	v_mov_b32_dpp v83, v75 row_shr:8 row_mask:0xf bank_mask:0xc
	v_mov_b32_dpp v72, v212 row_shl:8 row_mask:0xf bank_mask:0x3
	v_mov_b32_dpp v73, v213 row_shl:8 row_mask:0xf bank_mask:0x3
	v_mov_b32_dpp v74, v214 row_shl:8 row_mask:0xf bank_mask:0x3
	v_mov_b32_dpp v75, v215 row_shl:8 row_mask:0xf bank_mask:0x3
	v_mov_b32_e32 v212, v68
	v_mov_b32_e32 v213, v69
	v_mov_b32_e32 v214, v70
	v_mov_b32_e32 v215, v71
	s_nop 0
	v_mov_b32_dpp v68, v64 row_shr:8 row_mask:0xf bank_mask:0xc
	v_mov_b32_dpp v69, v65 row_shr:8 row_mask:0xf bank_mask:0xc
	v_mov_b32_dpp v70, v66 row_shr:8 row_mask:0xf bank_mask:0xc
	v_mov_b32_dpp v71, v67 row_shr:8 row_mask:0xf bank_mask:0xc
	v_mov_b32_dpp v64, v212 row_shl:8 row_mask:0xf bank_mask:0x3
	v_mov_b32_dpp v65, v213 row_shl:8 row_mask:0xf bank_mask:0x3
	v_mov_b32_dpp v66, v214 row_shl:8 row_mask:0xf bank_mask:0x3
	v_mov_b32_dpp v67, v215 row_shl:8 row_mask:0xf bank_mask:0x3
	v_pk_add_f32 v[92:93], v[92:93], v[180:181]
	v_pk_add_f32 v[94:95], v[94:95], v[182:183]
	v_pk_add_f32 v[88:89], v[88:89], v[184:185]
	v_pk_add_f32 v[90:91], v[90:91], v[186:187]
	v_pk_add_f32 v[84:85], v[84:85], v[188:189]
	v_pk_add_f32 v[86:87], v[86:87], v[190:191]
	v_pk_add_f32 v[76:77], v[76:77], v[192:193]
	v_pk_add_f32 v[78:79], v[78:79], v[194:195]
	v_pk_add_f32 v[80:81], v[80:81], v[196:197]
	v_pk_add_f32 v[82:83], v[82:83], v[198:199]
	v_pk_add_f32 v[72:73], v[72:73], v[200:201]
	v_pk_add_f32 v[74:75], v[74:75], v[202:203]
	v_pk_add_f32 v[68:69], v[68:69], v[204:205]
	v_pk_add_f32 v[70:71], v[70:71], v[206:207]
	v_pk_add_f32 v[64:65], v[64:65], v[208:209]
	v_pk_add_f32 v[66:67], v[66:67], v[210:211]
	global_store_dwordx4 v226, v[92:95], s[52:53]
	v_add_u32_e32 v144, v217, v233
	global_store_dwordx4 v144, v[88:91], s[52:53]
	global_store_dwordx4 v226, v[84:87], s[52:53] offset:512
	v_add_u32_e32 v144, v217, v233
	global_store_dwordx4 v144, v[76:79], s[52:53] offset:512
	global_store_dwordx4 v227, v[80:83], s[52:53]
	v_add_u32_e32 v144, v218, v233
	global_store_dwordx4 v144, v[72:75], s[52:53]
	global_store_dwordx4 v227, v[68:71], s[52:53] offset:512
	v_add_u32_e32 v144, v218, v233
	global_store_dwordx4 v144, v[64:67], s[52:53] offset:512
	global_load_dwordx4 v[180:183], v230, s[52:53]
	v_add_u32_e32 v144, v222, v233
	global_load_dwordx4 v[184:187], v144, s[52:53]
	global_load_dwordx4 v[188:191], v230, s[52:53] offset:512
	v_add_u32_e32 v144, v222, v233
	global_load_dwordx4 v[192:195], v144, s[52:53] offset:512
	global_load_dwordx4 v[196:199], v231, s[52:53]
	v_add_u32_e32 v144, v223, v233
	global_load_dwordx4 v[200:203], v144, s[52:53]
	global_load_dwordx4 v[204:207], v231, s[52:53] offset:512
	v_add_u32_e32 v144, v223, v233
	global_load_dwordx4 v[208:211], v144, s[52:53] offset:512
	s_waitcnt vmcnt(16)
;     __device__ __forceinline__ void operator()(AccRef acc, const Unit& u, int wr, int wc, int fr, int fq) const {
;     ...
;                         for (int n = 0; n < 2; ++n) bs[m][bj][n] = *(const f32x4*)(base + (size_t)(row0 + ai * 128 + (2 * mh + m) * 16) * D + col0 + bj * 128 + n * 16);
; #pragma unroll
;                 for (int m = 0; m < 2; ++m)
; #pragma unroll
;                     for (int bj = 0; bj < 2; ++bj)
; #pragma unroll
;                         for (int n = 0; n < 2; ++n) *(f32x4*)(out + (size_t)(row0 + ai * 128 + (2 * mh + m) * 16) * D + col0 + bj * 128 + n * 16) = bs[m][bj][n] + sv[bj][n] * (acc[ai][bj][2 * mh + m][n] + bv[bj][n]);
;                 asm volatile("" ::: "memory"); }
	v_mov_b32_e32 v212, v60
	v_mov_b32_e32 v213, v61
	v_mov_b32_e32 v214, v62
	v_mov_b32_e32 v215, v63
	s_nop 0
	v_mov_b32_dpp v60, v56 row_shr:8 row_mask:0xf bank_mask:0xc
	v_mov_b32_dpp v61, v57 row_shr:8 row_mask:0xf bank_mask:0xc
	v_mov_b32_dpp v62, v58 row_shr:8 row_mask:0xf bank_mask:0xc
	v_mov_b32_dpp v63, v59 row_shr:8 row_mask:0xf bank_mask:0xc
	v_mov_b32_dpp v56, v212 row_shl:8 row_mask:0xf bank_mask:0x3
	v_mov_b32_dpp v57, v213 row_shl:8 row_mask:0xf bank_mask:0x3
	v_mov_b32_dpp v58, v214 row_shl:8 row_mask:0xf bank_mask:0x3
	v_mov_b32_dpp v59, v215 row_shl:8 row_mask:0xf bank_mask:0x3
	v_mov_b32_e32 v212, v52
	v_mov_b32_e32 v213, v53
	v_mov_b32_e32 v214, v54
	v_mov_b32_e32 v215, v55
	s_nop 0
	v_mov_b32_dpp v52, v44 row_shr:8 row_mask:0xf bank_mask:0xc
	v_mov_b32_dpp v53, v45 row_shr:8 row_mask:0xf bank_mask:0xc
	v_mov_b32_dpp v54, v46 row_shr:8 row_mask:0xf bank_mask:0xc
	v_mov_b32_dpp v55, v47 row_shr:8 row_mask:0xf bank_mask:0xc
	v_mov_b32_dpp v44, v212 row_shl:8 row_mask:0xf bank_mask:0x3
	v_mov_b32_dpp v45, v213 row_shl:8 row_mask:0xf bank_mask:0x3
	v_mov_b32_dpp v46, v214 row_shl:8 row_mask:0xf bank_mask:0x3
	v_mov_b32_dpp v47, v215 row_shl:8 row_mask:0xf bank_mask:0x3
	v_mov_b32_e32 v212, v48
	v_mov_b32_e32 v213, v49
	v_mov_b32_e32 v214, v50
	v_mov_b32_e32 v215, v51
	s_nop 0
	v_mov_b32_dpp v48, v40 row_shr:8 row_mask:0xf bank_mask:0xc
	v_mov_b32_dpp v49, v41 row_shr:8 row_mask:0xf bank_mask:0xc
	v_mov_b32_dpp v50, v42 row_shr:8 row_mask:0xf bank_mask:0xc
	v_mov_b32_dpp v51, v43 row_shr:8 row_mask:0xf bank_mask:0xc
	v_mov_b32_dpp v40, v212 row_shl:8 row_mask:0xf bank_mask:0x3
	v_mov_b32_dpp v41, v213 row_shl:8 row_mask:0xf bank_mask:0x3
	v_mov_b32_dpp v42, v214 row_shl:8 row_mask:0xf bank_mask:0x3
	v_mov_b32_dpp v43, v215 row_shl:8 row_mask:0xf bank_mask:0x3
	v_mov_b32_e32 v212, v36
	v_mov_b32_e32 v213, v37
	v_mov_b32_e32 v214, v38
	v_mov_b32_e32 v215, v39
	s_nop 0
	v_mov_b32_dpp v36, v32 row_shr:8 row_mask:0xf bank_mask:0xc
	v_mov_b32_dpp v37, v33 row_shr:8 row_mask:0xf bank_mask:0xc
	v_mov_b32_dpp v38, v34 row_shr:8 row_mask:0xf bank_mask:0xc
	v_mov_b32_dpp v39, v35 row_shr:8 row_mask:0xf bank_mask:0xc
	v_mov_b32_dpp v32, v212 row_shl:8 row_mask:0xf bank_mask:0x3
	v_mov_b32_dpp v33, v213 row_shl:8 row_mask:0xf bank_mask:0x3
	v_mov_b32_dpp v34, v214 row_shl:8 row_mask:0xf bank_mask:0x3
	v_mov_b32_dpp v35, v215 row_shl:8 row_mask:0xf bank_mask:0x3
	v_pk_add_f32 v[60:61], v[60:61], v[140:141]
	v_pk_add_f32 v[62:63], v[62:63], v[142:143]
	v_pk_add_f32 v[56:57], v[56:57], v[152:153]
	v_pk_add_f32 v[58:59], v[58:59], v[154:155]
	v_pk_add_f32 v[52:53], v[52:53], v[156:157]
	v_pk_add_f32 v[54:55], v[54:55], v[158:159]
	v_pk_add_f32 v[44:45], v[44:45], v[160:161]
	v_pk_add_f32 v[46:47], v[46:47], v[162:163]
	v_pk_add_f32 v[48:49], v[48:49], v[164:165]
	v_pk_add_f32 v[50:51], v[50:51], v[166:167]
	v_pk_add_f32 v[40:41], v[40:41], v[168:169]
	v_pk_add_f32 v[42:43], v[42:43], v[170:171]
	v_pk_add_f32 v[36:37], v[36:37], v[172:173]
	v_pk_add_f32 v[38:39], v[38:39], v[174:175]
	v_pk_add_f32 v[32:33], v[32:33], v[176:177]
	v_pk_add_f32 v[34:35], v[34:35], v[178:179]
	global_store_dwordx4 v228, v[60:63], s[52:53]
	v_add_u32_e32 v144, v220, v233
	global_store_dwordx4 v144, v[56:59], s[52:53]
	global_store_dwordx4 v228, v[52:55], s[52:53] offset:512
	v_add_u32_e32 v144, v220, v233
	global_store_dwordx4 v144, v[44:47], s[52:53] offset:512
	global_store_dwordx4 v229, v[48:51], s[52:53]
	v_add_u32_e32 v144, v221, v233
	global_store_dwordx4 v144, v[40:43], s[52:53]
	global_store_dwordx4 v229, v[36:39], s[52:53] offset:512
	v_add_u32_e32 v144, v221, v233
	global_store_dwordx4 v144, v[32:35], s[52:53] offset:512
	s_waitcnt vmcnt(8)
; #define PG8_WAIT_V(n) asm volatile("s_waitcnt vmcnt(" #n ")" ::: "memory")
; #define PG8_BAR __builtin_amdgcn_s_barrier()
; template <class Epi>
; __device__ __forceinline__ void gemm_phase(LAS unsigned char* lds, const Gemm g, const StaticOrder& S, const Epi& E) {
;     ...
;         if (!has_next) break;
;         {
; #pragma unroll
;         for (int a = 0; a < 2; ++a)
; #pragma unroll
;             for (int b = 0; b < 2; ++b)
; #pragma unroll
;                 for (int m = 0; m < 4; ++m)
; #pragma unroll
;                     for (int n = 0; n < 2; ++n) acc[a][b][m][n] = (f32x4){0.f, 0.f, 0.f, 0.f};
;         }
;         cur = nxt; cA = nA; cB = nB; ++ui;
;     }
;     PG8_WAIT_V(0);
;     if (wr == 0) PG8_BAR;
;     __device__ __forceinline__ void operator()(AccRef acc, const Unit& u, int wr, int wc, int fr, int fq) const {
;     ...
;                         for (int n = 0; n < 2; ++n) bs[m][bj][n] = *(const f32x4*)(base + (size_t)(row0 + ai * 128 + (2 * mh + m) * 16) * D + col0 + bj * 128 + n * 16);
; #pragma unroll
;                 for (int m = 0; m < 2; ++m)
; #pragma unroll
;                     for (int bj = 0; bj < 2; ++bj)
; #pragma unroll
;                         for (int n = 0; n < 2; ++n) *(f32x4*)(out + (size_t)(row0 + ai * 128 + (2 * mh + m) * 16) * D + col0 + bj * 128 + n * 16) = bs[m][bj][n] + sv[bj][n] * (acc[ai][bj][2 * mh + m][n] + bv[bj][n]);
;                 asm volatile("" ::: "memory"); }
	v_mov_b32_e32 v212, v28
	v_mov_b32_e32 v213, v29
	v_mov_b32_e32 v214, v30
	v_mov_b32_e32 v215, v31
	s_nop 0
	v_mov_b32_dpp v28, v24 row_shr:8 row_mask:0xf bank_mask:0xc
	v_mov_b32_dpp v29, v25 row_shr:8 row_mask:0xf bank_mask:0xc
	v_mov_b32_dpp v30, v26 row_shr:8 row_mask:0xf bank_mask:0xc
	v_mov_b32_dpp v31, v27 row_shr:8 row_mask:0xf bank_mask:0xc
	v_mov_b32_dpp v24, v212 row_shl:8 row_mask:0xf bank_mask:0x3
	v_mov_b32_dpp v25, v213 row_shl:8 row_mask:0xf bank_mask:0x3
	v_mov_b32_dpp v26, v214 row_shl:8 row_mask:0xf bank_mask:0x3
	v_mov_b32_dpp v27, v215 row_shl:8 row_mask:0xf bank_mask:0x3
	v_mov_b32_e32 v212, v20
	v_mov_b32_e32 v213, v21
	v_mov_b32_e32 v214, v22
	v_mov_b32_e32 v215, v23
	s_nop 0
	v_mov_b32_dpp v20, v12 row_shr:8 row_mask:0xf bank_mask:0xc
	v_mov_b32_dpp v21, v13 row_shr:8 row_mask:0xf bank_mask:0xc
	v_mov_b32_dpp v22, v14 row_shr:8 row_mask:0xf bank_mask:0xc
	v_mov_b32_dpp v23, v15 row_shr:8 row_mask:0xf bank_mask:0xc
	v_mov_b32_dpp v12, v212 row_shl:8 row_mask:0xf bank_mask:0x3
	v_mov_b32_dpp v13, v213 row_shl:8 row_mask:0xf bank_mask:0x3
	v_mov_b32_dpp v14, v214 row_shl:8 row_mask:0xf bank_mask:0x3
	v_mov_b32_dpp v15, v215 row_shl:8 row_mask:0xf bank_mask:0x3
	v_mov_b32_e32 v212, v16
	v_mov_b32_e32 v213, v17
	v_mov_b32_e32 v214, v18
	v_mov_b32_e32 v215, v19
	s_nop 0
	v_mov_b32_dpp v16, v8 row_shr:8 row_mask:0xf bank_mask:0xc
	v_mov_b32_dpp v17, v9 row_shr:8 row_mask:0xf bank_mask:0xc
	v_mov_b32_dpp v18, v10 row_shr:8 row_mask:0xf bank_mask:0xc
	v_mov_b32_dpp v19, v11 row_shr:8 row_mask:0xf bank_mask:0xc
	v_mov_b32_dpp v8, v212 row_shl:8 row_mask:0xf bank_mask:0x3
	v_mov_b32_dpp v9, v213 row_shl:8 row_mask:0xf bank_mask:0x3
	v_mov_b32_dpp v10, v214 row_shl:8 row_mask:0xf bank_mask:0x3
	v_mov_b32_dpp v11, v215 row_shl:8 row_mask:0xf bank_mask:0x3
	v_mov_b32_e32 v212, v4
	v_mov_b32_e32 v213, v5
	v_mov_b32_e32 v214, v6
	v_mov_b32_e32 v215, v7
	s_nop 0
	v_mov_b32_dpp v4, v0 row_shr:8 row_mask:0xf bank_mask:0xc
	v_mov_b32_dpp v5, v1 row_shr:8 row_mask:0xf bank_mask:0xc
	v_mov_b32_dpp v6, v2 row_shr:8 row_mask:0xf bank_mask:0xc
	v_mov_b32_dpp v7, v3 row_shr:8 row_mask:0xf bank_mask:0xc
	v_mov_b32_dpp v0, v212 row_shl:8 row_mask:0xf bank_mask:0x3
	v_mov_b32_dpp v1, v213 row_shl:8 row_mask:0xf bank_mask:0x3
	v_mov_b32_dpp v2, v214 row_shl:8 row_mask:0xf bank_mask:0x3
	v_mov_b32_dpp v3, v215 row_shl:8 row_mask:0xf bank_mask:0x3
	v_pk_add_f32 v[28:29], v[28:29], v[180:181]
	v_pk_add_f32 v[30:31], v[30:31], v[182:183]
	v_pk_add_f32 v[24:25], v[24:25], v[184:185]
	v_pk_add_f32 v[26:27], v[26:27], v[186:187]
	v_pk_add_f32 v[20:21], v[20:21], v[188:189]
	v_pk_add_f32 v[22:23], v[22:23], v[190:191]
	v_pk_add_f32 v[12:13], v[12:13], v[192:193]
	v_pk_add_f32 v[14:15], v[14:15], v[194:195]
	v_pk_add_f32 v[16:17], v[16:17], v[196:197]
	v_pk_add_f32 v[18:19], v[18:19], v[198:199]
	v_pk_add_f32 v[8:9], v[8:9], v[200:201]
	v_pk_add_f32 v[10:11], v[10:11], v[202:203]
	v_pk_add_f32 v[4:5], v[4:5], v[204:205]
	v_pk_add_f32 v[6:7], v[6:7], v[206:207]
	v_pk_add_f32 v[0:1], v[0:1], v[208:209]
	v_pk_add_f32 v[2:3], v[2:3], v[210:211]
	global_store_dwordx4 v230, v[28:31], s[52:53]
	v_add_u32_e32 v144, v222, v233
	global_store_dwordx4 v144, v[24:27], s[52:53]
	global_store_dwordx4 v230, v[20:23], s[52:53] offset:512
	v_add_u32_e32 v144, v222, v233
	global_store_dwordx4 v144, v[12:15], s[52:53] offset:512
	global_store_dwordx4 v231, v[16:19], s[52:53]
	v_add_u32_e32 v144, v223, v233
	global_store_dwordx4 v144, v[8:11], s[52:53]
	global_store_dwordx4 v231, v[4:7], s[52:53] offset:512
	v_add_u32_e32 v144, v223, v233
	global_store_dwordx4 v144, v[0:3], s[52:53] offset:512
	s_cbranch_vccz .LBB0_1450
	s_waitcnt vmcnt(0)
	s_cmpk_gt_u32 s4, 0xff
	s_cbranch_scc1 .LBB0_1465
	s_barrier

; #define PG8_STAGE(bufoff, gbase, voff) do { _Pragma("unroll") for (int _i = 0; _i < 2; ++_i) \
;         __builtin_amdgcn_global_load_lds((const unsigned*)((const char*)(gbase) + (voff)[_i]), (LAS unsigned*)(lds + (bufoff) + ldsw + _i * 8192), 16, 0, 0); } while (0)
; #define PG8_LDA(dst, b, h) do { _Pragma("unroll") for (int m = 0; m < 4; ++m) _Pragma("unroll") for (int k = 0; k < 2; ++k) dst[m][k] = *(const LAS bf16x8*)(lds + PG8_SA(b, h) + aoff + m * 2048 + k * 1024); } while (0)
; #define PG8_LDB(dst, b, h) do { _Pragma("unroll") for (int n = 0; n < 2; ++n) _Pragma("unroll") for (int k = 0; k < 2; ++k) dst[n][k] = *(const LAS bf16x8*)(lds + PG8_SB(b, h) + boff + n * 2048 + k * 1024); } while (0)
; #define PG8_MMA(ai, bj, At, Bt) do { __builtin_amdgcn_s_setprio(1); _Pragma("unroll") for (int m = 0; m < 4; ++m) _Pragma("unroll") for (int n = 0; n < 2; ++n) _Pragma("unroll") for (int k = 0; k < 2; ++k) \
;         acc[ai][bj][m][n] = __builtin_amdgcn_mfma_f32_16x16x32_bf16(Bt[n][k], At[m][k], acc[ai][bj][m][n], 0, 0, 0); __builtin_amdgcn_s_setprio(0); } while (0)
; #define PG8_WAIT_V(n) asm volatile("s_waitcnt vmcnt(" #n ")" ::: "memory")
; #define PG8_WAIT_L(n) asm volatile("s_waitcnt lgkmcnt(" #n ")" ::: "memory")
; template <class Epi>
; __device__ __forceinline__ void gemm_phase(LAS unsigned char* lds, const Gemm g, const StaticOrder& S, const Epi& E) {
;     ...
;         for (int t = 0; t < nt; t += 2) {
;             const bool last = (t == nt - 2);
;             const char* a1 = cA + (size_t)(t + 1) * kstep;
;             const char* a2 = last ? nA : cA + (size_t)(t + 2) * kstep; const char* b2 = last ? nB : cB + (size_t)(t + 2) * kstep;
;             const char* a3 = a2 + kstep; const char* b3 = b2 + kstep;
;             PG8_LDB(B0, 0, 0); PG8_SCHED; PG8_LDA(At, 0, 0); PG8_STAGE(PG8_SA(1, 1), a1 + hstepA, voffA);
;             PG8_WAIT_L(8); PG8_BAR; PG8_WAIT_L(0); PG8_MMA(0, 0, At, B0); PG8_BAR; PG8_SCHED;
;             PG8_LDB(B1, 0, 1); PG8_STAGE(PG8_SB(0, 0), b2, voffB);
;             PG8_BAR; PG8_WAIT_L(0); PG8_MMA(0, 1, At, B1); PG8_BAR;
;             PG8_LDA(At, 0, 1); PG8_STAGE(PG8_SA(0, 0), a2, voffA);
;             PG8_BAR; PG8_WAIT_L(0); PG8_MMA(1, 0, At, B0); PG8_BAR; PG8_SCHED;
;             PG8_STAGE(PG8_SB(0, 1), b2 + hstepB, voffB);
;             PG8_WAIT_V(6); PG8_BAR; PG8_MMA(1, 1, At, B1); PG8_BAR;
.LBB0_1820:
	ds_read_b128 v[140:143], v149
	ds_read_b128 v[152:155], v149 offset:1024
	ds_read_b128 v[156:159], v149 offset:2048
	ds_read_b128 v[160:163], v149 offset:3072
	s_add_u32 s36, s34, 0xfffc0080
	s_addc_u32 s37, s35, -1
	s_cmp_eq_u32 s70, 12
	s_cselect_b32 s39, s25, s37
	s_cselect_b32 s38, s47, s36
	s_cselect_b32 s37, s23, s63
	s_cselect_b32 s36, s48, s49
	v_lshl_add_u64 v[144:145], s[34:35], 0, v[132:133]
	s_add_i32 m0, s8, 0xc000
	ds_read_b128 v[164:167], v150
	ds_read_b128 v[168:171], v150 offset:1024
	ds_read_b128 v[172:175], v150 offset:2048
	ds_read_b128 v[176:179], v150 offset:3072
	ds_read_b128 v[180:183], v150 offset:4096
	ds_read_b128 v[184:187], v150 offset:5120
	ds_read_b128 v[188:191], v150 offset:6144
	ds_read_b128 v[192:195], v150 offset:7168
	global_load_lds_dwordx4 v[144:145], off
	v_lshl_add_u64 v[144:145], s[34:35], 0, v[134:135]
	s_add_i32 m0, s8, 0xe000
	s_nop 0
	global_load_lds_dwordx4 v[144:145], off
	ds_read_b128 v[196:199], v151
	ds_read_b128 v[200:203], v151 offset:1024
	ds_read_b128 v[204:207], v151 offset:2048
	ds_read_b128 v[208:211], v151 offset:3072
	s_waitcnt lgkmcnt(0)
	s_barrier
	s_setprio 1
	v_mfma_f32_16x16x32_bf16 v[124:127], v[140:143], v[164:167], v[124:127]
	v_mfma_f32_16x16x32_bf16 v[120:123], v[156:159], v[164:167], v[120:123]
	v_mfma_f32_16x16x32_bf16 v[112:115], v[140:143], v[172:175], v[112:115]
	v_mfma_f32_16x16x32_bf16 v[104:107], v[156:159], v[172:175], v[104:107]
	v_mfma_f32_16x16x32_bf16 v[92:95], v[140:143], v[180:183], v[92:95]
	v_mfma_f32_16x16x32_bf16 v[88:91], v[156:159], v[180:183], v[88:91]
	v_mfma_f32_16x16x32_bf16 v[80:83], v[140:143], v[188:191], v[80:83]
	v_mfma_f32_16x16x32_bf16 v[72:75], v[156:159], v[188:191], v[72:75]
	v_mfma_f32_16x16x32_bf16 v[124:127], v[152:155], v[168:171], v[124:127]
	v_mfma_f32_16x16x32_bf16 v[120:123], v[160:163], v[168:171], v[120:123]
	v_mfma_f32_16x16x32_bf16 v[112:115], v[152:155], v[176:179], v[112:115]
	v_mfma_f32_16x16x32_bf16 v[104:107], v[160:163], v[176:179], v[104:107]
	v_mfma_f32_16x16x32_bf16 v[92:95], v[152:155], v[184:187], v[92:95]
	v_mfma_f32_16x16x32_bf16 v[88:91], v[160:163], v[184:187], v[88:91]
	v_mfma_f32_16x16x32_bf16 v[80:83], v[152:155], v[192:195], v[80:83]
	v_mfma_f32_16x16x32_bf16 v[72:75], v[160:163], v[192:195], v[72:75]
	v_mfma_f32_16x16x32_bf16 v[116:119], v[196:199], v[164:167], v[116:119]
	v_mfma_f32_16x16x32_bf16 v[108:111], v[204:207], v[164:167], v[108:111]
	v_mfma_f32_16x16x32_bf16 v[100:103], v[196:199], v[172:175], v[100:103]
	v_mfma_f32_16x16x32_bf16 v[96:99], v[204:207], v[172:175], v[96:99]
	v_mfma_f32_16x16x32_bf16 v[84:87], v[196:199], v[180:183], v[84:87]
	v_mfma_f32_16x16x32_bf16 v[76:79], v[204:207], v[180:183], v[76:79]
	v_mfma_f32_16x16x32_bf16 v[68:71], v[196:199], v[188:191], v[68:71]
	v_mfma_f32_16x16x32_bf16 v[64:67], v[204:207], v[188:191], v[64:67]
	v_mfma_f32_16x16x32_bf16 v[116:119], v[200:203], v[168:171], v[116:119]
	v_mfma_f32_16x16x32_bf16 v[108:111], v[208:211], v[168:171], v[108:111]
	v_mfma_f32_16x16x32_bf16 v[100:103], v[200:203], v[176:179], v[100:103]
	v_mfma_f32_16x16x32_bf16 v[96:99], v[208:211], v[176:179], v[96:99]
	v_mfma_f32_16x16x32_bf16 v[84:87], v[200:203], v[184:187], v[84:87]
	v_mfma_f32_16x16x32_bf16 v[76:79], v[208:211], v[184:187], v[76:79]
	v_mfma_f32_16x16x32_bf16 v[68:71], v[200:203], v[192:195], v[68:71]
	v_mfma_f32_16x16x32_bf16 v[64:67], v[208:211], v[192:195], v[64:67]
	s_setprio 0
	s_barrier
	s_nop 1
	ds_read_b128 v[164:167], v150 offset:16384
	ds_read_b128 v[168:171], v150 offset:17408
	ds_read_b128 v[172:175], v150 offset:18432
	ds_read_b128 v[176:179], v150 offset:19456
	ds_read_b128 v[180:183], v150 offset:20480
	ds_read_b128 v[184:187], v150 offset:21504
	ds_read_b128 v[188:191], v150 offset:22528
	ds_read_b128 v[192:195], v150 offset:23552
	s_add_i32 s71, s44, s7
	v_lshl_add_u64 v[144:145], s[36:37], 0, v[128:129]
	s_mov_b32 m0, s71
	s_nop 0
	global_load_lds_dwordx4 v[144:145], off
	v_lshl_add_u64 v[212:213], s[36:37], 0, v[130:131]
	s_add_i32 m0, s71, 0x2000
	s_nop 0
	global_load_lds_dwordx4 v[212:213], off
	s_mov_b32 m0, s8
	v_lshl_add_u64 v[214:215], s[38:39], 0, v[128:129]
	global_load_lds_dwordx4 v[214:215], off
	v_lshl_add_u64 v[216:217], s[38:39], 0, v[130:131]
	s_mov_b32 m0, s9
	s_nop 0
	global_load_lds_dwordx4 v[216:217], off
	s_add_u32 s72, s36, 0x40000
	s_addc_u32 s73, s37, 0
	s_add_i32 s71, s45, s7
	v_lshl_add_u64 v[254:255], s[72:73], 0, v[128:129]
	s_mov_b32 m0, s71
	s_nop 0
	global_load_lds_dwordx4 v[254:255], off
	v_lshl_add_u64 v[254:255], s[72:73], 0, v[130:131]
	s_add_i32 m0, s71, 0x2000
	s_nop 0
	global_load_lds_dwordx4 v[254:255], off
	s_waitcnt vmcnt(6)
	s_waitcnt lgkmcnt(0)
	s_barrier
; #define PG8_STAGE(bufoff, gbase, voff) do { _Pragma("unroll") for (int _i = 0; _i < 2; ++_i) \
;         __builtin_amdgcn_global_load_lds((const unsigned*)((const char*)(gbase) + (voff)[_i]), (LAS unsigned*)(lds + (bufoff) + ldsw + _i * 8192), 16, 0, 0); } while (0)
; #define PG8_LDA(dst, b, h) do { _Pragma("unroll") for (int m = 0; m < 4; ++m) _Pragma("unroll") for (int k = 0; k < 2; ++k) dst[m][k] = *(const LAS bf16x8*)(lds + PG8_SA(b, h) + aoff + m * 2048 + k * 1024); } while (0)
; #define PG8_LDB(dst, b, h) do { _Pragma("unroll") for (int n = 0; n < 2; ++n) _Pragma("unroll") for (int k = 0; k < 2; ++k) dst[n][k] = *(const LAS bf16x8*)(lds + PG8_SB(b, h) + boff + n * 2048 + k * 1024); } while (0)
; #define PG8_MMA(ai, bj, At, Bt) do { __builtin_amdgcn_s_setprio(1); _Pragma("unroll") for (int m = 0; m < 4; ++m) _Pragma("unroll") for (int n = 0; n < 2; ++n) _Pragma("unroll") for (int k = 0; k < 2; ++k) \
;         acc[ai][bj][m][n] = __builtin_amdgcn_mfma_f32_16x16x32_bf16(Bt[n][k], At[m][k], acc[ai][bj][m][n], 0, 0, 0); __builtin_amdgcn_s_setprio(0); } while (0)
; #define PG8_WAIT_V(n) asm volatile("s_waitcnt vmcnt(" #n ")" ::: "memory")
; #define PG8_WAIT_L(n) asm volatile("s_waitcnt lgkmcnt(" #n ")" ::: "memory")
; #define PG8_BAR __builtin_amdgcn_s_barrier()
; #define PG8_SCHED __builtin_amdgcn_sched_barrier(0)
; template <class Epi>
; __device__ __forceinline__ void gemm_phase(LAS unsigned char* lds, const Gemm g, const StaticOrder& S, const Epi& E) {
;     ...
;             PG8_WAIT_V(6); PG8_BAR; PG8_MMA(1, 1, At, B1); PG8_BAR;
;             PG8_LDB(B0, 1, 0); PG8_SCHED; PG8_LDA(At, 1, 0); PG8_STAGE(PG8_SA(0, 1), a2 + hstepA, voffA);
;             PG8_WAIT_L(8); PG8_BAR; PG8_WAIT_L(0); PG8_MMA(0, 0, At, B0); PG8_BAR; PG8_SCHED;
;             PG8_LDB(B1, 1, 1); PG8_STAGE(PG8_SB(1, 0), b3, voffB);
;             PG8_BAR; PG8_WAIT_L(0); PG8_MMA(0, 1, At, B1); PG8_BAR;
;             PG8_LDA(At, 1, 1); PG8_STAGE(PG8_SA(1, 0), a3, voffA);
;             PG8_BAR; PG8_WAIT_L(0); PG8_MMA(1, 0, At, B0); PG8_BAR; PG8_SCHED;
	s_setprio 1
	v_mfma_f32_16x16x32_bf16 v[60:63], v[140:143], v[164:167], v[60:63]
	v_mfma_f32_16x16x32_bf16 v[56:59], v[156:159], v[164:167], v[56:59]
	v_mfma_f32_16x16x32_bf16 v[48:51], v[140:143], v[172:175], v[48:51]
	v_mfma_f32_16x16x32_bf16 v[40:43], v[156:159], v[172:175], v[40:43]
	v_mfma_f32_16x16x32_bf16 v[28:31], v[140:143], v[180:183], v[28:31]
	v_mfma_f32_16x16x32_bf16 v[24:27], v[156:159], v[180:183], v[24:27]
	v_mfma_f32_16x16x32_bf16 v[16:19], v[140:143], v[188:191], v[16:19]
	v_mfma_f32_16x16x32_bf16 v[8:11], v[156:159], v[188:191], v[8:11]
	v_mfma_f32_16x16x32_bf16 v[60:63], v[152:155], v[168:171], v[60:63]
	v_mfma_f32_16x16x32_bf16 v[56:59], v[160:163], v[168:171], v[56:59]
	v_mfma_f32_16x16x32_bf16 v[48:51], v[152:155], v[176:179], v[48:51]
	v_mfma_f32_16x16x32_bf16 v[40:43], v[160:163], v[176:179], v[40:43]
	v_mfma_f32_16x16x32_bf16 v[28:31], v[152:155], v[184:187], v[28:31]
	v_mfma_f32_16x16x32_bf16 v[24:27], v[160:163], v[184:187], v[24:27]
	v_mfma_f32_16x16x32_bf16 v[16:19], v[152:155], v[192:195], v[16:19]
	v_mfma_f32_16x16x32_bf16 v[8:11], v[160:163], v[192:195], v[8:11]
	v_mfma_f32_16x16x32_bf16 v[52:55], v[196:199], v[164:167], v[52:55]
	v_mfma_f32_16x16x32_bf16 v[44:47], v[204:207], v[164:167], v[44:47]
	v_mfma_f32_16x16x32_bf16 v[36:39], v[196:199], v[172:175], v[36:39]
	v_mfma_f32_16x16x32_bf16 v[32:35], v[204:207], v[172:175], v[32:35]
	v_mfma_f32_16x16x32_bf16 v[20:23], v[196:199], v[180:183], v[20:23]
	v_mfma_f32_16x16x32_bf16 v[12:15], v[204:207], v[180:183], v[12:15]
	v_mfma_f32_16x16x32_bf16 v[4:7], v[196:199], v[188:191], v[4:7]
	v_mfma_f32_16x16x32_bf16 v[0:3], v[204:207], v[188:191], v[0:3]
	v_mfma_f32_16x16x32_bf16 v[52:55], v[200:203], v[168:171], v[52:55]
	v_mfma_f32_16x16x32_bf16 v[44:47], v[208:211], v[168:171], v[44:47]
	v_mfma_f32_16x16x32_bf16 v[36:39], v[200:203], v[176:179], v[36:39]
	v_mfma_f32_16x16x32_bf16 v[32:35], v[208:211], v[176:179], v[32:35]
	v_mfma_f32_16x16x32_bf16 v[20:23], v[200:203], v[184:187], v[20:23]
	v_mfma_f32_16x16x32_bf16 v[12:15], v[208:211], v[184:187], v[12:15]
	v_mfma_f32_16x16x32_bf16 v[4:7], v[200:203], v[192:195], v[4:7]
	v_mfma_f32_16x16x32_bf16 v[0:3], v[208:211], v[192:195], v[0:3]
	s_setprio 0
	s_add_i32 s71, 0, 0x18000
	v_add_u32_e32 v160, s71, v147
	s_barrier
	ds_read_b128 v[140:143], v160
	ds_read_b128 v[152:155], v160 offset:1024
	ds_read_b128 v[156:159], v160 offset:2048
	ds_read_b128 v[160:163], v160 offset:3072
	s_add_u32 s38, s38, 0x40000
	s_addc_u32 s39, s39, 0
	s_mov_b32 m0, s31
	v_lshl_add_u64 v[196:197], s[38:39], 0, v[128:129]
	ds_read_b128 v[164:167], v150 offset:32768
	ds_read_b128 v[168:171], v150 offset:33792
	ds_read_b128 v[172:175], v150 offset:34816
	ds_read_b128 v[176:179], v150 offset:35840
	ds_read_b128 v[180:183], v150 offset:36864
	ds_read_b128 v[184:187], v150 offset:37888
	ds_read_b128 v[188:191], v150 offset:38912
	ds_read_b128 v[192:195], v150 offset:39936
	global_load_lds_dwordx4 v[196:197], off
	v_lshl_add_u64 v[196:197], s[38:39], 0, v[130:131]
	s_mov_b32 m0, s40
	s_nop 0
	global_load_lds_dwordx4 v[196:197], off
	s_add_i32 s38, 0, 0x1c000
	v_add_u32_e32 v208, s38, v147
	ds_read_b128 v[196:199], v208
	ds_read_b128 v[200:203], v208 offset:1024
	ds_read_b128 v[204:207], v208 offset:2048
	ds_read_b128 v[208:211], v208 offset:3072
	s_waitcnt lgkmcnt(0)
	s_barrier
	s_setprio 1
	v_mfma_f32_16x16x32_bf16 v[124:127], v[140:143], v[164:167], v[124:127]
	v_mfma_f32_16x16x32_bf16 v[120:123], v[156:159], v[164:167], v[120:123]
	v_mfma_f32_16x16x32_bf16 v[112:115], v[140:143], v[172:175], v[112:115]
	v_mfma_f32_16x16x32_bf16 v[104:107], v[156:159], v[172:175], v[104:107]
	v_mfma_f32_16x16x32_bf16 v[92:95], v[140:143], v[180:183], v[92:95]
	v_mfma_f32_16x16x32_bf16 v[88:91], v[156:159], v[180:183], v[88:91]
	v_mfma_f32_16x16x32_bf16 v[80:83], v[140:143], v[188:191], v[80:83]
	v_mfma_f32_16x16x32_bf16 v[72:75], v[156:159], v[188:191], v[72:75]
	v_mfma_f32_16x16x32_bf16 v[124:127], v[152:155], v[168:171], v[124:127]
	v_mfma_f32_16x16x32_bf16 v[120:123], v[160:163], v[168:171], v[120:123]
	v_mfma_f32_16x16x32_bf16 v[112:115], v[152:155], v[176:179], v[112:115]
	v_mfma_f32_16x16x32_bf16 v[104:107], v[160:163], v[176:179], v[104:107]
	v_mfma_f32_16x16x32_bf16 v[92:95], v[152:155], v[184:187], v[92:95]
	v_mfma_f32_16x16x32_bf16 v[88:91], v[160:163], v[184:187], v[88:91]
	v_mfma_f32_16x16x32_bf16 v[80:83], v[152:155], v[192:195], v[80:83]
	v_mfma_f32_16x16x32_bf16 v[72:75], v[160:163], v[192:195], v[72:75]
	v_mfma_f32_16x16x32_bf16 v[116:119], v[196:199], v[164:167], v[116:119]
	v_mfma_f32_16x16x32_bf16 v[108:111], v[204:207], v[164:167], v[108:111]
	v_mfma_f32_16x16x32_bf16 v[100:103], v[196:199], v[172:175], v[100:103]
	v_mfma_f32_16x16x32_bf16 v[96:99], v[204:207], v[172:175], v[96:99]
	v_mfma_f32_16x16x32_bf16 v[84:87], v[196:199], v[180:183], v[84:87]
	v_mfma_f32_16x16x32_bf16 v[76:79], v[204:207], v[180:183], v[76:79]
	v_mfma_f32_16x16x32_bf16 v[68:71], v[196:199], v[188:191], v[68:71]
	v_mfma_f32_16x16x32_bf16 v[64:67], v[204:207], v[188:191], v[64:67]
	v_mfma_f32_16x16x32_bf16 v[116:119], v[200:203], v[168:171], v[116:119]
	v_mfma_f32_16x16x32_bf16 v[108:111], v[208:211], v[168:171], v[108:111]
	v_mfma_f32_16x16x32_bf16 v[100:103], v[200:203], v[176:179], v[100:103]
	v_mfma_f32_16x16x32_bf16 v[96:99], v[208:211], v[176:179], v[96:99]
	v_mfma_f32_16x16x32_bf16 v[84:87], v[200:203], v[184:187], v[84:87]
	v_mfma_f32_16x16x32_bf16 v[76:79], v[208:211], v[184:187], v[76:79]
	v_mfma_f32_16x16x32_bf16 v[68:71], v[200:203], v[192:195], v[68:71]
	v_mfma_f32_16x16x32_bf16 v[64:67], v[208:211], v[192:195], v[64:67]
	s_setprio 0
	s_barrier
; #define PG8_STAGE(bufoff, gbase, voff) do { _Pragma("unroll") for (int _i = 0; _i < 2; ++_i) \
;         __builtin_amdgcn_global_load_lds((const unsigned*)((const char*)(gbase) + (voff)[_i]), (LAS unsigned*)(lds + (bufoff) + ldsw + _i * 8192), 16, 0, 0); } while (0)
; #define PG8_LDA(dst, b, h) do { _Pragma("unroll") for (int m = 0; m < 4; ++m) _Pragma("unroll") for (int k = 0; k < 2; ++k) dst[m][k] = *(const LAS bf16x8*)(lds + PG8_SA(b, h) + aoff + m * 2048 + k * 1024); } while (0)
; #define PG8_MMA(ai, bj, At, Bt) do { __builtin_amdgcn_s_setprio(1); _Pragma("unroll") for (int m = 0; m < 4; ++m) _Pragma("unroll") for (int n = 0; n < 2; ++n) _Pragma("unroll") for (int k = 0; k < 2; ++k) \
;         acc[ai][bj][m][n] = __builtin_amdgcn_mfma_f32_16x16x32_bf16(Bt[n][k], At[m][k], acc[ai][bj][m][n], 0, 0, 0); __builtin_amdgcn_s_setprio(0); } while (0)
; template <class Epi>
; __device__ __forceinline__ void gemm_phase(LAS unsigned char* lds, const Gemm g, const StaticOrder& S, const Epi& E) {
;     ...
;             PG8_LDA(At, 1, 1); PG8_STAGE(PG8_SA(1, 0), a3, voffA);
;             PG8_BAR; PG8_WAIT_L(0); PG8_MMA(1, 0, At, B0); PG8_BAR; PG8_SCHED;
;             PG8_STAGE(PG8_SB(1, 1), b3 + hstepB, voffB);
;             PG8_WAIT_V(6); PG8_BAR; PG8_MMA(1, 1, At, B1); PG8_BAR;
;         }
;     __device__ __forceinline__ void operator()(AccRef acc, const Unit& u, int wr, int wc, int fr, int fq) const {
;         const int row0 = u.pm * 256 + wr * 64 + fr, col0 = u.pn * 256 + wc * 32 + 4 * fq;
;         f32x4 sv[2][2], bv[2][2];
; #pragma unroll
;         for (int bj = 0; bj < 2; ++bj)
; #pragma unroll
;             for (int n = 0; n < 2; ++n) {
;                 sv[bj][n] = scale ? *(const f32x4*)(scale + col0 + bj * 128 + n * 16) : (f32x4){1.f, 1.f, 1.f, 1.f};
;                 bv[bj][n] = bias ? *(const f32x4*)(bias + col0 + bj * 128 + n * 16) : (f32x4){0.f, 0.f, 0.f, 0.f}; }
; #pragma unroll
;         for (int ai = 0; ai < 2; ++ai)
; #pragma unroll
;             for (int mh = 0; mh < 2; ++mh) {
;                 f32x4 bs[2][2][2];
; #pragma unroll
;                 for (int m = 0; m < 2; ++m)
; #pragma unroll
;                     for (int bj = 0; bj < 2; ++bj)
; #pragma unroll
;                         for (int n = 0; n < 2; ++n) bs[m][bj][n] = *(const f32x4*)(base + (size_t)(row0 + ai * 128 + (2 * mh + m) * 16) * D + col0 + bj * 128 + n * 16);
	s_nop 1
	ds_read_b128 v[164:167], v150 offset:49152
	ds_read_b128 v[168:171], v150 offset:50176
	ds_read_b128 v[172:175], v150 offset:51200
	ds_read_b128 v[176:179], v150 offset:52224
	ds_read_b128 v[180:183], v150 offset:53248
	ds_read_b128 v[184:187], v150 offset:54272
	ds_read_b128 v[188:191], v150 offset:55296
	ds_read_b128 v[192:195], v150 offset:56320
	s_add_i32 s39, s71, s7
	v_lshl_add_u64 v[254:255], v[144:145], 0, s[12:13]
	s_mov_b32 m0, s39
	s_nop 0
	global_load_lds_dwordx4 v[254:255], off
	v_lshl_add_u64 v[254:255], v[212:213], 0, s[12:13]
	s_add_i32 m0, s39, 0x2000
	s_nop 0
	global_load_lds_dwordx4 v[254:255], off
	s_mov_b32 m0, s42
	v_lshl_add_u64 v[254:255], v[214:215], 0, s[12:13]
	global_load_lds_dwordx4 v[254:255], off
	v_lshl_add_u64 v[144:145], v[216:217], 0, s[12:13]
	s_mov_b32 m0, s43
	s_nop 0
	global_load_lds_dwordx4 v[144:145], off
	s_add_u32 s36, s36, 0x40080
	s_addc_u32 s37, s37, 0
	s_add_i32 s38, s38, s7
	v_lshl_add_u64 v[254:255], s[36:37], 0, v[128:129]
	s_mov_b32 m0, s38
	s_nop 0
	global_load_lds_dwordx4 v[254:255], off
	v_lshl_add_u64 v[254:255], s[36:37], 0, v[130:131]
	s_add_i32 m0, s38, 0x2000
	s_nop 0
	global_load_lds_dwordx4 v[254:255], off
	s_waitcnt vmcnt(6)
	s_waitcnt lgkmcnt(0)
	s_barrier
	s_setprio 1
	v_mfma_f32_16x16x32_bf16 v[60:63], v[140:143], v[164:167], v[60:63]
	v_mfma_f32_16x16x32_bf16 v[56:59], v[156:159], v[164:167], v[56:59]
	v_mfma_f32_16x16x32_bf16 v[48:51], v[140:143], v[172:175], v[48:51]
	v_mfma_f32_16x16x32_bf16 v[40:43], v[156:159], v[172:175], v[40:43]
	v_mfma_f32_16x16x32_bf16 v[28:31], v[140:143], v[180:183], v[28:31]
	v_mfma_f32_16x16x32_bf16 v[24:27], v[156:159], v[180:183], v[24:27]
	v_mfma_f32_16x16x32_bf16 v[16:19], v[140:143], v[188:191], v[16:19]
	v_mfma_f32_16x16x32_bf16 v[8:11], v[156:159], v[188:191], v[8:11]
	v_mfma_f32_16x16x32_bf16 v[60:63], v[152:155], v[168:171], v[60:63]
	v_mfma_f32_16x16x32_bf16 v[56:59], v[160:163], v[168:171], v[56:59]
	v_mfma_f32_16x16x32_bf16 v[48:51], v[152:155], v[176:179], v[48:51]
	v_mfma_f32_16x16x32_bf16 v[40:43], v[160:163], v[176:179], v[40:43]
	v_mfma_f32_16x16x32_bf16 v[28:31], v[152:155], v[184:187], v[28:31]
	v_mfma_f32_16x16x32_bf16 v[24:27], v[160:163], v[184:187], v[24:27]
	v_mfma_f32_16x16x32_bf16 v[16:19], v[152:155], v[192:195], v[16:19]
	v_mfma_f32_16x16x32_bf16 v[8:11], v[160:163], v[192:195], v[8:11]
	v_mfma_f32_16x16x32_bf16 v[52:55], v[196:199], v[164:167], v[52:55]
	v_mfma_f32_16x16x32_bf16 v[44:47], v[204:207], v[164:167], v[44:47]
	v_mfma_f32_16x16x32_bf16 v[36:39], v[196:199], v[172:175], v[36:39]
	v_mfma_f32_16x16x32_bf16 v[32:35], v[204:207], v[172:175], v[32:35]
	v_mfma_f32_16x16x32_bf16 v[20:23], v[196:199], v[180:183], v[20:23]
	v_mfma_f32_16x16x32_bf16 v[12:15], v[204:207], v[180:183], v[12:15]
	v_mfma_f32_16x16x32_bf16 v[4:7], v[196:199], v[188:191], v[4:7]
	v_mfma_f32_16x16x32_bf16 v[0:3], v[204:207], v[188:191], v[0:3]
	v_mfma_f32_16x16x32_bf16 v[52:55], v[200:203], v[168:171], v[52:55]
	v_mfma_f32_16x16x32_bf16 v[44:47], v[208:211], v[168:171], v[44:47]
	v_mfma_f32_16x16x32_bf16 v[36:39], v[200:203], v[176:179], v[36:39]
	v_mfma_f32_16x16x32_bf16 v[32:35], v[208:211], v[176:179], v[32:35]
	v_mfma_f32_16x16x32_bf16 v[20:23], v[200:203], v[184:187], v[20:23]
	v_mfma_f32_16x16x32_bf16 v[12:15], v[208:211], v[184:187], v[12:15]
	v_mfma_f32_16x16x32_bf16 v[4:7], v[200:203], v[192:195], v[4:7]
	v_mfma_f32_16x16x32_bf16 v[0:3], v[208:211], v[192:195], v[0:3]
	s_setprio 0
	s_add_i32 s70, s70, 2
	s_add_u32 s34, s34, 0x100
	s_addc_u32 s35, s35, 0
	s_add_u32 s49, s49, 0x100
	s_addc_u32 s63, s63, 0
	s_cmp_gt_u32 s70, 13
	s_barrier
	s_cbranch_scc0 .LBB0_1820
	v_lshl_or_b32 v144, s46, 8, v148
	v_lshl_add_u32 v145, s30, 8, v146
	v_lshlrev_b32_e32 v144, 2, v144
	v_lshl_add_u32 v145, v145, 12, v144
	v_add_u32_e32 v216, 0x10000, v145
	v_add_u32_e32 v217, 0x20000, v145
	v_add_u32_e32 v218, 0x30000, v145
	v_add_u32_e32 v220, 0x80000, v145
	v_add_u32_e32 v221, 0x90000, v145
	v_add_u32_e32 v222, 0xa0000, v145
	v_add_u32_e32 v223, 0xb0000, v145
	v_and_b32_e32 v235, 8, v146
	v_cmp_ne_u32_e32 vcc, 0, v235
	v_mov_b32_e32 v232, 0xffff8040
	s_nop 0
	v_cndmask_b32_e32 v232, 0, v232, vcc
	v_mov_b32_e32 v233, 64
	v_mov_b32_e32 v235, 0x8000
	v_cndmask_b32_e32 v233, v235, v233, vcc
	v_add_u32_e32 v224, v145, v232
	v_add_u32_e32 v225, v216, v232
	v_add_u32_e32 v226, v217, v232
	v_add_u32_e32 v227, v218, v232
	v_add_u32_e32 v228, v220, v232
	v_add_u32_e32 v229, v221, v232
	v_add_u32_e32 v230, v222, v232
	v_add_u32_e32 v231, v223, v232
	s_and_b64 vcc, exec, s[10:11]
	s_mov_b32 s46, s22
	s_mov_b32 s30, s24
	s_mov_b64 s[36:37], s[28:29]
	s_mov_b64 s[34:35], s[26:27]
	global_load_dwordx4 v[140:143], v224, s[52:53]
	v_add_u32_e32 v144, v145, v233
	global_load_dwordx4 v[152:155], v144, s[52:53]
	global_load_dwordx4 v[156:159], v224, s[52:53] offset:512
	v_add_u32_e32 v144, v145, v233
	global_load_dwordx4 v[160:163], v144, s[52:53] offset:512
	global_load_dwordx4 v[164:167], v225, s[52:53]
	v_add_u32_e32 v144, v216, v233
	global_load_dwordx4 v[168:171], v144, s[52:53]
	global_load_dwordx4 v[172:175], v225, s[52:53] offset:512
	v_add_u32_e32 v144, v216, v233
	global_load_dwordx4 v[176:179], v144, s[52:53] offset:512
	global_load_dwordx4 v[180:183], v226, s[52:53]
	v_add_u32_e32 v144, v217, v233
	global_load_dwordx4 v[184:187], v144, s[52:53]
	global_load_dwordx4 v[188:191], v226, s[52:53] offset:512
	v_add_u32_e32 v144, v217, v233
	global_load_dwordx4 v[192:195], v144, s[52:53] offset:512
	global_load_dwordx4 v[196:199], v227, s[52:53]
	v_add_u32_e32 v144, v218, v233
	global_load_dwordx4 v[200:203], v144, s[52:53]
	global_load_dwordx4 v[204:207], v227, s[52:53] offset:512
	v_add_u32_e32 v144, v218, v233
	global_load_dwordx4 v[208:211], v144, s[52:53] offset:512
	s_barrier
;     __device__ __forceinline__ void operator()(AccRef acc, const Unit& u, int wr, int wc, int fr, int fq) const {
;     ...
;                         for (int n = 0; n < 2; ++n) bs[m][bj][n] = *(const f32x4*)(base + (size_t)(row0 + ai * 128 + (2 * mh + m) * 16) * D + col0 + bj * 128 + n * 16);
; #pragma unroll
;                 for (int m = 0; m < 2; ++m)
; #pragma unroll
;                     for (int bj = 0; bj < 2; ++bj)
; #pragma unroll
;                         for (int n = 0; n < 2; ++n) *(f32x4*)(out + (size_t)(row0 + ai * 128 + (2 * mh + m) * 16) * D + col0 + bj * 128 + n * 16) = bs[m][bj][n] + sv[bj][n] * (acc[ai][bj][2 * mh + m][n] + bv[bj][n]);
	v_pk_add_f32 v[124:125], v[124:125], 0 op_sel_hi:[1,0]
	v_pk_add_f32 v[126:127], v[126:127], 0 op_sel_hi:[1,0]
	v_pk_add_f32 v[120:121], v[120:121], 0 op_sel_hi:[1,0]
	v_pk_add_f32 v[122:123], v[122:123], 0 op_sel_hi:[1,0]
	v_pk_add_f32 v[116:117], v[116:117], 0 op_sel_hi:[1,0]
	v_pk_add_f32 v[118:119], v[118:119], 0 op_sel_hi:[1,0]
	v_pk_add_f32 v[108:109], v[108:109], 0 op_sel_hi:[1,0]
	v_pk_add_f32 v[110:111], v[110:111], 0 op_sel_hi:[1,0]
	v_pk_add_f32 v[112:113], v[112:113], 0 op_sel_hi:[1,0]
	v_pk_add_f32 v[114:115], v[114:115], 0 op_sel_hi:[1,0]
	v_pk_add_f32 v[104:105], v[104:105], 0 op_sel_hi:[1,0]
	v_pk_add_f32 v[106:107], v[106:107], 0 op_sel_hi:[1,0]
	v_pk_add_f32 v[100:101], v[100:101], 0 op_sel_hi:[1,0]
	v_pk_add_f32 v[102:103], v[102:103], 0 op_sel_hi:[1,0]
	v_pk_add_f32 v[96:97], v[96:97], 0 op_sel_hi:[1,0]
	v_pk_add_f32 v[98:99], v[98:99], 0 op_sel_hi:[1,0]
	v_pk_add_f32 v[92:93], v[92:93], 0 op_sel_hi:[1,0]
	v_pk_add_f32 v[94:95], v[94:95], 0 op_sel_hi:[1,0]
	v_pk_add_f32 v[88:89], v[88:89], 0 op_sel_hi:[1,0]
	v_pk_add_f32 v[90:91], v[90:91], 0 op_sel_hi:[1,0]
	v_pk_add_f32 v[84:85], v[84:85], 0 op_sel_hi:[1,0]
	v_pk_add_f32 v[86:87], v[86:87], 0 op_sel_hi:[1,0]
	v_pk_add_f32 v[76:77], v[76:77], 0 op_sel_hi:[1,0]
	v_pk_add_f32 v[78:79], v[78:79], 0 op_sel_hi:[1,0]
	v_pk_add_f32 v[80:81], v[80:81], 0 op_sel_hi:[1,0]
	v_pk_add_f32 v[82:83], v[82:83], 0 op_sel_hi:[1,0]
	v_pk_add_f32 v[72:73], v[72:73], 0 op_sel_hi:[1,0]
	v_pk_add_f32 v[74:75], v[74:75], 0 op_sel_hi:[1,0]
	v_pk_add_f32 v[68:69], v[68:69], 0 op_sel_hi:[1,0]
	v_pk_add_f32 v[70:71], v[70:71], 0 op_sel_hi:[1,0]
	v_pk_add_f32 v[64:65], v[64:65], 0 op_sel_hi:[1,0]
	v_pk_add_f32 v[66:67], v[66:67], 0 op_sel_hi:[1,0]
	v_pk_add_f32 v[60:61], v[60:61], 0 op_sel_hi:[1,0]
	v_pk_add_f32 v[62:63], v[62:63], 0 op_sel_hi:[1,0]
	v_pk_add_f32 v[56:57], v[56:57], 0 op_sel_hi:[1,0]
	v_pk_add_f32 v[58:59], v[58:59], 0 op_sel_hi:[1,0]
	v_pk_add_f32 v[52:53], v[52:53], 0 op_sel_hi:[1,0]
	v_pk_add_f32 v[54:55], v[54:55], 0 op_sel_hi:[1,0]
	v_pk_add_f32 v[44:45], v[44:45], 0 op_sel_hi:[1,0]
	v_pk_add_f32 v[46:47], v[46:47], 0 op_sel_hi:[1,0]
	v_pk_add_f32 v[48:49], v[48:49], 0 op_sel_hi:[1,0]
	v_pk_add_f32 v[50:51], v[50:51], 0 op_sel_hi:[1,0]
	v_pk_add_f32 v[40:41], v[40:41], 0 op_sel_hi:[1,0]
	v_pk_add_f32 v[42:43], v[42:43], 0 op_sel_hi:[1,0]
	v_pk_add_f32 v[36:37], v[36:37], 0 op_sel_hi:[1,0]
	v_pk_add_f32 v[38:39], v[38:39], 0 op_sel_hi:[1,0]
	v_pk_add_f32 v[32:33], v[32:33], 0 op_sel_hi:[1,0]
	v_pk_add_f32 v[34:35], v[34:35], 0 op_sel_hi:[1,0]
	v_pk_add_f32 v[28:29], v[28:29], 0 op_sel_hi:[1,0]
	v_pk_add_f32 v[30:31], v[30:31], 0 op_sel_hi:[1,0]
	v_pk_add_f32 v[24:25], v[24:25], 0 op_sel_hi:[1,0]
	v_pk_add_f32 v[26:27], v[26:27], 0 op_sel_hi:[1,0]
	v_pk_add_f32 v[20:21], v[20:21], 0 op_sel_hi:[1,0]
	v_pk_add_f32 v[22:23], v[22:23], 0 op_sel_hi:[1,0]
	v_pk_add_f32 v[12:13], v[12:13], 0 op_sel_hi:[1,0]
	v_pk_add_f32 v[14:15], v[14:15], 0 op_sel_hi:[1,0]
	v_pk_add_f32 v[16:17], v[16:17], 0 op_sel_hi:[1,0]
	v_pk_add_f32 v[18:19], v[18:19], 0 op_sel_hi:[1,0]
	v_pk_add_f32 v[8:9], v[8:9], 0 op_sel_hi:[1,0]
	v_pk_add_f32 v[10:11], v[10:11], 0 op_sel_hi:[1,0]
	v_pk_add_f32 v[4:5], v[4:5], 0 op_sel_hi:[1,0]
	v_pk_add_f32 v[6:7], v[6:7], 0 op_sel_hi:[1,0]
	v_pk_add_f32 v[0:1], v[0:1], 0 op_sel_hi:[1,0]
	v_pk_add_f32 v[2:3], v[2:3], 0 op_sel_hi:[1,0]
	s_waitcnt vmcnt(8)
	v_mov_b32_e32 v212, v124
	v_mov_b32_e32 v213, v125
	v_mov_b32_e32 v214, v126
	v_mov_b32_e32 v215, v127
	s_nop 0
	v_mov_b32_dpp v124, v120 row_shr:8 row_mask:0xf bank_mask:0xc
	v_mov_b32_dpp v125, v121 row_shr:8 row_mask:0xf bank_mask:0xc
	v_mov_b32_dpp v126, v122 row_shr:8 row_mask:0xf bank_mask:0xc
	v_mov_b32_dpp v127, v123 row_shr:8 row_mask:0xf bank_mask:0xc
	v_mov_b32_dpp v120, v212 row_shl:8 row_mask:0xf bank_mask:0x3
	v_mov_b32_dpp v121, v213 row_shl:8 row_mask:0xf bank_mask:0x3
	v_mov_b32_dpp v122, v214 row_shl:8 row_mask:0xf bank_mask:0x3
	v_mov_b32_dpp v123, v215 row_shl:8 row_mask:0xf bank_mask:0x3
	v_mov_b32_e32 v212, v116
	v_mov_b32_e32 v213, v117
	v_mov_b32_e32 v214, v118
	v_mov_b32_e32 v215, v119
	s_nop 0
	v_mov_b32_dpp v116, v108 row_shr:8 row_mask:0xf bank_mask:0xc
	v_mov_b32_dpp v117, v109 row_shr:8 row_mask:0xf bank_mask:0xc
	v_mov_b32_dpp v118, v110 row_shr:8 row_mask:0xf bank_mask:0xc
	v_mov_b32_dpp v119, v111 row_shr:8 row_mask:0xf bank_mask:0xc
	v_mov_b32_dpp v108, v212 row_shl:8 row_mask:0xf bank_mask:0x3
	v_mov_b32_dpp v109, v213 row_shl:8 row_mask:0xf bank_mask:0x3
	v_mov_b32_dpp v110, v214 row_shl:8 row_mask:0xf bank_mask:0x3
	v_mov_b32_dpp v111, v215 row_shl:8 row_mask:0xf bank_mask:0x3
	v_mov_b32_e32 v212, v112
	v_mov_b32_e32 v213, v113
	v_mov_b32_e32 v214, v114
	v_mov_b32_e32 v215, v115
	s_nop 0
	v_mov_b32_dpp v112, v104 row_shr:8 row_mask:0xf bank_mask:0xc
	v_mov_b32_dpp v113, v105 row_shr:8 row_mask:0xf bank_mask:0xc
	v_mov_b32_dpp v114, v106 row_shr:8 row_mask:0xf bank_mask:0xc
	v_mov_b32_dpp v115, v107 row_shr:8 row_mask:0xf bank_mask:0xc
	v_mov_b32_dpp v104, v212 row_shl:8 row_mask:0xf bank_mask:0x3
	v_mov_b32_dpp v105, v213 row_shl:8 row_mask:0xf bank_mask:0x3
	v_mov_b32_dpp v106, v214 row_shl:8 row_mask:0xf bank_mask:0x3
	v_mov_b32_dpp v107, v215 row_shl:8 row_mask:0xf bank_mask:0x3
	v_mov_b32_e32 v212, v100
	v_mov_b32_e32 v213, v101
	v_mov_b32_e32 v214, v102
	v_mov_b32_e32 v215, v103
	s_nop 0
	v_mov_b32_dpp v100, v96 row_shr:8 row_mask:0xf bank_mask:0xc
	v_mov_b32_dpp v101, v97 row_shr:8 row_mask:0xf bank_mask:0xc
	v_mov_b32_dpp v102, v98 row_shr:8 row_mask:0xf bank_mask:0xc
	v_mov_b32_dpp v103, v99 row_shr:8 row_mask:0xf bank_mask:0xc
	v_mov_b32_dpp v96, v212 row_shl:8 row_mask:0xf bank_mask:0x3
;     __device__ __forceinline__ void operator()(AccRef acc, const Unit& u, int wr, int wc, int fr, int fq) const {
;     ...
;                         for (int n = 0; n < 2; ++n) bs[m][bj][n] = *(const f32x4*)(base + (size_t)(row0 + ai * 128 + (2 * mh + m) * 16) * D + col0 + bj * 128 + n * 16);
; #pragma unroll
;                 for (int m = 0; m < 2; ++m)
; #pragma unroll
;                     for (int bj = 0; bj < 2; ++bj)
; #pragma unroll
;                         for (int n = 0; n < 2; ++n) *(f32x4*)(out + (size_t)(row0 + ai * 128 + (2 * mh + m) * 16) * D + col0 + bj * 128 + n * 16) = bs[m][bj][n] + sv[bj][n] * (acc[ai][bj][2 * mh + m][n] + bv[bj][n]);
;                 asm volatile("" ::: "memory"); }
	v_mov_b32_dpp v97, v213 row_shl:8 row_mask:0xf bank_mask:0x3
	v_mov_b32_dpp v98, v214 row_shl:8 row_mask:0xf bank_mask:0x3
	v_mov_b32_dpp v99, v215 row_shl:8 row_mask:0xf bank_mask:0x3
	v_pk_add_f32 v[124:125], v[124:125], v[140:141]
	v_pk_add_f32 v[126:127], v[126:127], v[142:143]
	v_pk_add_f32 v[120:121], v[120:121], v[152:153]
	v_pk_add_f32 v[122:123], v[122:123], v[154:155]
	v_pk_add_f32 v[116:117], v[116:117], v[156:157]
	v_pk_add_f32 v[118:119], v[118:119], v[158:159]
	v_pk_add_f32 v[108:109], v[108:109], v[160:161]
	v_pk_add_f32 v[110:111], v[110:111], v[162:163]
	v_pk_add_f32 v[112:113], v[112:113], v[164:165]
	v_pk_add_f32 v[114:115], v[114:115], v[166:167]
	v_pk_add_f32 v[104:105], v[104:105], v[168:169]
	v_pk_add_f32 v[106:107], v[106:107], v[170:171]
	v_pk_add_f32 v[100:101], v[100:101], v[172:173]
	v_pk_add_f32 v[102:103], v[102:103], v[174:175]
	v_pk_add_f32 v[96:97], v[96:97], v[176:177]
	v_pk_add_f32 v[98:99], v[98:99], v[178:179]
	global_store_dwordx4 v224, v[124:127], s[52:53]
	v_add_u32_e32 v144, v145, v233
	global_store_dwordx4 v144, v[120:123], s[52:53]
	global_store_dwordx4 v224, v[116:119], s[52:53] offset:512
	v_add_u32_e32 v144, v145, v233
	global_store_dwordx4 v144, v[108:111], s[52:53] offset:512
	global_store_dwordx4 v225, v[112:115], s[52:53]
	v_add_u32_e32 v144, v216, v233
	global_store_dwordx4 v144, v[104:107], s[52:53]
	global_store_dwordx4 v225, v[100:103], s[52:53] offset:512
	v_add_u32_e32 v144, v216, v233
	global_store_dwordx4 v144, v[96:99], s[52:53] offset:512
	global_load_dwordx4 v[140:143], v228, s[52:53]
	v_add_u32_e32 v144, v220, v233
	global_load_dwordx4 v[152:155], v144, s[52:53]
	global_load_dwordx4 v[156:159], v228, s[52:53] offset:512
	v_add_u32_e32 v144, v220, v233
	global_load_dwordx4 v[160:163], v144, s[52:53] offset:512
	global_load_dwordx4 v[164:167], v229, s[52:53]
	v_add_u32_e32 v144, v221, v233
	global_load_dwordx4 v[168:171], v144, s[52:53]
	global_load_dwordx4 v[172:175], v229, s[52:53] offset:512
	v_add_u32_e32 v144, v221, v233
	global_load_dwordx4 v[176:179], v144, s[52:53] offset:512
	s_waitcnt vmcnt(16)
	v_mov_b32_e32 v212, v92
	v_mov_b32_e32 v213, v93
	v_mov_b32_e32 v214, v94
	v_mov_b32_e32 v215, v95
	s_nop 0
	v_mov_b32_dpp v92, v88 row_shr:8 row_mask:0xf bank_mask:0xc
	v_mov_b32_dpp v93, v89 row_shr:8 row_mask:0xf bank_mask:0xc
	v_mov_b32_dpp v94, v90 row_shr:8 row_mask:0xf bank_mask:0xc
	v_mov_b32_dpp v95, v91 row_shr:8 row_mask:0xf bank_mask:0xc
	v_mov_b32_dpp v88, v212 row_shl:8 row_mask:0xf bank_mask:0x3
	v_mov_b32_dpp v89, v213 row_shl:8 row_mask:0xf bank_mask:0x3
	v_mov_b32_dpp v90, v214 row_shl:8 row_mask:0xf bank_mask:0x3
	v_mov_b32_dpp v91, v215 row_shl:8 row_mask:0xf bank_mask:0x3
	v_mov_b32_e32 v212, v84
	v_mov_b32_e32 v213, v85
	v_mov_b32_e32 v214, v86
	v_mov_b32_e32 v215, v87
	s_nop 0
	v_mov_b32_dpp v84, v76 row_shr:8 row_mask:0xf bank_mask:0xc
	v_mov_b32_dpp v85, v77 row_shr:8 row_mask:0xf bank_mask:0xc
	v_mov_b32_dpp v86, v78 row_shr:8 row_mask:0xf bank_mask:0xc
	v_mov_b32_dpp v87, v79 row_shr:8 row_mask:0xf bank_mask:0xc
	v_mov_b32_dpp v76, v212 row_shl:8 row_mask:0xf bank_mask:0x3
	v_mov_b32_dpp v77, v213 row_shl:8 row_mask:0xf bank_mask:0x3
	v_mov_b32_dpp v78, v214 row_shl:8 row_mask:0xf bank_mask:0x3
	v_mov_b32_dpp v79, v215 row_shl:8 row_mask:0xf bank_mask:0x3
	v_mov_b32_e32 v212, v80
	v_mov_b32_e32 v213, v81
	v_mov_b32_e32 v214, v82
	v_mov_b32_e32 v215, v83
	s_nop 0
	v_mov_b32_dpp v80, v72 row_shr:8 row_mask:0xf bank_mask:0xc
	v_mov_b32_dpp v81, v73 row_shr:8 row_mask:0xf bank_mask:0xc
	v_mov_b32_dpp v82, v74 row_shr:8 row_mask:0xf bank_mask:0xc
	v_mov_b32_dpp v83, v75 row_shr:8 row_mask:0xf bank_mask:0xc
	v_mov_b32_dpp v72, v212 row_shl:8 row_mask:0xf bank_mask:0x3
	v_mov_b32_dpp v73, v213 row_shl:8 row_mask:0xf bank_mask:0x3
	v_mov_b32_dpp v74, v214 row_shl:8 row_mask:0xf bank_mask:0x3
	v_mov_b32_dpp v75, v215 row_shl:8 row_mask:0xf bank_mask:0x3
	v_mov_b32_e32 v212, v68
	v_mov_b32_e32 v213, v69
	v_mov_b32_e32 v214, v70
	v_mov_b32_e32 v215, v71
	s_nop 0
	v_mov_b32_dpp v68, v64 row_shr:8 row_mask:0xf bank_mask:0xc
	v_mov_b32_dpp v69, v65 row_shr:8 row_mask:0xf bank_mask:0xc
	v_mov_b32_dpp v70, v66 row_shr:8 row_mask:0xf bank_mask:0xc
	v_mov_b32_dpp v71, v67 row_shr:8 row_mask:0xf bank_mask:0xc
	v_mov_b32_dpp v64, v212 row_shl:8 row_mask:0xf bank_mask:0x3
	v_mov_b32_dpp v65, v213 row_shl:8 row_mask:0xf bank_mask:0x3
	v_mov_b32_dpp v66, v214 row_shl:8 row_mask:0xf bank_mask:0x3
	v_mov_b32_dpp v67, v215 row_shl:8 row_mask:0xf bank_mask:0x3
	v_pk_add_f32 v[92:93], v[92:93], v[180:181]
	v_pk_add_f32 v[94:95], v[94:95], v[182:183]
	v_pk_add_f32 v[88:89], v[88:89], v[184:185]
	v_pk_add_f32 v[90:91], v[90:91], v[186:187]
	v_pk_add_f32 v[84:85], v[84:85], v[188:189]
	v_pk_add_f32 v[86:87], v[86:87], v[190:191]
	v_pk_add_f32 v[76:77], v[76:77], v[192:193]
	v_pk_add_f32 v[78:79], v[78:79], v[194:195]
	v_pk_add_f32 v[80:81], v[80:81], v[196:197]
	v_pk_add_f32 v[82:83], v[82:83], v[198:199]
	v_pk_add_f32 v[72:73], v[72:73], v[200:201]
	v_pk_add_f32 v[74:75], v[74:75], v[202:203]
	v_pk_add_f32 v[68:69], v[68:69], v[204:205]
	v_pk_add_f32 v[70:71], v[70:71], v[206:207]
	v_pk_add_f32 v[64:65], v[64:65], v[208:209]
	v_pk_add_f32 v[66:67], v[66:67], v[210:211]
	global_store_dwordx4 v226, v[92:95], s[52:53]
	v_add_u32_e32 v144, v217, v233
	global_store_dwordx4 v144, v[88:91], s[52:53]
	global_store_dwordx4 v226, v[84:87], s[52:53] offset:512
	v_add_u32_e32 v144, v217, v233
	global_store_dwordx4 v144, v[76:79], s[52:53] offset:512
	global_store_dwordx4 v227, v[80:83], s[52:53]
	v_add_u32_e32 v144, v218, v233
	global_store_dwordx4 v144, v[72:75], s[52:53]
	global_store_dwordx4 v227, v[68:71], s[52:53] offset:512
	v_add_u32_e32 v144, v218, v233
	global_store_dwordx4 v144, v[64:67], s[52:53] offset:512
	global_load_dwordx4 v[180:183], v230, s[52:53]
	v_add_u32_e32 v144, v222, v233
	global_load_dwordx4 v[184:187], v144, s[52:53]
	global_load_dwordx4 v[188:191], v230, s[52:53] offset:512
	v_add_u32_e32 v144, v222, v233
	global_load_dwordx4 v[192:195], v144, s[52:53] offset:512
	global_load_dwordx4 v[196:199], v231, s[52:53]
	v_add_u32_e32 v144, v223, v233
	global_load_dwordx4 v[200:203], v144, s[52:53]
	global_load_dwordx4 v[204:207], v231, s[52:53] offset:512
	v_add_u32_e32 v144, v223, v233
	global_load_dwordx4 v[208:211], v144, s[52:53] offset:512
	s_waitcnt vmcnt(16)
;     __device__ __forceinline__ void operator()(AccRef acc, const Unit& u, int wr, int wc, int fr, int fq) const {
;     ...
;                         for (int n = 0; n < 2; ++n) bs[m][bj][n] = *(const f32x4*)(base + (size_t)(row0 + ai * 128 + (2 * mh + m) * 16) * D + col0 + bj * 128 + n * 16);
; #pragma unroll
;                 for (int m = 0; m < 2; ++m)
; #pragma unroll
;                     for (int bj = 0; bj < 2; ++bj)
; #pragma unroll
;                         for (int n = 0; n < 2; ++n) *(f32x4*)(out + (size_t)(row0 + ai * 128 + (2 * mh + m) * 16) * D + col0 + bj * 128 + n * 16) = bs[m][bj][n] + sv[bj][n] * (acc[ai][bj][2 * mh + m][n] + bv[bj][n]);
;                 asm volatile("" ::: "memory"); }
	v_mov_b32_e32 v212, v60
	v_mov_b32_e32 v213, v61
	v_mov_b32_e32 v214, v62
	v_mov_b32_e32 v215, v63
	s_nop 0
	v_mov_b32_dpp v60, v56 row_shr:8 row_mask:0xf bank_mask:0xc
	v_mov_b32_dpp v61, v57 row_shr:8 row_mask:0xf bank_mask:0xc
	v_mov_b32_dpp v62, v58 row_shr:8 row_mask:0xf bank_mask:0xc
	v_mov_b32_dpp v63, v59 row_shr:8 row_mask:0xf bank_mask:0xc
	v_mov_b32_dpp v56, v212 row_shl:8 row_mask:0xf bank_mask:0x3
	v_mov_b32_dpp v57, v213 row_shl:8 row_mask:0xf bank_mask:0x3
	v_mov_b32_dpp v58, v214 row_shl:8 row_mask:0xf bank_mask:0x3
	v_mov_b32_dpp v59, v215 row_shl:8 row_mask:0xf bank_mask:0x3
	v_mov_b32_e32 v212, v52
	v_mov_b32_e32 v213, v53
	v_mov_b32_e32 v214, v54
	v_mov_b32_e32 v215, v55
	s_nop 0
	v_mov_b32_dpp v52, v44 row_shr:8 row_mask:0xf bank_mask:0xc
	v_mov_b32_dpp v53, v45 row_shr:8 row_mask:0xf bank_mask:0xc
	v_mov_b32_dpp v54, v46 row_shr:8 row_mask:0xf bank_mask:0xc
	v_mov_b32_dpp v55, v47 row_shr:8 row_mask:0xf bank_mask:0xc
	v_mov_b32_dpp v44, v212 row_shl:8 row_mask:0xf bank_mask:0x3
	v_mov_b32_dpp v45, v213 row_shl:8 row_mask:0xf bank_mask:0x3
	v_mov_b32_dpp v46, v214 row_shl:8 row_mask:0xf bank_mask:0x3
	v_mov_b32_dpp v47, v215 row_shl:8 row_mask:0xf bank_mask:0x3
	v_mov_b32_e32 v212, v48
	v_mov_b32_e32 v213, v49
	v_mov_b32_e32 v214, v50
	v_mov_b32_e32 v215, v51
	s_nop 0
	v_mov_b32_dpp v48, v40 row_shr:8 row_mask:0xf bank_mask:0xc
	v_mov_b32_dpp v49, v41 row_shr:8 row_mask:0xf bank_mask:0xc
	v_mov_b32_dpp v50, v42 row_shr:8 row_mask:0xf bank_mask:0xc
	v_mov_b32_dpp v51, v43 row_shr:8 row_mask:0xf bank_mask:0xc
	v_mov_b32_dpp v40, v212 row_shl:8 row_mask:0xf bank_mask:0x3
	v_mov_b32_dpp v41, v213 row_shl:8 row_mask:0xf bank_mask:0x3
	v_mov_b32_dpp v42, v214 row_shl:8 row_mask:0xf bank_mask:0x3
	v_mov_b32_dpp v43, v215 row_shl:8 row_mask:0xf bank_mask:0x3
	v_mov_b32_e32 v212, v36
	v_mov_b32_e32 v213, v37
	v_mov_b32_e32 v214, v38
	v_mov_b32_e32 v215, v39
	s_nop 0
	v_mov_b32_dpp v36, v32 row_shr:8 row_mask:0xf bank_mask:0xc
	v_mov_b32_dpp v37, v33 row_shr:8 row_mask:0xf bank_mask:0xc
	v_mov_b32_dpp v38, v34 row_shr:8 row_mask:0xf bank_mask:0xc
	v_mov_b32_dpp v39, v35 row_shr:8 row_mask:0xf bank_mask:0xc
	v_mov_b32_dpp v32, v212 row_shl:8 row_mask:0xf bank_mask:0x3
	v_mov_b32_dpp v33, v213 row_shl:8 row_mask:0xf bank_mask:0x3
	v_mov_b32_dpp v34, v214 row_shl:8 row_mask:0xf bank_mask:0x3
	v_mov_b32_dpp v35, v215 row_shl:8 row_mask:0xf bank_mask:0x3
	v_pk_add_f32 v[60:61], v[60:61], v[140:141]
	v_pk_add_f32 v[62:63], v[62:63], v[142:143]
	v_pk_add_f32 v[56:57], v[56:57], v[152:153]
	v_pk_add_f32 v[58:59], v[58:59], v[154:155]
	v_pk_add_f32 v[52:53], v[52:53], v[156:157]
	v_pk_add_f32 v[54:55], v[54:55], v[158:159]
	v_pk_add_f32 v[44:45], v[44:45], v[160:161]
	v_pk_add_f32 v[46:47], v[46:47], v[162:163]
	v_pk_add_f32 v[48:49], v[48:49], v[164:165]
	v_pk_add_f32 v[50:51], v[50:51], v[166:167]
	v_pk_add_f32 v[40:41], v[40:41], v[168:169]
	v_pk_add_f32 v[42:43], v[42:43], v[170:171]
	v_pk_add_f32 v[36:37], v[36:37], v[172:173]
	v_pk_add_f32 v[38:39], v[38:39], v[174:175]
	v_pk_add_f32 v[32:33], v[32:33], v[176:177]
	v_pk_add_f32 v[34:35], v[34:35], v[178:179]
	global_store_dwordx4 v228, v[60:63], s[52:53]
	v_add_u32_e32 v144, v220, v233
	global_store_dwordx4 v144, v[56:59], s[52:53]
	global_store_dwordx4 v228, v[52:55], s[52:53] offset:512
	v_add_u32_e32 v144, v220, v233
	global_store_dwordx4 v144, v[44:47], s[52:53] offset:512
	global_store_dwordx4 v229, v[48:51], s[52:53]
	v_add_u32_e32 v144, v221, v233
	global_store_dwordx4 v144, v[40:43], s[52:53]
	global_store_dwordx4 v229, v[36:39], s[52:53] offset:512
	v_add_u32_e32 v144, v221, v233
	global_store_dwordx4 v144, v[32:35], s[52:53] offset:512
	s_waitcnt vmcnt(8)
; #define PG8_WAIT_V(n) asm volatile("s_waitcnt vmcnt(" #n ")" ::: "memory")
; #define PG8_BAR __builtin_amdgcn_s_barrier()
; template <class Epi>
; __device__ __forceinline__ void gemm_phase(LAS unsigned char* lds, const Gemm g, const StaticOrder& S, const Epi& E) {
;     ...
;         if (!has_next) break;
;         {
; #pragma unroll
;         for (int a = 0; a < 2; ++a)
; #pragma unroll
;             for (int b = 0; b < 2; ++b)
; #pragma unroll
;                 for (int m = 0; m < 4; ++m)
; #pragma unroll
;                     for (int n = 0; n < 2; ++n) acc[a][b][m][n] = (f32x4){0.f, 0.f, 0.f, 0.f};
;         }
;         cur = nxt; cA = nA; cB = nB; ++ui;
;     }
;     PG8_WAIT_V(0);
;     if (wr == 0) PG8_BAR;
;     __device__ __forceinline__ void operator()(AccRef acc, const Unit& u, int wr, int wc, int fr, int fq) const {
;     ...
;                         for (int n = 0; n < 2; ++n) bs[m][bj][n] = *(const f32x4*)(base + (size_t)(row0 + ai * 128 + (2 * mh + m) * 16) * D + col0 + bj * 128 + n * 16);
; #pragma unroll
;                 for (int m = 0; m < 2; ++m)
; #pragma unroll
;                     for (int bj = 0; bj < 2; ++bj)
; #pragma unroll
;                         for (int n = 0; n < 2; ++n) *(f32x4*)(out + (size_t)(row0 + ai * 128 + (2 * mh + m) * 16) * D + col0 + bj * 128 + n * 16) = bs[m][bj][n] + sv[bj][n] * (acc[ai][bj][2 * mh + m][n] + bv[bj][n]);
;                 asm volatile("" ::: "memory"); }
	v_mov_b32_e32 v212, v28
	v_mov_b32_e32 v213, v29
	v_mov_b32_e32 v214, v30
	v_mov_b32_e32 v215, v31
	s_nop 0
	v_mov_b32_dpp v28, v24 row_shr:8 row_mask:0xf bank_mask:0xc
	v_mov_b32_dpp v29, v25 row_shr:8 row_mask:0xf bank_mask:0xc
	v_mov_b32_dpp v30, v26 row_shr:8 row_mask:0xf bank_mask:0xc
	v_mov_b32_dpp v31, v27 row_shr:8 row_mask:0xf bank_mask:0xc
	v_mov_b32_dpp v24, v212 row_shl:8 row_mask:0xf bank_mask:0x3
	v_mov_b32_dpp v25, v213 row_shl:8 row_mask:0xf bank_mask:0x3
	v_mov_b32_dpp v26, v214 row_shl:8 row_mask:0xf bank_mask:0x3
	v_mov_b32_dpp v27, v215 row_shl:8 row_mask:0xf bank_mask:0x3
	v_mov_b32_e32 v212, v20
	v_mov_b32_e32 v213, v21
	v_mov_b32_e32 v214, v22
	v_mov_b32_e32 v215, v23
	s_nop 0
	v_mov_b32_dpp v20, v12 row_shr:8 row_mask:0xf bank_mask:0xc
	v_mov_b32_dpp v21, v13 row_shr:8 row_mask:0xf bank_mask:0xc
	v_mov_b32_dpp v22, v14 row_shr:8 row_mask:0xf bank_mask:0xc
	v_mov_b32_dpp v23, v15 row_shr:8 row_mask:0xf bank_mask:0xc
	v_mov_b32_dpp v12, v212 row_shl:8 row_mask:0xf bank_mask:0x3
	v_mov_b32_dpp v13, v213 row_shl:8 row_mask:0xf bank_mask:0x3
	v_mov_b32_dpp v14, v214 row_shl:8 row_mask:0xf bank_mask:0x3
	v_mov_b32_dpp v15, v215 row_shl:8 row_mask:0xf bank_mask:0x3
	v_mov_b32_e32 v212, v16
	v_mov_b32_e32 v213, v17
	v_mov_b32_e32 v214, v18
	v_mov_b32_e32 v215, v19
	s_nop 0
	v_mov_b32_dpp v16, v8 row_shr:8 row_mask:0xf bank_mask:0xc
	v_mov_b32_dpp v17, v9 row_shr:8 row_mask:0xf bank_mask:0xc
	v_mov_b32_dpp v18, v10 row_shr:8 row_mask:0xf bank_mask:0xc
	v_mov_b32_dpp v19, v11 row_shr:8 row_mask:0xf bank_mask:0xc
	v_mov_b32_dpp v8, v212 row_shl:8 row_mask:0xf bank_mask:0x3
	v_mov_b32_dpp v9, v213 row_shl:8 row_mask:0xf bank_mask:0x3
	v_mov_b32_dpp v10, v214 row_shl:8 row_mask:0xf bank_mask:0x3
	v_mov_b32_dpp v11, v215 row_shl:8 row_mask:0xf bank_mask:0x3
	v_mov_b32_e32 v212, v4
	v_mov_b32_e32 v213, v5
	v_mov_b32_e32 v214, v6
	v_mov_b32_e32 v215, v7
	s_nop 0
	v_mov_b32_dpp v4, v0 row_shr:8 row_mask:0xf bank_mask:0xc
	v_mov_b32_dpp v5, v1 row_shr:8 row_mask:0xf bank_mask:0xc
	v_mov_b32_dpp v6, v2 row_shr:8 row_mask:0xf bank_mask:0xc
	v_mov_b32_dpp v7, v3 row_shr:8 row_mask:0xf bank_mask:0xc
	v_mov_b32_dpp v0, v212 row_shl:8 row_mask:0xf bank_mask:0x3
	v_mov_b32_dpp v1, v213 row_shl:8 row_mask:0xf bank_mask:0x3
	v_mov_b32_dpp v2, v214 row_shl:8 row_mask:0xf bank_mask:0x3
	v_mov_b32_dpp v3, v215 row_shl:8 row_mask:0xf bank_mask:0x3
	v_pk_add_f32 v[28:29], v[28:29], v[180:181]
	v_pk_add_f32 v[30:31], v[30:31], v[182:183]
	v_pk_add_f32 v[24:25], v[24:25], v[184:185]
	v_pk_add_f32 v[26:27], v[26:27], v[186:187]
	v_pk_add_f32 v[20:21], v[20:21], v[188:189]
	v_pk_add_f32 v[22:23], v[22:23], v[190:191]
	v_pk_add_f32 v[12:13], v[12:13], v[192:193]
	v_pk_add_f32 v[14:15], v[14:15], v[194:195]
	v_pk_add_f32 v[16:17], v[16:17], v[196:197]
	v_pk_add_f32 v[18:19], v[18:19], v[198:199]
	v_pk_add_f32 v[8:9], v[8:9], v[200:201]
	v_pk_add_f32 v[10:11], v[10:11], v[202:203]
	v_pk_add_f32 v[4:5], v[4:5], v[204:205]
	v_pk_add_f32 v[6:7], v[6:7], v[206:207]
	v_pk_add_f32 v[0:1], v[0:1], v[208:209]
	v_pk_add_f32 v[2:3], v[2:3], v[210:211]
	global_store_dwordx4 v230, v[28:31], s[52:53]
	v_add_u32_e32 v144, v222, v233
	global_store_dwordx4 v144, v[24:27], s[52:53]
	global_store_dwordx4 v230, v[20:23], s[52:53] offset:512
	v_add_u32_e32 v144, v222, v233
	global_store_dwordx4 v144, v[12:15], s[52:53] offset:512
	global_store_dwordx4 v231, v[16:19], s[52:53]
	v_add_u32_e32 v144, v223, v233
	global_store_dwordx4 v144, v[8:11], s[52:53]
	global_store_dwordx4 v231, v[4:7], s[52:53] offset:512
	v_add_u32_e32 v144, v223, v233
	global_store_dwordx4 v144, v[0:3], s[52:53] offset:512
	s_cbranch_vccz .LBB0_1813
	s_waitcnt vmcnt(0)
	s_cmpk_gt_u32 s4, 0xff
	s_cbranch_scc1 .LBB0_1824
	s_barrier

; #define PG8_STAGE(bufoff, gbase, voff) do { _Pragma("unroll") for (int _i = 0; _i < 2; ++_i) \
;         __builtin_amdgcn_global_load_lds((const unsigned*)((const char*)(gbase) + (voff)[_i]), (LAS unsigned*)(lds + (bufoff) + ldsw + _i * 8192), 16, 0, 0); } while (0)
; #define PG8_LDA(dst, b, h) do { _Pragma("unroll") for (int m = 0; m < 4; ++m) _Pragma("unroll") for (int k = 0; k < 2; ++k) dst[m][k] = *(const LAS bf16x8*)(lds + PG8_SA(b, h) + aoff + m * 2048 + k * 1024); } while (0)
; #define PG8_LDB(dst, b, h) do { _Pragma("unroll") for (int n = 0; n < 2; ++n) _Pragma("unroll") for (int k = 0; k < 2; ++k) dst[n][k] = *(const LAS bf16x8*)(lds + PG8_SB(b, h) + boff + n * 2048 + k * 1024); } while (0)
; #define PG8_MMA(ai, bj, At, Bt) do { __builtin_amdgcn_s_setprio(1); _Pragma("unroll") for (int m = 0; m < 4; ++m) _Pragma("unroll") for (int n = 0; n < 2; ++n) _Pragma("unroll") for (int k = 0; k < 2; ++k) \
;         acc[ai][bj][m][n] = __builtin_amdgcn_mfma_f32_16x16x32_bf16(Bt[n][k], At[m][k], acc[ai][bj][m][n], 0, 0, 0); __builtin_amdgcn_s_setprio(0); } while (0)
; #define PG8_WAIT_V(n) asm volatile("s_waitcnt vmcnt(" #n ")" ::: "memory")
; #define PG8_WAIT_L(n) asm volatile("s_waitcnt lgkmcnt(" #n ")" ::: "memory")
; template <class Epi>
; __device__ __forceinline__ void gemm_phase(LAS unsigned char* lds, const Gemm g, const StaticOrder& S, const Epi& E) {
;     ...
;         for (int t = 0; t < nt; t += 2) {
;             const bool last = (t == nt - 2);
;             const char* a1 = cA + (size_t)(t + 1) * kstep;
;             const char* a2 = last ? nA : cA + (size_t)(t + 2) * kstep; const char* b2 = last ? nB : cB + (size_t)(t + 2) * kstep;
;             const char* a3 = a2 + kstep; const char* b3 = b2 + kstep;
;             PG8_LDB(B0, 0, 0); PG8_SCHED; PG8_LDA(At, 0, 0); PG8_STAGE(PG8_SA(1, 1), a1 + hstepA, voffA);
;             PG8_WAIT_L(8); PG8_BAR; PG8_WAIT_L(0); PG8_MMA(0, 0, At, B0); PG8_BAR; PG8_SCHED;
;             PG8_LDB(B1, 0, 1); PG8_STAGE(PG8_SB(0, 0), b2, voffB);
;             PG8_BAR; PG8_WAIT_L(0); PG8_MMA(0, 1, At, B1); PG8_BAR;
;             PG8_LDA(At, 0, 1); PG8_STAGE(PG8_SA(0, 0), a2, voffA);
;             PG8_BAR; PG8_WAIT_L(0); PG8_MMA(1, 0, At, B0); PG8_BAR; PG8_SCHED;
;             PG8_STAGE(PG8_SB(0, 1), b2 + hstepB, voffB);
;             PG8_WAIT_V(6); PG8_BAR; PG8_MMA(1, 1, At, B1); PG8_BAR;
.LBB0_2042:
	ds_read_b128 v[140:143], v149
	ds_read_b128 v[152:155], v149 offset:1024
	ds_read_b128 v[156:159], v149 offset:2048
	ds_read_b128 v[160:163], v149 offset:3072
	s_add_u32 s20, s18, 0x100
	s_addc_u32 s21, s19, 0
	s_cmp_eq_u32 s46, 40
	s_cselect_b32 s25, s5, s21
	s_cselect_b32 s24, s4, s20
	s_cselect_b32 s23, s7, s45
	s_cselect_b32 s22, s6, s44
	v_lshl_add_u64 v[144:145], s[18:19], 0, v[132:133]
	s_add_i32 m0, s30, 0xc000
	ds_read_b128 v[164:167], v150
	ds_read_b128 v[168:171], v150 offset:1024
	ds_read_b128 v[172:175], v150 offset:2048
	ds_read_b128 v[176:179], v150 offset:3072
	ds_read_b128 v[180:183], v150 offset:4096
	ds_read_b128 v[184:187], v150 offset:5120
	ds_read_b128 v[188:191], v150 offset:6144
	ds_read_b128 v[192:195], v150 offset:7168
	global_load_lds_dwordx4 v[144:145], off
	v_lshl_add_u64 v[144:145], s[18:19], 0, v[134:135]
	s_add_i32 m0, s30, 0xe000
	s_nop 0
	global_load_lds_dwordx4 v[144:145], off
	ds_read_b128 v[196:199], v151
	ds_read_b128 v[200:203], v151 offset:1024
	ds_read_b128 v[204:207], v151 offset:2048
	ds_read_b128 v[208:211], v151 offset:3072
	s_waitcnt lgkmcnt(0)
	s_barrier
	s_setprio 1
	v_mfma_f32_16x16x32_bf16 v[124:127], v[140:143], v[164:167], v[124:127]
	v_mfma_f32_16x16x32_bf16 v[120:123], v[156:159], v[164:167], v[120:123]
	v_mfma_f32_16x16x32_bf16 v[112:115], v[140:143], v[172:175], v[112:115]
	v_mfma_f32_16x16x32_bf16 v[104:107], v[156:159], v[172:175], v[104:107]
	v_mfma_f32_16x16x32_bf16 v[92:95], v[140:143], v[180:183], v[92:95]
	v_mfma_f32_16x16x32_bf16 v[88:91], v[156:159], v[180:183], v[88:91]
	v_mfma_f32_16x16x32_bf16 v[80:83], v[140:143], v[188:191], v[80:83]
	v_mfma_f32_16x16x32_bf16 v[72:75], v[156:159], v[188:191], v[72:75]
	v_mfma_f32_16x16x32_bf16 v[124:127], v[152:155], v[168:171], v[124:127]
	v_mfma_f32_16x16x32_bf16 v[120:123], v[160:163], v[168:171], v[120:123]
	v_mfma_f32_16x16x32_bf16 v[112:115], v[152:155], v[176:179], v[112:115]
	v_mfma_f32_16x16x32_bf16 v[104:107], v[160:163], v[176:179], v[104:107]
	v_mfma_f32_16x16x32_bf16 v[92:95], v[152:155], v[184:187], v[92:95]
	v_mfma_f32_16x16x32_bf16 v[88:91], v[160:163], v[184:187], v[88:91]
	v_mfma_f32_16x16x32_bf16 v[80:83], v[152:155], v[192:195], v[80:83]
	v_mfma_f32_16x16x32_bf16 v[72:75], v[160:163], v[192:195], v[72:75]
	v_mfma_f32_16x16x32_bf16 v[116:119], v[196:199], v[164:167], v[116:119]
	v_mfma_f32_16x16x32_bf16 v[108:111], v[204:207], v[164:167], v[108:111]
	v_mfma_f32_16x16x32_bf16 v[100:103], v[196:199], v[172:175], v[100:103]
	v_mfma_f32_16x16x32_bf16 v[96:99], v[204:207], v[172:175], v[96:99]
	v_mfma_f32_16x16x32_bf16 v[84:87], v[196:199], v[180:183], v[84:87]
	v_mfma_f32_16x16x32_bf16 v[76:79], v[204:207], v[180:183], v[76:79]
	v_mfma_f32_16x16x32_bf16 v[68:71], v[196:199], v[188:191], v[68:71]
	v_mfma_f32_16x16x32_bf16 v[64:67], v[204:207], v[188:191], v[64:67]
	v_mfma_f32_16x16x32_bf16 v[116:119], v[200:203], v[168:171], v[116:119]
	v_mfma_f32_16x16x32_bf16 v[108:111], v[208:211], v[168:171], v[108:111]
	v_mfma_f32_16x16x32_bf16 v[100:103], v[200:203], v[176:179], v[100:103]
	v_mfma_f32_16x16x32_bf16 v[96:99], v[208:211], v[176:179], v[96:99]
	v_mfma_f32_16x16x32_bf16 v[84:87], v[200:203], v[184:187], v[84:87]
	v_mfma_f32_16x16x32_bf16 v[76:79], v[208:211], v[184:187], v[76:79]
	v_mfma_f32_16x16x32_bf16 v[68:71], v[200:203], v[192:195], v[68:71]
	v_mfma_f32_16x16x32_bf16 v[64:67], v[208:211], v[192:195], v[64:67]
	s_setprio 0
	s_barrier
	s_nop 1
	ds_read_b128 v[164:167], v150 offset:16384
	ds_read_b128 v[168:171], v150 offset:17408
	ds_read_b128 v[172:175], v150 offset:18432
	ds_read_b128 v[176:179], v150 offset:19456
	ds_read_b128 v[180:183], v150 offset:20480
	ds_read_b128 v[184:187], v150 offset:21504
	ds_read_b128 v[188:191], v150 offset:22528
	ds_read_b128 v[192:195], v150 offset:23552
	s_add_i32 s18, s38, s29
	v_lshl_add_u64 v[144:145], s[22:23], 0, v[128:129]
	s_mov_b32 m0, s18
	s_nop 0
	global_load_lds_dwordx4 v[144:145], off
	v_lshl_add_u64 v[212:213], s[22:23], 0, v[130:131]
	s_add_i32 m0, s18, 0x2000
	s_nop 0
	global_load_lds_dwordx4 v[212:213], off
	s_mov_b32 m0, s30
	v_lshl_add_u64 v[214:215], s[24:25], 0, v[128:129]
	global_load_lds_dwordx4 v[214:215], off
	v_lshl_add_u64 v[216:217], s[24:25], 0, v[130:131]
	s_mov_b32 m0, s31
	s_nop 0
	global_load_lds_dwordx4 v[216:217], off
	s_add_u32 s18, s22, 0xb0000
	s_addc_u32 s19, s23, 0
	s_add_i32 s47, s39, s29
	v_lshl_add_u64 v[254:255], s[18:19], 0, v[128:129]
	s_mov_b32 m0, s47
	s_nop 0
	global_load_lds_dwordx4 v[254:255], off
	v_lshl_add_u64 v[254:255], s[18:19], 0, v[130:131]
	s_add_i32 m0, s47, 0x2000
	s_nop 0
	global_load_lds_dwordx4 v[254:255], off
	s_waitcnt vmcnt(6)
	s_waitcnt lgkmcnt(0)
	s_barrier
; #define PG8_STAGE(bufoff, gbase, voff) do { _Pragma("unroll") for (int _i = 0; _i < 2; ++_i) \
;         __builtin_amdgcn_global_load_lds((const unsigned*)((const char*)(gbase) + (voff)[_i]), (LAS unsigned*)(lds + (bufoff) + ldsw + _i * 8192), 16, 0, 0); } while (0)
; #define PG8_LDA(dst, b, h) do { _Pragma("unroll") for (int m = 0; m < 4; ++m) _Pragma("unroll") for (int k = 0; k < 2; ++k) dst[m][k] = *(const LAS bf16x8*)(lds + PG8_SA(b, h) + aoff + m * 2048 + k * 1024); } while (0)
; #define PG8_LDB(dst, b, h) do { _Pragma("unroll") for (int n = 0; n < 2; ++n) _Pragma("unroll") for (int k = 0; k < 2; ++k) dst[n][k] = *(const LAS bf16x8*)(lds + PG8_SB(b, h) + boff + n * 2048 + k * 1024); } while (0)
; #define PG8_MMA(ai, bj, At, Bt) do { __builtin_amdgcn_s_setprio(1); _Pragma("unroll") for (int m = 0; m < 4; ++m) _Pragma("unroll") for (int n = 0; n < 2; ++n) _Pragma("unroll") for (int k = 0; k < 2; ++k) \
;         acc[ai][bj][m][n] = __builtin_amdgcn_mfma_f32_16x16x32_bf16(Bt[n][k], At[m][k], acc[ai][bj][m][n], 0, 0, 0); __builtin_amdgcn_s_setprio(0); } while (0)
; #define PG8_WAIT_V(n) asm volatile("s_waitcnt vmcnt(" #n ")" ::: "memory")
; #define PG8_WAIT_L(n) asm volatile("s_waitcnt lgkmcnt(" #n ")" ::: "memory")
; #define PG8_BAR __builtin_amdgcn_s_barrier()
; #define PG8_SCHED __builtin_amdgcn_sched_barrier(0)
; template <class Epi>
; __device__ __forceinline__ void gemm_phase(LAS unsigned char* lds, const Gemm g, const StaticOrder& S, const Epi& E) {
;     ...
;             PG8_WAIT_V(6); PG8_BAR; PG8_MMA(1, 1, At, B1); PG8_BAR;
;             PG8_LDB(B0, 1, 0); PG8_SCHED; PG8_LDA(At, 1, 0); PG8_STAGE(PG8_SA(0, 1), a2 + hstepA, voffA);
;             PG8_WAIT_L(8); PG8_BAR; PG8_WAIT_L(0); PG8_MMA(0, 0, At, B0); PG8_BAR; PG8_SCHED;
;             PG8_LDB(B1, 1, 1); PG8_STAGE(PG8_SB(1, 0), b3, voffB);
;             PG8_BAR; PG8_WAIT_L(0); PG8_MMA(0, 1, At, B1); PG8_BAR;
;             PG8_LDA(At, 1, 1); PG8_STAGE(PG8_SA(1, 0), a3, voffA);
;             PG8_BAR; PG8_WAIT_L(0); PG8_MMA(1, 0, At, B0); PG8_BAR; PG8_SCHED;
	s_setprio 1
	v_mfma_f32_16x16x32_bf16 v[60:63], v[140:143], v[164:167], v[60:63]
	v_mfma_f32_16x16x32_bf16 v[56:59], v[156:159], v[164:167], v[56:59]
	v_mfma_f32_16x16x32_bf16 v[48:51], v[140:143], v[172:175], v[48:51]
	v_mfma_f32_16x16x32_bf16 v[40:43], v[156:159], v[172:175], v[40:43]
	v_mfma_f32_16x16x32_bf16 v[28:31], v[140:143], v[180:183], v[28:31]
	v_mfma_f32_16x16x32_bf16 v[24:27], v[156:159], v[180:183], v[24:27]
	v_mfma_f32_16x16x32_bf16 v[16:19], v[140:143], v[188:191], v[16:19]
	v_mfma_f32_16x16x32_bf16 v[8:11], v[156:159], v[188:191], v[8:11]
	v_mfma_f32_16x16x32_bf16 v[60:63], v[152:155], v[168:171], v[60:63]
	v_mfma_f32_16x16x32_bf16 v[56:59], v[160:163], v[168:171], v[56:59]
	v_mfma_f32_16x16x32_bf16 v[48:51], v[152:155], v[176:179], v[48:51]
	v_mfma_f32_16x16x32_bf16 v[40:43], v[160:163], v[176:179], v[40:43]
	v_mfma_f32_16x16x32_bf16 v[28:31], v[152:155], v[184:187], v[28:31]
	v_mfma_f32_16x16x32_bf16 v[24:27], v[160:163], v[184:187], v[24:27]
	v_mfma_f32_16x16x32_bf16 v[16:19], v[152:155], v[192:195], v[16:19]
	v_mfma_f32_16x16x32_bf16 v[8:11], v[160:163], v[192:195], v[8:11]
	v_mfma_f32_16x16x32_bf16 v[52:55], v[196:199], v[164:167], v[52:55]
	v_mfma_f32_16x16x32_bf16 v[44:47], v[204:207], v[164:167], v[44:47]
	v_mfma_f32_16x16x32_bf16 v[36:39], v[196:199], v[172:175], v[36:39]
	v_mfma_f32_16x16x32_bf16 v[32:35], v[204:207], v[172:175], v[32:35]
	v_mfma_f32_16x16x32_bf16 v[20:23], v[196:199], v[180:183], v[20:23]
	v_mfma_f32_16x16x32_bf16 v[12:15], v[204:207], v[180:183], v[12:15]
	v_mfma_f32_16x16x32_bf16 v[4:7], v[196:199], v[188:191], v[4:7]
	v_mfma_f32_16x16x32_bf16 v[0:3], v[204:207], v[188:191], v[0:3]
	v_mfma_f32_16x16x32_bf16 v[52:55], v[200:203], v[168:171], v[52:55]
	v_mfma_f32_16x16x32_bf16 v[44:47], v[208:211], v[168:171], v[44:47]
	v_mfma_f32_16x16x32_bf16 v[36:39], v[200:203], v[176:179], v[36:39]
	v_mfma_f32_16x16x32_bf16 v[32:35], v[208:211], v[176:179], v[32:35]
	v_mfma_f32_16x16x32_bf16 v[20:23], v[200:203], v[184:187], v[20:23]
	v_mfma_f32_16x16x32_bf16 v[12:15], v[208:211], v[184:187], v[12:15]
	v_mfma_f32_16x16x32_bf16 v[4:7], v[200:203], v[192:195], v[4:7]
	v_mfma_f32_16x16x32_bf16 v[0:3], v[208:211], v[192:195], v[0:3]
	s_setprio 0
	s_add_i32 s47, 0, 0x18000
	v_add_u32_e32 v160, s47, v147
	s_barrier
	ds_read_b128 v[140:143], v160
	ds_read_b128 v[152:155], v160 offset:1024
	ds_read_b128 v[156:159], v160 offset:2048
	ds_read_b128 v[160:163], v160 offset:3072
	s_add_u32 s18, s24, 0xb0000
	s_addc_u32 s19, s25, 0
	s_mov_b32 m0, s33
	v_lshl_add_u64 v[196:197], s[18:19], 0, v[128:129]
	ds_read_b128 v[164:167], v150 offset:32768
	ds_read_b128 v[168:171], v150 offset:33792
	ds_read_b128 v[172:175], v150 offset:34816
	ds_read_b128 v[176:179], v150 offset:35840
	ds_read_b128 v[180:183], v150 offset:36864
	ds_read_b128 v[184:187], v150 offset:37888
	ds_read_b128 v[188:191], v150 offset:38912
	ds_read_b128 v[192:195], v150 offset:39936
	global_load_lds_dwordx4 v[196:197], off
	v_lshl_add_u64 v[196:197], s[18:19], 0, v[130:131]
	s_mov_b32 m0, s34
	s_nop 0
	global_load_lds_dwordx4 v[196:197], off
	s_add_i32 s24, 0, 0x1c000
	v_add_u32_e32 v208, s24, v147
	ds_read_b128 v[196:199], v208
	ds_read_b128 v[200:203], v208 offset:1024
	ds_read_b128 v[204:207], v208 offset:2048
	ds_read_b128 v[208:211], v208 offset:3072
	s_waitcnt lgkmcnt(0)
	s_barrier
	s_setprio 1
	v_mfma_f32_16x16x32_bf16 v[124:127], v[140:143], v[164:167], v[124:127]
	v_mfma_f32_16x16x32_bf16 v[120:123], v[156:159], v[164:167], v[120:123]
	v_mfma_f32_16x16x32_bf16 v[112:115], v[140:143], v[172:175], v[112:115]
	v_mfma_f32_16x16x32_bf16 v[104:107], v[156:159], v[172:175], v[104:107]
	v_mfma_f32_16x16x32_bf16 v[92:95], v[140:143], v[180:183], v[92:95]
	v_mfma_f32_16x16x32_bf16 v[88:91], v[156:159], v[180:183], v[88:91]
	v_mfma_f32_16x16x32_bf16 v[80:83], v[140:143], v[188:191], v[80:83]
	v_mfma_f32_16x16x32_bf16 v[72:75], v[156:159], v[188:191], v[72:75]
	v_mfma_f32_16x16x32_bf16 v[124:127], v[152:155], v[168:171], v[124:127]
	v_mfma_f32_16x16x32_bf16 v[120:123], v[160:163], v[168:171], v[120:123]
	v_mfma_f32_16x16x32_bf16 v[112:115], v[152:155], v[176:179], v[112:115]
	v_mfma_f32_16x16x32_bf16 v[104:107], v[160:163], v[176:179], v[104:107]
	v_mfma_f32_16x16x32_bf16 v[92:95], v[152:155], v[184:187], v[92:95]
	v_mfma_f32_16x16x32_bf16 v[88:91], v[160:163], v[184:187], v[88:91]
	v_mfma_f32_16x16x32_bf16 v[80:83], v[152:155], v[192:195], v[80:83]
	v_mfma_f32_16x16x32_bf16 v[72:75], v[160:163], v[192:195], v[72:75]
	v_mfma_f32_16x16x32_bf16 v[116:119], v[196:199], v[164:167], v[116:119]
	v_mfma_f32_16x16x32_bf16 v[108:111], v[204:207], v[164:167], v[108:111]
	v_mfma_f32_16x16x32_bf16 v[100:103], v[196:199], v[172:175], v[100:103]
	v_mfma_f32_16x16x32_bf16 v[96:99], v[204:207], v[172:175], v[96:99]
	v_mfma_f32_16x16x32_bf16 v[84:87], v[196:199], v[180:183], v[84:87]
	v_mfma_f32_16x16x32_bf16 v[76:79], v[204:207], v[180:183], v[76:79]
	v_mfma_f32_16x16x32_bf16 v[68:71], v[196:199], v[188:191], v[68:71]
	v_mfma_f32_16x16x32_bf16 v[64:67], v[204:207], v[188:191], v[64:67]
	v_mfma_f32_16x16x32_bf16 v[116:119], v[200:203], v[168:171], v[116:119]
	v_mfma_f32_16x16x32_bf16 v[108:111], v[208:211], v[168:171], v[108:111]
	v_mfma_f32_16x16x32_bf16 v[100:103], v[200:203], v[176:179], v[100:103]
	v_mfma_f32_16x16x32_bf16 v[96:99], v[208:211], v[176:179], v[96:99]
	v_mfma_f32_16x16x32_bf16 v[84:87], v[200:203], v[184:187], v[84:87]
	v_mfma_f32_16x16x32_bf16 v[76:79], v[208:211], v[184:187], v[76:79]
	v_mfma_f32_16x16x32_bf16 v[68:71], v[200:203], v[192:195], v[68:71]
	v_mfma_f32_16x16x32_bf16 v[64:67], v[208:211], v[192:195], v[64:67]
	s_setprio 0
	s_barrier
; #define PG8_STAGE(bufoff, gbase, voff) do { _Pragma("unroll") for (int _i = 0; _i < 2; ++_i) \
;         __builtin_amdgcn_global_load_lds((const unsigned*)((const char*)(gbase) + (voff)[_i]), (LAS unsigned*)(lds + (bufoff) + ldsw + _i * 8192), 16, 0, 0); } while (0)
; #define PG8_LDA(dst, b, h) do { _Pragma("unroll") for (int m = 0; m < 4; ++m) _Pragma("unroll") for (int k = 0; k < 2; ++k) dst[m][k] = *(const LAS bf16x8*)(lds + PG8_SA(b, h) + aoff + m * 2048 + k * 1024); } while (0)
; #define PG8_MMA(ai, bj, At, Bt) do { __builtin_amdgcn_s_setprio(1); _Pragma("unroll") for (int m = 0; m < 4; ++m) _Pragma("unroll") for (int n = 0; n < 2; ++n) _Pragma("unroll") for (int k = 0; k < 2; ++k) \
;         acc[ai][bj][m][n] = __builtin_amdgcn_mfma_f32_16x16x32_bf16(Bt[n][k], At[m][k], acc[ai][bj][m][n], 0, 0, 0); __builtin_amdgcn_s_setprio(0); } while (0)
; template <class Epi>
; __device__ __forceinline__ void gemm_phase(LAS unsigned char* lds, const Gemm g, const StaticOrder& S, const Epi& E) {
;     ...
;             PG8_LDA(At, 1, 1); PG8_STAGE(PG8_SA(1, 0), a3, voffA);
;             PG8_BAR; PG8_WAIT_L(0); PG8_MMA(1, 0, At, B0); PG8_BAR; PG8_SCHED;
;             PG8_STAGE(PG8_SB(1, 1), b3 + hstepB, voffB);
;             PG8_WAIT_V(6); PG8_BAR; PG8_MMA(1, 1, At, B1); PG8_BAR;
;         }
;     __device__ __forceinline__ void operator()(AccRef acc, const Unit& u, int wr, int wc, int fr, int fq) const {
;         const int row0 = u.pm * 256 + wr * 64 + fr, col0 = u.pn * 256 + wc * 32 + 4 * fq;
;         f32x4 sv[2][2], bv[2][2];
; #pragma unroll
;         for (int bj = 0; bj < 2; ++bj)
; #pragma unroll
;             for (int n = 0; n < 2; ++n) {
;                 sv[bj][n] = scale ? *(const f32x4*)(scale + col0 + bj * 128 + n * 16) : (f32x4){1.f, 1.f, 1.f, 1.f};
;                 bv[bj][n] = bias ? *(const f32x4*)(bias + col0 + bj * 128 + n * 16) : (f32x4){0.f, 0.f, 0.f, 0.f}; }
; #pragma unroll
;         for (int ai = 0; ai < 2; ++ai)
; #pragma unroll
;             for (int mh = 0; mh < 2; ++mh) {
;                 f32x4 bs[2][2][2];
; #pragma unroll
;                 for (int m = 0; m < 2; ++m)
; #pragma unroll
;                     for (int bj = 0; bj < 2; ++bj)
; #pragma unroll
;                         for (int n = 0; n < 2; ++n) bs[m][bj][n] = *(const f32x4*)(base + (size_t)(row0 + ai * 128 + (2 * mh + m) * 16) * D + col0 + bj * 128 + n * 16);
	s_nop 1
	ds_read_b128 v[164:167], v150 offset:49152
	ds_read_b128 v[168:171], v150 offset:50176
	ds_read_b128 v[172:175], v150 offset:51200
	ds_read_b128 v[176:179], v150 offset:52224
	ds_read_b128 v[180:183], v150 offset:53248
	ds_read_b128 v[184:187], v150 offset:54272
	ds_read_b128 v[188:191], v150 offset:55296
	ds_read_b128 v[192:195], v150 offset:56320
	s_add_i32 s18, s47, s29
	v_lshl_add_u64 v[254:255], v[144:145], 0, s[10:11]
	s_mov_b32 m0, s18
	s_nop 0
	global_load_lds_dwordx4 v[254:255], off
	v_lshl_add_u64 v[254:255], v[212:213], 0, s[10:11]
	s_add_i32 m0, s18, 0x2000
	s_nop 0
	global_load_lds_dwordx4 v[254:255], off
	s_mov_b32 m0, s36
	v_lshl_add_u64 v[254:255], v[214:215], 0, s[10:11]
	global_load_lds_dwordx4 v[254:255], off
	v_lshl_add_u64 v[144:145], v[216:217], 0, s[10:11]
	s_mov_b32 m0, s37
	s_nop 0
	global_load_lds_dwordx4 v[144:145], off
	s_add_u32 s18, s22, 0xb0080
	s_addc_u32 s19, s23, 0
	s_add_i32 s22, s24, s29
	v_lshl_add_u64 v[254:255], s[18:19], 0, v[128:129]
	s_mov_b32 m0, s22
	s_nop 0
	global_load_lds_dwordx4 v[254:255], off
	v_lshl_add_u64 v[254:255], s[18:19], 0, v[130:131]
	s_add_i32 m0, s22, 0x2000
	s_nop 0
	global_load_lds_dwordx4 v[254:255], off
	s_waitcnt vmcnt(6)
	s_waitcnt lgkmcnt(0)
	s_barrier
	s_setprio 1
	v_mfma_f32_16x16x32_bf16 v[60:63], v[140:143], v[164:167], v[60:63]
	v_mfma_f32_16x16x32_bf16 v[56:59], v[156:159], v[164:167], v[56:59]
	v_mfma_f32_16x16x32_bf16 v[48:51], v[140:143], v[172:175], v[48:51]
	v_mfma_f32_16x16x32_bf16 v[40:43], v[156:159], v[172:175], v[40:43]
	v_mfma_f32_16x16x32_bf16 v[28:31], v[140:143], v[180:183], v[28:31]
	v_mfma_f32_16x16x32_bf16 v[24:27], v[156:159], v[180:183], v[24:27]
	v_mfma_f32_16x16x32_bf16 v[16:19], v[140:143], v[188:191], v[16:19]
	v_mfma_f32_16x16x32_bf16 v[8:11], v[156:159], v[188:191], v[8:11]
	v_mfma_f32_16x16x32_bf16 v[60:63], v[152:155], v[168:171], v[60:63]
	v_mfma_f32_16x16x32_bf16 v[56:59], v[160:163], v[168:171], v[56:59]
	v_mfma_f32_16x16x32_bf16 v[48:51], v[152:155], v[176:179], v[48:51]
	v_mfma_f32_16x16x32_bf16 v[40:43], v[160:163], v[176:179], v[40:43]
	v_mfma_f32_16x16x32_bf16 v[28:31], v[152:155], v[184:187], v[28:31]
	v_mfma_f32_16x16x32_bf16 v[24:27], v[160:163], v[184:187], v[24:27]
	v_mfma_f32_16x16x32_bf16 v[16:19], v[152:155], v[192:195], v[16:19]
	v_mfma_f32_16x16x32_bf16 v[8:11], v[160:163], v[192:195], v[8:11]
	v_mfma_f32_16x16x32_bf16 v[52:55], v[196:199], v[164:167], v[52:55]
	v_mfma_f32_16x16x32_bf16 v[44:47], v[204:207], v[164:167], v[44:47]
	v_mfma_f32_16x16x32_bf16 v[36:39], v[196:199], v[172:175], v[36:39]
	v_mfma_f32_16x16x32_bf16 v[32:35], v[204:207], v[172:175], v[32:35]
	v_mfma_f32_16x16x32_bf16 v[20:23], v[196:199], v[180:183], v[20:23]
	v_mfma_f32_16x16x32_bf16 v[12:15], v[204:207], v[180:183], v[12:15]
	v_mfma_f32_16x16x32_bf16 v[4:7], v[196:199], v[188:191], v[4:7]
	v_mfma_f32_16x16x32_bf16 v[0:3], v[204:207], v[188:191], v[0:3]
	v_mfma_f32_16x16x32_bf16 v[52:55], v[200:203], v[168:171], v[52:55]
	v_mfma_f32_16x16x32_bf16 v[44:47], v[208:211], v[168:171], v[44:47]
	v_mfma_f32_16x16x32_bf16 v[36:39], v[200:203], v[176:179], v[36:39]
	v_mfma_f32_16x16x32_bf16 v[32:35], v[208:211], v[176:179], v[32:35]
	v_mfma_f32_16x16x32_bf16 v[20:23], v[200:203], v[184:187], v[20:23]
	v_mfma_f32_16x16x32_bf16 v[12:15], v[208:211], v[184:187], v[12:15]
	v_mfma_f32_16x16x32_bf16 v[4:7], v[200:203], v[192:195], v[4:7]
	v_mfma_f32_16x16x32_bf16 v[0:3], v[208:211], v[192:195], v[0:3]
	s_setprio 0
	s_add_i32 s46, s46, 2
	s_add_u32 s44, s44, 0x100
	s_addc_u32 s45, s45, 0
	s_cmp_gt_u32 s46, 41
	s_mov_b64 s[18:19], s[20:21]
	s_barrier
	s_cbranch_scc0 .LBB0_2042
	v_lshl_or_b32 v144, s42, 8, v148
	v_lshl_add_u32 v145, s43, 8, v146
	v_lshlrev_b32_e32 v144, 2, v144
	v_lshl_add_u32 v145, v145, 12, v144
	v_add_u32_e32 v216, 0x10000, v145
	v_add_u32_e32 v217, 0x20000, v145
	v_add_u32_e32 v218, 0x30000, v145
	v_add_u32_e32 v220, 0x80000, v145
	v_add_u32_e32 v221, 0x90000, v145
	v_add_u32_e32 v222, 0xa0000, v145
	v_add_u32_e32 v223, 0xb0000, v145
	v_and_b32_e32 v235, 8, v146
	v_cmp_ne_u32_e32 vcc, 0, v235
	v_mov_b32_e32 v232, 0xffff8040
	s_nop 0
	v_cndmask_b32_e32 v232, 0, v232, vcc
	v_mov_b32_e32 v233, 64
	v_mov_b32_e32 v235, 0x8000
	v_cndmask_b32_e32 v233, v235, v233, vcc
	v_add_u32_e32 v224, v145, v232
	v_add_u32_e32 v225, v216, v232
	v_add_u32_e32 v226, v217, v232
	v_add_u32_e32 v227, v218, v232
	v_add_u32_e32 v228, v220, v232
	v_add_u32_e32 v229, v221, v232
	v_add_u32_e32 v230, v222, v232
	v_add_u32_e32 v231, v223, v232
	s_and_b64 vcc, exec, s[0:1]
	s_mov_b32 s42, s40
	s_mov_b32 s43, s41
	s_mov_b64 s[20:21], s[6:7]
	s_mov_b64 s[18:19], s[4:5]
	global_load_dwordx4 v[140:143], v224, s[52:53]
	v_add_u32_e32 v144, v145, v233
	global_load_dwordx4 v[152:155], v144, s[52:53]
	global_load_dwordx4 v[156:159], v224, s[52:53] offset:512
	v_add_u32_e32 v144, v145, v233
	global_load_dwordx4 v[160:163], v144, s[52:53] offset:512
	global_load_dwordx4 v[164:167], v225, s[52:53]
	v_add_u32_e32 v144, v216, v233
	global_load_dwordx4 v[168:171], v144, s[52:53]
	global_load_dwordx4 v[172:175], v225, s[52:53] offset:512
	v_add_u32_e32 v144, v216, v233
	global_load_dwordx4 v[176:179], v144, s[52:53] offset:512
	global_load_dwordx4 v[180:183], v226, s[52:53]
	v_add_u32_e32 v144, v217, v233
	global_load_dwordx4 v[184:187], v144, s[52:53]
	global_load_dwordx4 v[188:191], v226, s[52:53] offset:512
	v_add_u32_e32 v144, v217, v233
	global_load_dwordx4 v[192:195], v144, s[52:53] offset:512
	global_load_dwordx4 v[196:199], v227, s[52:53]
	v_add_u32_e32 v144, v218, v233
	global_load_dwordx4 v[200:203], v144, s[52:53]
	global_load_dwordx4 v[204:207], v227, s[52:53] offset:512
	v_add_u32_e32 v144, v218, v233
	global_load_dwordx4 v[208:211], v144, s[52:53] offset:512
	s_barrier
;     __device__ __forceinline__ void operator()(AccRef acc, const Unit& u, int wr, int wc, int fr, int fq) const {
;     ...
;                         for (int n = 0; n < 2; ++n) bs[m][bj][n] = *(const f32x4*)(base + (size_t)(row0 + ai * 128 + (2 * mh + m) * 16) * D + col0 + bj * 128 + n * 16);
; #pragma unroll
;                 for (int m = 0; m < 2; ++m)
; #pragma unroll
;                     for (int bj = 0; bj < 2; ++bj)
; #pragma unroll
;                         for (int n = 0; n < 2; ++n) *(f32x4*)(out + (size_t)(row0 + ai * 128 + (2 * mh + m) * 16) * D + col0 + bj * 128 + n * 16) = bs[m][bj][n] + sv[bj][n] * (acc[ai][bj][2 * mh + m][n] + bv[bj][n]);
	v_pk_add_f32 v[124:125], v[124:125], 0 op_sel_hi:[1,0]
	v_pk_add_f32 v[126:127], v[126:127], 0 op_sel_hi:[1,0]
	v_pk_add_f32 v[120:121], v[120:121], 0 op_sel_hi:[1,0]
	v_pk_add_f32 v[122:123], v[122:123], 0 op_sel_hi:[1,0]
	v_pk_add_f32 v[116:117], v[116:117], 0 op_sel_hi:[1,0]
	v_pk_add_f32 v[118:119], v[118:119], 0 op_sel_hi:[1,0]
	v_pk_add_f32 v[108:109], v[108:109], 0 op_sel_hi:[1,0]
	v_pk_add_f32 v[110:111], v[110:111], 0 op_sel_hi:[1,0]
	v_pk_add_f32 v[112:113], v[112:113], 0 op_sel_hi:[1,0]
	v_pk_add_f32 v[114:115], v[114:115], 0 op_sel_hi:[1,0]
	v_pk_add_f32 v[104:105], v[104:105], 0 op_sel_hi:[1,0]
	v_pk_add_f32 v[106:107], v[106:107], 0 op_sel_hi:[1,0]
	v_pk_add_f32 v[100:101], v[100:101], 0 op_sel_hi:[1,0]
	v_pk_add_f32 v[102:103], v[102:103], 0 op_sel_hi:[1,0]
	v_pk_add_f32 v[96:97], v[96:97], 0 op_sel_hi:[1,0]
	v_pk_add_f32 v[98:99], v[98:99], 0 op_sel_hi:[1,0]
	v_pk_add_f32 v[92:93], v[92:93], 0 op_sel_hi:[1,0]
	v_pk_add_f32 v[94:95], v[94:95], 0 op_sel_hi:[1,0]
	v_pk_add_f32 v[88:89], v[88:89], 0 op_sel_hi:[1,0]
	v_pk_add_f32 v[90:91], v[90:91], 0 op_sel_hi:[1,0]
	v_pk_add_f32 v[84:85], v[84:85], 0 op_sel_hi:[1,0]
	v_pk_add_f32 v[86:87], v[86:87], 0 op_sel_hi:[1,0]
	v_pk_add_f32 v[76:77], v[76:77], 0 op_sel_hi:[1,0]
	v_pk_add_f32 v[78:79], v[78:79], 0 op_sel_hi:[1,0]
	v_pk_add_f32 v[80:81], v[80:81], 0 op_sel_hi:[1,0]
	v_pk_add_f32 v[82:83], v[82:83], 0 op_sel_hi:[1,0]
	v_pk_add_f32 v[72:73], v[72:73], 0 op_sel_hi:[1,0]
	v_pk_add_f32 v[74:75], v[74:75], 0 op_sel_hi:[1,0]
	v_pk_add_f32 v[68:69], v[68:69], 0 op_sel_hi:[1,0]
	v_pk_add_f32 v[70:71], v[70:71], 0 op_sel_hi:[1,0]
	v_pk_add_f32 v[64:65], v[64:65], 0 op_sel_hi:[1,0]
	v_pk_add_f32 v[66:67], v[66:67], 0 op_sel_hi:[1,0]
	v_pk_add_f32 v[60:61], v[60:61], 0 op_sel_hi:[1,0]
	v_pk_add_f32 v[62:63], v[62:63], 0 op_sel_hi:[1,0]
	v_pk_add_f32 v[56:57], v[56:57], 0 op_sel_hi:[1,0]
	v_pk_add_f32 v[58:59], v[58:59], 0 op_sel_hi:[1,0]
	v_pk_add_f32 v[52:53], v[52:53], 0 op_sel_hi:[1,0]
	v_pk_add_f32 v[54:55], v[54:55], 0 op_sel_hi:[1,0]
	v_pk_add_f32 v[44:45], v[44:45], 0 op_sel_hi:[1,0]
	v_pk_add_f32 v[46:47], v[46:47], 0 op_sel_hi:[1,0]
	v_pk_add_f32 v[48:49], v[48:49], 0 op_sel_hi:[1,0]
	v_pk_add_f32 v[50:51], v[50:51], 0 op_sel_hi:[1,0]
	v_pk_add_f32 v[40:41], v[40:41], 0 op_sel_hi:[1,0]
	v_pk_add_f32 v[42:43], v[42:43], 0 op_sel_hi:[1,0]
	v_pk_add_f32 v[36:37], v[36:37], 0 op_sel_hi:[1,0]
	v_pk_add_f32 v[38:39], v[38:39], 0 op_sel_hi:[1,0]
	v_pk_add_f32 v[32:33], v[32:33], 0 op_sel_hi:[1,0]
	v_pk_add_f32 v[34:35], v[34:35], 0 op_sel_hi:[1,0]
	v_pk_add_f32 v[28:29], v[28:29], 0 op_sel_hi:[1,0]
	v_pk_add_f32 v[30:31], v[30:31], 0 op_sel_hi:[1,0]
	v_pk_add_f32 v[24:25], v[24:25], 0 op_sel_hi:[1,0]
	v_pk_add_f32 v[26:27], v[26:27], 0 op_sel_hi:[1,0]
	v_pk_add_f32 v[20:21], v[20:21], 0 op_sel_hi:[1,0]
	v_pk_add_f32 v[22:23], v[22:23], 0 op_sel_hi:[1,0]
	v_pk_add_f32 v[12:13], v[12:13], 0 op_sel_hi:[1,0]
	v_pk_add_f32 v[14:15], v[14:15], 0 op_sel_hi:[1,0]
	v_pk_add_f32 v[16:17], v[16:17], 0 op_sel_hi:[1,0]
	v_pk_add_f32 v[18:19], v[18:19], 0 op_sel_hi:[1,0]
	v_pk_add_f32 v[8:9], v[8:9], 0 op_sel_hi:[1,0]
	v_pk_add_f32 v[10:11], v[10:11], 0 op_sel_hi:[1,0]
	v_pk_add_f32 v[4:5], v[4:5], 0 op_sel_hi:[1,0]
	v_pk_add_f32 v[6:7], v[6:7], 0 op_sel_hi:[1,0]
	v_pk_add_f32 v[0:1], v[0:1], 0 op_sel_hi:[1,0]
	v_pk_add_f32 v[2:3], v[2:3], 0 op_sel_hi:[1,0]
	s_waitcnt vmcnt(8)
	v_mov_b32_e32 v212, v124
	v_mov_b32_e32 v213, v125
	v_mov_b32_e32 v214, v126
	v_mov_b32_e32 v215, v127
	s_nop 0
	v_mov_b32_dpp v124, v120 row_shr:8 row_mask:0xf bank_mask:0xc
	v_mov_b32_dpp v125, v121 row_shr:8 row_mask:0xf bank_mask:0xc
	v_mov_b32_dpp v126, v122 row_shr:8 row_mask:0xf bank_mask:0xc
	v_mov_b32_dpp v127, v123 row_shr:8 row_mask:0xf bank_mask:0xc
	v_mov_b32_dpp v120, v212 row_shl:8 row_mask:0xf bank_mask:0x3
	v_mov_b32_dpp v121, v213 row_shl:8 row_mask:0xf bank_mask:0x3
	v_mov_b32_dpp v122, v214 row_shl:8 row_mask:0xf bank_mask:0x3
	v_mov_b32_dpp v123, v215 row_shl:8 row_mask:0xf bank_mask:0x3
	v_mov_b32_e32 v212, v116
	v_mov_b32_e32 v213, v117
	v_mov_b32_e32 v214, v118
	v_mov_b32_e32 v215, v119
	s_nop 0
	v_mov_b32_dpp v116, v108 row_shr:8 row_mask:0xf bank_mask:0xc
	v_mov_b32_dpp v117, v109 row_shr:8 row_mask:0xf bank_mask:0xc
	v_mov_b32_dpp v118, v110 row_shr:8 row_mask:0xf bank_mask:0xc
	v_mov_b32_dpp v119, v111 row_shr:8 row_mask:0xf bank_mask:0xc
	v_mov_b32_dpp v108, v212 row_shl:8 row_mask:0xf bank_mask:0x3
	v_mov_b32_dpp v109, v213 row_shl:8 row_mask:0xf bank_mask:0x3
	v_mov_b32_dpp v110, v214 row_shl:8 row_mask:0xf bank_mask:0x3
	v_mov_b32_dpp v111, v215 row_shl:8 row_mask:0xf bank_mask:0x3
	v_mov_b32_e32 v212, v112
	v_mov_b32_e32 v213, v113
	v_mov_b32_e32 v214, v114
	v_mov_b32_e32 v215, v115
	s_nop 0
	v_mov_b32_dpp v112, v104 row_shr:8 row_mask:0xf bank_mask:0xc
	v_mov_b32_dpp v113, v105 row_shr:8 row_mask:0xf bank_mask:0xc
	v_mov_b32_dpp v114, v106 row_shr:8 row_mask:0xf bank_mask:0xc
	v_mov_b32_dpp v115, v107 row_shr:8 row_mask:0xf bank_mask:0xc
	v_mov_b32_dpp v104, v212 row_shl:8 row_mask:0xf bank_mask:0x3
	v_mov_b32_dpp v105, v213 row_shl:8 row_mask:0xf bank_mask:0x3
	v_mov_b32_dpp v106, v214 row_shl:8 row_mask:0xf bank_mask:0x3
	v_mov_b32_dpp v107, v215 row_shl:8 row_mask:0xf bank_mask:0x3
	v_mov_b32_e32 v212, v100
	v_mov_b32_e32 v213, v101
	v_mov_b32_e32 v214, v102
	v_mov_b32_e32 v215, v103
	s_nop 0
	v_mov_b32_dpp v100, v96 row_shr:8 row_mask:0xf bank_mask:0xc
	v_mov_b32_dpp v101, v97 row_shr:8 row_mask:0xf bank_mask:0xc
	v_mov_b32_dpp v102, v98 row_shr:8 row_mask:0xf bank_mask:0xc
	v_mov_b32_dpp v103, v99 row_shr:8 row_mask:0xf bank_mask:0xc
	v_mov_b32_dpp v96, v212 row_shl:8 row_mask:0xf bank_mask:0x3
;     __device__ __forceinline__ void operator()(AccRef acc, const Unit& u, int wr, int wc, int fr, int fq) const {
;         const int row0 = u.pm * 256 + wr * 64 + fr, col0 = u.pn * 256 + wc * 32 + 4 * fq;
;     ...
;                         for (int n = 0; n < 2; ++n) bs[m][bj][n] = *(const f32x4*)(base + (size_t)(row0 + ai * 128 + (2 * mh + m) * 16) * D + col0 + bj * 128 + n * 16);
; #pragma unroll
;                 for (int m = 0; m < 2; ++m)
; #pragma unroll
;                     for (int bj = 0; bj < 2; ++bj)
; #pragma unroll
;                         for (int n = 0; n < 2; ++n) *(f32x4*)(out + (size_t)(row0 + ai * 128 + (2 * mh + m) * 16) * D + col0 + bj * 128 + n * 16) = bs[m][bj][n] + sv[bj][n] * (acc[ai][bj][2 * mh + m][n] + bv[bj][n]);
;                 asm volatile("" ::: "memory"); }
	v_mov_b32_dpp v97, v213 row_shl:8 row_mask:0xf bank_mask:0x3
	v_mov_b32_dpp v98, v214 row_shl:8 row_mask:0xf bank_mask:0x3
	v_mov_b32_dpp v99, v215 row_shl:8 row_mask:0xf bank_mask:0x3
	v_pk_add_f32 v[124:125], v[124:125], v[140:141]
	v_pk_add_f32 v[126:127], v[126:127], v[142:143]
	v_pk_add_f32 v[120:121], v[120:121], v[152:153]
	v_pk_add_f32 v[122:123], v[122:123], v[154:155]
	v_pk_add_f32 v[116:117], v[116:117], v[156:157]
	v_pk_add_f32 v[118:119], v[118:119], v[158:159]
	v_pk_add_f32 v[108:109], v[108:109], v[160:161]
	v_pk_add_f32 v[110:111], v[110:111], v[162:163]
	v_pk_add_f32 v[112:113], v[112:113], v[164:165]
	v_pk_add_f32 v[114:115], v[114:115], v[166:167]
	v_pk_add_f32 v[104:105], v[104:105], v[168:169]
	v_pk_add_f32 v[106:107], v[106:107], v[170:171]
	v_pk_add_f32 v[100:101], v[100:101], v[172:173]
	v_pk_add_f32 v[102:103], v[102:103], v[174:175]
	v_pk_add_f32 v[96:97], v[96:97], v[176:177]
	v_pk_add_f32 v[98:99], v[98:99], v[178:179]
	global_store_dwordx4 v224, v[124:127], s[52:53]
	v_add_u32_e32 v144, v145, v233
	global_store_dwordx4 v144, v[120:123], s[52:53]
	global_store_dwordx4 v224, v[116:119], s[52:53] offset:512
	v_add_u32_e32 v144, v145, v233
	global_store_dwordx4 v144, v[108:111], s[52:53] offset:512
	global_store_dwordx4 v225, v[112:115], s[52:53]
	v_add_u32_e32 v144, v216, v233
	global_store_dwordx4 v144, v[104:107], s[52:53]
	global_store_dwordx4 v225, v[100:103], s[52:53] offset:512
	v_add_u32_e32 v144, v216, v233
	global_store_dwordx4 v144, v[96:99], s[52:53] offset:512
	global_load_dwordx4 v[140:143], v228, s[52:53]
	v_add_u32_e32 v144, v220, v233
	global_load_dwordx4 v[152:155], v144, s[52:53]
	global_load_dwordx4 v[156:159], v228, s[52:53] offset:512
	v_add_u32_e32 v144, v220, v233
	global_load_dwordx4 v[160:163], v144, s[52:53] offset:512
	global_load_dwordx4 v[164:167], v229, s[52:53]
	v_add_u32_e32 v144, v221, v233
	global_load_dwordx4 v[168:171], v144, s[52:53]
	global_load_dwordx4 v[172:175], v229, s[52:53] offset:512
	v_add_u32_e32 v144, v221, v233
	global_load_dwordx4 v[176:179], v144, s[52:53] offset:512
	s_waitcnt vmcnt(16)
	v_mov_b32_e32 v212, v92
	v_mov_b32_e32 v213, v93
	v_mov_b32_e32 v214, v94
	v_mov_b32_e32 v215, v95
	s_nop 0
	v_mov_b32_dpp v92, v88 row_shr:8 row_mask:0xf bank_mask:0xc
	v_mov_b32_dpp v93, v89 row_shr:8 row_mask:0xf bank_mask:0xc
	v_mov_b32_dpp v94, v90 row_shr:8 row_mask:0xf bank_mask:0xc
	v_mov_b32_dpp v95, v91 row_shr:8 row_mask:0xf bank_mask:0xc
	v_mov_b32_dpp v88, v212 row_shl:8 row_mask:0xf bank_mask:0x3
	v_mov_b32_dpp v89, v213 row_shl:8 row_mask:0xf bank_mask:0x3
	v_mov_b32_dpp v90, v214 row_shl:8 row_mask:0xf bank_mask:0x3
	v_mov_b32_dpp v91, v215 row_shl:8 row_mask:0xf bank_mask:0x3
	v_mov_b32_e32 v212, v84
	v_mov_b32_e32 v213, v85
	v_mov_b32_e32 v214, v86
	v_mov_b32_e32 v215, v87
	s_nop 0
	v_mov_b32_dpp v84, v76 row_shr:8 row_mask:0xf bank_mask:0xc
	v_mov_b32_dpp v85, v77 row_shr:8 row_mask:0xf bank_mask:0xc
	v_mov_b32_dpp v86, v78 row_shr:8 row_mask:0xf bank_mask:0xc
	v_mov_b32_dpp v87, v79 row_shr:8 row_mask:0xf bank_mask:0xc
	v_mov_b32_dpp v76, v212 row_shl:8 row_mask:0xf bank_mask:0x3
	v_mov_b32_dpp v77, v213 row_shl:8 row_mask:0xf bank_mask:0x3
	v_mov_b32_dpp v78, v214 row_shl:8 row_mask:0xf bank_mask:0x3
	v_mov_b32_dpp v79, v215 row_shl:8 row_mask:0xf bank_mask:0x3
	v_mov_b32_e32 v212, v80
	v_mov_b32_e32 v213, v81
	v_mov_b32_e32 v214, v82
	v_mov_b32_e32 v215, v83
	s_nop 0
	v_mov_b32_dpp v80, v72 row_shr:8 row_mask:0xf bank_mask:0xc
	v_mov_b32_dpp v81, v73 row_shr:8 row_mask:0xf bank_mask:0xc
	v_mov_b32_dpp v82, v74 row_shr:8 row_mask:0xf bank_mask:0xc
	v_mov_b32_dpp v83, v75 row_shr:8 row_mask:0xf bank_mask:0xc
	v_mov_b32_dpp v72, v212 row_shl:8 row_mask:0xf bank_mask:0x3
	v_mov_b32_dpp v73, v213 row_shl:8 row_mask:0xf bank_mask:0x3
	v_mov_b32_dpp v74, v214 row_shl:8 row_mask:0xf bank_mask:0x3
	v_mov_b32_dpp v75, v215 row_shl:8 row_mask:0xf bank_mask:0x3
	v_mov_b32_e32 v212, v68
	v_mov_b32_e32 v213, v69
	v_mov_b32_e32 v214, v70
	v_mov_b32_e32 v215, v71
	s_nop 0
	v_mov_b32_dpp v68, v64 row_shr:8 row_mask:0xf bank_mask:0xc
	v_mov_b32_dpp v69, v65 row_shr:8 row_mask:0xf bank_mask:0xc
	v_mov_b32_dpp v70, v66 row_shr:8 row_mask:0xf bank_mask:0xc
	v_mov_b32_dpp v71, v67 row_shr:8 row_mask:0xf bank_mask:0xc
	v_mov_b32_dpp v64, v212 row_shl:8 row_mask:0xf bank_mask:0x3
	v_mov_b32_dpp v65, v213 row_shl:8 row_mask:0xf bank_mask:0x3
	v_mov_b32_dpp v66, v214 row_shl:8 row_mask:0xf bank_mask:0x3
	v_mov_b32_dpp v67, v215 row_shl:8 row_mask:0xf bank_mask:0x3
	v_pk_add_f32 v[92:93], v[92:93], v[180:181]
	v_pk_add_f32 v[94:95], v[94:95], v[182:183]
	v_pk_add_f32 v[88:89], v[88:89], v[184:185]
	v_pk_add_f32 v[90:91], v[90:91], v[186:187]
	v_pk_add_f32 v[84:85], v[84:85], v[188:189]
	v_pk_add_f32 v[86:87], v[86:87], v[190:191]
	v_pk_add_f32 v[76:77], v[76:77], v[192:193]
	v_pk_add_f32 v[78:79], v[78:79], v[194:195]
	v_pk_add_f32 v[80:81], v[80:81], v[196:197]
	v_pk_add_f32 v[82:83], v[82:83], v[198:199]
	v_pk_add_f32 v[72:73], v[72:73], v[200:201]
	v_pk_add_f32 v[74:75], v[74:75], v[202:203]
	v_pk_add_f32 v[68:69], v[68:69], v[204:205]
	v_pk_add_f32 v[70:71], v[70:71], v[206:207]
	v_pk_add_f32 v[64:65], v[64:65], v[208:209]
	v_pk_add_f32 v[66:67], v[66:67], v[210:211]
	global_store_dwordx4 v226, v[92:95], s[52:53]
	v_add_u32_e32 v144, v217, v233
	global_store_dwordx4 v144, v[88:91], s[52:53]
	global_store_dwordx4 v226, v[84:87], s[52:53] offset:512
	v_add_u32_e32 v144, v217, v233
	global_store_dwordx4 v144, v[76:79], s[52:53] offset:512
	global_store_dwordx4 v227, v[80:83], s[52:53]
	v_add_u32_e32 v144, v218, v233
	global_store_dwordx4 v144, v[72:75], s[52:53]
	global_store_dwordx4 v227, v[68:71], s[52:53] offset:512
	v_add_u32_e32 v144, v218, v233
	global_store_dwordx4 v144, v[64:67], s[52:53] offset:512
	global_load_dwordx4 v[180:183], v230, s[52:53]
	v_add_u32_e32 v144, v222, v233
	global_load_dwordx4 v[184:187], v144, s[52:53]
	global_load_dwordx4 v[188:191], v230, s[52:53] offset:512
	v_add_u32_e32 v144, v222, v233
	global_load_dwordx4 v[192:195], v144, s[52:53] offset:512
	global_load_dwordx4 v[196:199], v231, s[52:53]
	v_add_u32_e32 v144, v223, v233
	global_load_dwordx4 v[200:203], v144, s[52:53]
	global_load_dwordx4 v[204:207], v231, s[52:53] offset:512
	v_add_u32_e32 v144, v223, v233
	global_load_dwordx4 v[208:211], v144, s[52:53] offset:512
	s_waitcnt vmcnt(16)
;     __device__ __forceinline__ void operator()(AccRef acc, const Unit& u, int wr, int wc, int fr, int fq) const {
;     ...
;                         for (int n = 0; n < 2; ++n) bs[m][bj][n] = *(const f32x4*)(base + (size_t)(row0 + ai * 128 + (2 * mh + m) * 16) * D + col0 + bj * 128 + n * 16);
; #pragma unroll
;                 for (int m = 0; m < 2; ++m)
; #pragma unroll
;                     for (int bj = 0; bj < 2; ++bj)
; #pragma unroll
;                         for (int n = 0; n < 2; ++n) *(f32x4*)(out + (size_t)(row0 + ai * 128 + (2 * mh + m) * 16) * D + col0 + bj * 128 + n * 16) = bs[m][bj][n] + sv[bj][n] * (acc[ai][bj][2 * mh + m][n] + bv[bj][n]);
;                 asm volatile("" ::: "memory"); }
	v_mov_b32_e32 v212, v60
	v_mov_b32_e32 v213, v61
	v_mov_b32_e32 v214, v62
	v_mov_b32_e32 v215, v63
	s_nop 0
	v_mov_b32_dpp v60, v56 row_shr:8 row_mask:0xf bank_mask:0xc
	v_mov_b32_dpp v61, v57 row_shr:8 row_mask:0xf bank_mask:0xc
	v_mov_b32_dpp v62, v58 row_shr:8 row_mask:0xf bank_mask:0xc
	v_mov_b32_dpp v63, v59 row_shr:8 row_mask:0xf bank_mask:0xc
	v_mov_b32_dpp v56, v212 row_shl:8 row_mask:0xf bank_mask:0x3
	v_mov_b32_dpp v57, v213 row_shl:8 row_mask:0xf bank_mask:0x3
	v_mov_b32_dpp v58, v214 row_shl:8 row_mask:0xf bank_mask:0x3
	v_mov_b32_dpp v59, v215 row_shl:8 row_mask:0xf bank_mask:0x3
	v_mov_b32_e32 v212, v52
	v_mov_b32_e32 v213, v53
	v_mov_b32_e32 v214, v54
	v_mov_b32_e32 v215, v55
	s_nop 0
	v_mov_b32_dpp v52, v44 row_shr:8 row_mask:0xf bank_mask:0xc
	v_mov_b32_dpp v53, v45 row_shr:8 row_mask:0xf bank_mask:0xc
	v_mov_b32_dpp v54, v46 row_shr:8 row_mask:0xf bank_mask:0xc
	v_mov_b32_dpp v55, v47 row_shr:8 row_mask:0xf bank_mask:0xc
	v_mov_b32_dpp v44, v212 row_shl:8 row_mask:0xf bank_mask:0x3
	v_mov_b32_dpp v45, v213 row_shl:8 row_mask:0xf bank_mask:0x3
	v_mov_b32_dpp v46, v214 row_shl:8 row_mask:0xf bank_mask:0x3
	v_mov_b32_dpp v47, v215 row_shl:8 row_mask:0xf bank_mask:0x3
	v_mov_b32_e32 v212, v48
	v_mov_b32_e32 v213, v49
	v_mov_b32_e32 v214, v50
	v_mov_b32_e32 v215, v51
	s_nop 0
	v_mov_b32_dpp v48, v40 row_shr:8 row_mask:0xf bank_mask:0xc
	v_mov_b32_dpp v49, v41 row_shr:8 row_mask:0xf bank_mask:0xc
	v_mov_b32_dpp v50, v42 row_shr:8 row_mask:0xf bank_mask:0xc
	v_mov_b32_dpp v51, v43 row_shr:8 row_mask:0xf bank_mask:0xc
	v_mov_b32_dpp v40, v212 row_shl:8 row_mask:0xf bank_mask:0x3
	v_mov_b32_dpp v41, v213 row_shl:8 row_mask:0xf bank_mask:0x3
	v_mov_b32_dpp v42, v214 row_shl:8 row_mask:0xf bank_mask:0x3
	v_mov_b32_dpp v43, v215 row_shl:8 row_mask:0xf bank_mask:0x3
	v_mov_b32_e32 v212, v36
	v_mov_b32_e32 v213, v37
	v_mov_b32_e32 v214, v38
	v_mov_b32_e32 v215, v39
	s_nop 0
	v_mov_b32_dpp v36, v32 row_shr:8 row_mask:0xf bank_mask:0xc
	v_mov_b32_dpp v37, v33 row_shr:8 row_mask:0xf bank_mask:0xc
	v_mov_b32_dpp v38, v34 row_shr:8 row_mask:0xf bank_mask:0xc
	v_mov_b32_dpp v39, v35 row_shr:8 row_mask:0xf bank_mask:0xc
	v_mov_b32_dpp v32, v212 row_shl:8 row_mask:0xf bank_mask:0x3
	v_mov_b32_dpp v33, v213 row_shl:8 row_mask:0xf bank_mask:0x3
	v_mov_b32_dpp v34, v214 row_shl:8 row_mask:0xf bank_mask:0x3
	v_mov_b32_dpp v35, v215 row_shl:8 row_mask:0xf bank_mask:0x3
	v_pk_add_f32 v[60:61], v[60:61], v[140:141]
	v_pk_add_f32 v[62:63], v[62:63], v[142:143]
	v_pk_add_f32 v[56:57], v[56:57], v[152:153]
	v_pk_add_f32 v[58:59], v[58:59], v[154:155]
	v_pk_add_f32 v[52:53], v[52:53], v[156:157]
	v_pk_add_f32 v[54:55], v[54:55], v[158:159]
	v_pk_add_f32 v[44:45], v[44:45], v[160:161]
	v_pk_add_f32 v[46:47], v[46:47], v[162:163]
	v_pk_add_f32 v[48:49], v[48:49], v[164:165]
	v_pk_add_f32 v[50:51], v[50:51], v[166:167]
	v_pk_add_f32 v[40:41], v[40:41], v[168:169]
	v_pk_add_f32 v[42:43], v[42:43], v[170:171]
	v_pk_add_f32 v[36:37], v[36:37], v[172:173]
	v_pk_add_f32 v[38:39], v[38:39], v[174:175]
	v_pk_add_f32 v[32:33], v[32:33], v[176:177]
	v_pk_add_f32 v[34:35], v[34:35], v[178:179]
	global_store_dwordx4 v228, v[60:63], s[52:53]
	v_add_u32_e32 v144, v220, v233
	global_store_dwordx4 v144, v[56:59], s[52:53]
	global_store_dwordx4 v228, v[52:55], s[52:53] offset:512
	v_add_u32_e32 v144, v220, v233
	global_store_dwordx4 v144, v[44:47], s[52:53] offset:512
	global_store_dwordx4 v229, v[48:51], s[52:53]
	v_add_u32_e32 v144, v221, v233
	global_store_dwordx4 v144, v[40:43], s[52:53]
	global_store_dwordx4 v229, v[36:39], s[52:53] offset:512
	v_add_u32_e32 v144, v221, v233
	global_store_dwordx4 v144, v[32:35], s[52:53] offset:512
	s_waitcnt vmcnt(8)
; #define PG8_WAIT_V(n) asm volatile("s_waitcnt vmcnt(" #n ")" ::: "memory")
; #define PG8_BAR __builtin_amdgcn_s_barrier()
; template <class Epi>
; __device__ __forceinline__ void gemm_phase(LAS unsigned char* lds, const Gemm g, const StaticOrder& S, const Epi& E) {
;     ...
;     PG8_WAIT_V(0);
;     if (wr == 0) PG8_BAR;
;     PG8_BAR;
;     __device__ __forceinline__ void operator()(AccRef acc, const Unit& u, int wr, int wc, int fr, int fq) const {
;     ...
;                         for (int n = 0; n < 2; ++n) bs[m][bj][n] = *(const f32x4*)(base + (size_t)(row0 + ai * 128 + (2 * mh + m) * 16) * D + col0 + bj * 128 + n * 16);
; #pragma unroll
;                 for (int m = 0; m < 2; ++m)
; #pragma unroll
;                     for (int bj = 0; bj < 2; ++bj)
; #pragma unroll
;                         for (int n = 0; n < 2; ++n) *(f32x4*)(out + (size_t)(row0 + ai * 128 + (2 * mh + m) * 16) * D + col0 + bj * 128 + n * 16) = bs[m][bj][n] + sv[bj][n] * (acc[ai][bj][2 * mh + m][n] + bv[bj][n]);
;                 asm volatile("" ::: "memory"); }
	v_mov_b32_e32 v212, v28
	v_mov_b32_e32 v213, v29
	v_mov_b32_e32 v214, v30
	v_mov_b32_e32 v215, v31
	s_nop 0
	v_mov_b32_dpp v28, v24 row_shr:8 row_mask:0xf bank_mask:0xc
	v_mov_b32_dpp v29, v25 row_shr:8 row_mask:0xf bank_mask:0xc
	v_mov_b32_dpp v30, v26 row_shr:8 row_mask:0xf bank_mask:0xc
	v_mov_b32_dpp v31, v27 row_shr:8 row_mask:0xf bank_mask:0xc
	v_mov_b32_dpp v24, v212 row_shl:8 row_mask:0xf bank_mask:0x3
	v_mov_b32_dpp v25, v213 row_shl:8 row_mask:0xf bank_mask:0x3
	v_mov_b32_dpp v26, v214 row_shl:8 row_mask:0xf bank_mask:0x3
	v_mov_b32_dpp v27, v215 row_shl:8 row_mask:0xf bank_mask:0x3
	v_mov_b32_e32 v212, v20
	v_mov_b32_e32 v213, v21
	v_mov_b32_e32 v214, v22
	v_mov_b32_e32 v215, v23
	s_nop 0
	v_mov_b32_dpp v20, v12 row_shr:8 row_mask:0xf bank_mask:0xc
	v_mov_b32_dpp v21, v13 row_shr:8 row_mask:0xf bank_mask:0xc
	v_mov_b32_dpp v22, v14 row_shr:8 row_mask:0xf bank_mask:0xc
	v_mov_b32_dpp v23, v15 row_shr:8 row_mask:0xf bank_mask:0xc
	v_mov_b32_dpp v12, v212 row_shl:8 row_mask:0xf bank_mask:0x3
	v_mov_b32_dpp v13, v213 row_shl:8 row_mask:0xf bank_mask:0x3
	v_mov_b32_dpp v14, v214 row_shl:8 row_mask:0xf bank_mask:0x3
	v_mov_b32_dpp v15, v215 row_shl:8 row_mask:0xf bank_mask:0x3
	v_mov_b32_e32 v212, v16
	v_mov_b32_e32 v213, v17
	v_mov_b32_e32 v214, v18
	v_mov_b32_e32 v215, v19
	s_nop 0
	v_mov_b32_dpp v16, v8 row_shr:8 row_mask:0xf bank_mask:0xc
	v_mov_b32_dpp v17, v9 row_shr:8 row_mask:0xf bank_mask:0xc
	v_mov_b32_dpp v18, v10 row_shr:8 row_mask:0xf bank_mask:0xc
	v_mov_b32_dpp v19, v11 row_shr:8 row_mask:0xf bank_mask:0xc
	v_mov_b32_dpp v8, v212 row_shl:8 row_mask:0xf bank_mask:0x3
	v_mov_b32_dpp v9, v213 row_shl:8 row_mask:0xf bank_mask:0x3
	v_mov_b32_dpp v10, v214 row_shl:8 row_mask:0xf bank_mask:0x3
	v_mov_b32_dpp v11, v215 row_shl:8 row_mask:0xf bank_mask:0x3
	v_mov_b32_e32 v212, v4
	v_mov_b32_e32 v213, v5
	v_mov_b32_e32 v214, v6
	v_mov_b32_e32 v215, v7
	s_nop 0
	v_mov_b32_dpp v4, v0 row_shr:8 row_mask:0xf bank_mask:0xc
	v_mov_b32_dpp v5, v1 row_shr:8 row_mask:0xf bank_mask:0xc
	v_mov_b32_dpp v6, v2 row_shr:8 row_mask:0xf bank_mask:0xc
	v_mov_b32_dpp v7, v3 row_shr:8 row_mask:0xf bank_mask:0xc
	v_mov_b32_dpp v0, v212 row_shl:8 row_mask:0xf bank_mask:0x3
	v_mov_b32_dpp v1, v213 row_shl:8 row_mask:0xf bank_mask:0x3
	v_mov_b32_dpp v2, v214 row_shl:8 row_mask:0xf bank_mask:0x3
	v_mov_b32_dpp v3, v215 row_shl:8 row_mask:0xf bank_mask:0x3
	v_pk_add_f32 v[28:29], v[28:29], v[180:181]
	v_pk_add_f32 v[30:31], v[30:31], v[182:183]
	v_pk_add_f32 v[24:25], v[24:25], v[184:185]
	v_pk_add_f32 v[26:27], v[26:27], v[186:187]
	v_pk_add_f32 v[20:21], v[20:21], v[188:189]
	v_pk_add_f32 v[22:23], v[22:23], v[190:191]
	v_pk_add_f32 v[12:13], v[12:13], v[192:193]
	v_pk_add_f32 v[14:15], v[14:15], v[194:195]
	v_pk_add_f32 v[16:17], v[16:17], v[196:197]
	v_pk_add_f32 v[18:19], v[18:19], v[198:199]
	v_pk_add_f32 v[8:9], v[8:9], v[200:201]
	v_pk_add_f32 v[10:11], v[10:11], v[202:203]
	v_pk_add_f32 v[4:5], v[4:5], v[204:205]
	v_pk_add_f32 v[6:7], v[6:7], v[206:207]
	v_pk_add_f32 v[0:1], v[0:1], v[208:209]
	v_pk_add_f32 v[2:3], v[2:3], v[210:211]
	global_store_dwordx4 v230, v[28:31], s[52:53]
	v_add_u32_e32 v144, v222, v233
	global_store_dwordx4 v144, v[24:27], s[52:53]
	global_store_dwordx4 v230, v[20:23], s[52:53] offset:512
	v_add_u32_e32 v144, v222, v233
	global_store_dwordx4 v144, v[12:15], s[52:53] offset:512
	global_store_dwordx4 v231, v[16:19], s[52:53]
	v_add_u32_e32 v144, v223, v233
	global_store_dwordx4 v144, v[8:11], s[52:53]
	global_store_dwordx4 v231, v[4:7], s[52:53] offset:512
	v_add_u32_e32 v144, v223, v233
	global_store_dwordx4 v144, v[0:3], s[52:53] offset:512
	s_cbranch_vccz .LBB0_2031
	s_waitcnt vmcnt(0)
	s_cmpk_gt_u32 s26, 0xff
	s_cbranch_scc1 .LBB0_2046
	s_barrier
